# GEMM k-loops: staging load / LDS write / fragment reads issued between individual MFMAs (in their issue shadow) instead of between groups of four
# speedup vs baseline: 1.0059x; 1.0050x over previous
; template <int MODE>
; __device__ __forceinline__ void gemm_tile(const Params& P, int tm, int tn, unsigned char* smem) {
;     ...
;     const int srow = tid >> 3, sc = tid & 7;
;     constexpr unsigned LDA = (MODE == 2 ? NZ : 1024) * 2u;
;     unsigned aoff, boff; int soff0;
;     {
;         int ar = m0 + srow;
;         if (MODE == 2) { const int b = ar >> 11, t = ar & 2047; ar = b * L + NMETA + t; }
;         aoff = (unsigned)ar * LDA + (unsigned)sc * 16u;
;         boff = (unsigned)(n0 + srow) * 2048u + (unsigned)sc * 16u;
;         soff0 = srow * 128 + ((sc ^ (srow & 7)) << 4);
;     }
;     const unsigned char* Ab = (const unsigned char*)A; const unsigned char* Bb = (const unsigned char*)Bt;
;     float4 ssp0, ssp1, ssp2, ssp3;
;     if (MODE == 3) {
;         const float* ssq = (const float*)(P.ws + WS_SSQ) + (size_t)(m0 + wr * 64 + lr) * 16 + 4 * g;
;         ssp0 = *(const float4*)(ssq); ssp1 = *(const float4*)(ssq + 16 * 16); ssp2 = *(const float4*)(ssq + 32 * 16); ssp3 = *(const float4*)(ssq + 48 * 16);
;     }
;     f32x4 acc[4][4];
; #pragma unroll
;     for (int i = 0; i < 4; ++i)
; #pragma unroll
;         for (int j = 0; j < 4; ++j) acc[i][j] = (f32x4){0.f, 0.f, 0.f, 0.f};
;     uint4 ra0, ra1, ra2, ra3, rb0, rb1, rb2, rb3;
;     ...
;     unsigned char* sA0 = smem; unsigned char* sB0 = smem + 16384; unsigned char* sA1 = smem + 32768; unsigned char* sB1 = smem + 49152;
;     G_LOAD(0)
;     G_WRITE(sA0, sB0)
;     __syncthreads();
;     const int arow_off = (wr * 64 + lr) * 128, brow_off = (wc * 64 + lr) * 128, sw = lr & 7;
;     G_LOAD(1)
;     for (int kt = 0; kt < 16; ++kt) {
;         unsigned char* sA = (kt & 1) ? sA1 : sA0; unsigned char* sB = (kt & 1) ? sB1 : sB0;
;         unsigned char* nA = (kt & 1) ? sA0 : sA1; unsigned char* nB = (kt & 1) ? sB0 : sB1;
;         bf16x8 fa[4], fb[4], ga[4], gb[4];
;         const int ch0 = ((g ^ sw) << 4), ch1 = (((4 + g) ^ sw) << 4);
;         const unsigned ko = (unsigned)(kt + 2) * 128u;
;         const unsigned koa = ko + ((MODE == 2 && kt + 2 >= 8) ? (unsigned)(ZC_FQ - 512) * 2u : 0u);
;         const bool wr_ok = kt < 15, ld_ok = kt < 14;
; #pragma unroll
;         for (int i = 0; i < 4; ++i) { fa[i] = *(const bf16x8*)(sA + arow_off + i * 2048 + ch0); fb[i] = *(const bf16x8*)(sB + brow_off + i * 2048 + ch0); }
;         __builtin_amdgcn_sched_barrier(0);
;         __builtin_amdgcn_s_setprio(2);
.LBB0_182:
	s_mul_hi_i32 s0, s35, 0x92492493
	s_add_i32 s0, s0, s35
	s_lshr_b32 s1, s0, 31
	s_ashr_i32 s0, s0, 7
	s_add_i32 s1, s0, s1
	s_mul_i32 s0, s1, 0xffffff20
	s_lshl_b32 s10, s1, 3
	s_add_i32 s0, s35, s0
	s_sub_i32 s10, 0x81, s10
	s_cmpk_gt_i32 s35, 0xdff
	s_cselect_b32 s10, s10, 8
	s_abs_i32 s11, s10
	v_cvt_f32_u32_e32 v2, s11
	s_ashr_i32 s0, s0, 31
	s_mul_i32 s13, s1, 0xe0
	s_sub_i32 s13, s0, s13
	v_rcp_iflag_f32_e32 v2, v2
	s_ashr_i32 s12, s10, 31
	s_add_i32 s13, s35, s13
	s_xor_b32 s12, s0, s12
	v_mul_f32_e32 v2, 0x4f7ffffe, v2
	v_cvt_u32_f32_e32 v2, v2
	s_xor_b32 s0, s13, s0
	s_sub_i32 s13, 0, s11
	s_mulk_i32 s1, 0xd8
	v_readfirstlane_b32 s42, v2
	s_mul_i32 s13, s13, s42
	s_mul_hi_u32 s13, s42, s13
	s_add_i32 s42, s42, s13
	s_mul_hi_u32 s13, s0, s42
	s_mul_i32 s42, s13, s11
	s_sub_i32 s0, s0, s42
	s_add_i32 s42, s13, 1
	s_sub_i32 s43, s0, s11
	s_cmp_ge_u32 s0, s11
	s_cselect_b32 s13, s42, s13
	s_cselect_b32 s0, s43, s0
	s_add_i32 s42, s13, 1
	s_cmp_ge_u32 s0, s11
	s_cselect_b32 s0, s42, s13
	s_xor_b32 s0, s0, s12
	s_sub_i32 s0, s0, s12
	s_mul_i32 s10, s10, s0
	s_add_i32 s10, s10, s1
	s_sub_i32 s1, s35, s10
	v_mov_b32_e32 v79, v0
	s_lshl_b32 s42, s1, 7
	v_ashrrev_i32_e32 v2, 3, v79
	v_lshlrev_b32_e32 v4, 4, v79
	s_lshl_b32 s10, s0, 7
	v_add_u32_e32 v3, s42, v2
	v_and_b32_e32 v4, 0x70, v4
	v_add_u32_e32 v5, s10, v2
	v_lshl_or_b32 v8, v3, 11, v4
	v_lshl_or_b32 v5, v5, 11, v4
	v_add_u32_e32 v3, 0x10000, v8
	v_add_u32_e32 v4, 0x20000, v8
	global_load_dwordx4 v[10:13], v3, s[36:37]
	global_load_dwordx4 v[14:17], v4, s[36:37]
	v_add_u32_e32 v3, 0x20000, v5
	v_add_u32_e32 v4, 0x30000, v5
	global_load_dwordx4 v[18:21], v3, s[4:5]
	global_load_dwordx4 v[22:25], v4, s[4:5]
	global_load_dwordx4 v[26:29], v8, s[36:37]
	global_load_dwordx4 v[30:33], v5, s[4:5]
	v_add_u32_e32 v3, 0x30000, v8
	v_add_u32_e32 v4, 0x10000, v5
	global_load_dwordx4 v[34:37], v3, s[36:37]
	global_load_dwordx4 v[38:41], v4, s[4:5]
	v_xor_b32_e32 v3, v2, v79
	v_lshlrev_b32_e32 v2, 7, v2
	v_lshlrev_b32_e32 v3, 4, v3
	v_and_or_b32 v2, v3, s20, v2
	v_add_u32_e32 v2, 0, v2
	v_or_b32_e32 v9, 0x80, v8
	v_or_b32_e32 v3, 0x80, v5
	v_add_u32_e32 v4, 0x10080, v5
	v_add_u32_e32 v6, 0x20080, v5
	v_add_u32_e32 v7, 0x30080, v5
	v_add_u32_e32 v42, 0x10080, v8
	v_add_u32_e32 v43, 0x20080, v8
	v_add_u32_e32 v44, 0x30080, v8
	v_and_b32_e32 v80, 15, v79
	v_ashrrev_i32_e32 v81, 7, v79
	v_bfe_u32 v82, v79, 6, 1
	v_bfe_u32 v83, v79, 4, 2
	s_waitcnt vmcnt(5)
	ds_write_b128 v2, v[18:21] offset:24576
	s_waitcnt vmcnt(4)
	ds_write_b128 v2, v[22:25] offset:28672
	s_waitcnt vmcnt(3)
	ds_write_b128 v2, v[26:29]
	s_waitcnt vmcnt(2)
	ds_write_b128 v2, v[30:33] offset:16384
	ds_write_b128 v2, v[10:13] offset:4096
	ds_write_b128 v2, v[14:17] offset:8192
	s_waitcnt vmcnt(1)
	ds_write_b128 v2, v[34:37] offset:12288
	s_waitcnt vmcnt(0)
	ds_write_b128 v2, v[38:41] offset:20480
	s_waitcnt lgkmcnt(0)
	s_barrier
	global_load_dwordx4 v[10:13], v9, s[36:37]
	global_load_dwordx4 v[14:17], v42, s[36:37]
	global_load_dwordx4 v[18:21], v43, s[36:37]
	global_load_dwordx4 v[22:25], v44, s[36:37]
	global_load_dwordx4 v[26:29], v3, s[4:5]
	global_load_dwordx4 v[30:33], v4, s[4:5]
	global_load_dwordx4 v[34:37], v6, s[4:5]
	global_load_dwordx4 v[38:41], v7, s[4:5]
	v_lshrrev_b32_e32 v3, 4, v79
	v_lshlrev_b32_e32 v4, 7, v80
	v_and_b32_e32 v9, 7, v79
	v_lshl_or_b32 v6, v81, 13, v4
	v_bitop3_b32 v3, v3, v9, 3 bitop3:0x6c
	v_lshl_or_b32 v4, v82, 13, v4
	v_lshlrev_b32_e32 v3, 4, v3
	v_add_u32_e32 v66, 0, v6
	v_add_u32_e32 v6, v66, v3
	v_add_u32_e32 v4, 0, v4
	v_add_u32_e32 v7, v4, v3
	ds_read_b128 v[42:45], v6
	ds_read_b128 v[46:49], v6 offset:2048
	ds_read_b128 v[50:53], v7 offset:16384
	ds_read_b128 v[54:57], v7 offset:18432
	ds_read_b128 v[58:61], v6 offset:4096
	ds_read_b128 v[62:65], v6 offset:6144
	ds_read_b128 v[84:87], v7 offset:20480
	ds_read_b128 v[88:91], v7 offset:22528
	v_bitop3_b32 v3, v83, v9, 4 bitop3:0x36
	v_lshlrev_b32_e32 v9, 4, v3
	s_setprio 2
	global_load_dwordx4 v[92:95], v8, s[36:37] offset:256
	s_waitcnt vmcnt(8)
	ds_write_b128 v2, v[10:13] offset:32768
	v_add_u32_e32 v3, v66, v9
	v_add_u32_e32 v4, v4, v9
	ds_read_b128 v[10:13], v3
	ds_read_b128 v[96:99], v4 offset:16384
	s_waitcnt lgkmcnt(8)
	v_mfma_f32_16x16x32_bf16 v[100:103], v[50:53], v[42:45], 0
	s_waitcnt lgkmcnt(7)
	v_mfma_f32_16x16x32_bf16 v[104:107], v[54:57], v[42:45], 0
	s_waitcnt lgkmcnt(4)
	v_mfma_f32_16x16x32_bf16 v[108:111], v[84:87], v[42:45], 0
	s_waitcnt lgkmcnt(3)
	v_mfma_f32_16x16x32_bf16 v[42:45], v[88:91], v[42:45], 0
	v_add_u32_e32 v216, 0x10000, v8
	global_load_dwordx4 v[112:115], v216, s[36:37] offset:256
	s_waitcnt vmcnt(8)
	ds_write_b128 v2, v[14:17] offset:36864
	ds_read_b128 v[14:17], v3 offset:2048
	ds_read_b128 v[116:119], v4 offset:18432
	v_mfma_f32_16x16x32_bf16 v[120:123], v[50:53], v[46:49], 0
	v_mfma_f32_16x16x32_bf16 v[124:127], v[54:57], v[46:49], 0
	v_mfma_f32_16x16x32_bf16 v[132:135], v[84:87], v[46:49], 0
	v_mfma_f32_16x16x32_bf16 v[46:49], v[88:91], v[46:49], 0
	v_add_u32_e32 v217, 0x20000, v8
	global_load_dwordx4 v[146:149], v217, s[36:37] offset:256
	s_waitcnt vmcnt(8)
	ds_write_b128 v2, v[18:21] offset:40960
	ds_read_b128 v[18:21], v3 offset:4096
	ds_read_b128 v[150:153], v4 offset:20480
	v_mfma_f32_16x16x32_bf16 v[154:157], v[50:53], v[58:61], 0
	v_mfma_f32_16x16x32_bf16 v[158:161], v[54:57], v[58:61], 0
	v_mfma_f32_16x16x32_bf16 v[162:165], v[84:87], v[58:61], 0
	v_mfma_f32_16x16x32_bf16 v[58:61], v[88:91], v[58:61], 0
	v_add_u32_e32 v218, 0x30000, v8
	global_load_dwordx4 v[166:169], v218, s[36:37] offset:256
	s_waitcnt vmcnt(8)
; template <int MODE>
; __device__ __forceinline__ void gemm_tile(const Params& P, int tm, int tn, unsigned char* smem) {
;     ...
; #pragma unroll
;         for (int i = 0; i < 4; ++i) { fa[i] = *(const bf16x8*)(sA + arow_off + i * 2048 + ch0); fb[i] = *(const bf16x8*)(sB + brow_off + i * 2048 + ch0); }
;         __builtin_amdgcn_sched_barrier(0);
;         __builtin_amdgcn_s_setprio(2);
;         if (wr_ok) *(uint4*)(nA + soff0) = ra0;
;         if (ld_ok) ra0 = *(const uint4*)(Ab + (aoff + 0u * LDA + koa));
;         ga[0] = *(const bf16x8*)(sA + arow_off + 0 * 2048 + ch1); gb[0] = *(const bf16x8*)(sB + brow_off + 0 * 2048 + ch1);
;         __builtin_amdgcn_sched_barrier(0);
; #pragma unroll
;         for (int j = 0; j < 4; ++j) acc[0][j] = __builtin_amdgcn_mfma_f32_16x16x32_bf16(fb[j], fa[0], acc[0][j], 0, 0, 0);
;         __builtin_amdgcn_sched_barrier(0);
;         if (wr_ok) *(uint4*)(nA + soff0 + 4096) = ra1;
;         if (ld_ok) ra1 = *(const uint4*)(Ab + (aoff + 32u * LDA + koa));
;         ga[1] = *(const bf16x8*)(sA + arow_off + 1 * 2048 + ch1); gb[1] = *(const bf16x8*)(sB + brow_off + 1 * 2048 + ch1);
;         __builtin_amdgcn_sched_barrier(0);
; #pragma unroll
;         for (int j = 0; j < 4; ++j) acc[1][j] = __builtin_amdgcn_mfma_f32_16x16x32_bf16(fb[j], fa[1], acc[1][j], 0, 0, 0);
;         __builtin_amdgcn_sched_barrier(0);
;         if (wr_ok) *(uint4*)(nA + soff0 + 8192) = ra2;
;         if (ld_ok) ra2 = *(const uint4*)(Ab + (aoff + 64u * LDA + koa));
;         ga[2] = *(const bf16x8*)(sA + arow_off + 2 * 2048 + ch1); gb[2] = *(const bf16x8*)(sB + brow_off + 2 * 2048 + ch1);
;         __builtin_amdgcn_sched_barrier(0);
; #pragma unroll
;         for (int j = 0; j < 4; ++j) acc[2][j] = __builtin_amdgcn_mfma_f32_16x16x32_bf16(fb[j], fa[2], acc[2][j], 0, 0, 0);
;         __builtin_amdgcn_sched_barrier(0);
;         if (wr_ok) *(uint4*)(nA + soff0 + 12288) = ra3;
;         if (ld_ok) ra3 = *(const uint4*)(Ab + (aoff + 96u * LDA + koa));
;         ga[3] = *(const bf16x8*)(sA + arow_off + 3 * 2048 + ch1); gb[3] = *(const bf16x8*)(sB + brow_off + 3 * 2048 + ch1);
;         __builtin_amdgcn_sched_barrier(0);
; #pragma unroll
;         for (int j = 0; j < 4; ++j) acc[3][j] = __builtin_amdgcn_mfma_f32_16x16x32_bf16(fb[j], fa[3], acc[3][j], 0, 0, 0);
;         __builtin_amdgcn_sched_barrier(0);
;         if (wr_ok) *(uint4*)(nB + soff0) = rb0;
	ds_write_b128 v2, v[22:25] offset:45056
	ds_read_b128 v[22:25], v3 offset:6144
	ds_read_b128 v[170:173], v4 offset:22528
	v_mfma_f32_16x16x32_bf16 v[50:53], v[50:53], v[62:65], 0
	v_mfma_f32_16x16x32_bf16 v[54:57], v[54:57], v[62:65], 0
	v_mfma_f32_16x16x32_bf16 v[84:87], v[84:87], v[62:65], 0
	v_mfma_f32_16x16x32_bf16 v[62:65], v[88:91], v[62:65], 0
	global_load_dwordx4 v[88:91], v5, s[4:5] offset:256
	s_waitcnt vmcnt(8)
	ds_write_b128 v2, v[26:29] offset:49152
	s_waitcnt lgkmcnt(10)
	v_mfma_f32_16x16x32_bf16 v[26:29], v[96:99], v[10:13], v[100:103]
	s_waitcnt lgkmcnt(7)
	v_mfma_f32_16x16x32_bf16 v[100:103], v[116:119], v[10:13], v[104:107]
	s_waitcnt lgkmcnt(4)
	v_mfma_f32_16x16x32_bf16 v[104:107], v[150:153], v[10:13], v[108:111]
	s_waitcnt lgkmcnt(1)
	v_mfma_f32_16x16x32_bf16 v[10:13], v[170:173], v[10:13], v[42:45]
	v_add_u32_e32 v219, 0x10000, v5
	global_load_dwordx4 v[42:45], v219, s[4:5] offset:256
	s_waitcnt vmcnt(8)
	ds_write_b128 v2, v[30:33] offset:53248
	v_mfma_f32_16x16x32_bf16 v[30:33], v[96:99], v[14:17], v[120:123]
	v_mfma_f32_16x16x32_bf16 v[108:111], v[116:119], v[14:17], v[124:127]
	v_mfma_f32_16x16x32_bf16 v[120:123], v[150:153], v[14:17], v[132:135]
	v_mfma_f32_16x16x32_bf16 v[14:17], v[170:173], v[14:17], v[46:49]
	v_add_u32_e32 v220, 0x20000, v5
	global_load_dwordx4 v[46:49], v220, s[4:5] offset:256
	s_waitcnt vmcnt(8)
	ds_write_b128 v2, v[34:37] offset:57344
	v_mfma_f32_16x16x32_bf16 v[34:37], v[96:99], v[18:21], v[154:157]
	v_mfma_f32_16x16x32_bf16 v[124:127], v[116:119], v[18:21], v[158:161]
	v_mfma_f32_16x16x32_bf16 v[132:135], v[150:153], v[18:21], v[162:165]
	v_mfma_f32_16x16x32_bf16 v[18:21], v[170:173], v[18:21], v[58:61]
	v_add_u32_e32 v221, 0x30000, v5
	global_load_dwordx4 v[58:61], v221, s[4:5] offset:256
	s_waitcnt vmcnt(8)
	ds_write_b128 v2, v[38:41] offset:61440
	v_mfma_f32_16x16x32_bf16 v[38:41], v[96:99], v[22:25], v[50:53]
	v_mfma_f32_16x16x32_bf16 v[50:53], v[116:119], v[22:25], v[54:57]
	v_mfma_f32_16x16x32_bf16 v[54:57], v[150:153], v[22:25], v[84:87]
	v_mfma_f32_16x16x32_bf16 v[22:25], v[170:173], v[22:25], v[62:65]
	s_setprio 0
	s_waitcnt lgkmcnt(0)
	s_barrier
	ds_read_b128 v[62:65], v6 offset:32768
	ds_read_b128 v[84:87], v6 offset:34816
	ds_read_b128 v[96:99], v7 offset:49152
	ds_read_b128 v[116:119], v7 offset:51200
	ds_read_b128 v[150:153], v6 offset:36864
	ds_read_b128 v[154:157], v6 offset:38912
	ds_read_b128 v[158:161], v7 offset:53248
	ds_read_b128 v[162:165], v7 offset:55296
	s_setprio 2
	global_load_dwordx4 v[170:173], v8, s[36:37] offset:384
	s_waitcnt vmcnt(8)
	ds_write_b128 v2, v[92:95]
	ds_read_b128 v[92:95], v3 offset:32768
	ds_read_b128 v[174:177], v4 offset:49152
	s_waitcnt lgkmcnt(8)
	v_mfma_f32_16x16x32_bf16 v[26:29], v[96:99], v[62:65], v[26:29]
	s_waitcnt lgkmcnt(3)
	v_mfma_f32_16x16x32_bf16 v[10:13], v[162:165], v[62:65], v[10:13]
	v_mfma_f32_16x16x32_bf16 v[100:103], v[116:119], v[62:65], v[100:103]
	v_mfma_f32_16x16x32_bf16 v[104:107], v[158:161], v[62:65], v[104:107]
	global_load_dwordx4 v[62:65], v216, s[36:37] offset:384
	v_mfma_f32_16x16x32_bf16 v[30:33], v[96:99], v[84:87], v[30:33]
	s_waitcnt vmcnt(8)
	ds_write_b128 v2, v[112:115] offset:4096
	v_mfma_f32_16x16x32_bf16 v[14:17], v[162:165], v[84:87], v[14:17]
	ds_read_b128 v[112:115], v3 offset:34816
	v_mfma_f32_16x16x32_bf16 v[108:111], v[116:119], v[84:87], v[108:111]
	ds_read_b128 v[178:181], v4 offset:51200
	v_mfma_f32_16x16x32_bf16 v[120:123], v[158:161], v[84:87], v[120:123]
	global_load_dwordx4 v[84:87], v217, s[36:37] offset:384
	v_mfma_f32_16x16x32_bf16 v[34:37], v[96:99], v[150:153], v[34:37]
	s_waitcnt vmcnt(8)
	ds_write_b128 v2, v[146:149] offset:8192
	v_mfma_f32_16x16x32_bf16 v[18:21], v[162:165], v[150:153], v[18:21]
	ds_read_b128 v[146:149], v3 offset:36864
	v_mfma_f32_16x16x32_bf16 v[124:127], v[116:119], v[150:153], v[124:127]
	ds_read_b128 v[182:185], v4 offset:53248
	v_mfma_f32_16x16x32_bf16 v[132:135], v[158:161], v[150:153], v[132:135]
	global_load_dwordx4 v[150:153], v218, s[36:37] offset:384
	v_mfma_f32_16x16x32_bf16 v[38:41], v[96:99], v[154:157], v[38:41]
	s_waitcnt vmcnt(8)
	ds_write_b128 v2, v[166:169] offset:12288
	v_mfma_f32_16x16x32_bf16 v[50:53], v[116:119], v[154:157], v[50:53]
	ds_read_b128 v[166:169], v3 offset:38912
	v_mfma_f32_16x16x32_bf16 v[54:57], v[158:161], v[154:157], v[54:57]
	ds_read_b128 v[186:189], v4 offset:55296
	v_mfma_f32_16x16x32_bf16 v[22:25], v[162:165], v[154:157], v[22:25]
	global_load_dwordx4 v[96:99], v5, s[4:5] offset:384
	s_waitcnt vmcnt(8)
	ds_write_b128 v2, v[88:91] offset:16384
	s_waitcnt lgkmcnt(10)
	v_mfma_f32_16x16x32_bf16 v[26:29], v[174:177], v[92:95], v[26:29]
	s_waitcnt lgkmcnt(1)
	v_mfma_f32_16x16x32_bf16 v[10:13], v[186:189], v[92:95], v[10:13]
	v_mfma_f32_16x16x32_bf16 v[88:91], v[178:181], v[92:95], v[100:103]
	v_mfma_f32_16x16x32_bf16 v[100:103], v[182:185], v[92:95], v[104:107]
	global_load_dwordx4 v[92:95], v219, s[4:5] offset:384
	s_waitcnt vmcnt(8)
	ds_write_b128 v2, v[42:45] offset:20480
	v_mfma_f32_16x16x32_bf16 v[30:33], v[174:177], v[112:115], v[30:33]
	v_mfma_f32_16x16x32_bf16 v[42:45], v[178:181], v[112:115], v[108:111]
	v_mfma_f32_16x16x32_bf16 v[14:17], v[186:189], v[112:115], v[14:17]
	v_mfma_f32_16x16x32_bf16 v[104:107], v[182:185], v[112:115], v[120:123]
	global_load_dwordx4 v[108:111], v220, s[4:5] offset:384
	s_waitcnt vmcnt(8)
	ds_write_b128 v2, v[46:49] offset:24576
	v_mfma_f32_16x16x32_bf16 v[34:37], v[174:177], v[146:149], v[34:37]
	v_mfma_f32_16x16x32_bf16 v[46:49], v[178:181], v[146:149], v[124:127]
	v_mfma_f32_16x16x32_bf16 v[18:21], v[186:189], v[146:149], v[18:21]
	v_mfma_f32_16x16x32_bf16 v[112:115], v[182:185], v[146:149], v[132:135]
	global_load_dwordx4 v[116:119], v221, s[4:5] offset:384
	v_mfma_f32_16x16x32_bf16 v[38:41], v[174:177], v[166:169], v[38:41]
	s_waitcnt vmcnt(8)
	ds_write_b128 v2, v[58:61] offset:28672
	v_mfma_f32_16x16x32_bf16 v[50:53], v[178:181], v[166:169], v[50:53]
	v_mfma_f32_16x16x32_bf16 v[54:57], v[182:185], v[166:169], v[54:57]
	v_mfma_f32_16x16x32_bf16 v[22:25], v[186:189], v[166:169], v[22:25]
	s_setprio 0
	s_waitcnt lgkmcnt(0)
	s_barrier
; template <int MODE>
; __device__ __forceinline__ void gemm_tile(const Params& P, int tm, int tn, unsigned char* smem) {
;     ...
; #pragma unroll
;         for (int i = 0; i < 4; ++i) { fa[i] = *(const bf16x8*)(sA + arow_off + i * 2048 + ch0); fb[i] = *(const bf16x8*)(sB + brow_off + i * 2048 + ch0); }
;         __builtin_amdgcn_sched_barrier(0);
;         __builtin_amdgcn_s_setprio(2);
;         if (wr_ok) *(uint4*)(nA + soff0) = ra0;
;         if (ld_ok) ra0 = *(const uint4*)(Ab + (aoff + 0u * LDA + koa));
;         ga[0] = *(const bf16x8*)(sA + arow_off + 0 * 2048 + ch1); gb[0] = *(const bf16x8*)(sB + brow_off + 0 * 2048 + ch1);
;         __builtin_amdgcn_sched_barrier(0);
; #pragma unroll
;         for (int j = 0; j < 4; ++j) acc[0][j] = __builtin_amdgcn_mfma_f32_16x16x32_bf16(fb[j], fa[0], acc[0][j], 0, 0, 0);
;         __builtin_amdgcn_sched_barrier(0);
;         if (wr_ok) *(uint4*)(nA + soff0 + 4096) = ra1;
;         if (ld_ok) ra1 = *(const uint4*)(Ab + (aoff + 32u * LDA + koa));
;         ga[1] = *(const bf16x8*)(sA + arow_off + 1 * 2048 + ch1); gb[1] = *(const bf16x8*)(sB + brow_off + 1 * 2048 + ch1);
;         __builtin_amdgcn_sched_barrier(0);
; #pragma unroll
;         for (int j = 0; j < 4; ++j) acc[1][j] = __builtin_amdgcn_mfma_f32_16x16x32_bf16(fb[j], fa[1], acc[1][j], 0, 0, 0);
;         __builtin_amdgcn_sched_barrier(0);
;         if (wr_ok) *(uint4*)(nA + soff0 + 8192) = ra2;
;         if (ld_ok) ra2 = *(const uint4*)(Ab + (aoff + 64u * LDA + koa));
;         ga[2] = *(const bf16x8*)(sA + arow_off + 2 * 2048 + ch1); gb[2] = *(const bf16x8*)(sB + brow_off + 2 * 2048 + ch1);
;         __builtin_amdgcn_sched_barrier(0);
; #pragma unroll
;         for (int j = 0; j < 4; ++j) acc[2][j] = __builtin_amdgcn_mfma_f32_16x16x32_bf16(fb[j], fa[2], acc[2][j], 0, 0, 0);
;         __builtin_amdgcn_sched_barrier(0);
;         if (wr_ok) *(uint4*)(nA + soff0 + 12288) = ra3;
;         if (ld_ok) ra3 = *(const uint4*)(Ab + (aoff + 96u * LDA + koa));
;         ga[3] = *(const bf16x8*)(sA + arow_off + 3 * 2048 + ch1); gb[3] = *(const bf16x8*)(sB + brow_off + 3 * 2048 + ch1);
;         __builtin_amdgcn_sched_barrier(0);
; #pragma unroll
;         for (int j = 0; j < 4; ++j) acc[3][j] = __builtin_amdgcn_mfma_f32_16x16x32_bf16(fb[j], fa[3], acc[3][j], 0, 0, 0);
;         __builtin_amdgcn_sched_barrier(0);
;         if (wr_ok) *(uint4*)(nB + soff0) = rb0;
	ds_read_b128 v[58:61], v6
	ds_read_b128 v[120:123], v6 offset:2048
	ds_read_b128 v[124:127], v7 offset:16384
	ds_read_b128 v[132:135], v7 offset:18432
	ds_read_b128 v[146:149], v6 offset:4096
	ds_read_b128 v[154:157], v6 offset:6144
	ds_read_b128 v[158:161], v7 offset:20480
	ds_read_b128 v[162:165], v7 offset:22528
	s_setprio 2
	global_load_dwordx4 v[166:169], v8, s[36:37] offset:512
	s_waitcnt vmcnt(8)
	ds_write_b128 v2, v[170:173] offset:32768
	ds_read_b128 v[170:173], v3
	ds_read_b128 v[174:177], v4 offset:16384
	s_waitcnt lgkmcnt(8)
	v_mfma_f32_16x16x32_bf16 v[26:29], v[124:127], v[58:61], v[26:29]
	s_waitcnt lgkmcnt(3)
	v_mfma_f32_16x16x32_bf16 v[10:13], v[162:165], v[58:61], v[10:13]
	v_mfma_f32_16x16x32_bf16 v[88:91], v[132:135], v[58:61], v[88:91]
	v_mfma_f32_16x16x32_bf16 v[100:103], v[158:161], v[58:61], v[100:103]
	global_load_dwordx4 v[58:61], v216, s[36:37] offset:512
	v_mfma_f32_16x16x32_bf16 v[30:33], v[124:127], v[120:123], v[30:33]
	s_waitcnt vmcnt(8)
	ds_write_b128 v2, v[62:65] offset:36864
	v_mfma_f32_16x16x32_bf16 v[42:45], v[132:135], v[120:123], v[42:45]
	ds_read_b128 v[62:65], v3 offset:2048
	v_mfma_f32_16x16x32_bf16 v[14:17], v[162:165], v[120:123], v[14:17]
	ds_read_b128 v[178:181], v4 offset:18432
	v_mfma_f32_16x16x32_bf16 v[104:107], v[158:161], v[120:123], v[104:107]
	global_load_dwordx4 v[120:123], v217, s[36:37] offset:512
	v_mfma_f32_16x16x32_bf16 v[34:37], v[124:127], v[146:149], v[34:37]
	s_waitcnt vmcnt(8)
	ds_write_b128 v2, v[84:87] offset:40960
	v_mfma_f32_16x16x32_bf16 v[46:49], v[132:135], v[146:149], v[46:49]
	ds_read_b128 v[84:87], v3 offset:4096
	v_mfma_f32_16x16x32_bf16 v[18:21], v[162:165], v[146:149], v[18:21]
	ds_read_b128 v[182:185], v4 offset:20480
	v_mfma_f32_16x16x32_bf16 v[112:115], v[158:161], v[146:149], v[112:115]
	global_load_dwordx4 v[146:149], v218, s[36:37] offset:512
	v_mfma_f32_16x16x32_bf16 v[38:41], v[124:127], v[154:157], v[38:41]
	s_waitcnt vmcnt(8)
	ds_write_b128 v2, v[150:153] offset:45056
	v_mfma_f32_16x16x32_bf16 v[50:53], v[132:135], v[154:157], v[50:53]
	ds_read_b128 v[150:153], v3 offset:6144
	v_mfma_f32_16x16x32_bf16 v[54:57], v[158:161], v[154:157], v[54:57]
	ds_read_b128 v[186:189], v4 offset:22528
	v_mfma_f32_16x16x32_bf16 v[22:25], v[162:165], v[154:157], v[22:25]
	global_load_dwordx4 v[124:127], v5, s[4:5] offset:512
	s_waitcnt vmcnt(8)
	ds_write_b128 v2, v[96:99] offset:49152
	s_waitcnt lgkmcnt(10)
	v_mfma_f32_16x16x32_bf16 v[26:29], v[174:177], v[170:173], v[26:29]
	s_waitcnt lgkmcnt(1)
	v_mfma_f32_16x16x32_bf16 v[10:13], v[186:189], v[170:173], v[10:13]
	v_mfma_f32_16x16x32_bf16 v[88:91], v[178:181], v[170:173], v[88:91]
	v_mfma_f32_16x16x32_bf16 v[96:99], v[182:185], v[170:173], v[100:103]
	global_load_dwordx4 v[100:103], v219, s[4:5] offset:512
	s_waitcnt vmcnt(8)
	ds_write_b128 v2, v[92:95] offset:53248
	v_mfma_f32_16x16x32_bf16 v[30:33], v[174:177], v[62:65], v[30:33]
	v_mfma_f32_16x16x32_bf16 v[42:45], v[178:181], v[62:65], v[42:45]
	v_mfma_f32_16x16x32_bf16 v[14:17], v[186:189], v[62:65], v[14:17]
	v_mfma_f32_16x16x32_bf16 v[92:95], v[182:185], v[62:65], v[104:107]
	global_load_dwordx4 v[62:65], v220, s[4:5] offset:512
	v_mfma_f32_16x16x32_bf16 v[34:37], v[174:177], v[84:87], v[34:37]
	s_waitcnt vmcnt(8)
	ds_write_b128 v2, v[108:111] offset:57344
	v_mfma_f32_16x16x32_bf16 v[46:49], v[178:181], v[84:87], v[46:49]
	v_mfma_f32_16x16x32_bf16 v[18:21], v[186:189], v[84:87], v[18:21]
	v_mfma_f32_16x16x32_bf16 v[104:107], v[182:185], v[84:87], v[112:115]
	global_load_dwordx4 v[84:87], v221, s[4:5] offset:512
	v_mfma_f32_16x16x32_bf16 v[38:41], v[174:177], v[150:153], v[38:41]
	s_waitcnt vmcnt(8)
	ds_write_b128 v2, v[116:119] offset:61440
	v_mfma_f32_16x16x32_bf16 v[50:53], v[178:181], v[150:153], v[50:53]
	v_mfma_f32_16x16x32_bf16 v[54:57], v[182:185], v[150:153], v[54:57]
	v_mfma_f32_16x16x32_bf16 v[22:25], v[186:189], v[150:153], v[22:25]
	s_setprio 0
	s_waitcnt lgkmcnt(0)
	s_barrier
	ds_read_b128 v[108:111], v6 offset:32768
	ds_read_b128 v[112:115], v6 offset:34816
	ds_read_b128 v[116:119], v7 offset:49152
	ds_read_b128 v[132:135], v7 offset:51200
	ds_read_b128 v[150:153], v6 offset:36864
	ds_read_b128 v[154:157], v6 offset:38912
	ds_read_b128 v[158:161], v7 offset:53248
	ds_read_b128 v[162:165], v7 offset:55296
	s_setprio 2
	global_load_dwordx4 v[170:173], v8, s[36:37] offset:640
	s_waitcnt vmcnt(8)
	ds_write_b128 v2, v[166:169]
	ds_read_b128 v[166:169], v3 offset:32768
	ds_read_b128 v[174:177], v4 offset:49152
	s_waitcnt lgkmcnt(8)
	v_mfma_f32_16x16x32_bf16 v[26:29], v[116:119], v[108:111], v[26:29]
	s_waitcnt lgkmcnt(3)
	v_mfma_f32_16x16x32_bf16 v[10:13], v[162:165], v[108:111], v[10:13]
	v_mfma_f32_16x16x32_bf16 v[88:91], v[132:135], v[108:111], v[88:91]
	v_mfma_f32_16x16x32_bf16 v[96:99], v[158:161], v[108:111], v[96:99]
	global_load_dwordx4 v[108:111], v216, s[36:37] offset:640
	v_mfma_f32_16x16x32_bf16 v[30:33], v[116:119], v[112:115], v[30:33]
	s_waitcnt vmcnt(8)
	ds_write_b128 v2, v[58:61] offset:4096
	v_mfma_f32_16x16x32_bf16 v[42:45], v[132:135], v[112:115], v[42:45]
	ds_read_b128 v[58:61], v3 offset:34816
	v_mfma_f32_16x16x32_bf16 v[14:17], v[162:165], v[112:115], v[14:17]
	ds_read_b128 v[178:181], v4 offset:51200
	v_mfma_f32_16x16x32_bf16 v[92:95], v[158:161], v[112:115], v[92:95]
	global_load_dwordx4 v[112:115], v217, s[36:37] offset:640
	v_mfma_f32_16x16x32_bf16 v[34:37], v[116:119], v[150:153], v[34:37]
	s_waitcnt vmcnt(8)
; template <int MODE>
; __device__ __forceinline__ void gemm_tile(const Params& P, int tm, int tn, unsigned char* smem) {
;     ...
; #pragma unroll
;         for (int i = 0; i < 4; ++i) { fa[i] = *(const bf16x8*)(sA + arow_off + i * 2048 + ch0); fb[i] = *(const bf16x8*)(sB + brow_off + i * 2048 + ch0); }
;         __builtin_amdgcn_sched_barrier(0);
;         __builtin_amdgcn_s_setprio(2);
;         if (wr_ok) *(uint4*)(nA + soff0) = ra0;
;         if (ld_ok) ra0 = *(const uint4*)(Ab + (aoff + 0u * LDA + koa));
;         ga[0] = *(const bf16x8*)(sA + arow_off + 0 * 2048 + ch1); gb[0] = *(const bf16x8*)(sB + brow_off + 0 * 2048 + ch1);
;         __builtin_amdgcn_sched_barrier(0);
; #pragma unroll
;         for (int j = 0; j < 4; ++j) acc[0][j] = __builtin_amdgcn_mfma_f32_16x16x32_bf16(fb[j], fa[0], acc[0][j], 0, 0, 0);
;         __builtin_amdgcn_sched_barrier(0);
;         if (wr_ok) *(uint4*)(nA + soff0 + 4096) = ra1;
;         if (ld_ok) ra1 = *(const uint4*)(Ab + (aoff + 32u * LDA + koa));
;         ga[1] = *(const bf16x8*)(sA + arow_off + 1 * 2048 + ch1); gb[1] = *(const bf16x8*)(sB + brow_off + 1 * 2048 + ch1);
;         __builtin_amdgcn_sched_barrier(0);
; #pragma unroll
;         for (int j = 0; j < 4; ++j) acc[1][j] = __builtin_amdgcn_mfma_f32_16x16x32_bf16(fb[j], fa[1], acc[1][j], 0, 0, 0);
;         __builtin_amdgcn_sched_barrier(0);
;         if (wr_ok) *(uint4*)(nA + soff0 + 8192) = ra2;
;         if (ld_ok) ra2 = *(const uint4*)(Ab + (aoff + 64u * LDA + koa));
;         ga[2] = *(const bf16x8*)(sA + arow_off + 2 * 2048 + ch1); gb[2] = *(const bf16x8*)(sB + brow_off + 2 * 2048 + ch1);
;         __builtin_amdgcn_sched_barrier(0);
; #pragma unroll
;         for (int j = 0; j < 4; ++j) acc[2][j] = __builtin_amdgcn_mfma_f32_16x16x32_bf16(fb[j], fa[2], acc[2][j], 0, 0, 0);
;         __builtin_amdgcn_sched_barrier(0);
;         if (wr_ok) *(uint4*)(nA + soff0 + 12288) = ra3;
;         if (ld_ok) ra3 = *(const uint4*)(Ab + (aoff + 96u * LDA + koa));
;         ga[3] = *(const bf16x8*)(sA + arow_off + 3 * 2048 + ch1); gb[3] = *(const bf16x8*)(sB + brow_off + 3 * 2048 + ch1);
;         __builtin_amdgcn_sched_barrier(0);
; #pragma unroll
;         for (int j = 0; j < 4; ++j) acc[3][j] = __builtin_amdgcn_mfma_f32_16x16x32_bf16(fb[j], fa[3], acc[3][j], 0, 0, 0);
;         __builtin_amdgcn_sched_barrier(0);
;         if (wr_ok) *(uint4*)(nB + soff0) = rb0;
	ds_write_b128 v2, v[120:123] offset:8192
	v_mfma_f32_16x16x32_bf16 v[46:49], v[132:135], v[150:153], v[46:49]
	ds_read_b128 v[120:123], v3 offset:36864
	v_mfma_f32_16x16x32_bf16 v[18:21], v[162:165], v[150:153], v[18:21]
	ds_read_b128 v[182:185], v4 offset:53248
	v_mfma_f32_16x16x32_bf16 v[104:107], v[158:161], v[150:153], v[104:107]
	global_load_dwordx4 v[150:153], v218, s[36:37] offset:640
	v_mfma_f32_16x16x32_bf16 v[38:41], v[116:119], v[154:157], v[38:41]
	s_waitcnt vmcnt(8)
	ds_write_b128 v2, v[146:149] offset:12288
	v_mfma_f32_16x16x32_bf16 v[50:53], v[132:135], v[154:157], v[50:53]
	ds_read_b128 v[146:149], v3 offset:38912
	v_mfma_f32_16x16x32_bf16 v[54:57], v[158:161], v[154:157], v[54:57]
	ds_read_b128 v[186:189], v4 offset:55296
	v_mfma_f32_16x16x32_bf16 v[22:25], v[162:165], v[154:157], v[22:25]
	global_load_dwordx4 v[116:119], v5, s[4:5] offset:640
	s_waitcnt vmcnt(8)
	ds_write_b128 v2, v[124:127] offset:16384
	s_waitcnt lgkmcnt(10)
	v_mfma_f32_16x16x32_bf16 v[26:29], v[174:177], v[166:169], v[26:29]
	s_waitcnt lgkmcnt(1)
	v_mfma_f32_16x16x32_bf16 v[10:13], v[186:189], v[166:169], v[10:13]
	v_mfma_f32_16x16x32_bf16 v[88:91], v[178:181], v[166:169], v[88:91]
	v_mfma_f32_16x16x32_bf16 v[96:99], v[182:185], v[166:169], v[96:99]
	global_load_dwordx4 v[124:127], v219, s[4:5] offset:640
	v_mfma_f32_16x16x32_bf16 v[30:33], v[174:177], v[58:61], v[30:33]
	s_waitcnt vmcnt(8)
	ds_write_b128 v2, v[100:103] offset:20480
	v_mfma_f32_16x16x32_bf16 v[42:45], v[178:181], v[58:61], v[42:45]
	v_mfma_f32_16x16x32_bf16 v[14:17], v[186:189], v[58:61], v[14:17]
	v_mfma_f32_16x16x32_bf16 v[92:95], v[182:185], v[58:61], v[92:95]
	global_load_dwordx4 v[58:61], v220, s[4:5] offset:640
	s_waitcnt vmcnt(8)
	ds_write_b128 v2, v[62:65] offset:24576
	v_mfma_f32_16x16x32_bf16 v[34:37], v[174:177], v[120:123], v[34:37]
	v_mfma_f32_16x16x32_bf16 v[46:49], v[178:181], v[120:123], v[46:49]
	v_mfma_f32_16x16x32_bf16 v[62:65], v[182:185], v[120:123], v[104:107]
	v_mfma_f32_16x16x32_bf16 v[18:21], v[186:189], v[120:123], v[18:21]
	global_load_dwordx4 v[100:103], v221, s[4:5] offset:640
	v_mfma_f32_16x16x32_bf16 v[38:41], v[174:177], v[146:149], v[38:41]
	s_waitcnt vmcnt(8)
	ds_write_b128 v2, v[84:87] offset:28672
	v_mfma_f32_16x16x32_bf16 v[50:53], v[178:181], v[146:149], v[50:53]
	v_mfma_f32_16x16x32_bf16 v[54:57], v[182:185], v[146:149], v[54:57]
	v_mfma_f32_16x16x32_bf16 v[22:25], v[186:189], v[146:149], v[22:25]
	s_setprio 0
	s_waitcnt lgkmcnt(0)
	s_barrier
	ds_read_b128 v[84:87], v6
	ds_read_b128 v[104:107], v6 offset:2048
	ds_read_b128 v[120:123], v7 offset:16384
	ds_read_b128 v[132:135], v7 offset:18432
	ds_read_b128 v[146:149], v6 offset:4096
	ds_read_b128 v[154:157], v6 offset:6144
	ds_read_b128 v[158:161], v7 offset:20480
	ds_read_b128 v[162:165], v7 offset:22528
	s_setprio 2
	global_load_dwordx4 v[166:169], v8, s[36:37] offset:768
	s_waitcnt vmcnt(8)
	ds_write_b128 v2, v[170:173] offset:32768
	ds_read_b128 v[170:173], v3
	ds_read_b128 v[174:177], v4 offset:16384
	s_waitcnt lgkmcnt(8)
	v_mfma_f32_16x16x32_bf16 v[26:29], v[120:123], v[84:87], v[26:29]
	s_waitcnt lgkmcnt(3)
	v_mfma_f32_16x16x32_bf16 v[10:13], v[162:165], v[84:87], v[10:13]
	v_mfma_f32_16x16x32_bf16 v[88:91], v[132:135], v[84:87], v[88:91]
	v_mfma_f32_16x16x32_bf16 v[96:99], v[158:161], v[84:87], v[96:99]
	global_load_dwordx4 v[84:87], v216, s[36:37] offset:768
	v_mfma_f32_16x16x32_bf16 v[30:33], v[120:123], v[104:107], v[30:33]
	s_waitcnt vmcnt(8)
	ds_write_b128 v2, v[108:111] offset:36864
	v_mfma_f32_16x16x32_bf16 v[42:45], v[132:135], v[104:107], v[42:45]
	ds_read_b128 v[108:111], v3 offset:2048
	v_mfma_f32_16x16x32_bf16 v[14:17], v[162:165], v[104:107], v[14:17]
	ds_read_b128 v[178:181], v4 offset:18432
	v_mfma_f32_16x16x32_bf16 v[92:95], v[158:161], v[104:107], v[92:95]
	global_load_dwordx4 v[104:107], v217, s[36:37] offset:768
	v_mfma_f32_16x16x32_bf16 v[34:37], v[120:123], v[146:149], v[34:37]
	s_waitcnt vmcnt(8)
	ds_write_b128 v2, v[112:115] offset:40960
	v_mfma_f32_16x16x32_bf16 v[46:49], v[132:135], v[146:149], v[46:49]
	ds_read_b128 v[112:115], v3 offset:4096
	v_mfma_f32_16x16x32_bf16 v[62:65], v[158:161], v[146:149], v[62:65]
	ds_read_b128 v[182:185], v4 offset:20480
	v_mfma_f32_16x16x32_bf16 v[18:21], v[162:165], v[146:149], v[18:21]
	global_load_dwordx4 v[146:149], v218, s[36:37] offset:768
	v_mfma_f32_16x16x32_bf16 v[38:41], v[120:123], v[154:157], v[38:41]
	s_waitcnt vmcnt(8)
	ds_write_b128 v2, v[150:153] offset:45056
	v_mfma_f32_16x16x32_bf16 v[50:53], v[132:135], v[154:157], v[50:53]
	ds_read_b128 v[150:153], v3 offset:6144
	v_mfma_f32_16x16x32_bf16 v[54:57], v[158:161], v[154:157], v[54:57]
	ds_read_b128 v[186:189], v4 offset:22528
	v_mfma_f32_16x16x32_bf16 v[22:25], v[162:165], v[154:157], v[22:25]
	global_load_dwordx4 v[120:123], v5, s[4:5] offset:768
	s_waitcnt vmcnt(8)
	ds_write_b128 v2, v[116:119] offset:49152
	s_waitcnt lgkmcnt(10)
	v_mfma_f32_16x16x32_bf16 v[26:29], v[174:177], v[170:173], v[26:29]
	s_waitcnt lgkmcnt(1)
	v_mfma_f32_16x16x32_bf16 v[10:13], v[186:189], v[170:173], v[10:13]
	v_mfma_f32_16x16x32_bf16 v[88:91], v[178:181], v[170:173], v[88:91]
	v_mfma_f32_16x16x32_bf16 v[96:99], v[182:185], v[170:173], v[96:99]
	global_load_dwordx4 v[116:119], v219, s[4:5] offset:768
	v_mfma_f32_16x16x32_bf16 v[30:33], v[174:177], v[108:111], v[30:33]
	s_waitcnt vmcnt(8)
	ds_write_b128 v2, v[124:127] offset:53248
	v_mfma_f32_16x16x32_bf16 v[42:45], v[178:181], v[108:111], v[42:45]
	v_mfma_f32_16x16x32_bf16 v[14:17], v[186:189], v[108:111], v[14:17]
	v_mfma_f32_16x16x32_bf16 v[92:95], v[182:185], v[108:111], v[92:95]
	global_load_dwordx4 v[108:111], v220, s[4:5] offset:768
	s_waitcnt vmcnt(8)
	ds_write_b128 v2, v[58:61] offset:57344
	v_mfma_f32_16x16x32_bf16 v[34:37], v[174:177], v[112:115], v[34:37]
	v_mfma_f32_16x16x32_bf16 v[46:49], v[178:181], v[112:115], v[46:49]
	v_mfma_f32_16x16x32_bf16 v[58:61], v[182:185], v[112:115], v[62:65]
	v_mfma_f32_16x16x32_bf16 v[18:21], v[186:189], v[112:115], v[18:21]
	global_load_dwordx4 v[62:65], v221, s[4:5] offset:768
	v_mfma_f32_16x16x32_bf16 v[38:41], v[174:177], v[150:153], v[38:41]
	s_waitcnt vmcnt(8)
	ds_write_b128 v2, v[100:103] offset:61440
	v_mfma_f32_16x16x32_bf16 v[50:53], v[178:181], v[150:153], v[50:53]
	v_mfma_f32_16x16x32_bf16 v[54:57], v[182:185], v[150:153], v[54:57]
	v_mfma_f32_16x16x32_bf16 v[22:25], v[186:189], v[150:153], v[22:25]
	s_setprio 0
	s_waitcnt lgkmcnt(0)
	s_barrier
; template <int MODE>
; __device__ __forceinline__ void gemm_tile(const Params& P, int tm, int tn, unsigned char* smem) {
;     ...
; #pragma unroll
;         for (int i = 0; i < 4; ++i) { fa[i] = *(const bf16x8*)(sA + arow_off + i * 2048 + ch0); fb[i] = *(const bf16x8*)(sB + brow_off + i * 2048 + ch0); }
;         __builtin_amdgcn_sched_barrier(0);
;         __builtin_amdgcn_s_setprio(2);
;         if (wr_ok) *(uint4*)(nA + soff0) = ra0;
;         if (ld_ok) ra0 = *(const uint4*)(Ab + (aoff + 0u * LDA + koa));
;         ga[0] = *(const bf16x8*)(sA + arow_off + 0 * 2048 + ch1); gb[0] = *(const bf16x8*)(sB + brow_off + 0 * 2048 + ch1);
;         __builtin_amdgcn_sched_barrier(0);
; #pragma unroll
;         for (int j = 0; j < 4; ++j) acc[0][j] = __builtin_amdgcn_mfma_f32_16x16x32_bf16(fb[j], fa[0], acc[0][j], 0, 0, 0);
;         __builtin_amdgcn_sched_barrier(0);
;         if (wr_ok) *(uint4*)(nA + soff0 + 4096) = ra1;
;         if (ld_ok) ra1 = *(const uint4*)(Ab + (aoff + 32u * LDA + koa));
;         ga[1] = *(const bf16x8*)(sA + arow_off + 1 * 2048 + ch1); gb[1] = *(const bf16x8*)(sB + brow_off + 1 * 2048 + ch1);
;         __builtin_amdgcn_sched_barrier(0);
; #pragma unroll
;         for (int j = 0; j < 4; ++j) acc[1][j] = __builtin_amdgcn_mfma_f32_16x16x32_bf16(fb[j], fa[1], acc[1][j], 0, 0, 0);
;         __builtin_amdgcn_sched_barrier(0);
;         if (wr_ok) *(uint4*)(nA + soff0 + 8192) = ra2;
;         if (ld_ok) ra2 = *(const uint4*)(Ab + (aoff + 64u * LDA + koa));
;         ga[2] = *(const bf16x8*)(sA + arow_off + 2 * 2048 + ch1); gb[2] = *(const bf16x8*)(sB + brow_off + 2 * 2048 + ch1);
;         __builtin_amdgcn_sched_barrier(0);
; #pragma unroll
;         for (int j = 0; j < 4; ++j) acc[2][j] = __builtin_amdgcn_mfma_f32_16x16x32_bf16(fb[j], fa[2], acc[2][j], 0, 0, 0);
;         __builtin_amdgcn_sched_barrier(0);
;         if (wr_ok) *(uint4*)(nA + soff0 + 12288) = ra3;
;         if (ld_ok) ra3 = *(const uint4*)(Ab + (aoff + 96u * LDA + koa));
;         ga[3] = *(const bf16x8*)(sA + arow_off + 3 * 2048 + ch1); gb[3] = *(const bf16x8*)(sB + brow_off + 3 * 2048 + ch1);
;         __builtin_amdgcn_sched_barrier(0);
; #pragma unroll
;         for (int j = 0; j < 4; ++j) acc[3][j] = __builtin_amdgcn_mfma_f32_16x16x32_bf16(fb[j], fa[3], acc[3][j], 0, 0, 0);
;         __builtin_amdgcn_sched_barrier(0);
;         if (wr_ok) *(uint4*)(nB + soff0) = rb0;
	ds_read_b128 v[100:103], v6 offset:32768
	ds_read_b128 v[112:115], v6 offset:34816
	ds_read_b128 v[124:127], v7 offset:49152
	ds_read_b128 v[132:135], v7 offset:51200
	ds_read_b128 v[150:153], v6 offset:36864
	ds_read_b128 v[154:157], v6 offset:38912
	ds_read_b128 v[158:161], v7 offset:53248
	ds_read_b128 v[162:165], v7 offset:55296
	s_setprio 2
	global_load_dwordx4 v[170:173], v8, s[36:37] offset:896
	s_waitcnt vmcnt(8)
	ds_write_b128 v2, v[166:169]
	ds_read_b128 v[166:169], v3 offset:32768
	ds_read_b128 v[174:177], v4 offset:49152
	s_waitcnt lgkmcnt(8)
	v_mfma_f32_16x16x32_bf16 v[26:29], v[124:127], v[100:103], v[26:29]
	s_waitcnt lgkmcnt(3)
	v_mfma_f32_16x16x32_bf16 v[10:13], v[162:165], v[100:103], v[10:13]
	v_mfma_f32_16x16x32_bf16 v[88:91], v[132:135], v[100:103], v[88:91]
	v_mfma_f32_16x16x32_bf16 v[96:99], v[158:161], v[100:103], v[96:99]
	global_load_dwordx4 v[100:103], v216, s[36:37] offset:896
	v_mfma_f32_16x16x32_bf16 v[30:33], v[124:127], v[112:115], v[30:33]
	s_waitcnt vmcnt(8)
	ds_write_b128 v2, v[84:87] offset:4096
	v_mfma_f32_16x16x32_bf16 v[42:45], v[132:135], v[112:115], v[42:45]
	ds_read_b128 v[84:87], v3 offset:34816
	v_mfma_f32_16x16x32_bf16 v[14:17], v[162:165], v[112:115], v[14:17]
	ds_read_b128 v[178:181], v4 offset:51200
	v_mfma_f32_16x16x32_bf16 v[92:95], v[158:161], v[112:115], v[92:95]
	global_load_dwordx4 v[112:115], v217, s[36:37] offset:896
	v_mfma_f32_16x16x32_bf16 v[34:37], v[124:127], v[150:153], v[34:37]
	s_waitcnt vmcnt(8)
	ds_write_b128 v2, v[104:107] offset:8192
	v_mfma_f32_16x16x32_bf16 v[46:49], v[132:135], v[150:153], v[46:49]
	ds_read_b128 v[104:107], v3 offset:36864
	v_mfma_f32_16x16x32_bf16 v[58:61], v[158:161], v[150:153], v[58:61]
	ds_read_b128 v[182:185], v4 offset:53248
	v_mfma_f32_16x16x32_bf16 v[18:21], v[162:165], v[150:153], v[18:21]
	global_load_dwordx4 v[150:153], v218, s[36:37] offset:896
	v_mfma_f32_16x16x32_bf16 v[38:41], v[124:127], v[154:157], v[38:41]
	s_waitcnt vmcnt(8)
	ds_write_b128 v2, v[146:149] offset:12288
	v_mfma_f32_16x16x32_bf16 v[50:53], v[132:135], v[154:157], v[50:53]
	ds_read_b128 v[146:149], v3 offset:38912
	v_mfma_f32_16x16x32_bf16 v[54:57], v[158:161], v[154:157], v[54:57]
	ds_read_b128 v[186:189], v4 offset:55296
	v_mfma_f32_16x16x32_bf16 v[22:25], v[162:165], v[154:157], v[22:25]
	global_load_dwordx4 v[124:127], v5, s[4:5] offset:896
	s_waitcnt vmcnt(8)
	ds_write_b128 v2, v[120:123] offset:16384
	s_waitcnt lgkmcnt(10)
	v_mfma_f32_16x16x32_bf16 v[26:29], v[174:177], v[166:169], v[26:29]
	s_waitcnt lgkmcnt(1)
	v_mfma_f32_16x16x32_bf16 v[10:13], v[186:189], v[166:169], v[10:13]
	v_mfma_f32_16x16x32_bf16 v[88:91], v[178:181], v[166:169], v[88:91]
	v_mfma_f32_16x16x32_bf16 v[96:99], v[182:185], v[166:169], v[96:99]
	global_load_dwordx4 v[120:123], v219, s[4:5] offset:896
	v_mfma_f32_16x16x32_bf16 v[30:33], v[174:177], v[84:87], v[30:33]
	s_waitcnt vmcnt(8)
	ds_write_b128 v2, v[116:119] offset:20480
	v_mfma_f32_16x16x32_bf16 v[42:45], v[178:181], v[84:87], v[42:45]
	v_mfma_f32_16x16x32_bf16 v[14:17], v[186:189], v[84:87], v[14:17]
	v_mfma_f32_16x16x32_bf16 v[92:95], v[182:185], v[84:87], v[92:95]
	global_load_dwordx4 v[84:87], v220, s[4:5] offset:896
	v_mfma_f32_16x16x32_bf16 v[34:37], v[174:177], v[104:107], v[34:37]
	s_waitcnt vmcnt(8)
	ds_write_b128 v2, v[108:111] offset:24576
	v_mfma_f32_16x16x32_bf16 v[46:49], v[178:181], v[104:107], v[46:49]
	v_mfma_f32_16x16x32_bf16 v[58:61], v[182:185], v[104:107], v[58:61]
	v_mfma_f32_16x16x32_bf16 v[18:21], v[186:189], v[104:107], v[18:21]
	global_load_dwordx4 v[104:107], v221, s[4:5] offset:896
	v_mfma_f32_16x16x32_bf16 v[38:41], v[174:177], v[146:149], v[38:41]
	s_waitcnt vmcnt(8)
	ds_write_b128 v2, v[62:65] offset:28672
	v_mfma_f32_16x16x32_bf16 v[50:53], v[178:181], v[146:149], v[50:53]
	v_mfma_f32_16x16x32_bf16 v[54:57], v[182:185], v[146:149], v[54:57]
	v_mfma_f32_16x16x32_bf16 v[22:25], v[186:189], v[146:149], v[22:25]
	s_setprio 0
	s_waitcnt lgkmcnt(0)
	s_barrier
	ds_read_b128 v[62:65], v6
	ds_read_b128 v[108:111], v6 offset:2048
	ds_read_b128 v[116:119], v7 offset:16384
	ds_read_b128 v[132:135], v7 offset:18432
	ds_read_b128 v[146:149], v6 offset:4096
	ds_read_b128 v[154:157], v6 offset:6144
	ds_read_b128 v[158:161], v7 offset:20480
	ds_read_b128 v[162:165], v7 offset:22528
	s_setprio 2
	global_load_dwordx4 v[166:169], v8, s[36:37] offset:1024
	s_waitcnt vmcnt(8)
	ds_write_b128 v2, v[170:173] offset:32768
	ds_read_b128 v[170:173], v3
	ds_read_b128 v[174:177], v4 offset:16384
	s_waitcnt lgkmcnt(8)
	v_mfma_f32_16x16x32_bf16 v[26:29], v[116:119], v[62:65], v[26:29]
	s_waitcnt lgkmcnt(3)
	v_mfma_f32_16x16x32_bf16 v[10:13], v[162:165], v[62:65], v[10:13]
	v_mfma_f32_16x16x32_bf16 v[88:91], v[132:135], v[62:65], v[88:91]
	v_mfma_f32_16x16x32_bf16 v[96:99], v[158:161], v[62:65], v[96:99]
	global_load_dwordx4 v[62:65], v216, s[36:37] offset:1024
	v_mfma_f32_16x16x32_bf16 v[30:33], v[116:119], v[108:111], v[30:33]
	s_waitcnt vmcnt(8)
	ds_write_b128 v2, v[100:103] offset:36864
	v_mfma_f32_16x16x32_bf16 v[42:45], v[132:135], v[108:111], v[42:45]
	ds_read_b128 v[100:103], v3 offset:2048
	v_mfma_f32_16x16x32_bf16 v[14:17], v[162:165], v[108:111], v[14:17]
	ds_read_b128 v[178:181], v4 offset:18432
	v_mfma_f32_16x16x32_bf16 v[92:95], v[158:161], v[108:111], v[92:95]
	global_load_dwordx4 v[108:111], v217, s[36:37] offset:1024
	v_mfma_f32_16x16x32_bf16 v[34:37], v[116:119], v[146:149], v[34:37]
	s_waitcnt vmcnt(8)
; template <int MODE>
; __device__ __forceinline__ void gemm_tile(const Params& P, int tm, int tn, unsigned char* smem) {
;     ...
;     for (int kt = 0; kt < 16; ++kt) {
;         unsigned char* sA = (kt & 1) ? sA1 : sA0; unsigned char* sB = (kt & 1) ? sB1 : sB0;
;         unsigned char* nA = (kt & 1) ? sA0 : sA1; unsigned char* nB = (kt & 1) ? sB0 : sB1;
;         bf16x8 fa[4], fb[4], ga[4], gb[4];
;         const int ch0 = ((g ^ sw) << 4), ch1 = (((4 + g) ^ sw) << 4);
;         const unsigned ko = (unsigned)(kt + 2) * 128u;
;         const unsigned koa = ko + ((MODE == 2 && kt + 2 >= 8) ? (unsigned)(ZC_FQ - 512) * 2u : 0u);
;         const bool wr_ok = kt < 15, ld_ok = kt < 14;
; #pragma unroll
;         for (int i = 0; i < 4; ++i) { fa[i] = *(const bf16x8*)(sA + arow_off + i * 2048 + ch0); fb[i] = *(const bf16x8*)(sB + brow_off + i * 2048 + ch0); }
;         __builtin_amdgcn_sched_barrier(0);
;         __builtin_amdgcn_s_setprio(2);
;         if (wr_ok) *(uint4*)(nA + soff0) = ra0;
;         if (ld_ok) ra0 = *(const uint4*)(Ab + (aoff + 0u * LDA + koa));
;         ga[0] = *(const bf16x8*)(sA + arow_off + 0 * 2048 + ch1); gb[0] = *(const bf16x8*)(sB + brow_off + 0 * 2048 + ch1);
;         __builtin_amdgcn_sched_barrier(0);
; #pragma unroll
;         for (int j = 0; j < 4; ++j) acc[0][j] = __builtin_amdgcn_mfma_f32_16x16x32_bf16(fb[j], fa[0], acc[0][j], 0, 0, 0);
;         __builtin_amdgcn_sched_barrier(0);
;         if (wr_ok) *(uint4*)(nA + soff0 + 4096) = ra1;
;         if (ld_ok) ra1 = *(const uint4*)(Ab + (aoff + 32u * LDA + koa));
;         ga[1] = *(const bf16x8*)(sA + arow_off + 1 * 2048 + ch1); gb[1] = *(const bf16x8*)(sB + brow_off + 1 * 2048 + ch1);
;         __builtin_amdgcn_sched_barrier(0);
; #pragma unroll
;         for (int j = 0; j < 4; ++j) acc[1][j] = __builtin_amdgcn_mfma_f32_16x16x32_bf16(fb[j], fa[1], acc[1][j], 0, 0, 0);
;         __builtin_amdgcn_sched_barrier(0);
;         if (wr_ok) *(uint4*)(nA + soff0 + 8192) = ra2;
;         if (ld_ok) ra2 = *(const uint4*)(Ab + (aoff + 64u * LDA + koa));
;         ga[2] = *(const bf16x8*)(sA + arow_off + 2 * 2048 + ch1); gb[2] = *(const bf16x8*)(sB + brow_off + 2 * 2048 + ch1);
;         __builtin_amdgcn_sched_barrier(0);
; #pragma unroll
;         for (int j = 0; j < 4; ++j) acc[2][j] = __builtin_amdgcn_mfma_f32_16x16x32_bf16(fb[j], fa[2], acc[2][j], 0, 0, 0);
	ds_write_b128 v2, v[112:115] offset:40960
	v_mfma_f32_16x16x32_bf16 v[46:49], v[132:135], v[146:149], v[46:49]
	ds_read_b128 v[112:115], v3 offset:4096
	v_mfma_f32_16x16x32_bf16 v[58:61], v[158:161], v[146:149], v[58:61]
	ds_read_b128 v[182:185], v4 offset:20480
	v_mfma_f32_16x16x32_bf16 v[18:21], v[162:165], v[146:149], v[18:21]
	global_load_dwordx4 v[146:149], v218, s[36:37] offset:1024
	v_mfma_f32_16x16x32_bf16 v[38:41], v[116:119], v[154:157], v[38:41]
	s_waitcnt vmcnt(8)
	ds_write_b128 v2, v[150:153] offset:45056
	v_mfma_f32_16x16x32_bf16 v[50:53], v[132:135], v[154:157], v[50:53]
	ds_read_b128 v[150:153], v3 offset:6144
	v_mfma_f32_16x16x32_bf16 v[54:57], v[158:161], v[154:157], v[54:57]
	ds_read_b128 v[186:189], v4 offset:22528
	v_mfma_f32_16x16x32_bf16 v[22:25], v[162:165], v[154:157], v[22:25]
	global_load_dwordx4 v[116:119], v5, s[4:5] offset:1024
	s_waitcnt vmcnt(8)
	ds_write_b128 v2, v[124:127] offset:49152
	s_waitcnt lgkmcnt(10)
	v_mfma_f32_16x16x32_bf16 v[26:29], v[174:177], v[170:173], v[26:29]
	s_waitcnt lgkmcnt(1)
	v_mfma_f32_16x16x32_bf16 v[10:13], v[186:189], v[170:173], v[10:13]
	v_mfma_f32_16x16x32_bf16 v[88:91], v[178:181], v[170:173], v[88:91]
	v_mfma_f32_16x16x32_bf16 v[96:99], v[182:185], v[170:173], v[96:99]
	global_load_dwordx4 v[124:127], v219, s[4:5] offset:1024
	v_mfma_f32_16x16x32_bf16 v[30:33], v[174:177], v[100:103], v[30:33]
	s_waitcnt vmcnt(8)
	ds_write_b128 v2, v[120:123] offset:53248
	v_mfma_f32_16x16x32_bf16 v[42:45], v[178:181], v[100:103], v[42:45]
	v_mfma_f32_16x16x32_bf16 v[14:17], v[186:189], v[100:103], v[14:17]
	v_mfma_f32_16x16x32_bf16 v[92:95], v[182:185], v[100:103], v[92:95]
	global_load_dwordx4 v[100:103], v220, s[4:5] offset:1024
	v_mfma_f32_16x16x32_bf16 v[34:37], v[174:177], v[112:115], v[34:37]
	s_waitcnt vmcnt(8)
	ds_write_b128 v2, v[84:87] offset:57344
	v_mfma_f32_16x16x32_bf16 v[46:49], v[178:181], v[112:115], v[46:49]
	v_mfma_f32_16x16x32_bf16 v[58:61], v[182:185], v[112:115], v[58:61]
	v_mfma_f32_16x16x32_bf16 v[18:21], v[186:189], v[112:115], v[18:21]
	global_load_dwordx4 v[84:87], v221, s[4:5] offset:1024
	v_mfma_f32_16x16x32_bf16 v[38:41], v[174:177], v[150:153], v[38:41]
	s_waitcnt vmcnt(8)
	ds_write_b128 v2, v[104:107] offset:61440
	v_mfma_f32_16x16x32_bf16 v[50:53], v[178:181], v[150:153], v[50:53]
	v_mfma_f32_16x16x32_bf16 v[54:57], v[182:185], v[150:153], v[54:57]
	v_mfma_f32_16x16x32_bf16 v[22:25], v[186:189], v[150:153], v[22:25]
	s_setprio 0
	s_waitcnt lgkmcnt(0)
	s_barrier
	ds_read_b128 v[104:107], v6 offset:32768
	ds_read_b128 v[112:115], v6 offset:34816
	ds_read_b128 v[120:123], v7 offset:49152
	ds_read_b128 v[132:135], v7 offset:51200
	ds_read_b128 v[150:153], v6 offset:36864
	ds_read_b128 v[154:157], v6 offset:38912
	ds_read_b128 v[158:161], v7 offset:53248
	ds_read_b128 v[162:165], v7 offset:55296
	s_setprio 2
	global_load_dwordx4 v[170:173], v8, s[36:37] offset:1152
	s_waitcnt vmcnt(8)
	ds_write_b128 v2, v[166:169]
	ds_read_b128 v[166:169], v3 offset:32768
	ds_read_b128 v[174:177], v4 offset:49152
	s_waitcnt lgkmcnt(8)
	v_mfma_f32_16x16x32_bf16 v[26:29], v[120:123], v[104:107], v[26:29]
	s_waitcnt lgkmcnt(3)
	v_mfma_f32_16x16x32_bf16 v[10:13], v[162:165], v[104:107], v[10:13]
	v_mfma_f32_16x16x32_bf16 v[88:91], v[132:135], v[104:107], v[88:91]
	v_mfma_f32_16x16x32_bf16 v[96:99], v[158:161], v[104:107], v[96:99]
	global_load_dwordx4 v[104:107], v216, s[36:37] offset:1152
	v_mfma_f32_16x16x32_bf16 v[30:33], v[120:123], v[112:115], v[30:33]
	s_waitcnt vmcnt(8)
	ds_write_b128 v2, v[62:65] offset:4096
	v_mfma_f32_16x16x32_bf16 v[42:45], v[132:135], v[112:115], v[42:45]
	ds_read_b128 v[62:65], v3 offset:34816
	v_mfma_f32_16x16x32_bf16 v[14:17], v[162:165], v[112:115], v[14:17]
	ds_read_b128 v[178:181], v4 offset:51200
	v_mfma_f32_16x16x32_bf16 v[92:95], v[158:161], v[112:115], v[92:95]
	global_load_dwordx4 v[112:115], v217, s[36:37] offset:1152
	v_mfma_f32_16x16x32_bf16 v[34:37], v[120:123], v[150:153], v[34:37]
	s_waitcnt vmcnt(8)
	ds_write_b128 v2, v[108:111] offset:8192
	v_mfma_f32_16x16x32_bf16 v[46:49], v[132:135], v[150:153], v[46:49]
	ds_read_b128 v[108:111], v3 offset:36864
	v_mfma_f32_16x16x32_bf16 v[58:61], v[158:161], v[150:153], v[58:61]
	ds_read_b128 v[182:185], v4 offset:53248
	v_mfma_f32_16x16x32_bf16 v[18:21], v[162:165], v[150:153], v[18:21]
	global_load_dwordx4 v[150:153], v218, s[36:37] offset:1152
	v_mfma_f32_16x16x32_bf16 v[38:41], v[120:123], v[154:157], v[38:41]
	s_waitcnt vmcnt(8)
	ds_write_b128 v2, v[146:149] offset:12288
	v_mfma_f32_16x16x32_bf16 v[50:53], v[132:135], v[154:157], v[50:53]
	ds_read_b128 v[146:149], v3 offset:38912
	v_mfma_f32_16x16x32_bf16 v[54:57], v[158:161], v[154:157], v[54:57]
	ds_read_b128 v[186:189], v4 offset:55296
	v_mfma_f32_16x16x32_bf16 v[22:25], v[162:165], v[154:157], v[22:25]
	global_load_dwordx4 v[120:123], v5, s[4:5] offset:1152
	s_waitcnt vmcnt(8)
	ds_write_b128 v2, v[116:119] offset:16384
	s_waitcnt lgkmcnt(10)
	v_mfma_f32_16x16x32_bf16 v[26:29], v[174:177], v[166:169], v[26:29]
	s_waitcnt lgkmcnt(1)
	v_mfma_f32_16x16x32_bf16 v[10:13], v[186:189], v[166:169], v[10:13]
	v_mfma_f32_16x16x32_bf16 v[88:91], v[178:181], v[166:169], v[88:91]
	v_mfma_f32_16x16x32_bf16 v[96:99], v[182:185], v[166:169], v[96:99]
	global_load_dwordx4 v[116:119], v219, s[4:5] offset:1152
	v_mfma_f32_16x16x32_bf16 v[30:33], v[174:177], v[62:65], v[30:33]
	s_waitcnt vmcnt(8)
	ds_write_b128 v2, v[124:127] offset:20480
	v_mfma_f32_16x16x32_bf16 v[42:45], v[178:181], v[62:65], v[42:45]
	v_mfma_f32_16x16x32_bf16 v[14:17], v[186:189], v[62:65], v[14:17]
	v_mfma_f32_16x16x32_bf16 v[92:95], v[182:185], v[62:65], v[92:95]
	global_load_dwordx4 v[62:65], v220, s[4:5] offset:1152
	v_mfma_f32_16x16x32_bf16 v[34:37], v[174:177], v[108:111], v[34:37]
	s_waitcnt vmcnt(8)
	ds_write_b128 v2, v[100:103] offset:24576
	v_mfma_f32_16x16x32_bf16 v[46:49], v[178:181], v[108:111], v[46:49]
	v_mfma_f32_16x16x32_bf16 v[58:61], v[182:185], v[108:111], v[58:61]
	v_mfma_f32_16x16x32_bf16 v[18:21], v[186:189], v[108:111], v[18:21]
	global_load_dwordx4 v[100:103], v221, s[4:5] offset:1152
	v_mfma_f32_16x16x32_bf16 v[38:41], v[174:177], v[146:149], v[38:41]
	s_waitcnt vmcnt(8)
	ds_write_b128 v2, v[84:87] offset:28672
	v_mfma_f32_16x16x32_bf16 v[50:53], v[178:181], v[146:149], v[50:53]
	v_mfma_f32_16x16x32_bf16 v[54:57], v[182:185], v[146:149], v[54:57]
	v_mfma_f32_16x16x32_bf16 v[22:25], v[186:189], v[146:149], v[22:25]
	s_setprio 0
	s_waitcnt lgkmcnt(0)
	s_barrier
; template <int MODE>
; __device__ __forceinline__ void gemm_tile(const Params& P, int tm, int tn, unsigned char* smem) {
;     ...
;     for (int kt = 0; kt < 16; ++kt) {
;         unsigned char* sA = (kt & 1) ? sA1 : sA0; unsigned char* sB = (kt & 1) ? sB1 : sB0;
;         unsigned char* nA = (kt & 1) ? sA0 : sA1; unsigned char* nB = (kt & 1) ? sB0 : sB1;
;         bf16x8 fa[4], fb[4], ga[4], gb[4];
;         const int ch0 = ((g ^ sw) << 4), ch1 = (((4 + g) ^ sw) << 4);
;         const unsigned ko = (unsigned)(kt + 2) * 128u;
;         const unsigned koa = ko + ((MODE == 2 && kt + 2 >= 8) ? (unsigned)(ZC_FQ - 512) * 2u : 0u);
;         const bool wr_ok = kt < 15, ld_ok = kt < 14;
; #pragma unroll
;         for (int i = 0; i < 4; ++i) { fa[i] = *(const bf16x8*)(sA + arow_off + i * 2048 + ch0); fb[i] = *(const bf16x8*)(sB + brow_off + i * 2048 + ch0); }
;         __builtin_amdgcn_sched_barrier(0);
;         __builtin_amdgcn_s_setprio(2);
;         if (wr_ok) *(uint4*)(nA + soff0) = ra0;
;         if (ld_ok) ra0 = *(const uint4*)(Ab + (aoff + 0u * LDA + koa));
;         ga[0] = *(const bf16x8*)(sA + arow_off + 0 * 2048 + ch1); gb[0] = *(const bf16x8*)(sB + brow_off + 0 * 2048 + ch1);
;         __builtin_amdgcn_sched_barrier(0);
; #pragma unroll
;         for (int j = 0; j < 4; ++j) acc[0][j] = __builtin_amdgcn_mfma_f32_16x16x32_bf16(fb[j], fa[0], acc[0][j], 0, 0, 0);
;         __builtin_amdgcn_sched_barrier(0);
;         if (wr_ok) *(uint4*)(nA + soff0 + 4096) = ra1;
;         if (ld_ok) ra1 = *(const uint4*)(Ab + (aoff + 32u * LDA + koa));
;         ga[1] = *(const bf16x8*)(sA + arow_off + 1 * 2048 + ch1); gb[1] = *(const bf16x8*)(sB + brow_off + 1 * 2048 + ch1);
;         __builtin_amdgcn_sched_barrier(0);
; #pragma unroll
;         for (int j = 0; j < 4; ++j) acc[1][j] = __builtin_amdgcn_mfma_f32_16x16x32_bf16(fb[j], fa[1], acc[1][j], 0, 0, 0);
;         __builtin_amdgcn_sched_barrier(0);
;         if (wr_ok) *(uint4*)(nA + soff0 + 8192) = ra2;
;         if (ld_ok) ra2 = *(const uint4*)(Ab + (aoff + 64u * LDA + koa));
;         ga[2] = *(const bf16x8*)(sA + arow_off + 2 * 2048 + ch1); gb[2] = *(const bf16x8*)(sB + brow_off + 2 * 2048 + ch1);
;         __builtin_amdgcn_sched_barrier(0);
; #pragma unroll
;         for (int j = 0; j < 4; ++j) acc[2][j] = __builtin_amdgcn_mfma_f32_16x16x32_bf16(fb[j], fa[2], acc[2][j], 0, 0, 0);
	ds_read_b128 v[84:87], v6
	ds_read_b128 v[108:111], v6 offset:2048
	ds_read_b128 v[124:127], v7 offset:16384
	ds_read_b128 v[132:135], v7 offset:18432
	ds_read_b128 v[146:149], v6 offset:4096
	ds_read_b128 v[154:157], v6 offset:6144
	ds_read_b128 v[158:161], v7 offset:20480
	ds_read_b128 v[162:165], v7 offset:22528
	s_setprio 2
	global_load_dwordx4 v[166:169], v8, s[36:37] offset:1280
	s_waitcnt vmcnt(8)
	ds_write_b128 v2, v[170:173] offset:32768
	ds_read_b128 v[170:173], v3
	ds_read_b128 v[174:177], v4 offset:16384
	s_waitcnt lgkmcnt(8)
	v_mfma_f32_16x16x32_bf16 v[26:29], v[124:127], v[84:87], v[26:29]
	s_waitcnt lgkmcnt(3)
	v_mfma_f32_16x16x32_bf16 v[10:13], v[162:165], v[84:87], v[10:13]
	v_mfma_f32_16x16x32_bf16 v[88:91], v[132:135], v[84:87], v[88:91]
	v_mfma_f32_16x16x32_bf16 v[96:99], v[158:161], v[84:87], v[96:99]
	global_load_dwordx4 v[84:87], v216, s[36:37] offset:1280
	v_mfma_f32_16x16x32_bf16 v[30:33], v[124:127], v[108:111], v[30:33]
	s_waitcnt vmcnt(8)
	ds_write_b128 v2, v[104:107] offset:36864
	v_mfma_f32_16x16x32_bf16 v[42:45], v[132:135], v[108:111], v[42:45]
	ds_read_b128 v[104:107], v3 offset:2048
	v_mfma_f32_16x16x32_bf16 v[14:17], v[162:165], v[108:111], v[14:17]
	ds_read_b128 v[178:181], v4 offset:18432
	v_mfma_f32_16x16x32_bf16 v[92:95], v[158:161], v[108:111], v[92:95]
	global_load_dwordx4 v[108:111], v217, s[36:37] offset:1280
	v_mfma_f32_16x16x32_bf16 v[34:37], v[124:127], v[146:149], v[34:37]
	s_waitcnt vmcnt(8)
	ds_write_b128 v2, v[112:115] offset:40960
	v_mfma_f32_16x16x32_bf16 v[46:49], v[132:135], v[146:149], v[46:49]
	ds_read_b128 v[112:115], v3 offset:4096
	v_mfma_f32_16x16x32_bf16 v[58:61], v[158:161], v[146:149], v[58:61]
	ds_read_b128 v[182:185], v4 offset:20480
	v_mfma_f32_16x16x32_bf16 v[18:21], v[162:165], v[146:149], v[18:21]
	global_load_dwordx4 v[146:149], v218, s[36:37] offset:1280
	v_mfma_f32_16x16x32_bf16 v[38:41], v[124:127], v[154:157], v[38:41]
	s_waitcnt vmcnt(8)
	ds_write_b128 v2, v[150:153] offset:45056
	v_mfma_f32_16x16x32_bf16 v[50:53], v[132:135], v[154:157], v[50:53]
	ds_read_b128 v[150:153], v3 offset:6144
	v_mfma_f32_16x16x32_bf16 v[54:57], v[158:161], v[154:157], v[54:57]
	ds_read_b128 v[186:189], v4 offset:22528
	v_mfma_f32_16x16x32_bf16 v[22:25], v[162:165], v[154:157], v[22:25]
	global_load_dwordx4 v[124:127], v5, s[4:5] offset:1280
	s_waitcnt vmcnt(8)
	ds_write_b128 v2, v[120:123] offset:49152
	s_waitcnt lgkmcnt(10)
	v_mfma_f32_16x16x32_bf16 v[26:29], v[174:177], v[170:173], v[26:29]
	s_waitcnt lgkmcnt(1)
	v_mfma_f32_16x16x32_bf16 v[10:13], v[186:189], v[170:173], v[10:13]
	v_mfma_f32_16x16x32_bf16 v[88:91], v[178:181], v[170:173], v[88:91]
	v_mfma_f32_16x16x32_bf16 v[96:99], v[182:185], v[170:173], v[96:99]
	global_load_dwordx4 v[120:123], v219, s[4:5] offset:1280
	v_mfma_f32_16x16x32_bf16 v[30:33], v[174:177], v[104:107], v[30:33]
	s_waitcnt vmcnt(8)
	ds_write_b128 v2, v[116:119] offset:53248
	v_mfma_f32_16x16x32_bf16 v[42:45], v[178:181], v[104:107], v[42:45]
	v_mfma_f32_16x16x32_bf16 v[14:17], v[186:189], v[104:107], v[14:17]
	v_mfma_f32_16x16x32_bf16 v[92:95], v[182:185], v[104:107], v[92:95]
	global_load_dwordx4 v[104:107], v220, s[4:5] offset:1280
	v_mfma_f32_16x16x32_bf16 v[34:37], v[174:177], v[112:115], v[34:37]
	s_waitcnt vmcnt(8)
	ds_write_b128 v2, v[62:65] offset:57344
	v_mfma_f32_16x16x32_bf16 v[46:49], v[178:181], v[112:115], v[46:49]
	v_mfma_f32_16x16x32_bf16 v[58:61], v[182:185], v[112:115], v[58:61]
	v_mfma_f32_16x16x32_bf16 v[18:21], v[186:189], v[112:115], v[18:21]
	global_load_dwordx4 v[62:65], v221, s[4:5] offset:1280
	v_mfma_f32_16x16x32_bf16 v[38:41], v[174:177], v[150:153], v[38:41]
	s_waitcnt vmcnt(8)
	ds_write_b128 v2, v[100:103] offset:61440
	v_mfma_f32_16x16x32_bf16 v[50:53], v[178:181], v[150:153], v[50:53]
	v_mfma_f32_16x16x32_bf16 v[54:57], v[182:185], v[150:153], v[54:57]
	v_mfma_f32_16x16x32_bf16 v[22:25], v[186:189], v[150:153], v[22:25]
	s_setprio 0
	s_waitcnt lgkmcnt(0)
	s_barrier
	ds_read_b128 v[100:103], v6 offset:32768
	ds_read_b128 v[112:115], v6 offset:34816
	ds_read_b128 v[116:119], v7 offset:49152
	ds_read_b128 v[132:135], v7 offset:51200
	ds_read_b128 v[150:153], v6 offset:36864
	ds_read_b128 v[154:157], v6 offset:38912
	ds_read_b128 v[158:161], v7 offset:53248
	ds_read_b128 v[162:165], v7 offset:55296
	s_setprio 2
	global_load_dwordx4 v[170:173], v8, s[36:37] offset:1408
	s_waitcnt vmcnt(8)
	ds_write_b128 v2, v[166:169]
	ds_read_b128 v[166:169], v3 offset:32768
	ds_read_b128 v[174:177], v4 offset:49152
	s_waitcnt lgkmcnt(8)
	v_mfma_f32_16x16x32_bf16 v[26:29], v[116:119], v[100:103], v[26:29]
	s_waitcnt lgkmcnt(3)
	v_mfma_f32_16x16x32_bf16 v[10:13], v[162:165], v[100:103], v[10:13]
	v_mfma_f32_16x16x32_bf16 v[88:91], v[132:135], v[100:103], v[88:91]
	v_mfma_f32_16x16x32_bf16 v[96:99], v[158:161], v[100:103], v[96:99]
	global_load_dwordx4 v[100:103], v216, s[36:37] offset:1408
	v_mfma_f32_16x16x32_bf16 v[30:33], v[116:119], v[112:115], v[30:33]
	s_waitcnt vmcnt(8)
	ds_write_b128 v2, v[84:87] offset:4096
	v_mfma_f32_16x16x32_bf16 v[42:45], v[132:135], v[112:115], v[42:45]
	ds_read_b128 v[84:87], v3 offset:34816
	v_mfma_f32_16x16x32_bf16 v[14:17], v[162:165], v[112:115], v[14:17]
	ds_read_b128 v[178:181], v4 offset:51200
	v_mfma_f32_16x16x32_bf16 v[92:95], v[158:161], v[112:115], v[92:95]
	global_load_dwordx4 v[112:115], v217, s[36:37] offset:1408
	v_mfma_f32_16x16x32_bf16 v[34:37], v[116:119], v[150:153], v[34:37]
	s_waitcnt vmcnt(8)
; template <int MODE>
; __device__ __forceinline__ void gemm_tile(const Params& P, int tm, int tn, unsigned char* smem) {
;     ...
;     for (int kt = 0; kt < 16; ++kt) {
;         unsigned char* sA = (kt & 1) ? sA1 : sA0; unsigned char* sB = (kt & 1) ? sB1 : sB0;
;         unsigned char* nA = (kt & 1) ? sA0 : sA1; unsigned char* nB = (kt & 1) ? sB0 : sB1;
;         bf16x8 fa[4], fb[4], ga[4], gb[4];
;         const int ch0 = ((g ^ sw) << 4), ch1 = (((4 + g) ^ sw) << 4);
;         const unsigned ko = (unsigned)(kt + 2) * 128u;
;         const unsigned koa = ko + ((MODE == 2 && kt + 2 >= 8) ? (unsigned)(ZC_FQ - 512) * 2u : 0u);
;         const bool wr_ok = kt < 15, ld_ok = kt < 14;
; #pragma unroll
;         for (int i = 0; i < 4; ++i) { fa[i] = *(const bf16x8*)(sA + arow_off + i * 2048 + ch0); fb[i] = *(const bf16x8*)(sB + brow_off + i * 2048 + ch0); }
;         __builtin_amdgcn_sched_barrier(0);
;         __builtin_amdgcn_s_setprio(2);
;         if (wr_ok) *(uint4*)(nA + soff0) = ra0;
;         if (ld_ok) ra0 = *(const uint4*)(Ab + (aoff + 0u * LDA + koa));
;         ga[0] = *(const bf16x8*)(sA + arow_off + 0 * 2048 + ch1); gb[0] = *(const bf16x8*)(sB + brow_off + 0 * 2048 + ch1);
;         __builtin_amdgcn_sched_barrier(0);
; #pragma unroll
;         for (int j = 0; j < 4; ++j) acc[0][j] = __builtin_amdgcn_mfma_f32_16x16x32_bf16(fb[j], fa[0], acc[0][j], 0, 0, 0);
;         __builtin_amdgcn_sched_barrier(0);
;         if (wr_ok) *(uint4*)(nA + soff0 + 4096) = ra1;
;         if (ld_ok) ra1 = *(const uint4*)(Ab + (aoff + 32u * LDA + koa));
;         ga[1] = *(const bf16x8*)(sA + arow_off + 1 * 2048 + ch1); gb[1] = *(const bf16x8*)(sB + brow_off + 1 * 2048 + ch1);
;         __builtin_amdgcn_sched_barrier(0);
; #pragma unroll
;         for (int j = 0; j < 4; ++j) acc[1][j] = __builtin_amdgcn_mfma_f32_16x16x32_bf16(fb[j], fa[1], acc[1][j], 0, 0, 0);
;         __builtin_amdgcn_sched_barrier(0);
;         if (wr_ok) *(uint4*)(nA + soff0 + 8192) = ra2;
;         if (ld_ok) ra2 = *(const uint4*)(Ab + (aoff + 64u * LDA + koa));
;         ga[2] = *(const bf16x8*)(sA + arow_off + 2 * 2048 + ch1); gb[2] = *(const bf16x8*)(sB + brow_off + 2 * 2048 + ch1);
;         __builtin_amdgcn_sched_barrier(0);
; #pragma unroll
;         for (int j = 0; j < 4; ++j) acc[2][j] = __builtin_amdgcn_mfma_f32_16x16x32_bf16(fb[j], fa[2], acc[2][j], 0, 0, 0);
	ds_write_b128 v2, v[108:111] offset:8192
	v_mfma_f32_16x16x32_bf16 v[46:49], v[132:135], v[150:153], v[46:49]
	ds_read_b128 v[108:111], v3 offset:36864
	v_mfma_f32_16x16x32_bf16 v[58:61], v[158:161], v[150:153], v[58:61]
	ds_read_b128 v[182:185], v4 offset:53248
	v_mfma_f32_16x16x32_bf16 v[18:21], v[162:165], v[150:153], v[18:21]
	global_load_dwordx4 v[150:153], v218, s[36:37] offset:1408
	v_mfma_f32_16x16x32_bf16 v[38:41], v[116:119], v[154:157], v[38:41]
	s_waitcnt vmcnt(8)
	ds_write_b128 v2, v[146:149] offset:12288
	v_mfma_f32_16x16x32_bf16 v[50:53], v[132:135], v[154:157], v[50:53]
	ds_read_b128 v[146:149], v3 offset:38912
	v_mfma_f32_16x16x32_bf16 v[54:57], v[158:161], v[154:157], v[54:57]
	ds_read_b128 v[186:189], v4 offset:55296
	v_mfma_f32_16x16x32_bf16 v[22:25], v[162:165], v[154:157], v[22:25]
	global_load_dwordx4 v[116:119], v5, s[4:5] offset:1408
	s_waitcnt vmcnt(8)
	ds_write_b128 v2, v[124:127] offset:16384
	s_waitcnt lgkmcnt(10)
	v_mfma_f32_16x16x32_bf16 v[26:29], v[174:177], v[166:169], v[26:29]
	s_waitcnt lgkmcnt(1)
	v_mfma_f32_16x16x32_bf16 v[10:13], v[186:189], v[166:169], v[10:13]
	v_mfma_f32_16x16x32_bf16 v[88:91], v[178:181], v[166:169], v[88:91]
	v_mfma_f32_16x16x32_bf16 v[96:99], v[182:185], v[166:169], v[96:99]
	global_load_dwordx4 v[124:127], v219, s[4:5] offset:1408
	v_mfma_f32_16x16x32_bf16 v[30:33], v[174:177], v[84:87], v[30:33]
	s_waitcnt vmcnt(8)
	ds_write_b128 v2, v[120:123] offset:20480
	v_mfma_f32_16x16x32_bf16 v[42:45], v[178:181], v[84:87], v[42:45]
	v_mfma_f32_16x16x32_bf16 v[14:17], v[186:189], v[84:87], v[14:17]
	v_mfma_f32_16x16x32_bf16 v[92:95], v[182:185], v[84:87], v[92:95]
	global_load_dwordx4 v[84:87], v220, s[4:5] offset:1408
	v_mfma_f32_16x16x32_bf16 v[34:37], v[174:177], v[108:111], v[34:37]
	s_waitcnt vmcnt(8)
	ds_write_b128 v2, v[104:107] offset:24576
	v_mfma_f32_16x16x32_bf16 v[46:49], v[178:181], v[108:111], v[46:49]
	v_mfma_f32_16x16x32_bf16 v[58:61], v[182:185], v[108:111], v[58:61]
	v_mfma_f32_16x16x32_bf16 v[18:21], v[186:189], v[108:111], v[18:21]
	global_load_dwordx4 v[104:107], v221, s[4:5] offset:1408
	v_mfma_f32_16x16x32_bf16 v[38:41], v[174:177], v[146:149], v[38:41]
	s_waitcnt vmcnt(8)
	ds_write_b128 v2, v[62:65] offset:28672
	v_mfma_f32_16x16x32_bf16 v[50:53], v[178:181], v[146:149], v[50:53]
	v_mfma_f32_16x16x32_bf16 v[54:57], v[182:185], v[146:149], v[54:57]
	v_mfma_f32_16x16x32_bf16 v[22:25], v[186:189], v[146:149], v[22:25]
	s_setprio 0
	s_waitcnt lgkmcnt(0)
	s_barrier
	ds_read_b128 v[62:65], v6
	ds_read_b128 v[108:111], v6 offset:2048
	ds_read_b128 v[120:123], v7 offset:16384
	ds_read_b128 v[132:135], v7 offset:18432
	ds_read_b128 v[146:149], v6 offset:4096
	ds_read_b128 v[154:157], v6 offset:6144
	ds_read_b128 v[158:161], v7 offset:20480
	ds_read_b128 v[162:165], v7 offset:22528
	s_setprio 2
	global_load_dwordx4 v[166:169], v8, s[36:37] offset:1536
	s_waitcnt vmcnt(8)
	ds_write_b128 v2, v[170:173] offset:32768
	ds_read_b128 v[170:173], v3
	ds_read_b128 v[174:177], v4 offset:16384
	s_waitcnt lgkmcnt(8)
	v_mfma_f32_16x16x32_bf16 v[26:29], v[120:123], v[62:65], v[26:29]
	s_waitcnt lgkmcnt(3)
	v_mfma_f32_16x16x32_bf16 v[10:13], v[162:165], v[62:65], v[10:13]
	v_mfma_f32_16x16x32_bf16 v[88:91], v[132:135], v[62:65], v[88:91]
	v_mfma_f32_16x16x32_bf16 v[96:99], v[158:161], v[62:65], v[96:99]
	global_load_dwordx4 v[62:65], v216, s[36:37] offset:1536
	v_mfma_f32_16x16x32_bf16 v[30:33], v[120:123], v[108:111], v[30:33]
	s_waitcnt vmcnt(8)
	ds_write_b128 v2, v[100:103] offset:36864
	v_mfma_f32_16x16x32_bf16 v[42:45], v[132:135], v[108:111], v[42:45]
	ds_read_b128 v[100:103], v3 offset:2048
	v_mfma_f32_16x16x32_bf16 v[14:17], v[162:165], v[108:111], v[14:17]
	ds_read_b128 v[178:181], v4 offset:18432
	v_mfma_f32_16x16x32_bf16 v[92:95], v[158:161], v[108:111], v[92:95]
	global_load_dwordx4 v[108:111], v217, s[36:37] offset:1536
	v_mfma_f32_16x16x32_bf16 v[34:37], v[120:123], v[146:149], v[34:37]
	s_waitcnt vmcnt(8)
	ds_write_b128 v2, v[112:115] offset:40960
	v_mfma_f32_16x16x32_bf16 v[46:49], v[132:135], v[146:149], v[46:49]
	ds_read_b128 v[112:115], v3 offset:4096
	v_mfma_f32_16x16x32_bf16 v[58:61], v[158:161], v[146:149], v[58:61]
	ds_read_b128 v[182:185], v4 offset:20480
	v_mfma_f32_16x16x32_bf16 v[18:21], v[162:165], v[146:149], v[18:21]
	global_load_dwordx4 v[146:149], v218, s[36:37] offset:1536
	v_mfma_f32_16x16x32_bf16 v[38:41], v[120:123], v[154:157], v[38:41]
	s_waitcnt vmcnt(8)
	ds_write_b128 v2, v[150:153] offset:45056
	v_mfma_f32_16x16x32_bf16 v[50:53], v[132:135], v[154:157], v[50:53]
	ds_read_b128 v[150:153], v3 offset:6144
	v_mfma_f32_16x16x32_bf16 v[54:57], v[158:161], v[154:157], v[54:57]
	ds_read_b128 v[186:189], v4 offset:22528
	v_mfma_f32_16x16x32_bf16 v[22:25], v[162:165], v[154:157], v[22:25]
	global_load_dwordx4 v[120:123], v5, s[4:5] offset:1536
	s_waitcnt vmcnt(8)
	ds_write_b128 v2, v[116:119] offset:49152
	s_waitcnt lgkmcnt(10)
	v_mfma_f32_16x16x32_bf16 v[26:29], v[174:177], v[170:173], v[26:29]
	s_waitcnt lgkmcnt(1)
	v_mfma_f32_16x16x32_bf16 v[10:13], v[186:189], v[170:173], v[10:13]
	v_mfma_f32_16x16x32_bf16 v[88:91], v[178:181], v[170:173], v[88:91]
	v_mfma_f32_16x16x32_bf16 v[96:99], v[182:185], v[170:173], v[96:99]
	global_load_dwordx4 v[116:119], v219, s[4:5] offset:1536
	v_mfma_f32_16x16x32_bf16 v[30:33], v[174:177], v[100:103], v[30:33]
	s_waitcnt vmcnt(8)
	ds_write_b128 v2, v[124:127] offset:53248
	v_mfma_f32_16x16x32_bf16 v[42:45], v[178:181], v[100:103], v[42:45]
	v_mfma_f32_16x16x32_bf16 v[14:17], v[186:189], v[100:103], v[14:17]
	v_mfma_f32_16x16x32_bf16 v[92:95], v[182:185], v[100:103], v[92:95]
	global_load_dwordx4 v[100:103], v220, s[4:5] offset:1536
	v_mfma_f32_16x16x32_bf16 v[34:37], v[174:177], v[112:115], v[34:37]
	s_waitcnt vmcnt(8)
	ds_write_b128 v2, v[84:87] offset:57344
	v_mfma_f32_16x16x32_bf16 v[46:49], v[178:181], v[112:115], v[46:49]
	v_mfma_f32_16x16x32_bf16 v[58:61], v[182:185], v[112:115], v[58:61]
	v_mfma_f32_16x16x32_bf16 v[18:21], v[186:189], v[112:115], v[18:21]
	global_load_dwordx4 v[84:87], v221, s[4:5] offset:1536
	v_mfma_f32_16x16x32_bf16 v[38:41], v[174:177], v[150:153], v[38:41]
	s_waitcnt vmcnt(8)
	ds_write_b128 v2, v[104:107] offset:61440
	v_mfma_f32_16x16x32_bf16 v[50:53], v[178:181], v[150:153], v[50:53]
	v_mfma_f32_16x16x32_bf16 v[54:57], v[182:185], v[150:153], v[54:57]
	v_mfma_f32_16x16x32_bf16 v[22:25], v[186:189], v[150:153], v[22:25]
	s_setprio 0
	s_waitcnt lgkmcnt(0)
	s_barrier
; template <int MODE>
; __device__ __forceinline__ void gemm_tile(const Params& P, int tm, int tn, unsigned char* smem) {
;     ...
;     for (int kt = 0; kt < 16; ++kt) {
;         unsigned char* sA = (kt & 1) ? sA1 : sA0; unsigned char* sB = (kt & 1) ? sB1 : sB0;
;         unsigned char* nA = (kt & 1) ? sA0 : sA1; unsigned char* nB = (kt & 1) ? sB0 : sB1;
;         bf16x8 fa[4], fb[4], ga[4], gb[4];
;         const int ch0 = ((g ^ sw) << 4), ch1 = (((4 + g) ^ sw) << 4);
;         const unsigned ko = (unsigned)(kt + 2) * 128u;
;         const unsigned koa = ko + ((MODE == 2 && kt + 2 >= 8) ? (unsigned)(ZC_FQ - 512) * 2u : 0u);
;         const bool wr_ok = kt < 15, ld_ok = kt < 14;
; #pragma unroll
;         for (int i = 0; i < 4; ++i) { fa[i] = *(const bf16x8*)(sA + arow_off + i * 2048 + ch0); fb[i] = *(const bf16x8*)(sB + brow_off + i * 2048 + ch0); }
;         __builtin_amdgcn_sched_barrier(0);
;         __builtin_amdgcn_s_setprio(2);
;         if (wr_ok) *(uint4*)(nA + soff0) = ra0;
;         if (ld_ok) ra0 = *(const uint4*)(Ab + (aoff + 0u * LDA + koa));
;         ga[0] = *(const bf16x8*)(sA + arow_off + 0 * 2048 + ch1); gb[0] = *(const bf16x8*)(sB + brow_off + 0 * 2048 + ch1);
;         __builtin_amdgcn_sched_barrier(0);
; #pragma unroll
;         for (int j = 0; j < 4; ++j) acc[0][j] = __builtin_amdgcn_mfma_f32_16x16x32_bf16(fb[j], fa[0], acc[0][j], 0, 0, 0);
;         __builtin_amdgcn_sched_barrier(0);
;         if (wr_ok) *(uint4*)(nA + soff0 + 4096) = ra1;
;         if (ld_ok) ra1 = *(const uint4*)(Ab + (aoff + 32u * LDA + koa));
;         ga[1] = *(const bf16x8*)(sA + arow_off + 1 * 2048 + ch1); gb[1] = *(const bf16x8*)(sB + brow_off + 1 * 2048 + ch1);
;         __builtin_amdgcn_sched_barrier(0);
; #pragma unroll
;         for (int j = 0; j < 4; ++j) acc[1][j] = __builtin_amdgcn_mfma_f32_16x16x32_bf16(fb[j], fa[1], acc[1][j], 0, 0, 0);
;         __builtin_amdgcn_sched_barrier(0);
;         if (wr_ok) *(uint4*)(nA + soff0 + 8192) = ra2;
;         if (ld_ok) ra2 = *(const uint4*)(Ab + (aoff + 64u * LDA + koa));
;         ga[2] = *(const bf16x8*)(sA + arow_off + 2 * 2048 + ch1); gb[2] = *(const bf16x8*)(sB + brow_off + 2 * 2048 + ch1);
;         __builtin_amdgcn_sched_barrier(0);
; #pragma unroll
;         for (int j = 0; j < 4; ++j) acc[2][j] = __builtin_amdgcn_mfma_f32_16x16x32_bf16(fb[j], fa[2], acc[2][j], 0, 0, 0);
	ds_read_b128 v[104:107], v6 offset:32768
	ds_read_b128 v[112:115], v6 offset:34816
	ds_read_b128 v[124:127], v7 offset:49152
	ds_read_b128 v[132:135], v7 offset:51200
	ds_read_b128 v[150:153], v6 offset:36864
	ds_read_b128 v[154:157], v6 offset:38912
	ds_read_b128 v[158:161], v7 offset:53248
	ds_read_b128 v[162:165], v7 offset:55296
	s_setprio 2
	global_load_dwordx4 v[170:173], v8, s[36:37] offset:1664
	s_waitcnt vmcnt(8)
	ds_write_b128 v2, v[166:169]
	ds_read_b128 v[166:169], v3 offset:32768
	ds_read_b128 v[174:177], v4 offset:49152
	s_waitcnt lgkmcnt(8)
	v_mfma_f32_16x16x32_bf16 v[26:29], v[124:127], v[104:107], v[26:29]
	s_waitcnt lgkmcnt(3)
	v_mfma_f32_16x16x32_bf16 v[10:13], v[162:165], v[104:107], v[10:13]
	v_mfma_f32_16x16x32_bf16 v[88:91], v[132:135], v[104:107], v[88:91]
	v_mfma_f32_16x16x32_bf16 v[96:99], v[158:161], v[104:107], v[96:99]
	global_load_dwordx4 v[104:107], v216, s[36:37] offset:1664
	v_mfma_f32_16x16x32_bf16 v[30:33], v[124:127], v[112:115], v[30:33]
	s_waitcnt vmcnt(8)
	ds_write_b128 v2, v[62:65] offset:4096
	v_mfma_f32_16x16x32_bf16 v[42:45], v[132:135], v[112:115], v[42:45]
	ds_read_b128 v[62:65], v3 offset:34816
	v_mfma_f32_16x16x32_bf16 v[14:17], v[162:165], v[112:115], v[14:17]
	ds_read_b128 v[178:181], v4 offset:51200
	v_mfma_f32_16x16x32_bf16 v[92:95], v[158:161], v[112:115], v[92:95]
	global_load_dwordx4 v[112:115], v217, s[36:37] offset:1664
	v_mfma_f32_16x16x32_bf16 v[34:37], v[124:127], v[150:153], v[34:37]
	s_waitcnt vmcnt(8)
	ds_write_b128 v2, v[108:111] offset:8192
	v_mfma_f32_16x16x32_bf16 v[46:49], v[132:135], v[150:153], v[46:49]
	ds_read_b128 v[108:111], v3 offset:36864
	v_mfma_f32_16x16x32_bf16 v[58:61], v[158:161], v[150:153], v[58:61]
	ds_read_b128 v[182:185], v4 offset:53248
	v_mfma_f32_16x16x32_bf16 v[18:21], v[162:165], v[150:153], v[18:21]
	global_load_dwordx4 v[150:153], v218, s[36:37] offset:1664
	v_mfma_f32_16x16x32_bf16 v[38:41], v[124:127], v[154:157], v[38:41]
	s_waitcnt vmcnt(8)
	ds_write_b128 v2, v[146:149] offset:12288
	v_mfma_f32_16x16x32_bf16 v[50:53], v[132:135], v[154:157], v[50:53]
	ds_read_b128 v[146:149], v3 offset:38912
	v_mfma_f32_16x16x32_bf16 v[54:57], v[158:161], v[154:157], v[54:57]
	ds_read_b128 v[186:189], v4 offset:55296
	v_mfma_f32_16x16x32_bf16 v[22:25], v[162:165], v[154:157], v[22:25]
	global_load_dwordx4 v[124:127], v5, s[4:5] offset:1664
	s_waitcnt vmcnt(8)
	ds_write_b128 v2, v[120:123] offset:16384
	s_waitcnt lgkmcnt(10)
	v_mfma_f32_16x16x32_bf16 v[26:29], v[174:177], v[166:169], v[26:29]
	s_waitcnt lgkmcnt(1)
	v_mfma_f32_16x16x32_bf16 v[10:13], v[186:189], v[166:169], v[10:13]
	v_mfma_f32_16x16x32_bf16 v[88:91], v[178:181], v[166:169], v[88:91]
	v_mfma_f32_16x16x32_bf16 v[96:99], v[182:185], v[166:169], v[96:99]
	global_load_dwordx4 v[120:123], v219, s[4:5] offset:1664
	v_mfma_f32_16x16x32_bf16 v[30:33], v[174:177], v[62:65], v[30:33]
	s_waitcnt vmcnt(8)
	ds_write_b128 v2, v[116:119] offset:20480
	v_mfma_f32_16x16x32_bf16 v[42:45], v[178:181], v[62:65], v[42:45]
	v_mfma_f32_16x16x32_bf16 v[14:17], v[186:189], v[62:65], v[14:17]
	v_mfma_f32_16x16x32_bf16 v[92:95], v[182:185], v[62:65], v[92:95]
	global_load_dwordx4 v[62:65], v220, s[4:5] offset:1664
	v_mfma_f32_16x16x32_bf16 v[34:37], v[174:177], v[108:111], v[34:37]
	s_waitcnt vmcnt(8)
	ds_write_b128 v2, v[100:103] offset:24576
	v_mfma_f32_16x16x32_bf16 v[46:49], v[178:181], v[108:111], v[46:49]
	v_mfma_f32_16x16x32_bf16 v[58:61], v[182:185], v[108:111], v[58:61]
	v_mfma_f32_16x16x32_bf16 v[18:21], v[186:189], v[108:111], v[18:21]
	global_load_dwordx4 v[100:103], v221, s[4:5] offset:1664
	v_mfma_f32_16x16x32_bf16 v[38:41], v[174:177], v[146:149], v[38:41]
	s_waitcnt vmcnt(8)
	ds_write_b128 v2, v[84:87] offset:28672
	v_mfma_f32_16x16x32_bf16 v[50:53], v[178:181], v[146:149], v[50:53]
	v_mfma_f32_16x16x32_bf16 v[54:57], v[182:185], v[146:149], v[54:57]
	v_mfma_f32_16x16x32_bf16 v[22:25], v[186:189], v[146:149], v[22:25]
	s_setprio 0
	s_waitcnt lgkmcnt(0)
	s_barrier
	ds_read_b128 v[84:87], v6
	ds_read_b128 v[108:111], v6 offset:2048
	ds_read_b128 v[116:119], v7 offset:16384
	ds_read_b128 v[132:135], v7 offset:18432
	ds_read_b128 v[146:149], v6 offset:4096
	ds_read_b128 v[154:157], v6 offset:6144
	ds_read_b128 v[158:161], v7 offset:20480
	ds_read_b128 v[162:165], v7 offset:22528
	s_setprio 2
	global_load_dwordx4 v[166:169], v8, s[36:37] offset:1792
	s_waitcnt vmcnt(8)
	ds_write_b128 v2, v[170:173] offset:32768
	ds_read_b128 v[170:173], v3
	ds_read_b128 v[174:177], v4 offset:16384
	s_waitcnt lgkmcnt(8)
	v_mfma_f32_16x16x32_bf16 v[26:29], v[116:119], v[84:87], v[26:29]
	s_waitcnt lgkmcnt(3)
	v_mfma_f32_16x16x32_bf16 v[10:13], v[162:165], v[84:87], v[10:13]
	v_mfma_f32_16x16x32_bf16 v[88:91], v[132:135], v[84:87], v[88:91]
	v_mfma_f32_16x16x32_bf16 v[96:99], v[158:161], v[84:87], v[96:99]
	global_load_dwordx4 v[84:87], v216, s[36:37] offset:1792
	v_mfma_f32_16x16x32_bf16 v[30:33], v[116:119], v[108:111], v[30:33]
	s_waitcnt vmcnt(8)
	ds_write_b128 v2, v[104:107] offset:36864
	v_mfma_f32_16x16x32_bf16 v[42:45], v[132:135], v[108:111], v[42:45]
	ds_read_b128 v[104:107], v3 offset:2048
	v_mfma_f32_16x16x32_bf16 v[14:17], v[162:165], v[108:111], v[14:17]
	ds_read_b128 v[178:181], v4 offset:18432
	v_mfma_f32_16x16x32_bf16 v[92:95], v[158:161], v[108:111], v[92:95]
	global_load_dwordx4 v[108:111], v217, s[36:37] offset:1792
	v_mfma_f32_16x16x32_bf16 v[34:37], v[116:119], v[146:149], v[34:37]
	s_waitcnt vmcnt(8)
; template <int MODE>
; __device__ __forceinline__ void gemm_tile(const Params& P, int tm, int tn, unsigned char* smem) {
;     ...
;     for (int kt = 0; kt < 16; ++kt) {
;         unsigned char* sA = (kt & 1) ? sA1 : sA0; unsigned char* sB = (kt & 1) ? sB1 : sB0;
;         unsigned char* nA = (kt & 1) ? sA0 : sA1; unsigned char* nB = (kt & 1) ? sB0 : sB1;
;         bf16x8 fa[4], fb[4], ga[4], gb[4];
;         const int ch0 = ((g ^ sw) << 4), ch1 = (((4 + g) ^ sw) << 4);
;         const unsigned ko = (unsigned)(kt + 2) * 128u;
;         const unsigned koa = ko + ((MODE == 2 && kt + 2 >= 8) ? (unsigned)(ZC_FQ - 512) * 2u : 0u);
;         const bool wr_ok = kt < 15, ld_ok = kt < 14;
; #pragma unroll
;         for (int i = 0; i < 4; ++i) { fa[i] = *(const bf16x8*)(sA + arow_off + i * 2048 + ch0); fb[i] = *(const bf16x8*)(sB + brow_off + i * 2048 + ch0); }
;         __builtin_amdgcn_sched_barrier(0);
;         __builtin_amdgcn_s_setprio(2);
;         if (wr_ok) *(uint4*)(nA + soff0) = ra0;
;         if (ld_ok) ra0 = *(const uint4*)(Ab + (aoff + 0u * LDA + koa));
;         ga[0] = *(const bf16x8*)(sA + arow_off + 0 * 2048 + ch1); gb[0] = *(const bf16x8*)(sB + brow_off + 0 * 2048 + ch1);
;         __builtin_amdgcn_sched_barrier(0);
; #pragma unroll
;         for (int j = 0; j < 4; ++j) acc[0][j] = __builtin_amdgcn_mfma_f32_16x16x32_bf16(fb[j], fa[0], acc[0][j], 0, 0, 0);
;         __builtin_amdgcn_sched_barrier(0);
;         if (wr_ok) *(uint4*)(nA + soff0 + 4096) = ra1;
;         if (ld_ok) ra1 = *(const uint4*)(Ab + (aoff + 32u * LDA + koa));
;         ga[1] = *(const bf16x8*)(sA + arow_off + 1 * 2048 + ch1); gb[1] = *(const bf16x8*)(sB + brow_off + 1 * 2048 + ch1);
;         __builtin_amdgcn_sched_barrier(0);
; #pragma unroll
;         for (int j = 0; j < 4; ++j) acc[1][j] = __builtin_amdgcn_mfma_f32_16x16x32_bf16(fb[j], fa[1], acc[1][j], 0, 0, 0);
;         __builtin_amdgcn_sched_barrier(0);
;         if (wr_ok) *(uint4*)(nA + soff0 + 8192) = ra2;
;         if (ld_ok) ra2 = *(const uint4*)(Ab + (aoff + 64u * LDA + koa));
;         ga[2] = *(const bf16x8*)(sA + arow_off + 2 * 2048 + ch1); gb[2] = *(const bf16x8*)(sB + brow_off + 2 * 2048 + ch1);
;         __builtin_amdgcn_sched_barrier(0);
; #pragma unroll
;         for (int j = 0; j < 4; ++j) acc[2][j] = __builtin_amdgcn_mfma_f32_16x16x32_bf16(fb[j], fa[2], acc[2][j], 0, 0, 0);
	ds_write_b128 v2, v[112:115] offset:40960
	v_mfma_f32_16x16x32_bf16 v[46:49], v[132:135], v[146:149], v[46:49]
	ds_read_b128 v[112:115], v3 offset:4096
	v_mfma_f32_16x16x32_bf16 v[58:61], v[158:161], v[146:149], v[58:61]
	ds_read_b128 v[182:185], v4 offset:20480
	v_mfma_f32_16x16x32_bf16 v[18:21], v[162:165], v[146:149], v[18:21]
	global_load_dwordx4 v[146:149], v218, s[36:37] offset:1792
	v_mfma_f32_16x16x32_bf16 v[38:41], v[116:119], v[154:157], v[38:41]
	s_waitcnt vmcnt(8)
	ds_write_b128 v2, v[150:153] offset:45056
	v_mfma_f32_16x16x32_bf16 v[50:53], v[132:135], v[154:157], v[50:53]
	ds_read_b128 v[150:153], v3 offset:6144
	v_mfma_f32_16x16x32_bf16 v[54:57], v[158:161], v[154:157], v[54:57]
	ds_read_b128 v[186:189], v4 offset:22528
	v_mfma_f32_16x16x32_bf16 v[22:25], v[162:165], v[154:157], v[22:25]
	global_load_dwordx4 v[116:119], v5, s[4:5] offset:1792
	s_waitcnt vmcnt(8)
	ds_write_b128 v2, v[124:127] offset:49152
	s_waitcnt lgkmcnt(10)
	v_mfma_f32_16x16x32_bf16 v[26:29], v[174:177], v[170:173], v[26:29]
	s_waitcnt lgkmcnt(1)
	v_mfma_f32_16x16x32_bf16 v[10:13], v[186:189], v[170:173], v[10:13]
	v_mfma_f32_16x16x32_bf16 v[88:91], v[178:181], v[170:173], v[88:91]
	v_mfma_f32_16x16x32_bf16 v[96:99], v[182:185], v[170:173], v[96:99]
	global_load_dwordx4 v[124:127], v219, s[4:5] offset:1792
	v_mfma_f32_16x16x32_bf16 v[30:33], v[174:177], v[104:107], v[30:33]
	s_waitcnt vmcnt(8)
	ds_write_b128 v2, v[120:123] offset:53248
	v_mfma_f32_16x16x32_bf16 v[42:45], v[178:181], v[104:107], v[42:45]
	v_mfma_f32_16x16x32_bf16 v[14:17], v[186:189], v[104:107], v[14:17]
	v_mfma_f32_16x16x32_bf16 v[92:95], v[182:185], v[104:107], v[92:95]
	global_load_dwordx4 v[104:107], v220, s[4:5] offset:1792
	v_mfma_f32_16x16x32_bf16 v[34:37], v[174:177], v[112:115], v[34:37]
	s_waitcnt vmcnt(8)
	ds_write_b128 v2, v[62:65] offset:57344
	v_mfma_f32_16x16x32_bf16 v[46:49], v[178:181], v[112:115], v[46:49]
	v_mfma_f32_16x16x32_bf16 v[58:61], v[182:185], v[112:115], v[58:61]
	v_mfma_f32_16x16x32_bf16 v[18:21], v[186:189], v[112:115], v[18:21]
	global_load_dwordx4 v[62:65], v221, s[4:5] offset:1792
	v_mfma_f32_16x16x32_bf16 v[38:41], v[174:177], v[150:153], v[38:41]
	s_waitcnt vmcnt(8)
	ds_write_b128 v2, v[100:103] offset:61440
	v_mfma_f32_16x16x32_bf16 v[50:53], v[178:181], v[150:153], v[50:53]
	v_mfma_f32_16x16x32_bf16 v[54:57], v[182:185], v[150:153], v[54:57]
	v_mfma_f32_16x16x32_bf16 v[22:25], v[186:189], v[150:153], v[22:25]
	s_setprio 0
	s_waitcnt lgkmcnt(0)
	s_barrier
	ds_read_b128 v[100:103], v6 offset:32768
	ds_read_b128 v[112:115], v6 offset:34816
	ds_read_b128 v[120:123], v7 offset:49152
	ds_read_b128 v[132:135], v7 offset:51200
	ds_read_b128 v[150:153], v6 offset:36864
	ds_read_b128 v[154:157], v6 offset:38912
	ds_read_b128 v[158:161], v7 offset:53248
	ds_read_b128 v[162:165], v7 offset:55296
	s_setprio 2
	global_load_dwordx4 v[170:173], v8, s[36:37] offset:1920
	s_waitcnt vmcnt(8)
	ds_write_b128 v2, v[166:169]
	ds_read_b128 v[166:169], v3 offset:32768
	ds_read_b128 v[174:177], v4 offset:49152
	s_waitcnt lgkmcnt(8)
	v_mfma_f32_16x16x32_bf16 v[26:29], v[120:123], v[100:103], v[26:29]
	s_waitcnt lgkmcnt(3)
	v_mfma_f32_16x16x32_bf16 v[10:13], v[162:165], v[100:103], v[10:13]
	v_mfma_f32_16x16x32_bf16 v[88:91], v[132:135], v[100:103], v[88:91]
	v_mfma_f32_16x16x32_bf16 v[96:99], v[158:161], v[100:103], v[96:99]
	global_load_dwordx4 v[100:103], v216, s[36:37] offset:1920
	v_mfma_f32_16x16x32_bf16 v[30:33], v[120:123], v[112:115], v[30:33]
	s_waitcnt vmcnt(8)
	ds_write_b128 v2, v[84:87] offset:4096
	v_mfma_f32_16x16x32_bf16 v[42:45], v[132:135], v[112:115], v[42:45]
	ds_read_b128 v[84:87], v3 offset:34816
	v_mfma_f32_16x16x32_bf16 v[14:17], v[162:165], v[112:115], v[14:17]
	ds_read_b128 v[178:181], v4 offset:51200
	v_mfma_f32_16x16x32_bf16 v[92:95], v[158:161], v[112:115], v[92:95]
	global_load_dwordx4 v[112:115], v217, s[36:37] offset:1920
	v_mfma_f32_16x16x32_bf16 v[34:37], v[120:123], v[150:153], v[34:37]
	s_waitcnt vmcnt(8)
	ds_write_b128 v2, v[108:111] offset:8192
	v_mfma_f32_16x16x32_bf16 v[46:49], v[132:135], v[150:153], v[46:49]
	ds_read_b128 v[108:111], v3 offset:36864
	v_mfma_f32_16x16x32_bf16 v[58:61], v[158:161], v[150:153], v[58:61]
	ds_read_b128 v[182:185], v4 offset:53248
	v_mfma_f32_16x16x32_bf16 v[18:21], v[162:165], v[150:153], v[18:21]
	v_add_u32_e32 v8, 0x30780, v8
	global_load_dwordx4 v[150:153], v8, s[36:37]
	s_waitcnt vmcnt(8)
	ds_write_b128 v2, v[146:149] offset:12288
	ds_read_b128 v[146:149], v3 offset:38912
	ds_read_b128 v[186:189], v4 offset:55296
	v_mfma_f32_16x16x32_bf16 v[38:41], v[120:123], v[154:157], v[38:41]
	v_mfma_f32_16x16x32_bf16 v[50:53], v[132:135], v[154:157], v[50:53]
	v_mfma_f32_16x16x32_bf16 v[54:57], v[158:161], v[154:157], v[54:57]
	v_mfma_f32_16x16x32_bf16 v[22:25], v[162:165], v[154:157], v[22:25]
	global_load_dwordx4 v[120:123], v5, s[4:5] offset:1920
	s_waitcnt vmcnt(8)
	ds_write_b128 v2, v[116:119] offset:16384
	s_waitcnt lgkmcnt(10)
	v_mfma_f32_16x16x32_bf16 v[26:29], v[174:177], v[166:169], v[26:29]
	s_waitcnt lgkmcnt(1)
	v_mfma_f32_16x16x32_bf16 v[8:11], v[186:189], v[166:169], v[10:13]
	v_mfma_f32_16x16x32_bf16 v[88:91], v[178:181], v[166:169], v[88:91]
	v_mfma_f32_16x16x32_bf16 v[96:99], v[182:185], v[166:169], v[96:99]
	s_nop 0
	global_load_dwordx4 v[116:119], v219, s[4:5] offset:1920
	s_waitcnt vmcnt(8)
	ds_write_b128 v2, v[124:127] offset:20480
	v_mfma_f32_16x16x32_bf16 v[30:33], v[174:177], v[84:87], v[30:33]
	v_mfma_f32_16x16x32_bf16 v[42:45], v[178:181], v[84:87], v[42:45]
	v_mfma_f32_16x16x32_bf16 v[12:15], v[186:189], v[84:87], v[14:17]
	v_mfma_f32_16x16x32_bf16 v[92:95], v[182:185], v[84:87], v[92:95]
	s_nop 1
	global_load_dwordx4 v[84:87], v220, s[4:5] offset:1920
	s_waitcnt vmcnt(8)
	ds_write_b128 v2, v[104:107] offset:24576
	v_mfma_f32_16x16x32_bf16 v[34:37], v[174:177], v[108:111], v[34:37]
	v_mfma_f32_16x16x32_bf16 v[46:49], v[178:181], v[108:111], v[46:49]
	v_mfma_f32_16x16x32_bf16 v[58:61], v[182:185], v[108:111], v[58:61]
	v_mfma_f32_16x16x32_bf16 v[16:19], v[186:189], v[108:111], v[18:21]
	v_add_u32_e32 v5, 0x30780, v5
	global_load_dwordx4 v[104:107], v5, s[4:5]
	s_waitcnt vmcnt(8)
	ds_write_b128 v2, v[62:65] offset:28672
	v_mfma_f32_16x16x32_bf16 v[38:41], v[174:177], v[146:149], v[38:41]
	v_mfma_f32_16x16x32_bf16 v[50:53], v[178:181], v[146:149], v[50:53]
	v_mfma_f32_16x16x32_bf16 v[54:57], v[182:185], v[146:149], v[54:57]
	v_mfma_f32_16x16x32_bf16 v[20:23], v[186:189], v[146:149], v[22:25]
	s_setprio 0
	s_waitcnt lgkmcnt(0)
	s_barrier
; template <int MODE>
; __device__ __forceinline__ void gemm_tile(const Params& P, int tm, int tn, unsigned char* smem) {
;     ...
;     for (int kt = 0; kt < 16; ++kt) {
;         unsigned char* sA = (kt & 1) ? sA1 : sA0; unsigned char* sB = (kt & 1) ? sB1 : sB0;
;         unsigned char* nA = (kt & 1) ? sA0 : sA1; unsigned char* nB = (kt & 1) ? sB0 : sB1;
;         bf16x8 fa[4], fb[4], ga[4], gb[4];
;         const int ch0 = ((g ^ sw) << 4), ch1 = (((4 + g) ^ sw) << 4);
;         const unsigned ko = (unsigned)(kt + 2) * 128u;
;         const unsigned koa = ko + ((MODE == 2 && kt + 2 >= 8) ? (unsigned)(ZC_FQ - 512) * 2u : 0u);
;         const bool wr_ok = kt < 15, ld_ok = kt < 14;
; #pragma unroll
;         for (int i = 0; i < 4; ++i) { fa[i] = *(const bf16x8*)(sA + arow_off + i * 2048 + ch0); fb[i] = *(const bf16x8*)(sB + brow_off + i * 2048 + ch0); }
;         __builtin_amdgcn_sched_barrier(0);
;         __builtin_amdgcn_s_setprio(2);
;         if (wr_ok) *(uint4*)(nA + soff0) = ra0;
;         if (ld_ok) ra0 = *(const uint4*)(Ab + (aoff + 0u * LDA + koa));
;         ga[0] = *(const bf16x8*)(sA + arow_off + 0 * 2048 + ch1); gb[0] = *(const bf16x8*)(sB + brow_off + 0 * 2048 + ch1);
;         __builtin_amdgcn_sched_barrier(0);
; #pragma unroll
;         for (int j = 0; j < 4; ++j) acc[0][j] = __builtin_amdgcn_mfma_f32_16x16x32_bf16(fb[j], fa[0], acc[0][j], 0, 0, 0);
;         __builtin_amdgcn_sched_barrier(0);
;         if (wr_ok) *(uint4*)(nA + soff0 + 4096) = ra1;
;         if (ld_ok) ra1 = *(const uint4*)(Ab + (aoff + 32u * LDA + koa));
;         ga[1] = *(const bf16x8*)(sA + arow_off + 1 * 2048 + ch1); gb[1] = *(const bf16x8*)(sB + brow_off + 1 * 2048 + ch1);
;         __builtin_amdgcn_sched_barrier(0);
; #pragma unroll
;         for (int j = 0; j < 4; ++j) acc[1][j] = __builtin_amdgcn_mfma_f32_16x16x32_bf16(fb[j], fa[1], acc[1][j], 0, 0, 0);
;         __builtin_amdgcn_sched_barrier(0);
;         if (wr_ok) *(uint4*)(nA + soff0 + 8192) = ra2;
;         if (ld_ok) ra2 = *(const uint4*)(Ab + (aoff + 64u * LDA + koa));
;         ga[2] = *(const bf16x8*)(sA + arow_off + 2 * 2048 + ch1); gb[2] = *(const bf16x8*)(sB + brow_off + 2 * 2048 + ch1);
;         __builtin_amdgcn_sched_barrier(0);
; #pragma unroll
;         for (int j = 0; j < 4; ++j) acc[2][j] = __builtin_amdgcn_mfma_f32_16x16x32_bf16(fb[j], fa[2], acc[2][j], 0, 0, 0);
	ds_read_b128 v[62:65], v6
	ds_read_b128 v[108:111], v6 offset:2048
	ds_read_b128 v[124:127], v7 offset:16384
	ds_read_b128 v[132:135], v7 offset:18432
	ds_read_b128 v[146:149], v6 offset:4096
	ds_read_b128 v[154:157], v6 offset:6144
	ds_read_b128 v[158:161], v7 offset:20480
	ds_read_b128 v[162:165], v7 offset:22528
	s_setprio 2
	s_waitcnt vmcnt(7)
	ds_write_b128 v2, v[170:173] offset:32768
	ds_read_b128 v[166:169], v3
	ds_read_b128 v[170:173], v4 offset:16384
	s_waitcnt lgkmcnt(8)
	v_mfma_f32_16x16x32_bf16 v[24:27], v[124:127], v[62:65], v[26:29]
	s_waitcnt lgkmcnt(3)
	v_mfma_f32_16x16x32_bf16 v[8:11], v[162:165], v[62:65], v[8:11]
	v_mfma_f32_16x16x32_bf16 v[88:91], v[132:135], v[62:65], v[88:91]
	v_mfma_f32_16x16x32_bf16 v[96:99], v[158:161], v[62:65], v[96:99]
	v_mfma_f32_16x16x32_bf16 v[28:31], v[124:127], v[108:111], v[30:33]
	s_waitcnt vmcnt(6)
	ds_write_b128 v2, v[100:103] offset:36864
	v_mfma_f32_16x16x32_bf16 v[42:45], v[132:135], v[108:111], v[42:45]
	ds_read_b128 v[62:65], v3 offset:2048
	v_mfma_f32_16x16x32_bf16 v[12:15], v[162:165], v[108:111], v[12:15]
	ds_read_b128 v[100:103], v4 offset:18432
	v_mfma_f32_16x16x32_bf16 v[92:95], v[158:161], v[108:111], v[92:95]
	v_mfma_f32_16x16x32_bf16 v[32:35], v[124:127], v[146:149], v[34:37]
	s_waitcnt vmcnt(5)
	ds_write_b128 v2, v[112:115] offset:40960
	v_mfma_f32_16x16x32_bf16 v[46:49], v[132:135], v[146:149], v[46:49]
	ds_read_b128 v[108:111], v3 offset:4096
	v_mfma_f32_16x16x32_bf16 v[58:61], v[158:161], v[146:149], v[58:61]
	ds_read_b128 v[112:115], v4 offset:20480
	v_mfma_f32_16x16x32_bf16 v[16:19], v[162:165], v[146:149], v[16:19]
	v_mfma_f32_16x16x32_bf16 v[36:39], v[124:127], v[154:157], v[38:41]
	s_waitcnt vmcnt(4)
	ds_write_b128 v2, v[150:153] offset:45056
	v_mfma_f32_16x16x32_bf16 v[50:53], v[132:135], v[154:157], v[50:53]
	ds_read_b128 v[146:149], v3 offset:6144
	v_mfma_f32_16x16x32_bf16 v[54:57], v[158:161], v[154:157], v[54:57]
	ds_read_b128 v[150:153], v4 offset:22528
	v_mfma_f32_16x16x32_bf16 v[20:23], v[162:165], v[154:157], v[20:23]
	s_waitcnt vmcnt(3)
	ds_write_b128 v2, v[120:123] offset:49152
	s_waitcnt lgkmcnt(10)
	v_mfma_f32_16x16x32_bf16 v[24:27], v[170:173], v[166:169], v[24:27]
	s_waitcnt lgkmcnt(1)
	v_mfma_f32_16x16x32_bf16 v[8:11], v[150:153], v[166:169], v[8:11]
	v_mfma_f32_16x16x32_bf16 v[88:91], v[100:103], v[166:169], v[88:91]
	v_mfma_f32_16x16x32_bf16 v[96:99], v[112:115], v[166:169], v[96:99]
	v_mfma_f32_16x16x32_bf16 v[28:31], v[170:173], v[62:65], v[28:31]
	s_waitcnt vmcnt(2)
	ds_write_b128 v2, v[116:119] offset:53248
	v_mfma_f32_16x16x32_bf16 v[40:43], v[100:103], v[62:65], v[42:45]
	v_mfma_f32_16x16x32_bf16 v[12:15], v[150:153], v[62:65], v[12:15]
	v_mfma_f32_16x16x32_bf16 v[92:95], v[112:115], v[62:65], v[92:95]
	v_mfma_f32_16x16x32_bf16 v[32:35], v[170:173], v[108:111], v[32:35]
	s_waitcnt vmcnt(1)
	ds_write_b128 v2, v[84:87] offset:57344
	v_mfma_f32_16x16x32_bf16 v[44:47], v[100:103], v[108:111], v[46:49]
	v_mfma_f32_16x16x32_bf16 v[58:61], v[112:115], v[108:111], v[58:61]
	v_mfma_f32_16x16x32_bf16 v[16:19], v[150:153], v[108:111], v[16:19]
	v_mfma_f32_16x16x32_bf16 v[36:39], v[170:173], v[146:149], v[36:39]
	s_waitcnt vmcnt(0)
	ds_write_b128 v2, v[104:107] offset:61440
	v_mfma_f32_16x16x32_bf16 v[48:51], v[100:103], v[146:149], v[50:53]
	v_mfma_f32_16x16x32_bf16 v[52:55], v[112:115], v[146:149], v[54:57]
	v_mfma_f32_16x16x32_bf16 v[20:23], v[150:153], v[146:149], v[20:23]
	s_setprio 0
	s_waitcnt lgkmcnt(0)
	s_barrier
	ds_read_b128 v[62:65], v6 offset:32768
	ds_read_b128 v[84:87], v6 offset:34816
	ds_read_b128 v[100:103], v7 offset:49152
	ds_read_b128 v[104:107], v7 offset:51200
	ds_read_b128 v[108:111], v6 offset:36864
	ds_read_b128 v[112:115], v6 offset:38912
	ds_read_b128 v[116:119], v7 offset:53248
	ds_read_b128 v[120:123], v7 offset:55296
	s_setprio 2
	ds_read_b128 v[124:127], v3 offset:32768
	ds_read_b128 v[132:135], v4 offset:49152
	s_waitcnt lgkmcnt(7)
	v_mfma_f32_16x16x32_bf16 v[24:27], v[100:103], v[62:65], v[24:27]
	s_waitcnt lgkmcnt(2)
	v_mfma_f32_16x16x32_bf16 v[6:9], v[120:123], v[62:65], v[8:11]
	v_mfma_f32_16x16x32_bf16 v[88:91], v[104:107], v[62:65], v[88:91]
	v_mfma_f32_16x16x32_bf16 v[96:99], v[116:119], v[62:65], v[96:99]
	v_mfma_f32_16x16x32_bf16 v[28:31], v[100:103], v[84:87], v[28:31]
	ds_read_b128 v[146:149], v3 offset:34816
	v_mfma_f32_16x16x32_bf16 v[40:43], v[104:107], v[84:87], v[40:43]
	ds_read_b128 v[150:153], v4 offset:51200
	v_mfma_f32_16x16x32_bf16 v[10:13], v[120:123], v[84:87], v[12:15]
	v_mfma_f32_16x16x32_bf16 v[92:95], v[116:119], v[84:87], v[92:95]
	v_mfma_f32_16x16x32_bf16 v[14:17], v[120:123], v[108:111], v[16:19]
	ds_read_b128 v[84:87], v3 offset:36864
	v_mfma_f32_16x16x32_bf16 v[158:161], v[100:103], v[108:111], v[32:35]
	ds_read_b128 v[154:157], v4 offset:53248
	v_mfma_f32_16x16x32_bf16 v[162:165], v[104:107], v[108:111], v[44:47]
	v_mfma_f32_16x16x32_bf16 v[166:169], v[116:119], v[108:111], v[58:61]
	v_mfma_f32_16x16x32_bf16 v[100:103], v[100:103], v[112:115], v[36:39]
	ds_read_b128 v[108:111], v3 offset:38912
	v_mfma_f32_16x16x32_bf16 v[104:107], v[104:107], v[112:115], v[48:51]
	ds_read_b128 v[2:5], v4 offset:55296
	v_mfma_f32_16x16x32_bf16 v[116:119], v[116:119], v[112:115], v[52:55]
	v_mfma_f32_16x16x32_bf16 v[112:115], v[120:123], v[112:115], v[20:23]
	s_waitcnt lgkmcnt(6)
	v_mfma_f32_16x16x32_bf16 v[62:65], v[132:135], v[124:127], v[24:27]
	s_waitcnt lgkmcnt(4)
	v_mfma_f32_16x16x32_bf16 v[58:61], v[150:153], v[124:127], v[88:91]
	s_waitcnt lgkmcnt(2)
	v_mfma_f32_16x16x32_bf16 v[54:57], v[154:157], v[124:127], v[96:99]
	s_waitcnt lgkmcnt(0)
	v_mfma_f32_16x16x32_bf16 v[50:53], v[2:5], v[124:127], v[6:9]
	v_mfma_f32_16x16x32_bf16 v[46:49], v[132:135], v[146:149], v[28:31]
	v_mfma_f32_16x16x32_bf16 v[42:45], v[150:153], v[146:149], v[40:43]
	v_mfma_f32_16x16x32_bf16 v[38:41], v[154:157], v[146:149], v[92:95]
	v_mfma_f32_16x16x32_bf16 v[34:37], v[2:5], v[146:149], v[10:13]
	v_mfma_f32_16x16x32_bf16 v[30:33], v[132:135], v[84:87], v[158:161]
	v_mfma_f32_16x16x32_bf16 v[26:29], v[150:153], v[84:87], v[162:165]
	v_mfma_f32_16x16x32_bf16 v[22:25], v[154:157], v[84:87], v[166:169]
	v_mfma_f32_16x16x32_bf16 v[18:21], v[2:5], v[84:87], v[14:17]
	v_mfma_f32_16x16x32_bf16 v[14:17], v[132:135], v[108:111], v[100:103]
	v_mfma_f32_16x16x32_bf16 v[10:13], v[150:153], v[108:111], v[104:107]
	v_mfma_f32_16x16x32_bf16 v[6:9], v[154:157], v[108:111], v[116:119]
	v_mfma_f32_16x16x32_bf16 v[2:5], v[2:5], v[108:111], v[112:115]
	s_setprio 0
	s_and_b32 s1, s0, -8
	s_cmp_lg_u32 s1, 16
	s_barrier
; template <int MODE>
; __device__ __forceinline__ void gemm_tile(const Params& P, int tm, int tn, unsigned char* smem) {
;     ...
;     if (MODE == 1) {
;         if (n0 >= ZC_FQ && n0 < ZC_FV) {
;             const bool isk = n0 >= ZC_FK;
;             const float* gain = isk ? P.f_k_norm : P.f_q_norm;
;             const float scl = isk ? 1.0f : 0.125f * LOG2E;
;             float gn[4][4];
; #pragma unroll
;             for (int j = 0; j < 4; ++j)
; #pragma unroll
;                 for (int r = 0; r < 4; ++r) gn[j][r] = gain[16 * j + 4 * g + r];
; #pragma unroll
;             for (int i = 0; i < 4; ++i) {
;                 float ss = 0.f;
; #pragma unroll
;                 for (int j = 0; j < 4; ++j)
; #pragma unroll
;                     for (int r = 0; r < 4; ++r) ss += acc[i][j][r] * acc[i][j][r];
;                 ss = x4_sum(ss);
;                 const float rstd = rsqrtf(ss * (1.0f / 64.0f) + EPS) * scl;
	s_cbranch_scc1 .LBB0_181
	v_mul_f32_e32 v66, v63, v63
	v_fmac_f32_e32 v66, v62, v62
	v_fmac_f32_e32 v66, v64, v64
	v_fmac_f32_e32 v66, v65, v65
	v_fmac_f32_e32 v66, v58, v58
	v_fmac_f32_e32 v66, v59, v59
	v_fmac_f32_e32 v66, v60, v60
	v_fmac_f32_e32 v66, v61, v61
	v_fmac_f32_e32 v66, v54, v54
	v_fmac_f32_e32 v66, v55, v55
	v_fmac_f32_e32 v66, v56, v56
	v_fmac_f32_e32 v66, v57, v57
	v_pk_mul_f32 v[84:85], v[50:51], v[50:51]
	v_pk_mul_f32 v[68:69], v[52:53], v[52:53]
	v_add_f32_e32 v66, v84, v66
	v_add_f32_e32 v66, v85, v66
	v_add_f32_e32 v66, v68, v66
	v_add_f32_e32 v66, v69, v66
	v_mov_b32_e32 v68, v66
	s_nop 1
	v_permlane32_swap_b32_e32 v66, v68
	v_add_f32_e32 v69, v66, v68
	v_mul_f32_e32 v66, v47, v47
	v_fmac_f32_e32 v66, v46, v46
	v_fmac_f32_e32 v66, v48, v48
	v_fmac_f32_e32 v66, v49, v49
	v_fmac_f32_e32 v66, v42, v42
	v_fmac_f32_e32 v66, v43, v43
	v_fmac_f32_e32 v66, v44, v44
	v_fmac_f32_e32 v66, v45, v45
	v_fmac_f32_e32 v66, v38, v38
	v_fmac_f32_e32 v66, v39, v39
	v_fmac_f32_e32 v66, v40, v40
	v_fmac_f32_e32 v66, v41, v41
	v_pk_mul_f32 v[88:89], v[34:35], v[34:35]
	v_pk_mul_f32 v[86:87], v[36:37], v[36:37]
	v_add_f32_e32 v66, v88, v66
	v_add_f32_e32 v66, v89, v66
	v_add_f32_e32 v66, v86, v66
	v_add_f32_e32 v66, v87, v66
	v_mov_b32_e32 v68, v66
	s_nop 1
	v_permlane32_swap_b32_e32 v66, v68
	v_add_f32_e32 v68, v66, v68
	v_mov_b32_e32 v85, v69
	v_mov_b32_e32 v84, v68
	s_nop 0
	v_permlane16_swap_b32_e32 v69, v85
	v_permlane16_swap_b32_e32 v68, v84
	v_pk_add_f32 v[84:85], v[68:69], v[84:85]
	v_mov_b64_e32 v[68:69], s[8:9]
	v_mul_f32_e32 v97, v31, v31
	s_cmp_gt_u32 s0, 19
	v_pk_fma_f32 v[88:89], v[84:85], s[6:7], v[68:69] op_sel_hi:[1,0,0]
	v_fmac_f32_e32 v97, v30, v30
	s_cselect_b64 s[0:1], -1, 0
	v_mul_f32_e32 v66, 0x4b800000, v89
	v_cmp_gt_f32_e32 vcc, s21, v89
	v_fmac_f32_e32 v97, v32, v32
	v_cndmask_b32_e64 v108, v78, 1.0, s[0:1]
	s_and_b64 s[0:1], s[0:1], exec
	v_cndmask_b32_e32 v66, v89, v66, vcc
	v_fmac_f32_e32 v97, v33, v33
	v_rsq_f32_e32 v66, v66
	v_mul_f32_e32 v70, 0x4b800000, v88
	v_cmp_gt_f32_e64 s[0:1], s21, v88
	v_fmac_f32_e32 v97, v26, v26
	v_fmac_f32_e32 v97, v27, v27
	v_cndmask_b32_e64 v70, v88, v70, s[0:1]
	v_rsq_f32_e32 v88, v70
	v_fmac_f32_e32 v97, v28, v28
	s_cselect_b32 s13, s41, s39
	s_cselect_b32 s12, s40, s38
	v_lshlrev_b32_e32 v96, 4, v83
	v_fmac_f32_e32 v97, v29, v29
	global_load_dwordx4 v[84:87], v96, s[12:13]
	v_mul_f32_e32 v70, 0x45800000, v66
	v_fmac_f32_e32 v97, v22, v22
	v_cndmask_b32_e32 v66, v66, v70, vcc
	v_fmac_f32_e32 v97, v23, v23
	v_mul_f32_e32 v70, v108, v66
	v_mul_f32_e32 v66, 0x45800000, v88
	v_fmac_f32_e32 v97, v24, v24
	v_cndmask_b32_e64 v66, v88, v66, s[0:1]
	global_load_dwordx4 v[88:91], v96, s[12:13] offset:64
	v_fmac_f32_e32 v97, v25, v25
	v_pk_mul_f32 v[94:95], v[18:19], v[18:19]
	v_pk_mul_f32 v[92:93], v[20:21], v[20:21]
	v_add_f32_e32 v94, v94, v97
	v_add_f32_e32 v94, v95, v94
	v_add_f32_e32 v92, v92, v94
	v_add_f32_e32 v97, v93, v92
	global_load_dwordx4 v[92:95], v96, s[12:13] offset:128
	v_mov_b32_e32 v98, v97
	s_nop 1
	v_permlane32_swap_b32_e32 v97, v98
	v_add_f32_e32 v101, v97, v98
	global_load_dwordx4 v[96:99], v96, s[12:13] offset:192
	v_mul_f32_e32 v100, v15, v15
	v_fmac_f32_e32 v100, v14, v14
	v_fmac_f32_e32 v100, v16, v16
	v_fmac_f32_e32 v100, v17, v17
	v_fmac_f32_e32 v100, v10, v10
	v_fmac_f32_e32 v100, v11, v11
	v_fmac_f32_e32 v100, v12, v12
	v_fmac_f32_e32 v100, v13, v13
	v_fmac_f32_e32 v100, v6, v6
	v_fmac_f32_e32 v100, v7, v7
	v_fmac_f32_e32 v100, v8, v8
	v_fmac_f32_e32 v100, v9, v9
	v_pk_mul_f32 v[106:107], v[2:3], v[2:3]
	v_pk_mul_f32 v[104:105], v[4:5], v[4:5]
	v_add_f32_e32 v100, v106, v100
	v_add_f32_e32 v100, v107, v100
	v_add_f32_e32 v100, v104, v100
	v_add_f32_e32 v100, v105, v100
	v_mov_b32_e32 v102, v100
	s_nop 1
	v_permlane32_swap_b32_e32 v100, v102
	v_add_f32_e32 v100, v100, v102
	v_mov_b32_e32 v103, v101
	v_mov_b32_e32 v102, v100
	s_nop 0
	v_permlane16_swap_b32_e32 v101, v103
	v_permlane16_swap_b32_e32 v100, v102
	v_pk_add_f32 v[100:101], v[100:101], v[102:103]
	v_mul_f32_e32 v66, v108, v66
	v_pk_fma_f32 v[68:69], v[100:101], s[6:7], v[68:69] op_sel_hi:[1,0,0]
	s_waitcnt vmcnt(3)
; template <int MODE>
; __device__ __forceinline__ void gemm_tile(const Params& P, int tm, int tn, unsigned char* smem) {
;     ...
;                 const float rstd = rsqrtf(ss * (1.0f / 64.0f) + EPS) * scl;
; #pragma unroll
;                 for (int j = 0; j < 4; ++j)
; #pragma unroll
;                     for (int r = 0; r < 4; ++r) acc[i][j][r] *= rstd * gn[j][r];
;             }
;         }
	v_pk_mul_f32 v[102:103], v[84:85], v[70:71] op_sel_hi:[1,0]
	v_mul_f32_e32 v100, 0x4b800000, v69
	v_cmp_gt_f32_e32 vcc, s21, v69
	v_cmp_gt_f32_e64 s[0:1], s21, v68
	v_pk_mul_f32 v[62:63], v[62:63], v[102:103]
	v_cndmask_b32_e32 v69, v69, v100, vcc
	v_mul_f32_e32 v100, 0x4b800000, v68
	v_rsq_f32_e32 v69, v69
	v_cndmask_b32_e64 v68, v68, v100, s[0:1]
	v_rsq_f32_e32 v100, v68
	v_pk_mul_f32 v[102:103], v[84:85], v[66:67] op_sel_hi:[1,0]
	v_mul_f32_e32 v68, 0x45800000, v69
	v_cndmask_b32_e32 v68, v69, v68, vcc
	v_mul_f32_e32 v69, 0x45800000, v100
	v_cndmask_b32_e64 v69, v100, v69, s[0:1]
	v_mul_f32_e32 v68, v108, v68
	v_mul_f32_e32 v100, v108, v69
	v_pk_mul_f32 v[104:105], v[86:87], v[70:71] op_sel_hi:[1,0]
	v_pk_mul_f32 v[46:47], v[46:47], v[102:103]
	v_pk_mul_f32 v[102:103], v[84:85], v[68:69] op_sel_hi:[1,0]
	v_pk_mul_f32 v[84:85], v[84:85], v[100:101] op_sel_hi:[1,0]
	v_pk_mul_f32 v[64:65], v[64:65], v[104:105]
	v_pk_mul_f32 v[104:105], v[86:87], v[66:67] op_sel_hi:[1,0]
	v_pk_mul_f32 v[14:15], v[14:15], v[84:85]
	s_waitcnt vmcnt(2)
	v_pk_mul_f32 v[84:85], v[88:89], v[70:71] op_sel_hi:[1,0]
	v_pk_mul_f32 v[48:49], v[48:49], v[104:105]
	v_pk_mul_f32 v[104:105], v[86:87], v[68:69] op_sel_hi:[1,0]
	v_pk_mul_f32 v[86:87], v[86:87], v[100:101] op_sel_hi:[1,0]
	v_pk_mul_f32 v[58:59], v[58:59], v[84:85]
	v_pk_mul_f32 v[84:85], v[88:89], v[66:67] op_sel_hi:[1,0]
	v_pk_mul_f32 v[16:17], v[16:17], v[86:87]
	v_pk_mul_f32 v[86:87], v[90:91], v[70:71] op_sel_hi:[1,0]
	v_pk_mul_f32 v[42:43], v[42:43], v[84:85]
	v_pk_mul_f32 v[84:85], v[88:89], v[68:69] op_sel_hi:[1,0]
	v_pk_mul_f32 v[60:61], v[60:61], v[86:87]
	v_pk_mul_f32 v[86:87], v[90:91], v[66:67] op_sel_hi:[1,0]
	v_pk_mul_f32 v[26:27], v[26:27], v[84:85]
	v_pk_mul_f32 v[84:85], v[88:89], v[100:101] op_sel_hi:[1,0]
	v_pk_mul_f32 v[44:45], v[44:45], v[86:87]
	v_pk_mul_f32 v[86:87], v[90:91], v[68:69] op_sel_hi:[1,0]
	v_pk_mul_f32 v[10:11], v[10:11], v[84:85]
	s_waitcnt vmcnt(1)
	v_pk_mul_f32 v[84:85], v[92:93], v[70:71] op_sel_hi:[1,0]
	v_pk_mul_f32 v[28:29], v[28:29], v[86:87]
	v_pk_mul_f32 v[86:87], v[90:91], v[100:101] op_sel_hi:[1,0]
	v_pk_mul_f32 v[54:55], v[54:55], v[84:85]
	v_pk_mul_f32 v[84:85], v[92:93], v[66:67] op_sel_hi:[1,0]
	v_pk_mul_f32 v[12:13], v[12:13], v[86:87]
	v_pk_mul_f32 v[86:87], v[94:95], v[70:71] op_sel_hi:[1,0]
	v_pk_mul_f32 v[38:39], v[38:39], v[84:85]
	v_pk_mul_f32 v[84:85], v[92:93], v[68:69] op_sel_hi:[1,0]
	v_pk_mul_f32 v[56:57], v[56:57], v[86:87]
	v_pk_mul_f32 v[86:87], v[94:95], v[66:67] op_sel_hi:[1,0]
	v_pk_mul_f32 v[22:23], v[22:23], v[84:85]
	v_pk_mul_f32 v[84:85], v[92:93], v[100:101] op_sel_hi:[1,0]
	v_pk_mul_f32 v[40:41], v[40:41], v[86:87]
	v_pk_mul_f32 v[86:87], v[94:95], v[68:69] op_sel_hi:[1,0]
	v_pk_mul_f32 v[6:7], v[6:7], v[84:85]
	s_waitcnt vmcnt(0)
	v_pk_mul_f32 v[84:85], v[96:97], v[70:71] op_sel_hi:[1,0]
	v_pk_mul_f32 v[24:25], v[24:25], v[86:87]
	v_pk_mul_f32 v[86:87], v[94:95], v[100:101] op_sel_hi:[1,0]
	v_pk_mul_f32 v[50:51], v[50:51], v[84:85]
	v_pk_mul_f32 v[84:85], v[96:97], v[66:67] op_sel_hi:[1,0]
	v_pk_mul_f32 v[8:9], v[8:9], v[86:87]
	v_pk_mul_f32 v[86:87], v[98:99], v[70:71] op_sel_hi:[1,0]
	v_pk_mul_f32 v[34:35], v[34:35], v[84:85]
	v_pk_mul_f32 v[84:85], v[96:97], v[68:69] op_sel_hi:[1,0]
	v_pk_mul_f32 v[68:69], v[98:99], v[68:69] op_sel_hi:[1,0]
	v_pk_mul_f32 v[52:53], v[52:53], v[86:87]
	v_pk_mul_f32 v[86:87], v[98:99], v[66:67] op_sel_hi:[1,0]
	v_pk_mul_f32 v[20:21], v[20:21], v[68:69]
	v_pk_mul_f32 v[18:19], v[18:19], v[84:85]
	v_pk_mul_f32 v[68:69], v[96:97], v[100:101] op_sel_hi:[1,0]
	v_pk_mul_f32 v[84:85], v[98:99], v[100:101] op_sel_hi:[1,0]
	v_pk_mul_f32 v[32:33], v[32:33], v[104:105]
	v_pk_mul_f32 v[30:31], v[30:31], v[102:103]
	v_pk_mul_f32 v[36:37], v[36:37], v[86:87]
	v_pk_mul_f32 v[4:5], v[4:5], v[84:85]
	v_pk_mul_f32 v[2:3], v[2:3], v[68:69]
	s_branch .LBB0_181

; template <int MODE>
; __device__ __forceinline__ void gemm_tile(const Params& P, int tm, int tn, unsigned char* smem) {
;     ...
;     const int tid = opaque_tid(), lane = tid & 63, wave = tid >> 6, wr = wave >> 1, wc = wave & 1, g = lane >> 4, lr = lane & 15;
;     const int m0 = tm * 128, n0 = tn * 128;
;     const int srow = tid >> 3, sc = tid & 7;
;     constexpr unsigned LDA = (MODE == 2 ? NZ : 1024) * 2u;
;     unsigned aoff, boff; int soff0;
;     {
;         int ar = m0 + srow;
;         if (MODE == 2) { const int b = ar >> 11, t = ar & 2047; ar = b * L + NMETA + t; }
;         aoff = (unsigned)ar * LDA + (unsigned)sc * 16u;
;         boff = (unsigned)(n0 + srow) * 2048u + (unsigned)sc * 16u;
;         soff0 = srow * 128 + ((sc ^ (srow & 7)) << 4);
;     }
;     const unsigned char* Ab = (const unsigned char*)A; const unsigned char* Bb = (const unsigned char*)Bt;
;     float4 ssp0, ssp1, ssp2, ssp3;
;     if (MODE == 3) {
;         const float* ssq = (const float*)(P.ws + WS_SSQ) + (size_t)(m0 + wr * 64 + lr) * 16 + 4 * g;
;         ssp0 = *(const float4*)(ssq); ssp1 = *(const float4*)(ssq + 16 * 16); ssp2 = *(const float4*)(ssq + 32 * 16); ssp3 = *(const float4*)(ssq + 48 * 16);
;     }
;     f32x4 acc[4][4];
; #pragma unroll
;     for (int i = 0; i < 4; ++i)
; #pragma unroll
;         for (int j = 0; j < 4; ++j) acc[i][j] = (f32x4){0.f, 0.f, 0.f, 0.f};
;     uint4 ra0, ra1, ra2, ra3, rb0, rb1, rb2, rb3;
;     ...
;     unsigned char* sA0 = smem; unsigned char* sB0 = smem + 16384; unsigned char* sA1 = smem + 32768; unsigned char* sB1 = smem + 49152;
;     G_LOAD(0)
;     G_WRITE(sA0, sB0)
;     __syncthreads();
;     const int arow_off = (wr * 64 + lr) * 128, brow_off = (wc * 64 + lr) * 128, sw = lr & 7;
;     G_LOAD(1)
;     for (int kt = 0; kt < 16; ++kt) {
;         unsigned char* sA = (kt & 1) ? sA1 : sA0; unsigned char* sB = (kt & 1) ? sB1 : sB0;
;         unsigned char* nA = (kt & 1) ? sA0 : sA1; unsigned char* nB = (kt & 1) ? sB0 : sB1;
;         bf16x8 fa[4], fb[4], ga[4], gb[4];
;         const int ch0 = ((g ^ sw) << 4), ch1 = (((4 + g) ^ sw) << 4);
;         const unsigned ko = (unsigned)(kt + 2) * 128u;
;         const unsigned koa = ko + ((MODE == 2 && kt + 2 >= 8) ? (unsigned)(ZC_FQ - 512) * 2u : 0u);
; __global__ void __launch_bounds__(256, 2) mega(Params P) {
;     ...
;         for (int tile = vb; tile < full; tile += G) P1_TILE(tile)
.LBB0_221:
	s_add_i32 s0, s14, s3
	s_mul_hi_i32 s1, s0, 0x92492493
	s_add_i32 s1, s1, s0
	s_lshr_b32 s6, s1, 31
	s_ashr_i32 s1, s1, 7
	s_add_i32 s1, s1, s6
	s_mul_i32 s6, s1, 0xffffff20
	s_lshl_b32 s1, s1, 3
	s_add_i32 s6, s6, s0
	s_sub_i32 s7, 0x81, s1
	s_cmpk_gt_i32 s0, 0xdff
	s_cselect_b32 s0, s7, 8
	s_abs_i32 s7, s0
	v_cvt_f32_u32_e32 v2, s7
	s_sub_i32 s10, 0, s7
	s_abs_i32 s8, s6
	s_xor_b32 s9, s6, s0
	v_rcp_iflag_f32_e32 v2, v2
	s_ashr_i32 s9, s9, 31
	v_mov_b32_e32 v69, v0
	v_mul_f32_e32 v2, 0x4f7ffffe, v2
	v_cvt_u32_f32_e32 v2, v2
	v_lshlrev_b32_e32 v3, 4, v69
	v_and_b32_e32 v5, 0x70, v3
	v_and_b32_e32 v78, 15, v69
	v_readfirstlane_b32 s11, v2
	s_mul_i32 s10, s10, s11
	s_mul_hi_u32 s10, s11, s10
	s_add_i32 s11, s11, s10
	s_mul_hi_u32 s10, s8, s11
	s_mul_i32 s11, s10, s7
	s_sub_i32 s8, s8, s11
	s_add_i32 s12, s10, 1
	s_sub_i32 s11, s8, s7
	s_cmp_ge_u32 s8, s7
	s_cselect_b32 s10, s12, s10
	s_cselect_b32 s8, s11, s8
	s_add_i32 s11, s10, 1
	s_cmp_ge_u32 s8, s7
	s_cselect_b32 s7, s11, s10
	s_xor_b32 s7, s7, s9
	s_sub_i32 s7, s7, s9
	s_mul_i32 s0, s7, s0
	s_add_i32 s6, s6, s1
	s_sub_i32 s0, s6, s0
	s_lshl_b32 s11, s0, 7
	v_ashrrev_i32_e32 v2, 3, v69
	s_lshl_b32 s6, s7, 7
	v_add_u32_e32 v4, s11, v2
	v_add_u32_e32 v3, s6, v2
	v_lshl_or_b32 v8, v4, 11, v5
	v_lshl_or_b32 v3, v3, 11, v5
	s_add_u32 s0, s28, 0xc075800
	v_add_u32_e32 v9, 0x10000, v8
	s_addc_u32 s1, s29, 0
	v_add_u32_e32 v22, 0x20000, v8
	global_load_dwordx4 v[4:7], v9, s[36:37]
	global_load_dwordx4 v[10:13], v22, s[36:37]
	global_load_dwordx4 v[14:17], v8, s[36:37]
	global_load_dwordx4 v[18:21], v3, s[0:1]
	v_add_u32_e32 v9, 0x20000, v3
	v_add_u32_e32 v30, 0x30000, v3
	global_load_dwordx4 v[22:25], v9, s[0:1]
	global_load_dwordx4 v[26:29], v30, s[0:1]
	v_add_u32_e32 v9, 0x30000, v8
	v_add_u32_e32 v38, 0x10000, v3
	global_load_dwordx4 v[30:33], v9, s[36:37]
	global_load_dwordx4 v[34:37], v38, s[0:1]
	v_xor_b32_e32 v9, v2, v69
	s_movk_i32 s8, 0x70
	v_lshlrev_b32_e32 v2, 7, v2
	v_lshlrev_b32_e32 v9, 4, v9
	v_and_or_b32 v2, v9, s8, v2
	v_add_u32_e32 v2, 0, v2
	v_or_b32_e32 v45, 0x80, v8
	v_or_b32_e32 v9, 0x80, v3
	v_add_u32_e32 v42, 0x10080, v3
	v_add_u32_e32 v43, 0x20080, v3
	v_add_u32_e32 v44, 0x30080, v3
	v_add_u32_e32 v46, 0x10080, v8
	v_add_u32_e32 v47, 0x20080, v8
	v_add_u32_e32 v48, 0x30080, v8
	v_ashrrev_i32_e32 v79, 7, v69
	v_bfe_u32 v80, v69, 6, 1
	v_bfe_u32 v81, v69, 4, 2
	s_waitcnt vmcnt(5)
	ds_write_b128 v2, v[14:17]
	s_waitcnt vmcnt(4)
	ds_write_b128 v2, v[18:21] offset:16384
	s_waitcnt vmcnt(3)
	ds_write_b128 v2, v[22:25] offset:24576
	s_waitcnt vmcnt(2)
	ds_write_b128 v2, v[26:29] offset:28672
	ds_write_b128 v2, v[4:7] offset:4096
	ds_write_b128 v2, v[10:13] offset:8192
	s_waitcnt vmcnt(1)
	ds_write_b128 v2, v[30:33] offset:12288
	s_waitcnt vmcnt(0)
	ds_write_b128 v2, v[34:37] offset:20480
	s_waitcnt lgkmcnt(0)
	s_barrier
	global_load_dwordx4 v[10:13], v45, s[36:37]
	global_load_dwordx4 v[14:17], v46, s[36:37]
	global_load_dwordx4 v[18:21], v47, s[36:37]
	global_load_dwordx4 v[22:25], v48, s[36:37]
	global_load_dwordx4 v[26:29], v9, s[0:1]
	global_load_dwordx4 v[30:33], v42, s[0:1]
	global_load_dwordx4 v[34:37], v43, s[0:1]
	global_load_dwordx4 v[38:41], v44, s[0:1]
	v_lshrrev_b32_e32 v4, 4, v69
	v_lshlrev_b32_e32 v5, 7, v78
	v_and_b32_e32 v9, 7, v69
	v_lshl_or_b32 v6, v79, 13, v5
	v_bitop3_b32 v4, v4, v9, 3 bitop3:0x6c
	v_lshl_or_b32 v5, v80, 13, v5
	v_lshlrev_b32_e32 v4, 4, v4
	v_add_u32_e32 v66, 0, v6
	v_add_u32_e32 v6, v66, v4
	v_add_u32_e32 v5, 0, v5
	v_add_u32_e32 v7, v5, v4
	ds_read_b128 v[42:45], v6
	ds_read_b128 v[46:49], v6 offset:2048
	ds_read_b128 v[50:53], v7 offset:16384
	ds_read_b128 v[54:57], v7 offset:18432
	ds_read_b128 v[58:61], v6 offset:4096
	ds_read_b128 v[62:65], v6 offset:6144
	ds_read_b128 v[82:85], v7 offset:20480
	ds_read_b128 v[86:89], v7 offset:22528
	v_bitop3_b32 v4, v81, v9, 4 bitop3:0x36
	v_lshlrev_b32_e32 v9, 4, v4
	s_setprio 2
	global_load_dwordx4 v[90:93], v8, s[36:37] offset:256
	s_waitcnt vmcnt(8)
	ds_write_b128 v2, v[10:13] offset:32768
	v_add_u32_e32 v4, v66, v9
	v_add_u32_e32 v5, v5, v9
	ds_read_b128 v[10:13], v4
	ds_read_b128 v[94:97], v5 offset:16384
	s_waitcnt lgkmcnt(8)
	v_mfma_f32_16x16x32_bf16 v[98:101], v[50:53], v[42:45], 0
	s_waitcnt lgkmcnt(7)
	v_mfma_f32_16x16x32_bf16 v[102:105], v[54:57], v[42:45], 0
	s_waitcnt lgkmcnt(4)
	v_mfma_f32_16x16x32_bf16 v[106:109], v[82:85], v[42:45], 0
	s_waitcnt lgkmcnt(3)
	v_mfma_f32_16x16x32_bf16 v[42:45], v[86:89], v[42:45], 0
	v_add_u32_e32 v222, 0x10000, v8
	global_load_dwordx4 v[110:113], v222, s[36:37] offset:256
	s_waitcnt vmcnt(8)
	ds_write_b128 v2, v[14:17] offset:36864
	ds_read_b128 v[14:17], v4 offset:2048
	ds_read_b128 v[114:117], v5 offset:18432
	v_mfma_f32_16x16x32_bf16 v[118:121], v[50:53], v[46:49], 0
	v_mfma_f32_16x16x32_bf16 v[122:125], v[54:57], v[46:49], 0
	v_mfma_f32_16x16x32_bf16 v[126:129], v[82:85], v[46:49], 0
	v_mfma_f32_16x16x32_bf16 v[46:49], v[86:89], v[46:49], 0
	v_add_u32_e32 v223, 0x20000, v8
	global_load_dwordx4 v[132:135], v223, s[36:37] offset:256
	s_waitcnt vmcnt(8)
	ds_write_b128 v2, v[18:21] offset:40960
	ds_read_b128 v[18:21], v4 offset:4096
	ds_read_b128 v[146:149], v5 offset:20480
	v_mfma_f32_16x16x32_bf16 v[150:153], v[50:53], v[58:61], 0
	v_mfma_f32_16x16x32_bf16 v[154:157], v[54:57], v[58:61], 0
	v_mfma_f32_16x16x32_bf16 v[158:161], v[82:85], v[58:61], 0
	v_mfma_f32_16x16x32_bf16 v[58:61], v[86:89], v[58:61], 0
	v_add_u32_e32 v224, 0x30000, v8
	global_load_dwordx4 v[162:165], v224, s[36:37] offset:256
	s_waitcnt vmcnt(8)
; template <int MODE>
; __device__ __forceinline__ void gemm_tile(const Params& P, int tm, int tn, unsigned char* smem) {
;     ...
;     for (int kt = 0; kt < 16; ++kt) {
;         unsigned char* sA = (kt & 1) ? sA1 : sA0; unsigned char* sB = (kt & 1) ? sB1 : sB0;
;         unsigned char* nA = (kt & 1) ? sA0 : sA1; unsigned char* nB = (kt & 1) ? sB0 : sB1;
;         bf16x8 fa[4], fb[4], ga[4], gb[4];
;         const int ch0 = ((g ^ sw) << 4), ch1 = (((4 + g) ^ sw) << 4);
;         const unsigned ko = (unsigned)(kt + 2) * 128u;
;         const unsigned koa = ko + ((MODE == 2 && kt + 2 >= 8) ? (unsigned)(ZC_FQ - 512) * 2u : 0u);
;         const bool wr_ok = kt < 15, ld_ok = kt < 14;
; #pragma unroll
;         for (int i = 0; i < 4; ++i) { fa[i] = *(const bf16x8*)(sA + arow_off + i * 2048 + ch0); fb[i] = *(const bf16x8*)(sB + brow_off + i * 2048 + ch0); }
;         __builtin_amdgcn_sched_barrier(0);
;         __builtin_amdgcn_s_setprio(2);
;         if (wr_ok) *(uint4*)(nA + soff0) = ra0;
;         if (ld_ok) ra0 = *(const uint4*)(Ab + (aoff + 0u * LDA + koa));
;         ga[0] = *(const bf16x8*)(sA + arow_off + 0 * 2048 + ch1); gb[0] = *(const bf16x8*)(sB + brow_off + 0 * 2048 + ch1);
;         __builtin_amdgcn_sched_barrier(0);
; #pragma unroll
;         for (int j = 0; j < 4; ++j) acc[0][j] = __builtin_amdgcn_mfma_f32_16x16x32_bf16(fb[j], fa[0], acc[0][j], 0, 0, 0);
;         __builtin_amdgcn_sched_barrier(0);
;         if (wr_ok) *(uint4*)(nA + soff0 + 4096) = ra1;
;         if (ld_ok) ra1 = *(const uint4*)(Ab + (aoff + 32u * LDA + koa));
;         ga[1] = *(const bf16x8*)(sA + arow_off + 1 * 2048 + ch1); gb[1] = *(const bf16x8*)(sB + brow_off + 1 * 2048 + ch1);
;         __builtin_amdgcn_sched_barrier(0);
; #pragma unroll
;         for (int j = 0; j < 4; ++j) acc[1][j] = __builtin_amdgcn_mfma_f32_16x16x32_bf16(fb[j], fa[1], acc[1][j], 0, 0, 0);
;         __builtin_amdgcn_sched_barrier(0);
;         if (wr_ok) *(uint4*)(nA + soff0 + 8192) = ra2;
;         if (ld_ok) ra2 = *(const uint4*)(Ab + (aoff + 64u * LDA + koa));
;         ga[2] = *(const bf16x8*)(sA + arow_off + 2 * 2048 + ch1); gb[2] = *(const bf16x8*)(sB + brow_off + 2 * 2048 + ch1);
;         __builtin_amdgcn_sched_barrier(0);
; #pragma unroll
;         for (int j = 0; j < 4; ++j) acc[2][j] = __builtin_amdgcn_mfma_f32_16x16x32_bf16(fb[j], fa[2], acc[2][j], 0, 0, 0);
	ds_write_b128 v2, v[22:25] offset:45056
	ds_read_b128 v[22:25], v4 offset:6144
	ds_read_b128 v[166:169], v5 offset:22528
	v_mfma_f32_16x16x32_bf16 v[50:53], v[50:53], v[62:65], 0
	v_mfma_f32_16x16x32_bf16 v[54:57], v[54:57], v[62:65], 0
	v_mfma_f32_16x16x32_bf16 v[82:85], v[82:85], v[62:65], 0
	v_mfma_f32_16x16x32_bf16 v[62:65], v[86:89], v[62:65], 0
	global_load_dwordx4 v[86:89], v3, s[0:1] offset:256
	s_waitcnt vmcnt(8)
	ds_write_b128 v2, v[26:29] offset:49152
	s_waitcnt lgkmcnt(10)
	v_mfma_f32_16x16x32_bf16 v[26:29], v[94:97], v[10:13], v[98:101]
	s_waitcnt lgkmcnt(7)
	v_mfma_f32_16x16x32_bf16 v[98:101], v[114:117], v[10:13], v[102:105]
	s_waitcnt lgkmcnt(4)
	v_mfma_f32_16x16x32_bf16 v[102:105], v[146:149], v[10:13], v[106:109]
	s_waitcnt lgkmcnt(1)
	v_mfma_f32_16x16x32_bf16 v[10:13], v[166:169], v[10:13], v[42:45]
	v_add_u32_e32 v225, 0x10000, v3
	global_load_dwordx4 v[42:45], v225, s[0:1] offset:256
	s_waitcnt vmcnt(8)
	ds_write_b128 v2, v[30:33] offset:53248
	v_mfma_f32_16x16x32_bf16 v[30:33], v[94:97], v[14:17], v[118:121]
	v_mfma_f32_16x16x32_bf16 v[106:109], v[114:117], v[14:17], v[122:125]
	v_mfma_f32_16x16x32_bf16 v[118:121], v[146:149], v[14:17], v[126:129]
	v_mfma_f32_16x16x32_bf16 v[14:17], v[166:169], v[14:17], v[46:49]
	v_add_u32_e32 v226, 0x20000, v3
	global_load_dwordx4 v[46:49], v226, s[0:1] offset:256
	s_waitcnt vmcnt(8)
	ds_write_b128 v2, v[34:37] offset:57344
	v_mfma_f32_16x16x32_bf16 v[34:37], v[94:97], v[18:21], v[150:153]
	v_mfma_f32_16x16x32_bf16 v[122:125], v[114:117], v[18:21], v[154:157]
	v_mfma_f32_16x16x32_bf16 v[126:129], v[146:149], v[18:21], v[158:161]
	v_mfma_f32_16x16x32_bf16 v[18:21], v[166:169], v[18:21], v[58:61]
	v_add_u32_e32 v227, 0x30000, v3
	global_load_dwordx4 v[58:61], v227, s[0:1] offset:256
	s_waitcnt vmcnt(8)
	ds_write_b128 v2, v[38:41] offset:61440
	v_mfma_f32_16x16x32_bf16 v[38:41], v[94:97], v[22:25], v[50:53]
	v_mfma_f32_16x16x32_bf16 v[50:53], v[114:117], v[22:25], v[54:57]
	v_mfma_f32_16x16x32_bf16 v[54:57], v[146:149], v[22:25], v[82:85]
	v_mfma_f32_16x16x32_bf16 v[22:25], v[166:169], v[22:25], v[62:65]
	s_setprio 0
	s_waitcnt lgkmcnt(0)
	s_barrier
	ds_read_b128 v[62:65], v6 offset:32768
	ds_read_b128 v[82:85], v6 offset:34816
	ds_read_b128 v[94:97], v7 offset:49152
	ds_read_b128 v[114:117], v7 offset:51200
	ds_read_b128 v[146:149], v6 offset:36864
	ds_read_b128 v[150:153], v6 offset:38912
	ds_read_b128 v[154:157], v7 offset:53248
	ds_read_b128 v[158:161], v7 offset:55296
	s_setprio 2
	global_load_dwordx4 v[166:169], v8, s[36:37] offset:384
	s_waitcnt vmcnt(8)
	ds_write_b128 v2, v[90:93]
	ds_read_b128 v[90:93], v4 offset:32768
	ds_read_b128 v[170:173], v5 offset:49152
	s_waitcnt lgkmcnt(8)
	v_mfma_f32_16x16x32_bf16 v[26:29], v[94:97], v[62:65], v[26:29]
	s_waitcnt lgkmcnt(3)
	v_mfma_f32_16x16x32_bf16 v[10:13], v[158:161], v[62:65], v[10:13]
	v_mfma_f32_16x16x32_bf16 v[98:101], v[114:117], v[62:65], v[98:101]
	v_mfma_f32_16x16x32_bf16 v[102:105], v[154:157], v[62:65], v[102:105]
	global_load_dwordx4 v[62:65], v222, s[36:37] offset:384
	v_mfma_f32_16x16x32_bf16 v[30:33], v[94:97], v[82:85], v[30:33]
	s_waitcnt vmcnt(8)
	ds_write_b128 v2, v[110:113] offset:4096
	v_mfma_f32_16x16x32_bf16 v[14:17], v[158:161], v[82:85], v[14:17]
	ds_read_b128 v[110:113], v4 offset:34816
	v_mfma_f32_16x16x32_bf16 v[106:109], v[114:117], v[82:85], v[106:109]
	ds_read_b128 v[174:177], v5 offset:51200
	v_mfma_f32_16x16x32_bf16 v[118:121], v[154:157], v[82:85], v[118:121]
	global_load_dwordx4 v[82:85], v223, s[36:37] offset:384
	v_mfma_f32_16x16x32_bf16 v[34:37], v[94:97], v[146:149], v[34:37]
	s_waitcnt vmcnt(8)
	ds_write_b128 v2, v[132:135] offset:8192
	v_mfma_f32_16x16x32_bf16 v[18:21], v[158:161], v[146:149], v[18:21]
	ds_read_b128 v[132:135], v4 offset:36864
	v_mfma_f32_16x16x32_bf16 v[122:125], v[114:117], v[146:149], v[122:125]
	ds_read_b128 v[178:181], v5 offset:53248
	v_mfma_f32_16x16x32_bf16 v[126:129], v[154:157], v[146:149], v[126:129]
	global_load_dwordx4 v[146:149], v224, s[36:37] offset:384
	v_mfma_f32_16x16x32_bf16 v[38:41], v[94:97], v[150:153], v[38:41]
	s_waitcnt vmcnt(8)
	ds_write_b128 v2, v[162:165] offset:12288
	v_mfma_f32_16x16x32_bf16 v[50:53], v[114:117], v[150:153], v[50:53]
	ds_read_b128 v[162:165], v4 offset:38912
	v_mfma_f32_16x16x32_bf16 v[54:57], v[154:157], v[150:153], v[54:57]
	ds_read_b128 v[182:185], v5 offset:55296
	v_mfma_f32_16x16x32_bf16 v[22:25], v[158:161], v[150:153], v[22:25]
	global_load_dwordx4 v[94:97], v3, s[0:1] offset:384
	s_waitcnt vmcnt(8)
	ds_write_b128 v2, v[86:89] offset:16384
	s_waitcnt lgkmcnt(10)
	v_mfma_f32_16x16x32_bf16 v[26:29], v[170:173], v[90:93], v[26:29]
	s_waitcnt lgkmcnt(1)
	v_mfma_f32_16x16x32_bf16 v[10:13], v[182:185], v[90:93], v[10:13]
	v_mfma_f32_16x16x32_bf16 v[86:89], v[174:177], v[90:93], v[98:101]
	v_mfma_f32_16x16x32_bf16 v[98:101], v[178:181], v[90:93], v[102:105]
	global_load_dwordx4 v[90:93], v225, s[0:1] offset:384
	s_waitcnt vmcnt(8)
	ds_write_b128 v2, v[42:45] offset:20480
	v_mfma_f32_16x16x32_bf16 v[30:33], v[170:173], v[110:113], v[30:33]
	v_mfma_f32_16x16x32_bf16 v[42:45], v[174:177], v[110:113], v[106:109]
	v_mfma_f32_16x16x32_bf16 v[14:17], v[182:185], v[110:113], v[14:17]
	v_mfma_f32_16x16x32_bf16 v[102:105], v[178:181], v[110:113], v[118:121]
	global_load_dwordx4 v[106:109], v226, s[0:1] offset:384
	s_waitcnt vmcnt(8)
	ds_write_b128 v2, v[46:49] offset:24576
	v_mfma_f32_16x16x32_bf16 v[34:37], v[170:173], v[132:135], v[34:37]
	v_mfma_f32_16x16x32_bf16 v[46:49], v[174:177], v[132:135], v[122:125]
	v_mfma_f32_16x16x32_bf16 v[18:21], v[182:185], v[132:135], v[18:21]
	v_mfma_f32_16x16x32_bf16 v[110:113], v[178:181], v[132:135], v[126:129]
	global_load_dwordx4 v[114:117], v227, s[0:1] offset:384
	v_mfma_f32_16x16x32_bf16 v[38:41], v[170:173], v[162:165], v[38:41]
	s_waitcnt vmcnt(8)
	ds_write_b128 v2, v[58:61] offset:28672
	v_mfma_f32_16x16x32_bf16 v[50:53], v[174:177], v[162:165], v[50:53]
	v_mfma_f32_16x16x32_bf16 v[54:57], v[178:181], v[162:165], v[54:57]
	v_mfma_f32_16x16x32_bf16 v[22:25], v[182:185], v[162:165], v[22:25]
	s_setprio 0
	s_waitcnt lgkmcnt(0)
	s_barrier
; template <int MODE>
; __device__ __forceinline__ void gemm_tile(const Params& P, int tm, int tn, unsigned char* smem) {
;     ...
;     for (int kt = 0; kt < 16; ++kt) {
;         unsigned char* sA = (kt & 1) ? sA1 : sA0; unsigned char* sB = (kt & 1) ? sB1 : sB0;
;         unsigned char* nA = (kt & 1) ? sA0 : sA1; unsigned char* nB = (kt & 1) ? sB0 : sB1;
;         bf16x8 fa[4], fb[4], ga[4], gb[4];
;         const int ch0 = ((g ^ sw) << 4), ch1 = (((4 + g) ^ sw) << 4);
;         const unsigned ko = (unsigned)(kt + 2) * 128u;
;         const unsigned koa = ko + ((MODE == 2 && kt + 2 >= 8) ? (unsigned)(ZC_FQ - 512) * 2u : 0u);
;         const bool wr_ok = kt < 15, ld_ok = kt < 14;
; #pragma unroll
;         for (int i = 0; i < 4; ++i) { fa[i] = *(const bf16x8*)(sA + arow_off + i * 2048 + ch0); fb[i] = *(const bf16x8*)(sB + brow_off + i * 2048 + ch0); }
;         __builtin_amdgcn_sched_barrier(0);
;         __builtin_amdgcn_s_setprio(2);
;         if (wr_ok) *(uint4*)(nA + soff0) = ra0;
;         if (ld_ok) ra0 = *(const uint4*)(Ab + (aoff + 0u * LDA + koa));
;         ga[0] = *(const bf16x8*)(sA + arow_off + 0 * 2048 + ch1); gb[0] = *(const bf16x8*)(sB + brow_off + 0 * 2048 + ch1);
;         __builtin_amdgcn_sched_barrier(0);
; #pragma unroll
;         for (int j = 0; j < 4; ++j) acc[0][j] = __builtin_amdgcn_mfma_f32_16x16x32_bf16(fb[j], fa[0], acc[0][j], 0, 0, 0);
;         __builtin_amdgcn_sched_barrier(0);
;         if (wr_ok) *(uint4*)(nA + soff0 + 4096) = ra1;
;         if (ld_ok) ra1 = *(const uint4*)(Ab + (aoff + 32u * LDA + koa));
;         ga[1] = *(const bf16x8*)(sA + arow_off + 1 * 2048 + ch1); gb[1] = *(const bf16x8*)(sB + brow_off + 1 * 2048 + ch1);
;         __builtin_amdgcn_sched_barrier(0);
; #pragma unroll
;         for (int j = 0; j < 4; ++j) acc[1][j] = __builtin_amdgcn_mfma_f32_16x16x32_bf16(fb[j], fa[1], acc[1][j], 0, 0, 0);
;         __builtin_amdgcn_sched_barrier(0);
;         if (wr_ok) *(uint4*)(nA + soff0 + 8192) = ra2;
;         if (ld_ok) ra2 = *(const uint4*)(Ab + (aoff + 64u * LDA + koa));
;         ga[2] = *(const bf16x8*)(sA + arow_off + 2 * 2048 + ch1); gb[2] = *(const bf16x8*)(sB + brow_off + 2 * 2048 + ch1);
;         __builtin_amdgcn_sched_barrier(0);
; #pragma unroll
;         for (int j = 0; j < 4; ++j) acc[2][j] = __builtin_amdgcn_mfma_f32_16x16x32_bf16(fb[j], fa[2], acc[2][j], 0, 0, 0);
	ds_read_b128 v[58:61], v6
	ds_read_b128 v[118:121], v6 offset:2048
	ds_read_b128 v[122:125], v7 offset:16384
	ds_read_b128 v[126:129], v7 offset:18432
	ds_read_b128 v[132:135], v6 offset:4096
	ds_read_b128 v[150:153], v6 offset:6144
	ds_read_b128 v[154:157], v7 offset:20480
	ds_read_b128 v[158:161], v7 offset:22528
	s_setprio 2
	global_load_dwordx4 v[162:165], v8, s[36:37] offset:512
	s_waitcnt vmcnt(8)
	ds_write_b128 v2, v[166:169] offset:32768
	ds_read_b128 v[166:169], v4
	ds_read_b128 v[170:173], v5 offset:16384
	s_waitcnt lgkmcnt(8)
	v_mfma_f32_16x16x32_bf16 v[26:29], v[122:125], v[58:61], v[26:29]
	s_waitcnt lgkmcnt(3)
	v_mfma_f32_16x16x32_bf16 v[10:13], v[158:161], v[58:61], v[10:13]
	v_mfma_f32_16x16x32_bf16 v[86:89], v[126:129], v[58:61], v[86:89]
	v_mfma_f32_16x16x32_bf16 v[98:101], v[154:157], v[58:61], v[98:101]
	global_load_dwordx4 v[58:61], v222, s[36:37] offset:512
	v_mfma_f32_16x16x32_bf16 v[30:33], v[122:125], v[118:121], v[30:33]
	s_waitcnt vmcnt(8)
	ds_write_b128 v2, v[62:65] offset:36864
	v_mfma_f32_16x16x32_bf16 v[42:45], v[126:129], v[118:121], v[42:45]
	ds_read_b128 v[62:65], v4 offset:2048
	v_mfma_f32_16x16x32_bf16 v[14:17], v[158:161], v[118:121], v[14:17]
	ds_read_b128 v[174:177], v5 offset:18432
	v_mfma_f32_16x16x32_bf16 v[102:105], v[154:157], v[118:121], v[102:105]
	global_load_dwordx4 v[118:121], v223, s[36:37] offset:512
	v_mfma_f32_16x16x32_bf16 v[34:37], v[122:125], v[132:135], v[34:37]
	s_waitcnt vmcnt(8)
	ds_write_b128 v2, v[82:85] offset:40960
	v_mfma_f32_16x16x32_bf16 v[46:49], v[126:129], v[132:135], v[46:49]
	ds_read_b128 v[82:85], v4 offset:4096
	v_mfma_f32_16x16x32_bf16 v[18:21], v[158:161], v[132:135], v[18:21]
	ds_read_b128 v[178:181], v5 offset:20480
	v_mfma_f32_16x16x32_bf16 v[110:113], v[154:157], v[132:135], v[110:113]
	global_load_dwordx4 v[132:135], v224, s[36:37] offset:512
	v_mfma_f32_16x16x32_bf16 v[38:41], v[122:125], v[150:153], v[38:41]
	s_waitcnt vmcnt(8)
	ds_write_b128 v2, v[146:149] offset:45056
	v_mfma_f32_16x16x32_bf16 v[50:53], v[126:129], v[150:153], v[50:53]
	ds_read_b128 v[146:149], v4 offset:6144
	v_mfma_f32_16x16x32_bf16 v[54:57], v[154:157], v[150:153], v[54:57]
	ds_read_b128 v[182:185], v5 offset:22528
	v_mfma_f32_16x16x32_bf16 v[22:25], v[158:161], v[150:153], v[22:25]
	global_load_dwordx4 v[122:125], v3, s[0:1] offset:512
	s_waitcnt vmcnt(8)
	ds_write_b128 v2, v[94:97] offset:49152
	s_waitcnt lgkmcnt(10)
	v_mfma_f32_16x16x32_bf16 v[26:29], v[170:173], v[166:169], v[26:29]
	s_waitcnt lgkmcnt(1)
	v_mfma_f32_16x16x32_bf16 v[10:13], v[182:185], v[166:169], v[10:13]
	v_mfma_f32_16x16x32_bf16 v[86:89], v[174:177], v[166:169], v[86:89]
	v_mfma_f32_16x16x32_bf16 v[94:97], v[178:181], v[166:169], v[98:101]
	global_load_dwordx4 v[98:101], v225, s[0:1] offset:512
	s_waitcnt vmcnt(8)
	ds_write_b128 v2, v[90:93] offset:53248
	v_mfma_f32_16x16x32_bf16 v[30:33], v[170:173], v[62:65], v[30:33]
	v_mfma_f32_16x16x32_bf16 v[42:45], v[174:177], v[62:65], v[42:45]
	v_mfma_f32_16x16x32_bf16 v[14:17], v[182:185], v[62:65], v[14:17]
	v_mfma_f32_16x16x32_bf16 v[90:93], v[178:181], v[62:65], v[102:105]
	global_load_dwordx4 v[62:65], v226, s[0:1] offset:512
	v_mfma_f32_16x16x32_bf16 v[34:37], v[170:173], v[82:85], v[34:37]
	s_waitcnt vmcnt(8)
	ds_write_b128 v2, v[106:109] offset:57344
	v_mfma_f32_16x16x32_bf16 v[46:49], v[174:177], v[82:85], v[46:49]
	v_mfma_f32_16x16x32_bf16 v[18:21], v[182:185], v[82:85], v[18:21]
	v_mfma_f32_16x16x32_bf16 v[102:105], v[178:181], v[82:85], v[110:113]
	global_load_dwordx4 v[82:85], v227, s[0:1] offset:512
	v_mfma_f32_16x16x32_bf16 v[38:41], v[170:173], v[146:149], v[38:41]
	s_waitcnt vmcnt(8)
	ds_write_b128 v2, v[114:117] offset:61440
	v_mfma_f32_16x16x32_bf16 v[50:53], v[174:177], v[146:149], v[50:53]
	v_mfma_f32_16x16x32_bf16 v[54:57], v[178:181], v[146:149], v[54:57]
	v_mfma_f32_16x16x32_bf16 v[22:25], v[182:185], v[146:149], v[22:25]
	s_setprio 0
	s_waitcnt lgkmcnt(0)
	s_barrier
	ds_read_b128 v[106:109], v6 offset:32768
	ds_read_b128 v[110:113], v6 offset:34816
	ds_read_b128 v[114:117], v7 offset:49152
	ds_read_b128 v[126:129], v7 offset:51200
	ds_read_b128 v[146:149], v6 offset:36864
	ds_read_b128 v[150:153], v6 offset:38912
	ds_read_b128 v[154:157], v7 offset:53248
	ds_read_b128 v[158:161], v7 offset:55296
	s_setprio 2
	global_load_dwordx4 v[166:169], v8, s[36:37] offset:640
	s_waitcnt vmcnt(8)
	ds_write_b128 v2, v[162:165]
	ds_read_b128 v[162:165], v4 offset:32768
	ds_read_b128 v[170:173], v5 offset:49152
	s_waitcnt lgkmcnt(8)
	v_mfma_f32_16x16x32_bf16 v[26:29], v[114:117], v[106:109], v[26:29]
	s_waitcnt lgkmcnt(3)
	v_mfma_f32_16x16x32_bf16 v[10:13], v[158:161], v[106:109], v[10:13]
	v_mfma_f32_16x16x32_bf16 v[86:89], v[126:129], v[106:109], v[86:89]
	v_mfma_f32_16x16x32_bf16 v[94:97], v[154:157], v[106:109], v[94:97]
	global_load_dwordx4 v[106:109], v222, s[36:37] offset:640
	v_mfma_f32_16x16x32_bf16 v[30:33], v[114:117], v[110:113], v[30:33]
	s_waitcnt vmcnt(8)
	ds_write_b128 v2, v[58:61] offset:4096
	v_mfma_f32_16x16x32_bf16 v[42:45], v[126:129], v[110:113], v[42:45]
	ds_read_b128 v[58:61], v4 offset:34816
	v_mfma_f32_16x16x32_bf16 v[14:17], v[158:161], v[110:113], v[14:17]
	ds_read_b128 v[174:177], v5 offset:51200
	v_mfma_f32_16x16x32_bf16 v[90:93], v[154:157], v[110:113], v[90:93]
	global_load_dwordx4 v[110:113], v223, s[36:37] offset:640
	v_mfma_f32_16x16x32_bf16 v[34:37], v[114:117], v[146:149], v[34:37]
	s_waitcnt vmcnt(8)
; template <int MODE>
; __device__ __forceinline__ void gemm_tile(const Params& P, int tm, int tn, unsigned char* smem) {
;     ...
;     for (int kt = 0; kt < 16; ++kt) {
;         unsigned char* sA = (kt & 1) ? sA1 : sA0; unsigned char* sB = (kt & 1) ? sB1 : sB0;
;         unsigned char* nA = (kt & 1) ? sA0 : sA1; unsigned char* nB = (kt & 1) ? sB0 : sB1;
;         bf16x8 fa[4], fb[4], ga[4], gb[4];
;         const int ch0 = ((g ^ sw) << 4), ch1 = (((4 + g) ^ sw) << 4);
;         const unsigned ko = (unsigned)(kt + 2) * 128u;
;         const unsigned koa = ko + ((MODE == 2 && kt + 2 >= 8) ? (unsigned)(ZC_FQ - 512) * 2u : 0u);
;         const bool wr_ok = kt < 15, ld_ok = kt < 14;
; #pragma unroll
;         for (int i = 0; i < 4; ++i) { fa[i] = *(const bf16x8*)(sA + arow_off + i * 2048 + ch0); fb[i] = *(const bf16x8*)(sB + brow_off + i * 2048 + ch0); }
;         __builtin_amdgcn_sched_barrier(0);
;         __builtin_amdgcn_s_setprio(2);
;         if (wr_ok) *(uint4*)(nA + soff0) = ra0;
;         if (ld_ok) ra0 = *(const uint4*)(Ab + (aoff + 0u * LDA + koa));
;         ga[0] = *(const bf16x8*)(sA + arow_off + 0 * 2048 + ch1); gb[0] = *(const bf16x8*)(sB + brow_off + 0 * 2048 + ch1);
;         __builtin_amdgcn_sched_barrier(0);
; #pragma unroll
;         for (int j = 0; j < 4; ++j) acc[0][j] = __builtin_amdgcn_mfma_f32_16x16x32_bf16(fb[j], fa[0], acc[0][j], 0, 0, 0);
;         __builtin_amdgcn_sched_barrier(0);
;         if (wr_ok) *(uint4*)(nA + soff0 + 4096) = ra1;
;         if (ld_ok) ra1 = *(const uint4*)(Ab + (aoff + 32u * LDA + koa));
;         ga[1] = *(const bf16x8*)(sA + arow_off + 1 * 2048 + ch1); gb[1] = *(const bf16x8*)(sB + brow_off + 1 * 2048 + ch1);
;         __builtin_amdgcn_sched_barrier(0);
; #pragma unroll
;         for (int j = 0; j < 4; ++j) acc[1][j] = __builtin_amdgcn_mfma_f32_16x16x32_bf16(fb[j], fa[1], acc[1][j], 0, 0, 0);
;         __builtin_amdgcn_sched_barrier(0);
;         if (wr_ok) *(uint4*)(nA + soff0 + 8192) = ra2;
;         if (ld_ok) ra2 = *(const uint4*)(Ab + (aoff + 64u * LDA + koa));
;         ga[2] = *(const bf16x8*)(sA + arow_off + 2 * 2048 + ch1); gb[2] = *(const bf16x8*)(sB + brow_off + 2 * 2048 + ch1);
;         __builtin_amdgcn_sched_barrier(0);
; #pragma unroll
;         for (int j = 0; j < 4; ++j) acc[2][j] = __builtin_amdgcn_mfma_f32_16x16x32_bf16(fb[j], fa[2], acc[2][j], 0, 0, 0);
	ds_write_b128 v2, v[118:121] offset:8192
	v_mfma_f32_16x16x32_bf16 v[46:49], v[126:129], v[146:149], v[46:49]
	ds_read_b128 v[118:121], v4 offset:36864
	v_mfma_f32_16x16x32_bf16 v[18:21], v[158:161], v[146:149], v[18:21]
	ds_read_b128 v[178:181], v5 offset:53248
	v_mfma_f32_16x16x32_bf16 v[102:105], v[154:157], v[146:149], v[102:105]
	global_load_dwordx4 v[146:149], v224, s[36:37] offset:640
	v_mfma_f32_16x16x32_bf16 v[38:41], v[114:117], v[150:153], v[38:41]
	s_waitcnt vmcnt(8)
	ds_write_b128 v2, v[132:135] offset:12288
	v_mfma_f32_16x16x32_bf16 v[50:53], v[126:129], v[150:153], v[50:53]
	ds_read_b128 v[132:135], v4 offset:38912
	v_mfma_f32_16x16x32_bf16 v[54:57], v[154:157], v[150:153], v[54:57]
	ds_read_b128 v[182:185], v5 offset:55296
	v_mfma_f32_16x16x32_bf16 v[22:25], v[158:161], v[150:153], v[22:25]
	global_load_dwordx4 v[114:117], v3, s[0:1] offset:640
	s_waitcnt vmcnt(8)
	ds_write_b128 v2, v[122:125] offset:16384
	s_waitcnt lgkmcnt(10)
	v_mfma_f32_16x16x32_bf16 v[26:29], v[170:173], v[162:165], v[26:29]
	s_waitcnt lgkmcnt(1)
	v_mfma_f32_16x16x32_bf16 v[10:13], v[182:185], v[162:165], v[10:13]
	v_mfma_f32_16x16x32_bf16 v[86:89], v[174:177], v[162:165], v[86:89]
	v_mfma_f32_16x16x32_bf16 v[94:97], v[178:181], v[162:165], v[94:97]
	global_load_dwordx4 v[122:125], v225, s[0:1] offset:640
	v_mfma_f32_16x16x32_bf16 v[30:33], v[170:173], v[58:61], v[30:33]
	s_waitcnt vmcnt(8)
	ds_write_b128 v2, v[98:101] offset:20480
	v_mfma_f32_16x16x32_bf16 v[42:45], v[174:177], v[58:61], v[42:45]
	v_mfma_f32_16x16x32_bf16 v[14:17], v[182:185], v[58:61], v[14:17]
	v_mfma_f32_16x16x32_bf16 v[90:93], v[178:181], v[58:61], v[90:93]
	global_load_dwordx4 v[58:61], v226, s[0:1] offset:640
	s_waitcnt vmcnt(8)
	ds_write_b128 v2, v[62:65] offset:24576
	v_mfma_f32_16x16x32_bf16 v[34:37], v[170:173], v[118:121], v[34:37]
	v_mfma_f32_16x16x32_bf16 v[46:49], v[174:177], v[118:121], v[46:49]
	v_mfma_f32_16x16x32_bf16 v[62:65], v[178:181], v[118:121], v[102:105]
	v_mfma_f32_16x16x32_bf16 v[18:21], v[182:185], v[118:121], v[18:21]
	global_load_dwordx4 v[98:101], v227, s[0:1] offset:640
	v_mfma_f32_16x16x32_bf16 v[38:41], v[170:173], v[132:135], v[38:41]
	s_waitcnt vmcnt(8)
	ds_write_b128 v2, v[82:85] offset:28672
	v_mfma_f32_16x16x32_bf16 v[50:53], v[174:177], v[132:135], v[50:53]
	v_mfma_f32_16x16x32_bf16 v[54:57], v[178:181], v[132:135], v[54:57]
	v_mfma_f32_16x16x32_bf16 v[22:25], v[182:185], v[132:135], v[22:25]
	s_setprio 0
	s_waitcnt lgkmcnt(0)
	s_barrier
	ds_read_b128 v[82:85], v6
	ds_read_b128 v[102:105], v6 offset:2048
	ds_read_b128 v[118:121], v7 offset:16384
	ds_read_b128 v[126:129], v7 offset:18432
	ds_read_b128 v[132:135], v6 offset:4096
	ds_read_b128 v[150:153], v6 offset:6144
	ds_read_b128 v[154:157], v7 offset:20480
	ds_read_b128 v[158:161], v7 offset:22528
	s_setprio 2
	global_load_dwordx4 v[162:165], v8, s[36:37] offset:768
	s_waitcnt vmcnt(8)
	ds_write_b128 v2, v[166:169] offset:32768
	ds_read_b128 v[166:169], v4
	ds_read_b128 v[170:173], v5 offset:16384
	s_waitcnt lgkmcnt(8)
	v_mfma_f32_16x16x32_bf16 v[26:29], v[118:121], v[82:85], v[26:29]
	s_waitcnt lgkmcnt(3)
	v_mfma_f32_16x16x32_bf16 v[10:13], v[158:161], v[82:85], v[10:13]
	v_mfma_f32_16x16x32_bf16 v[86:89], v[126:129], v[82:85], v[86:89]
	v_mfma_f32_16x16x32_bf16 v[94:97], v[154:157], v[82:85], v[94:97]
	global_load_dwordx4 v[82:85], v222, s[36:37] offset:768
	v_mfma_f32_16x16x32_bf16 v[30:33], v[118:121], v[102:105], v[30:33]
	s_waitcnt vmcnt(8)
	ds_write_b128 v2, v[106:109] offset:36864
	v_mfma_f32_16x16x32_bf16 v[42:45], v[126:129], v[102:105], v[42:45]
	ds_read_b128 v[106:109], v4 offset:2048
	v_mfma_f32_16x16x32_bf16 v[14:17], v[158:161], v[102:105], v[14:17]
	ds_read_b128 v[174:177], v5 offset:18432
	v_mfma_f32_16x16x32_bf16 v[90:93], v[154:157], v[102:105], v[90:93]
	global_load_dwordx4 v[102:105], v223, s[36:37] offset:768
	v_mfma_f32_16x16x32_bf16 v[34:37], v[118:121], v[132:135], v[34:37]
	s_waitcnt vmcnt(8)
	ds_write_b128 v2, v[110:113] offset:40960
	v_mfma_f32_16x16x32_bf16 v[46:49], v[126:129], v[132:135], v[46:49]
	ds_read_b128 v[110:113], v4 offset:4096
	v_mfma_f32_16x16x32_bf16 v[62:65], v[154:157], v[132:135], v[62:65]
	ds_read_b128 v[178:181], v5 offset:20480
	v_mfma_f32_16x16x32_bf16 v[18:21], v[158:161], v[132:135], v[18:21]
	global_load_dwordx4 v[132:135], v224, s[36:37] offset:768
	v_mfma_f32_16x16x32_bf16 v[38:41], v[118:121], v[150:153], v[38:41]
	s_waitcnt vmcnt(8)
	ds_write_b128 v2, v[146:149] offset:45056
	v_mfma_f32_16x16x32_bf16 v[50:53], v[126:129], v[150:153], v[50:53]
	ds_read_b128 v[146:149], v4 offset:6144
	v_mfma_f32_16x16x32_bf16 v[54:57], v[154:157], v[150:153], v[54:57]
	ds_read_b128 v[182:185], v5 offset:22528
	v_mfma_f32_16x16x32_bf16 v[22:25], v[158:161], v[150:153], v[22:25]
	global_load_dwordx4 v[118:121], v3, s[0:1] offset:768
	s_waitcnt vmcnt(8)
	ds_write_b128 v2, v[114:117] offset:49152
	s_waitcnt lgkmcnt(10)
	v_mfma_f32_16x16x32_bf16 v[26:29], v[170:173], v[166:169], v[26:29]
	s_waitcnt lgkmcnt(1)
	v_mfma_f32_16x16x32_bf16 v[10:13], v[182:185], v[166:169], v[10:13]
	v_mfma_f32_16x16x32_bf16 v[86:89], v[174:177], v[166:169], v[86:89]
	v_mfma_f32_16x16x32_bf16 v[94:97], v[178:181], v[166:169], v[94:97]
	global_load_dwordx4 v[114:117], v225, s[0:1] offset:768
	v_mfma_f32_16x16x32_bf16 v[30:33], v[170:173], v[106:109], v[30:33]
	s_waitcnt vmcnt(8)
	ds_write_b128 v2, v[122:125] offset:53248
	v_mfma_f32_16x16x32_bf16 v[42:45], v[174:177], v[106:109], v[42:45]
	v_mfma_f32_16x16x32_bf16 v[14:17], v[182:185], v[106:109], v[14:17]
	v_mfma_f32_16x16x32_bf16 v[90:93], v[178:181], v[106:109], v[90:93]
	global_load_dwordx4 v[106:109], v226, s[0:1] offset:768
	s_waitcnt vmcnt(8)
	ds_write_b128 v2, v[58:61] offset:57344
	v_mfma_f32_16x16x32_bf16 v[34:37], v[170:173], v[110:113], v[34:37]
	v_mfma_f32_16x16x32_bf16 v[46:49], v[174:177], v[110:113], v[46:49]
	v_mfma_f32_16x16x32_bf16 v[58:61], v[178:181], v[110:113], v[62:65]
	v_mfma_f32_16x16x32_bf16 v[18:21], v[182:185], v[110:113], v[18:21]
	global_load_dwordx4 v[62:65], v227, s[0:1] offset:768
	v_mfma_f32_16x16x32_bf16 v[38:41], v[170:173], v[146:149], v[38:41]
	s_waitcnt vmcnt(8)
	ds_write_b128 v2, v[98:101] offset:61440
	v_mfma_f32_16x16x32_bf16 v[50:53], v[174:177], v[146:149], v[50:53]
	v_mfma_f32_16x16x32_bf16 v[54:57], v[178:181], v[146:149], v[54:57]
	v_mfma_f32_16x16x32_bf16 v[22:25], v[182:185], v[146:149], v[22:25]
	s_setprio 0
	s_waitcnt lgkmcnt(0)
	s_barrier
; template <int MODE>
; __device__ __forceinline__ void gemm_tile(const Params& P, int tm, int tn, unsigned char* smem) {
;     ...
;     for (int kt = 0; kt < 16; ++kt) {
;         unsigned char* sA = (kt & 1) ? sA1 : sA0; unsigned char* sB = (kt & 1) ? sB1 : sB0;
;         unsigned char* nA = (kt & 1) ? sA0 : sA1; unsigned char* nB = (kt & 1) ? sB0 : sB1;
;         bf16x8 fa[4], fb[4], ga[4], gb[4];
;         const int ch0 = ((g ^ sw) << 4), ch1 = (((4 + g) ^ sw) << 4);
;         const unsigned ko = (unsigned)(kt + 2) * 128u;
;         const unsigned koa = ko + ((MODE == 2 && kt + 2 >= 8) ? (unsigned)(ZC_FQ - 512) * 2u : 0u);
;         const bool wr_ok = kt < 15, ld_ok = kt < 14;
; #pragma unroll
;         for (int i = 0; i < 4; ++i) { fa[i] = *(const bf16x8*)(sA + arow_off + i * 2048 + ch0); fb[i] = *(const bf16x8*)(sB + brow_off + i * 2048 + ch0); }
;         __builtin_amdgcn_sched_barrier(0);
;         __builtin_amdgcn_s_setprio(2);
;         if (wr_ok) *(uint4*)(nA + soff0) = ra0;
;         if (ld_ok) ra0 = *(const uint4*)(Ab + (aoff + 0u * LDA + koa));
;         ga[0] = *(const bf16x8*)(sA + arow_off + 0 * 2048 + ch1); gb[0] = *(const bf16x8*)(sB + brow_off + 0 * 2048 + ch1);
;         __builtin_amdgcn_sched_barrier(0);
; #pragma unroll
;         for (int j = 0; j < 4; ++j) acc[0][j] = __builtin_amdgcn_mfma_f32_16x16x32_bf16(fb[j], fa[0], acc[0][j], 0, 0, 0);
;         __builtin_amdgcn_sched_barrier(0);
;         if (wr_ok) *(uint4*)(nA + soff0 + 4096) = ra1;
;         if (ld_ok) ra1 = *(const uint4*)(Ab + (aoff + 32u * LDA + koa));
;         ga[1] = *(const bf16x8*)(sA + arow_off + 1 * 2048 + ch1); gb[1] = *(const bf16x8*)(sB + brow_off + 1 * 2048 + ch1);
;         __builtin_amdgcn_sched_barrier(0);
; #pragma unroll
;         for (int j = 0; j < 4; ++j) acc[1][j] = __builtin_amdgcn_mfma_f32_16x16x32_bf16(fb[j], fa[1], acc[1][j], 0, 0, 0);
;         __builtin_amdgcn_sched_barrier(0);
;         if (wr_ok) *(uint4*)(nA + soff0 + 8192) = ra2;
;         if (ld_ok) ra2 = *(const uint4*)(Ab + (aoff + 64u * LDA + koa));
;         ga[2] = *(const bf16x8*)(sA + arow_off + 2 * 2048 + ch1); gb[2] = *(const bf16x8*)(sB + brow_off + 2 * 2048 + ch1);
;         __builtin_amdgcn_sched_barrier(0);
; #pragma unroll
;         for (int j = 0; j < 4; ++j) acc[2][j] = __builtin_amdgcn_mfma_f32_16x16x32_bf16(fb[j], fa[2], acc[2][j], 0, 0, 0);
	ds_read_b128 v[98:101], v6 offset:32768
	ds_read_b128 v[110:113], v6 offset:34816
	ds_read_b128 v[122:125], v7 offset:49152
	ds_read_b128 v[126:129], v7 offset:51200
	ds_read_b128 v[146:149], v6 offset:36864
	ds_read_b128 v[150:153], v6 offset:38912
	ds_read_b128 v[154:157], v7 offset:53248
	ds_read_b128 v[158:161], v7 offset:55296
	s_setprio 2
	global_load_dwordx4 v[166:169], v8, s[36:37] offset:896
	s_waitcnt vmcnt(8)
	ds_write_b128 v2, v[162:165]
	ds_read_b128 v[162:165], v4 offset:32768
	ds_read_b128 v[170:173], v5 offset:49152
	s_waitcnt lgkmcnt(8)
	v_mfma_f32_16x16x32_bf16 v[26:29], v[122:125], v[98:101], v[26:29]
	s_waitcnt lgkmcnt(3)
	v_mfma_f32_16x16x32_bf16 v[10:13], v[158:161], v[98:101], v[10:13]
	v_mfma_f32_16x16x32_bf16 v[86:89], v[126:129], v[98:101], v[86:89]
	v_mfma_f32_16x16x32_bf16 v[94:97], v[154:157], v[98:101], v[94:97]
	global_load_dwordx4 v[98:101], v222, s[36:37] offset:896
	v_mfma_f32_16x16x32_bf16 v[30:33], v[122:125], v[110:113], v[30:33]
	s_waitcnt vmcnt(8)
	ds_write_b128 v2, v[82:85] offset:4096
	v_mfma_f32_16x16x32_bf16 v[42:45], v[126:129], v[110:113], v[42:45]
	ds_read_b128 v[82:85], v4 offset:34816
	v_mfma_f32_16x16x32_bf16 v[14:17], v[158:161], v[110:113], v[14:17]
	ds_read_b128 v[174:177], v5 offset:51200
	v_mfma_f32_16x16x32_bf16 v[90:93], v[154:157], v[110:113], v[90:93]
	global_load_dwordx4 v[110:113], v223, s[36:37] offset:896
	v_mfma_f32_16x16x32_bf16 v[34:37], v[122:125], v[146:149], v[34:37]
	s_waitcnt vmcnt(8)
	ds_write_b128 v2, v[102:105] offset:8192
	v_mfma_f32_16x16x32_bf16 v[46:49], v[126:129], v[146:149], v[46:49]
	ds_read_b128 v[102:105], v4 offset:36864
	v_mfma_f32_16x16x32_bf16 v[58:61], v[154:157], v[146:149], v[58:61]
	ds_read_b128 v[178:181], v5 offset:53248
	v_mfma_f32_16x16x32_bf16 v[18:21], v[158:161], v[146:149], v[18:21]
	global_load_dwordx4 v[146:149], v224, s[36:37] offset:896
	v_mfma_f32_16x16x32_bf16 v[38:41], v[122:125], v[150:153], v[38:41]
	s_waitcnt vmcnt(8)
	ds_write_b128 v2, v[132:135] offset:12288
	v_mfma_f32_16x16x32_bf16 v[50:53], v[126:129], v[150:153], v[50:53]
	ds_read_b128 v[132:135], v4 offset:38912
	v_mfma_f32_16x16x32_bf16 v[54:57], v[154:157], v[150:153], v[54:57]
	ds_read_b128 v[182:185], v5 offset:55296
	v_mfma_f32_16x16x32_bf16 v[22:25], v[158:161], v[150:153], v[22:25]
	global_load_dwordx4 v[122:125], v3, s[0:1] offset:896
	s_waitcnt vmcnt(8)
	ds_write_b128 v2, v[118:121] offset:16384
	s_waitcnt lgkmcnt(10)
	v_mfma_f32_16x16x32_bf16 v[26:29], v[170:173], v[162:165], v[26:29]
	s_waitcnt lgkmcnt(1)
	v_mfma_f32_16x16x32_bf16 v[10:13], v[182:185], v[162:165], v[10:13]
	v_mfma_f32_16x16x32_bf16 v[86:89], v[174:177], v[162:165], v[86:89]
	v_mfma_f32_16x16x32_bf16 v[94:97], v[178:181], v[162:165], v[94:97]
	global_load_dwordx4 v[118:121], v225, s[0:1] offset:896
	v_mfma_f32_16x16x32_bf16 v[30:33], v[170:173], v[82:85], v[30:33]
	s_waitcnt vmcnt(8)
	ds_write_b128 v2, v[114:117] offset:20480
	v_mfma_f32_16x16x32_bf16 v[42:45], v[174:177], v[82:85], v[42:45]
	v_mfma_f32_16x16x32_bf16 v[14:17], v[182:185], v[82:85], v[14:17]
	v_mfma_f32_16x16x32_bf16 v[90:93], v[178:181], v[82:85], v[90:93]
	global_load_dwordx4 v[82:85], v226, s[0:1] offset:896
	v_mfma_f32_16x16x32_bf16 v[34:37], v[170:173], v[102:105], v[34:37]
	s_waitcnt vmcnt(8)
	ds_write_b128 v2, v[106:109] offset:24576
	v_mfma_f32_16x16x32_bf16 v[46:49], v[174:177], v[102:105], v[46:49]
	v_mfma_f32_16x16x32_bf16 v[58:61], v[178:181], v[102:105], v[58:61]
	v_mfma_f32_16x16x32_bf16 v[18:21], v[182:185], v[102:105], v[18:21]
	global_load_dwordx4 v[102:105], v227, s[0:1] offset:896
	v_mfma_f32_16x16x32_bf16 v[38:41], v[170:173], v[132:135], v[38:41]
	s_waitcnt vmcnt(8)
	ds_write_b128 v2, v[62:65] offset:28672
	v_mfma_f32_16x16x32_bf16 v[50:53], v[174:177], v[132:135], v[50:53]
	v_mfma_f32_16x16x32_bf16 v[54:57], v[178:181], v[132:135], v[54:57]
	v_mfma_f32_16x16x32_bf16 v[22:25], v[182:185], v[132:135], v[22:25]
	s_setprio 0
	s_waitcnt lgkmcnt(0)
	s_barrier
	ds_read_b128 v[62:65], v6
	ds_read_b128 v[106:109], v6 offset:2048
	ds_read_b128 v[114:117], v7 offset:16384
	ds_read_b128 v[126:129], v7 offset:18432
	ds_read_b128 v[132:135], v6 offset:4096
	ds_read_b128 v[150:153], v6 offset:6144
	ds_read_b128 v[154:157], v7 offset:20480
	ds_read_b128 v[158:161], v7 offset:22528
	s_setprio 2
	global_load_dwordx4 v[162:165], v8, s[36:37] offset:1024
	s_waitcnt vmcnt(8)
	ds_write_b128 v2, v[166:169] offset:32768
	ds_read_b128 v[166:169], v4
	ds_read_b128 v[170:173], v5 offset:16384
	s_waitcnt lgkmcnt(8)
	v_mfma_f32_16x16x32_bf16 v[26:29], v[114:117], v[62:65], v[26:29]
	s_waitcnt lgkmcnt(3)
	v_mfma_f32_16x16x32_bf16 v[10:13], v[158:161], v[62:65], v[10:13]
	v_mfma_f32_16x16x32_bf16 v[86:89], v[126:129], v[62:65], v[86:89]
	v_mfma_f32_16x16x32_bf16 v[94:97], v[154:157], v[62:65], v[94:97]
	global_load_dwordx4 v[62:65], v222, s[36:37] offset:1024
	v_mfma_f32_16x16x32_bf16 v[30:33], v[114:117], v[106:109], v[30:33]
	s_waitcnt vmcnt(8)
	ds_write_b128 v2, v[98:101] offset:36864
	v_mfma_f32_16x16x32_bf16 v[42:45], v[126:129], v[106:109], v[42:45]
	ds_read_b128 v[98:101], v4 offset:2048
	v_mfma_f32_16x16x32_bf16 v[14:17], v[158:161], v[106:109], v[14:17]
	ds_read_b128 v[174:177], v5 offset:18432
	v_mfma_f32_16x16x32_bf16 v[90:93], v[154:157], v[106:109], v[90:93]
	global_load_dwordx4 v[106:109], v223, s[36:37] offset:1024
	v_mfma_f32_16x16x32_bf16 v[34:37], v[114:117], v[132:135], v[34:37]
	s_waitcnt vmcnt(8)
; template <int MODE>
; __device__ __forceinline__ void gemm_tile(const Params& P, int tm, int tn, unsigned char* smem) {
;     ...
;     for (int kt = 0; kt < 16; ++kt) {
;         unsigned char* sA = (kt & 1) ? sA1 : sA0; unsigned char* sB = (kt & 1) ? sB1 : sB0;
;         unsigned char* nA = (kt & 1) ? sA0 : sA1; unsigned char* nB = (kt & 1) ? sB0 : sB1;
;         bf16x8 fa[4], fb[4], ga[4], gb[4];
;         const int ch0 = ((g ^ sw) << 4), ch1 = (((4 + g) ^ sw) << 4);
;         const unsigned ko = (unsigned)(kt + 2) * 128u;
;         const unsigned koa = ko + ((MODE == 2 && kt + 2 >= 8) ? (unsigned)(ZC_FQ - 512) * 2u : 0u);
;         const bool wr_ok = kt < 15, ld_ok = kt < 14;
; #pragma unroll
;         for (int i = 0; i < 4; ++i) { fa[i] = *(const bf16x8*)(sA + arow_off + i * 2048 + ch0); fb[i] = *(const bf16x8*)(sB + brow_off + i * 2048 + ch0); }
;         __builtin_amdgcn_sched_barrier(0);
;         __builtin_amdgcn_s_setprio(2);
;         if (wr_ok) *(uint4*)(nA + soff0) = ra0;
;         if (ld_ok) ra0 = *(const uint4*)(Ab + (aoff + 0u * LDA + koa));
;         ga[0] = *(const bf16x8*)(sA + arow_off + 0 * 2048 + ch1); gb[0] = *(const bf16x8*)(sB + brow_off + 0 * 2048 + ch1);
;         __builtin_amdgcn_sched_barrier(0);
; #pragma unroll
;         for (int j = 0; j < 4; ++j) acc[0][j] = __builtin_amdgcn_mfma_f32_16x16x32_bf16(fb[j], fa[0], acc[0][j], 0, 0, 0);
;         __builtin_amdgcn_sched_barrier(0);
;         if (wr_ok) *(uint4*)(nA + soff0 + 4096) = ra1;
;         if (ld_ok) ra1 = *(const uint4*)(Ab + (aoff + 32u * LDA + koa));
;         ga[1] = *(const bf16x8*)(sA + arow_off + 1 * 2048 + ch1); gb[1] = *(const bf16x8*)(sB + brow_off + 1 * 2048 + ch1);
;         __builtin_amdgcn_sched_barrier(0);
; #pragma unroll
;         for (int j = 0; j < 4; ++j) acc[1][j] = __builtin_amdgcn_mfma_f32_16x16x32_bf16(fb[j], fa[1], acc[1][j], 0, 0, 0);
;         __builtin_amdgcn_sched_barrier(0);
;         if (wr_ok) *(uint4*)(nA + soff0 + 8192) = ra2;
;         if (ld_ok) ra2 = *(const uint4*)(Ab + (aoff + 64u * LDA + koa));
;         ga[2] = *(const bf16x8*)(sA + arow_off + 2 * 2048 + ch1); gb[2] = *(const bf16x8*)(sB + brow_off + 2 * 2048 + ch1);
;         __builtin_amdgcn_sched_barrier(0);
; #pragma unroll
;         for (int j = 0; j < 4; ++j) acc[2][j] = __builtin_amdgcn_mfma_f32_16x16x32_bf16(fb[j], fa[2], acc[2][j], 0, 0, 0);
	ds_write_b128 v2, v[110:113] offset:40960
	v_mfma_f32_16x16x32_bf16 v[46:49], v[126:129], v[132:135], v[46:49]
	ds_read_b128 v[110:113], v4 offset:4096
	v_mfma_f32_16x16x32_bf16 v[58:61], v[154:157], v[132:135], v[58:61]
	ds_read_b128 v[178:181], v5 offset:20480
	v_mfma_f32_16x16x32_bf16 v[18:21], v[158:161], v[132:135], v[18:21]
	global_load_dwordx4 v[132:135], v224, s[36:37] offset:1024
	v_mfma_f32_16x16x32_bf16 v[38:41], v[114:117], v[150:153], v[38:41]
	s_waitcnt vmcnt(8)
	ds_write_b128 v2, v[146:149] offset:45056
	v_mfma_f32_16x16x32_bf16 v[50:53], v[126:129], v[150:153], v[50:53]
	ds_read_b128 v[146:149], v4 offset:6144
	v_mfma_f32_16x16x32_bf16 v[54:57], v[154:157], v[150:153], v[54:57]
	ds_read_b128 v[182:185], v5 offset:22528
	v_mfma_f32_16x16x32_bf16 v[22:25], v[158:161], v[150:153], v[22:25]
	global_load_dwordx4 v[114:117], v3, s[0:1] offset:1024
	s_waitcnt vmcnt(8)
	ds_write_b128 v2, v[122:125] offset:49152
	s_waitcnt lgkmcnt(10)
	v_mfma_f32_16x16x32_bf16 v[26:29], v[170:173], v[166:169], v[26:29]
	s_waitcnt lgkmcnt(1)
	v_mfma_f32_16x16x32_bf16 v[10:13], v[182:185], v[166:169], v[10:13]
	v_mfma_f32_16x16x32_bf16 v[86:89], v[174:177], v[166:169], v[86:89]
	v_mfma_f32_16x16x32_bf16 v[94:97], v[178:181], v[166:169], v[94:97]
	global_load_dwordx4 v[122:125], v225, s[0:1] offset:1024
	v_mfma_f32_16x16x32_bf16 v[30:33], v[170:173], v[98:101], v[30:33]
	s_waitcnt vmcnt(8)
	ds_write_b128 v2, v[118:121] offset:53248
	v_mfma_f32_16x16x32_bf16 v[42:45], v[174:177], v[98:101], v[42:45]
	v_mfma_f32_16x16x32_bf16 v[14:17], v[182:185], v[98:101], v[14:17]
	v_mfma_f32_16x16x32_bf16 v[90:93], v[178:181], v[98:101], v[90:93]
	global_load_dwordx4 v[98:101], v226, s[0:1] offset:1024
	v_mfma_f32_16x16x32_bf16 v[34:37], v[170:173], v[110:113], v[34:37]
	s_waitcnt vmcnt(8)
	ds_write_b128 v2, v[82:85] offset:57344
	v_mfma_f32_16x16x32_bf16 v[46:49], v[174:177], v[110:113], v[46:49]
	v_mfma_f32_16x16x32_bf16 v[58:61], v[178:181], v[110:113], v[58:61]
	v_mfma_f32_16x16x32_bf16 v[18:21], v[182:185], v[110:113], v[18:21]
	global_load_dwordx4 v[82:85], v227, s[0:1] offset:1024
	v_mfma_f32_16x16x32_bf16 v[38:41], v[170:173], v[146:149], v[38:41]
	s_waitcnt vmcnt(8)
	ds_write_b128 v2, v[102:105] offset:61440
	v_mfma_f32_16x16x32_bf16 v[50:53], v[174:177], v[146:149], v[50:53]
	v_mfma_f32_16x16x32_bf16 v[54:57], v[178:181], v[146:149], v[54:57]
	v_mfma_f32_16x16x32_bf16 v[22:25], v[182:185], v[146:149], v[22:25]
	s_setprio 0
	s_waitcnt lgkmcnt(0)
	s_barrier
	ds_read_b128 v[102:105], v6 offset:32768
	ds_read_b128 v[110:113], v6 offset:34816
	ds_read_b128 v[118:121], v7 offset:49152
	ds_read_b128 v[126:129], v7 offset:51200
	ds_read_b128 v[146:149], v6 offset:36864
	ds_read_b128 v[150:153], v6 offset:38912
	ds_read_b128 v[154:157], v7 offset:53248
	ds_read_b128 v[158:161], v7 offset:55296
	s_setprio 2
	global_load_dwordx4 v[166:169], v8, s[36:37] offset:1152
	s_waitcnt vmcnt(8)
	ds_write_b128 v2, v[162:165]
	ds_read_b128 v[162:165], v4 offset:32768
	ds_read_b128 v[170:173], v5 offset:49152
	s_waitcnt lgkmcnt(8)
	v_mfma_f32_16x16x32_bf16 v[26:29], v[118:121], v[102:105], v[26:29]
	s_waitcnt lgkmcnt(3)
	v_mfma_f32_16x16x32_bf16 v[10:13], v[158:161], v[102:105], v[10:13]
	v_mfma_f32_16x16x32_bf16 v[86:89], v[126:129], v[102:105], v[86:89]
	v_mfma_f32_16x16x32_bf16 v[94:97], v[154:157], v[102:105], v[94:97]
	global_load_dwordx4 v[102:105], v222, s[36:37] offset:1152
	v_mfma_f32_16x16x32_bf16 v[30:33], v[118:121], v[110:113], v[30:33]
	s_waitcnt vmcnt(8)
	ds_write_b128 v2, v[62:65] offset:4096
	v_mfma_f32_16x16x32_bf16 v[42:45], v[126:129], v[110:113], v[42:45]
	ds_read_b128 v[62:65], v4 offset:34816
	v_mfma_f32_16x16x32_bf16 v[14:17], v[158:161], v[110:113], v[14:17]
	ds_read_b128 v[174:177], v5 offset:51200
	v_mfma_f32_16x16x32_bf16 v[90:93], v[154:157], v[110:113], v[90:93]
	global_load_dwordx4 v[110:113], v223, s[36:37] offset:1152
	v_mfma_f32_16x16x32_bf16 v[34:37], v[118:121], v[146:149], v[34:37]
	s_waitcnt vmcnt(8)
	ds_write_b128 v2, v[106:109] offset:8192
	v_mfma_f32_16x16x32_bf16 v[46:49], v[126:129], v[146:149], v[46:49]
	ds_read_b128 v[106:109], v4 offset:36864
	v_mfma_f32_16x16x32_bf16 v[58:61], v[154:157], v[146:149], v[58:61]
	ds_read_b128 v[178:181], v5 offset:53248
	v_mfma_f32_16x16x32_bf16 v[18:21], v[158:161], v[146:149], v[18:21]
	global_load_dwordx4 v[146:149], v224, s[36:37] offset:1152
	v_mfma_f32_16x16x32_bf16 v[38:41], v[118:121], v[150:153], v[38:41]
	s_waitcnt vmcnt(8)
	ds_write_b128 v2, v[132:135] offset:12288
	v_mfma_f32_16x16x32_bf16 v[50:53], v[126:129], v[150:153], v[50:53]
	ds_read_b128 v[132:135], v4 offset:38912
	v_mfma_f32_16x16x32_bf16 v[54:57], v[154:157], v[150:153], v[54:57]
	ds_read_b128 v[182:185], v5 offset:55296
	v_mfma_f32_16x16x32_bf16 v[22:25], v[158:161], v[150:153], v[22:25]
	global_load_dwordx4 v[118:121], v3, s[0:1] offset:1152
	s_waitcnt vmcnt(8)
	ds_write_b128 v2, v[114:117] offset:16384
	s_waitcnt lgkmcnt(10)
	v_mfma_f32_16x16x32_bf16 v[26:29], v[170:173], v[162:165], v[26:29]
	s_waitcnt lgkmcnt(1)
	v_mfma_f32_16x16x32_bf16 v[10:13], v[182:185], v[162:165], v[10:13]
	v_mfma_f32_16x16x32_bf16 v[86:89], v[174:177], v[162:165], v[86:89]
	v_mfma_f32_16x16x32_bf16 v[94:97], v[178:181], v[162:165], v[94:97]
	global_load_dwordx4 v[114:117], v225, s[0:1] offset:1152
	v_mfma_f32_16x16x32_bf16 v[30:33], v[170:173], v[62:65], v[30:33]
	s_waitcnt vmcnt(8)
	ds_write_b128 v2, v[122:125] offset:20480
	v_mfma_f32_16x16x32_bf16 v[42:45], v[174:177], v[62:65], v[42:45]
	v_mfma_f32_16x16x32_bf16 v[14:17], v[182:185], v[62:65], v[14:17]
	v_mfma_f32_16x16x32_bf16 v[90:93], v[178:181], v[62:65], v[90:93]
	global_load_dwordx4 v[62:65], v226, s[0:1] offset:1152
	v_mfma_f32_16x16x32_bf16 v[34:37], v[170:173], v[106:109], v[34:37]
	s_waitcnt vmcnt(8)
	ds_write_b128 v2, v[98:101] offset:24576
	v_mfma_f32_16x16x32_bf16 v[46:49], v[174:177], v[106:109], v[46:49]
	v_mfma_f32_16x16x32_bf16 v[58:61], v[178:181], v[106:109], v[58:61]
	v_mfma_f32_16x16x32_bf16 v[18:21], v[182:185], v[106:109], v[18:21]
	global_load_dwordx4 v[98:101], v227, s[0:1] offset:1152
	v_mfma_f32_16x16x32_bf16 v[38:41], v[170:173], v[132:135], v[38:41]
	s_waitcnt vmcnt(8)
	ds_write_b128 v2, v[82:85] offset:28672
	v_mfma_f32_16x16x32_bf16 v[50:53], v[174:177], v[132:135], v[50:53]
	v_mfma_f32_16x16x32_bf16 v[54:57], v[178:181], v[132:135], v[54:57]
	v_mfma_f32_16x16x32_bf16 v[22:25], v[182:185], v[132:135], v[22:25]
	s_setprio 0
	s_waitcnt lgkmcnt(0)
	s_barrier
; template <int MODE>
; __device__ __forceinline__ void gemm_tile(const Params& P, int tm, int tn, unsigned char* smem) {
;     ...
;     for (int kt = 0; kt < 16; ++kt) {
;         unsigned char* sA = (kt & 1) ? sA1 : sA0; unsigned char* sB = (kt & 1) ? sB1 : sB0;
;         unsigned char* nA = (kt & 1) ? sA0 : sA1; unsigned char* nB = (kt & 1) ? sB0 : sB1;
;         bf16x8 fa[4], fb[4], ga[4], gb[4];
;         const int ch0 = ((g ^ sw) << 4), ch1 = (((4 + g) ^ sw) << 4);
;         const unsigned ko = (unsigned)(kt + 2) * 128u;
;         const unsigned koa = ko + ((MODE == 2 && kt + 2 >= 8) ? (unsigned)(ZC_FQ - 512) * 2u : 0u);
;         const bool wr_ok = kt < 15, ld_ok = kt < 14;
; #pragma unroll
;         for (int i = 0; i < 4; ++i) { fa[i] = *(const bf16x8*)(sA + arow_off + i * 2048 + ch0); fb[i] = *(const bf16x8*)(sB + brow_off + i * 2048 + ch0); }
;         __builtin_amdgcn_sched_barrier(0);
;         __builtin_amdgcn_s_setprio(2);
;         if (wr_ok) *(uint4*)(nA + soff0) = ra0;
;         if (ld_ok) ra0 = *(const uint4*)(Ab + (aoff + 0u * LDA + koa));
;         ga[0] = *(const bf16x8*)(sA + arow_off + 0 * 2048 + ch1); gb[0] = *(const bf16x8*)(sB + brow_off + 0 * 2048 + ch1);
;         __builtin_amdgcn_sched_barrier(0);
; #pragma unroll
;         for (int j = 0; j < 4; ++j) acc[0][j] = __builtin_amdgcn_mfma_f32_16x16x32_bf16(fb[j], fa[0], acc[0][j], 0, 0, 0);
;         __builtin_amdgcn_sched_barrier(0);
;         if (wr_ok) *(uint4*)(nA + soff0 + 4096) = ra1;
;         if (ld_ok) ra1 = *(const uint4*)(Ab + (aoff + 32u * LDA + koa));
;         ga[1] = *(const bf16x8*)(sA + arow_off + 1 * 2048 + ch1); gb[1] = *(const bf16x8*)(sB + brow_off + 1 * 2048 + ch1);
;         __builtin_amdgcn_sched_barrier(0);
; #pragma unroll
;         for (int j = 0; j < 4; ++j) acc[1][j] = __builtin_amdgcn_mfma_f32_16x16x32_bf16(fb[j], fa[1], acc[1][j], 0, 0, 0);
;         __builtin_amdgcn_sched_barrier(0);
;         if (wr_ok) *(uint4*)(nA + soff0 + 8192) = ra2;
;         if (ld_ok) ra2 = *(const uint4*)(Ab + (aoff + 64u * LDA + koa));
;         ga[2] = *(const bf16x8*)(sA + arow_off + 2 * 2048 + ch1); gb[2] = *(const bf16x8*)(sB + brow_off + 2 * 2048 + ch1);
;         __builtin_amdgcn_sched_barrier(0);
; #pragma unroll
;         for (int j = 0; j < 4; ++j) acc[2][j] = __builtin_amdgcn_mfma_f32_16x16x32_bf16(fb[j], fa[2], acc[2][j], 0, 0, 0);
	ds_read_b128 v[82:85], v6
	ds_read_b128 v[106:109], v6 offset:2048
	ds_read_b128 v[122:125], v7 offset:16384
	ds_read_b128 v[126:129], v7 offset:18432
	ds_read_b128 v[132:135], v6 offset:4096
	ds_read_b128 v[150:153], v6 offset:6144
	ds_read_b128 v[154:157], v7 offset:20480
	ds_read_b128 v[158:161], v7 offset:22528
	s_setprio 2
	global_load_dwordx4 v[162:165], v8, s[36:37] offset:1280
	s_waitcnt vmcnt(8)
	ds_write_b128 v2, v[166:169] offset:32768
	ds_read_b128 v[166:169], v4
	ds_read_b128 v[170:173], v5 offset:16384
	s_waitcnt lgkmcnt(8)
	v_mfma_f32_16x16x32_bf16 v[26:29], v[122:125], v[82:85], v[26:29]
	s_waitcnt lgkmcnt(3)
	v_mfma_f32_16x16x32_bf16 v[10:13], v[158:161], v[82:85], v[10:13]
	v_mfma_f32_16x16x32_bf16 v[86:89], v[126:129], v[82:85], v[86:89]
	v_mfma_f32_16x16x32_bf16 v[94:97], v[154:157], v[82:85], v[94:97]
	global_load_dwordx4 v[82:85], v222, s[36:37] offset:1280
	v_mfma_f32_16x16x32_bf16 v[30:33], v[122:125], v[106:109], v[30:33]
	s_waitcnt vmcnt(8)
	ds_write_b128 v2, v[102:105] offset:36864
	v_mfma_f32_16x16x32_bf16 v[42:45], v[126:129], v[106:109], v[42:45]
	ds_read_b128 v[102:105], v4 offset:2048
	v_mfma_f32_16x16x32_bf16 v[14:17], v[158:161], v[106:109], v[14:17]
	ds_read_b128 v[174:177], v5 offset:18432
	v_mfma_f32_16x16x32_bf16 v[90:93], v[154:157], v[106:109], v[90:93]
	global_load_dwordx4 v[106:109], v223, s[36:37] offset:1280
	v_mfma_f32_16x16x32_bf16 v[34:37], v[122:125], v[132:135], v[34:37]
	s_waitcnt vmcnt(8)
	ds_write_b128 v2, v[110:113] offset:40960
	v_mfma_f32_16x16x32_bf16 v[46:49], v[126:129], v[132:135], v[46:49]
	ds_read_b128 v[110:113], v4 offset:4096
	v_mfma_f32_16x16x32_bf16 v[58:61], v[154:157], v[132:135], v[58:61]
	ds_read_b128 v[178:181], v5 offset:20480
	v_mfma_f32_16x16x32_bf16 v[18:21], v[158:161], v[132:135], v[18:21]
	global_load_dwordx4 v[132:135], v224, s[36:37] offset:1280
	v_mfma_f32_16x16x32_bf16 v[38:41], v[122:125], v[150:153], v[38:41]
	s_waitcnt vmcnt(8)
	ds_write_b128 v2, v[146:149] offset:45056
	v_mfma_f32_16x16x32_bf16 v[50:53], v[126:129], v[150:153], v[50:53]
	ds_read_b128 v[146:149], v4 offset:6144
	v_mfma_f32_16x16x32_bf16 v[54:57], v[154:157], v[150:153], v[54:57]
	ds_read_b128 v[182:185], v5 offset:22528
	v_mfma_f32_16x16x32_bf16 v[22:25], v[158:161], v[150:153], v[22:25]
	global_load_dwordx4 v[122:125], v3, s[0:1] offset:1280
	s_waitcnt vmcnt(8)
	ds_write_b128 v2, v[118:121] offset:49152
	s_waitcnt lgkmcnt(10)
	v_mfma_f32_16x16x32_bf16 v[26:29], v[170:173], v[166:169], v[26:29]
	s_waitcnt lgkmcnt(1)
	v_mfma_f32_16x16x32_bf16 v[10:13], v[182:185], v[166:169], v[10:13]
	v_mfma_f32_16x16x32_bf16 v[86:89], v[174:177], v[166:169], v[86:89]
	v_mfma_f32_16x16x32_bf16 v[94:97], v[178:181], v[166:169], v[94:97]
	global_load_dwordx4 v[118:121], v225, s[0:1] offset:1280
	v_mfma_f32_16x16x32_bf16 v[30:33], v[170:173], v[102:105], v[30:33]
	s_waitcnt vmcnt(8)
	ds_write_b128 v2, v[114:117] offset:53248
	v_mfma_f32_16x16x32_bf16 v[42:45], v[174:177], v[102:105], v[42:45]
	v_mfma_f32_16x16x32_bf16 v[14:17], v[182:185], v[102:105], v[14:17]
	v_mfma_f32_16x16x32_bf16 v[90:93], v[178:181], v[102:105], v[90:93]
	global_load_dwordx4 v[102:105], v226, s[0:1] offset:1280
	v_mfma_f32_16x16x32_bf16 v[34:37], v[170:173], v[110:113], v[34:37]
	s_waitcnt vmcnt(8)
	ds_write_b128 v2, v[62:65] offset:57344
	v_mfma_f32_16x16x32_bf16 v[46:49], v[174:177], v[110:113], v[46:49]
	v_mfma_f32_16x16x32_bf16 v[58:61], v[178:181], v[110:113], v[58:61]
	v_mfma_f32_16x16x32_bf16 v[18:21], v[182:185], v[110:113], v[18:21]
	global_load_dwordx4 v[62:65], v227, s[0:1] offset:1280
	v_mfma_f32_16x16x32_bf16 v[38:41], v[170:173], v[146:149], v[38:41]
	s_waitcnt vmcnt(8)
	ds_write_b128 v2, v[98:101] offset:61440
	v_mfma_f32_16x16x32_bf16 v[50:53], v[174:177], v[146:149], v[50:53]
	v_mfma_f32_16x16x32_bf16 v[54:57], v[178:181], v[146:149], v[54:57]
	v_mfma_f32_16x16x32_bf16 v[22:25], v[182:185], v[146:149], v[22:25]
	s_setprio 0
	s_waitcnt lgkmcnt(0)
	s_barrier
	ds_read_b128 v[98:101], v6 offset:32768
	ds_read_b128 v[110:113], v6 offset:34816
	ds_read_b128 v[114:117], v7 offset:49152
	ds_read_b128 v[126:129], v7 offset:51200
	ds_read_b128 v[146:149], v6 offset:36864
	ds_read_b128 v[150:153], v6 offset:38912
	ds_read_b128 v[154:157], v7 offset:53248
	ds_read_b128 v[158:161], v7 offset:55296
	s_setprio 2
	global_load_dwordx4 v[166:169], v8, s[36:37] offset:1408
	s_waitcnt vmcnt(8)
	ds_write_b128 v2, v[162:165]
	ds_read_b128 v[162:165], v4 offset:32768
	ds_read_b128 v[170:173], v5 offset:49152
	s_waitcnt lgkmcnt(8)
	v_mfma_f32_16x16x32_bf16 v[26:29], v[114:117], v[98:101], v[26:29]
	s_waitcnt lgkmcnt(3)
	v_mfma_f32_16x16x32_bf16 v[10:13], v[158:161], v[98:101], v[10:13]
	v_mfma_f32_16x16x32_bf16 v[86:89], v[126:129], v[98:101], v[86:89]
	v_mfma_f32_16x16x32_bf16 v[94:97], v[154:157], v[98:101], v[94:97]
	global_load_dwordx4 v[98:101], v222, s[36:37] offset:1408
	v_mfma_f32_16x16x32_bf16 v[30:33], v[114:117], v[110:113], v[30:33]
	s_waitcnt vmcnt(8)
	ds_write_b128 v2, v[82:85] offset:4096
	v_mfma_f32_16x16x32_bf16 v[42:45], v[126:129], v[110:113], v[42:45]
	ds_read_b128 v[82:85], v4 offset:34816
	v_mfma_f32_16x16x32_bf16 v[14:17], v[158:161], v[110:113], v[14:17]
	ds_read_b128 v[174:177], v5 offset:51200
	v_mfma_f32_16x16x32_bf16 v[90:93], v[154:157], v[110:113], v[90:93]
	global_load_dwordx4 v[110:113], v223, s[36:37] offset:1408
	v_mfma_f32_16x16x32_bf16 v[34:37], v[114:117], v[146:149], v[34:37]
	s_waitcnt vmcnt(8)
; template <int MODE>
; __device__ __forceinline__ void gemm_tile(const Params& P, int tm, int tn, unsigned char* smem) {
;     ...
;     for (int kt = 0; kt < 16; ++kt) {
;         unsigned char* sA = (kt & 1) ? sA1 : sA0; unsigned char* sB = (kt & 1) ? sB1 : sB0;
;         unsigned char* nA = (kt & 1) ? sA0 : sA1; unsigned char* nB = (kt & 1) ? sB0 : sB1;
;         bf16x8 fa[4], fb[4], ga[4], gb[4];
;         const int ch0 = ((g ^ sw) << 4), ch1 = (((4 + g) ^ sw) << 4);
;         const unsigned ko = (unsigned)(kt + 2) * 128u;
;         const unsigned koa = ko + ((MODE == 2 && kt + 2 >= 8) ? (unsigned)(ZC_FQ - 512) * 2u : 0u);
;         const bool wr_ok = kt < 15, ld_ok = kt < 14;
; #pragma unroll
;         for (int i = 0; i < 4; ++i) { fa[i] = *(const bf16x8*)(sA + arow_off + i * 2048 + ch0); fb[i] = *(const bf16x8*)(sB + brow_off + i * 2048 + ch0); }
;         __builtin_amdgcn_sched_barrier(0);
;         __builtin_amdgcn_s_setprio(2);
;         if (wr_ok) *(uint4*)(nA + soff0) = ra0;
;         if (ld_ok) ra0 = *(const uint4*)(Ab + (aoff + 0u * LDA + koa));
;         ga[0] = *(const bf16x8*)(sA + arow_off + 0 * 2048 + ch1); gb[0] = *(const bf16x8*)(sB + brow_off + 0 * 2048 + ch1);
;         __builtin_amdgcn_sched_barrier(0);
; #pragma unroll
;         for (int j = 0; j < 4; ++j) acc[0][j] = __builtin_amdgcn_mfma_f32_16x16x32_bf16(fb[j], fa[0], acc[0][j], 0, 0, 0);
;         __builtin_amdgcn_sched_barrier(0);
;         if (wr_ok) *(uint4*)(nA + soff0 + 4096) = ra1;
;         if (ld_ok) ra1 = *(const uint4*)(Ab + (aoff + 32u * LDA + koa));
;         ga[1] = *(const bf16x8*)(sA + arow_off + 1 * 2048 + ch1); gb[1] = *(const bf16x8*)(sB + brow_off + 1 * 2048 + ch1);
;         __builtin_amdgcn_sched_barrier(0);
; #pragma unroll
;         for (int j = 0; j < 4; ++j) acc[1][j] = __builtin_amdgcn_mfma_f32_16x16x32_bf16(fb[j], fa[1], acc[1][j], 0, 0, 0);
;         __builtin_amdgcn_sched_barrier(0);
;         if (wr_ok) *(uint4*)(nA + soff0 + 8192) = ra2;
;         if (ld_ok) ra2 = *(const uint4*)(Ab + (aoff + 64u * LDA + koa));
;         ga[2] = *(const bf16x8*)(sA + arow_off + 2 * 2048 + ch1); gb[2] = *(const bf16x8*)(sB + brow_off + 2 * 2048 + ch1);
;         __builtin_amdgcn_sched_barrier(0);
; #pragma unroll
;         for (int j = 0; j < 4; ++j) acc[2][j] = __builtin_amdgcn_mfma_f32_16x16x32_bf16(fb[j], fa[2], acc[2][j], 0, 0, 0);
	ds_write_b128 v2, v[106:109] offset:8192
	v_mfma_f32_16x16x32_bf16 v[46:49], v[126:129], v[146:149], v[46:49]
	ds_read_b128 v[106:109], v4 offset:36864
	v_mfma_f32_16x16x32_bf16 v[58:61], v[154:157], v[146:149], v[58:61]
	ds_read_b128 v[178:181], v5 offset:53248
	v_mfma_f32_16x16x32_bf16 v[18:21], v[158:161], v[146:149], v[18:21]
	global_load_dwordx4 v[146:149], v224, s[36:37] offset:1408
	v_mfma_f32_16x16x32_bf16 v[38:41], v[114:117], v[150:153], v[38:41]
	s_waitcnt vmcnt(8)
	ds_write_b128 v2, v[132:135] offset:12288
	v_mfma_f32_16x16x32_bf16 v[50:53], v[126:129], v[150:153], v[50:53]
	ds_read_b128 v[132:135], v4 offset:38912
	v_mfma_f32_16x16x32_bf16 v[54:57], v[154:157], v[150:153], v[54:57]
	ds_read_b128 v[182:185], v5 offset:55296
	v_mfma_f32_16x16x32_bf16 v[22:25], v[158:161], v[150:153], v[22:25]
	global_load_dwordx4 v[114:117], v3, s[0:1] offset:1408
	s_waitcnt vmcnt(8)
	ds_write_b128 v2, v[122:125] offset:16384
	s_waitcnt lgkmcnt(10)
	v_mfma_f32_16x16x32_bf16 v[26:29], v[170:173], v[162:165], v[26:29]
	s_waitcnt lgkmcnt(1)
	v_mfma_f32_16x16x32_bf16 v[10:13], v[182:185], v[162:165], v[10:13]
	v_mfma_f32_16x16x32_bf16 v[86:89], v[174:177], v[162:165], v[86:89]
	v_mfma_f32_16x16x32_bf16 v[94:97], v[178:181], v[162:165], v[94:97]
	global_load_dwordx4 v[122:125], v225, s[0:1] offset:1408
	v_mfma_f32_16x16x32_bf16 v[30:33], v[170:173], v[82:85], v[30:33]
	s_waitcnt vmcnt(8)
	ds_write_b128 v2, v[118:121] offset:20480
	v_mfma_f32_16x16x32_bf16 v[42:45], v[174:177], v[82:85], v[42:45]
	v_mfma_f32_16x16x32_bf16 v[14:17], v[182:185], v[82:85], v[14:17]
	v_mfma_f32_16x16x32_bf16 v[90:93], v[178:181], v[82:85], v[90:93]
	global_load_dwordx4 v[82:85], v226, s[0:1] offset:1408
	v_mfma_f32_16x16x32_bf16 v[34:37], v[170:173], v[106:109], v[34:37]
	s_waitcnt vmcnt(8)
	ds_write_b128 v2, v[102:105] offset:24576
	v_mfma_f32_16x16x32_bf16 v[46:49], v[174:177], v[106:109], v[46:49]
	v_mfma_f32_16x16x32_bf16 v[58:61], v[178:181], v[106:109], v[58:61]
	v_mfma_f32_16x16x32_bf16 v[18:21], v[182:185], v[106:109], v[18:21]
	global_load_dwordx4 v[102:105], v227, s[0:1] offset:1408
	v_mfma_f32_16x16x32_bf16 v[38:41], v[170:173], v[132:135], v[38:41]
	s_waitcnt vmcnt(8)
	ds_write_b128 v2, v[62:65] offset:28672
	v_mfma_f32_16x16x32_bf16 v[50:53], v[174:177], v[132:135], v[50:53]
	v_mfma_f32_16x16x32_bf16 v[54:57], v[178:181], v[132:135], v[54:57]
	v_mfma_f32_16x16x32_bf16 v[22:25], v[182:185], v[132:135], v[22:25]
	s_setprio 0
	s_waitcnt lgkmcnt(0)
	s_barrier
	ds_read_b128 v[62:65], v6
	ds_read_b128 v[106:109], v6 offset:2048
	ds_read_b128 v[118:121], v7 offset:16384
	ds_read_b128 v[126:129], v7 offset:18432
	ds_read_b128 v[132:135], v6 offset:4096
	ds_read_b128 v[150:153], v6 offset:6144
	ds_read_b128 v[154:157], v7 offset:20480
	ds_read_b128 v[158:161], v7 offset:22528
	s_setprio 2
	global_load_dwordx4 v[162:165], v8, s[36:37] offset:1536
	s_waitcnt vmcnt(8)
	ds_write_b128 v2, v[166:169] offset:32768
	ds_read_b128 v[166:169], v4
	ds_read_b128 v[170:173], v5 offset:16384
	s_waitcnt lgkmcnt(8)
	v_mfma_f32_16x16x32_bf16 v[26:29], v[118:121], v[62:65], v[26:29]
	s_waitcnt lgkmcnt(3)
	v_mfma_f32_16x16x32_bf16 v[10:13], v[158:161], v[62:65], v[10:13]
	v_mfma_f32_16x16x32_bf16 v[86:89], v[126:129], v[62:65], v[86:89]
	v_mfma_f32_16x16x32_bf16 v[94:97], v[154:157], v[62:65], v[94:97]
	global_load_dwordx4 v[62:65], v222, s[36:37] offset:1536
	v_mfma_f32_16x16x32_bf16 v[30:33], v[118:121], v[106:109], v[30:33]
	s_waitcnt vmcnt(8)
	ds_write_b128 v2, v[98:101] offset:36864
	v_mfma_f32_16x16x32_bf16 v[42:45], v[126:129], v[106:109], v[42:45]
	ds_read_b128 v[98:101], v4 offset:2048
	v_mfma_f32_16x16x32_bf16 v[14:17], v[158:161], v[106:109], v[14:17]
	ds_read_b128 v[174:177], v5 offset:18432
	v_mfma_f32_16x16x32_bf16 v[90:93], v[154:157], v[106:109], v[90:93]
	global_load_dwordx4 v[106:109], v223, s[36:37] offset:1536
	v_mfma_f32_16x16x32_bf16 v[34:37], v[118:121], v[132:135], v[34:37]
	s_waitcnt vmcnt(8)
	ds_write_b128 v2, v[110:113] offset:40960
	v_mfma_f32_16x16x32_bf16 v[46:49], v[126:129], v[132:135], v[46:49]
	ds_read_b128 v[110:113], v4 offset:4096
	v_mfma_f32_16x16x32_bf16 v[58:61], v[154:157], v[132:135], v[58:61]
	ds_read_b128 v[178:181], v5 offset:20480
	v_mfma_f32_16x16x32_bf16 v[18:21], v[158:161], v[132:135], v[18:21]
	global_load_dwordx4 v[132:135], v224, s[36:37] offset:1536
	v_mfma_f32_16x16x32_bf16 v[38:41], v[118:121], v[150:153], v[38:41]
	s_waitcnt vmcnt(8)
	ds_write_b128 v2, v[146:149] offset:45056
	v_mfma_f32_16x16x32_bf16 v[50:53], v[126:129], v[150:153], v[50:53]
	ds_read_b128 v[146:149], v4 offset:6144
	v_mfma_f32_16x16x32_bf16 v[54:57], v[154:157], v[150:153], v[54:57]
	ds_read_b128 v[182:185], v5 offset:22528
	v_mfma_f32_16x16x32_bf16 v[22:25], v[158:161], v[150:153], v[22:25]
	global_load_dwordx4 v[118:121], v3, s[0:1] offset:1536
	s_waitcnt vmcnt(8)
	ds_write_b128 v2, v[114:117] offset:49152
	s_waitcnt lgkmcnt(10)
	v_mfma_f32_16x16x32_bf16 v[26:29], v[170:173], v[166:169], v[26:29]
	s_waitcnt lgkmcnt(1)
	v_mfma_f32_16x16x32_bf16 v[10:13], v[182:185], v[166:169], v[10:13]
	v_mfma_f32_16x16x32_bf16 v[86:89], v[174:177], v[166:169], v[86:89]
	v_mfma_f32_16x16x32_bf16 v[94:97], v[178:181], v[166:169], v[94:97]
	global_load_dwordx4 v[114:117], v225, s[0:1] offset:1536
	v_mfma_f32_16x16x32_bf16 v[30:33], v[170:173], v[98:101], v[30:33]
	s_waitcnt vmcnt(8)
	ds_write_b128 v2, v[122:125] offset:53248
	v_mfma_f32_16x16x32_bf16 v[42:45], v[174:177], v[98:101], v[42:45]
	v_mfma_f32_16x16x32_bf16 v[14:17], v[182:185], v[98:101], v[14:17]
	v_mfma_f32_16x16x32_bf16 v[90:93], v[178:181], v[98:101], v[90:93]
	global_load_dwordx4 v[98:101], v226, s[0:1] offset:1536
	v_mfma_f32_16x16x32_bf16 v[34:37], v[170:173], v[110:113], v[34:37]
	s_waitcnt vmcnt(8)
	ds_write_b128 v2, v[82:85] offset:57344
	v_mfma_f32_16x16x32_bf16 v[46:49], v[174:177], v[110:113], v[46:49]
	v_mfma_f32_16x16x32_bf16 v[58:61], v[178:181], v[110:113], v[58:61]
	v_mfma_f32_16x16x32_bf16 v[18:21], v[182:185], v[110:113], v[18:21]
	global_load_dwordx4 v[82:85], v227, s[0:1] offset:1536
	v_mfma_f32_16x16x32_bf16 v[38:41], v[170:173], v[146:149], v[38:41]
	s_waitcnt vmcnt(8)
	ds_write_b128 v2, v[102:105] offset:61440
	v_mfma_f32_16x16x32_bf16 v[50:53], v[174:177], v[146:149], v[50:53]
	v_mfma_f32_16x16x32_bf16 v[54:57], v[178:181], v[146:149], v[54:57]
	v_mfma_f32_16x16x32_bf16 v[22:25], v[182:185], v[146:149], v[22:25]
	s_setprio 0
	s_waitcnt lgkmcnt(0)
	s_barrier
; template <int MODE>
; __device__ __forceinline__ void gemm_tile(const Params& P, int tm, int tn, unsigned char* smem) {
;     ...
;     for (int kt = 0; kt < 16; ++kt) {
;         unsigned char* sA = (kt & 1) ? sA1 : sA0; unsigned char* sB = (kt & 1) ? sB1 : sB0;
;         unsigned char* nA = (kt & 1) ? sA0 : sA1; unsigned char* nB = (kt & 1) ? sB0 : sB1;
;         bf16x8 fa[4], fb[4], ga[4], gb[4];
;         const int ch0 = ((g ^ sw) << 4), ch1 = (((4 + g) ^ sw) << 4);
;         const unsigned ko = (unsigned)(kt + 2) * 128u;
;         const unsigned koa = ko + ((MODE == 2 && kt + 2 >= 8) ? (unsigned)(ZC_FQ - 512) * 2u : 0u);
;         const bool wr_ok = kt < 15, ld_ok = kt < 14;
; #pragma unroll
;         for (int i = 0; i < 4; ++i) { fa[i] = *(const bf16x8*)(sA + arow_off + i * 2048 + ch0); fb[i] = *(const bf16x8*)(sB + brow_off + i * 2048 + ch0); }
;         __builtin_amdgcn_sched_barrier(0);
;         __builtin_amdgcn_s_setprio(2);
;         if (wr_ok) *(uint4*)(nA + soff0) = ra0;
;         if (ld_ok) ra0 = *(const uint4*)(Ab + (aoff + 0u * LDA + koa));
;         ga[0] = *(const bf16x8*)(sA + arow_off + 0 * 2048 + ch1); gb[0] = *(const bf16x8*)(sB + brow_off + 0 * 2048 + ch1);
;         __builtin_amdgcn_sched_barrier(0);
; #pragma unroll
;         for (int j = 0; j < 4; ++j) acc[0][j] = __builtin_amdgcn_mfma_f32_16x16x32_bf16(fb[j], fa[0], acc[0][j], 0, 0, 0);
;         __builtin_amdgcn_sched_barrier(0);
;         if (wr_ok) *(uint4*)(nA + soff0 + 4096) = ra1;
;         if (ld_ok) ra1 = *(const uint4*)(Ab + (aoff + 32u * LDA + koa));
;         ga[1] = *(const bf16x8*)(sA + arow_off + 1 * 2048 + ch1); gb[1] = *(const bf16x8*)(sB + brow_off + 1 * 2048 + ch1);
;         __builtin_amdgcn_sched_barrier(0);
; #pragma unroll
;         for (int j = 0; j < 4; ++j) acc[1][j] = __builtin_amdgcn_mfma_f32_16x16x32_bf16(fb[j], fa[1], acc[1][j], 0, 0, 0);
;         __builtin_amdgcn_sched_barrier(0);
;         if (wr_ok) *(uint4*)(nA + soff0 + 8192) = ra2;
;         if (ld_ok) ra2 = *(const uint4*)(Ab + (aoff + 64u * LDA + koa));
;         ga[2] = *(const bf16x8*)(sA + arow_off + 2 * 2048 + ch1); gb[2] = *(const bf16x8*)(sB + brow_off + 2 * 2048 + ch1);
;         __builtin_amdgcn_sched_barrier(0);
; #pragma unroll
;         for (int j = 0; j < 4; ++j) acc[2][j] = __builtin_amdgcn_mfma_f32_16x16x32_bf16(fb[j], fa[2], acc[2][j], 0, 0, 0);
	ds_read_b128 v[102:105], v6 offset:32768
	ds_read_b128 v[110:113], v6 offset:34816
	ds_read_b128 v[122:125], v7 offset:49152
	ds_read_b128 v[126:129], v7 offset:51200
	ds_read_b128 v[146:149], v6 offset:36864
	ds_read_b128 v[150:153], v6 offset:38912
	ds_read_b128 v[154:157], v7 offset:53248
	ds_read_b128 v[158:161], v7 offset:55296
	s_setprio 2
	global_load_dwordx4 v[166:169], v8, s[36:37] offset:1664
	s_waitcnt vmcnt(8)
	ds_write_b128 v2, v[162:165]
	ds_read_b128 v[162:165], v4 offset:32768
	ds_read_b128 v[170:173], v5 offset:49152
	s_waitcnt lgkmcnt(8)
	v_mfma_f32_16x16x32_bf16 v[26:29], v[122:125], v[102:105], v[26:29]
	s_waitcnt lgkmcnt(3)
	v_mfma_f32_16x16x32_bf16 v[10:13], v[158:161], v[102:105], v[10:13]
	v_mfma_f32_16x16x32_bf16 v[86:89], v[126:129], v[102:105], v[86:89]
	v_mfma_f32_16x16x32_bf16 v[94:97], v[154:157], v[102:105], v[94:97]
	global_load_dwordx4 v[102:105], v222, s[36:37] offset:1664
	v_mfma_f32_16x16x32_bf16 v[30:33], v[122:125], v[110:113], v[30:33]
	s_waitcnt vmcnt(8)
	ds_write_b128 v2, v[62:65] offset:4096
	v_mfma_f32_16x16x32_bf16 v[42:45], v[126:129], v[110:113], v[42:45]
	ds_read_b128 v[62:65], v4 offset:34816
	v_mfma_f32_16x16x32_bf16 v[14:17], v[158:161], v[110:113], v[14:17]
	ds_read_b128 v[174:177], v5 offset:51200
	v_mfma_f32_16x16x32_bf16 v[90:93], v[154:157], v[110:113], v[90:93]
	global_load_dwordx4 v[110:113], v223, s[36:37] offset:1664
	v_mfma_f32_16x16x32_bf16 v[34:37], v[122:125], v[146:149], v[34:37]
	s_waitcnt vmcnt(8)
	ds_write_b128 v2, v[106:109] offset:8192
	v_mfma_f32_16x16x32_bf16 v[46:49], v[126:129], v[146:149], v[46:49]
	ds_read_b128 v[106:109], v4 offset:36864
	v_mfma_f32_16x16x32_bf16 v[58:61], v[154:157], v[146:149], v[58:61]
	ds_read_b128 v[178:181], v5 offset:53248
	v_mfma_f32_16x16x32_bf16 v[18:21], v[158:161], v[146:149], v[18:21]
	global_load_dwordx4 v[146:149], v224, s[36:37] offset:1664
	v_mfma_f32_16x16x32_bf16 v[38:41], v[122:125], v[150:153], v[38:41]
	s_waitcnt vmcnt(8)
	ds_write_b128 v2, v[132:135] offset:12288
	v_mfma_f32_16x16x32_bf16 v[50:53], v[126:129], v[150:153], v[50:53]
	ds_read_b128 v[132:135], v4 offset:38912
	v_mfma_f32_16x16x32_bf16 v[54:57], v[154:157], v[150:153], v[54:57]
	ds_read_b128 v[182:185], v5 offset:55296
	v_mfma_f32_16x16x32_bf16 v[22:25], v[158:161], v[150:153], v[22:25]
	global_load_dwordx4 v[122:125], v3, s[0:1] offset:1664
	s_waitcnt vmcnt(8)
	ds_write_b128 v2, v[118:121] offset:16384
	s_waitcnt lgkmcnt(10)
	v_mfma_f32_16x16x32_bf16 v[26:29], v[170:173], v[162:165], v[26:29]
	s_waitcnt lgkmcnt(1)
	v_mfma_f32_16x16x32_bf16 v[10:13], v[182:185], v[162:165], v[10:13]
	v_mfma_f32_16x16x32_bf16 v[86:89], v[174:177], v[162:165], v[86:89]
	v_mfma_f32_16x16x32_bf16 v[94:97], v[178:181], v[162:165], v[94:97]
	global_load_dwordx4 v[118:121], v225, s[0:1] offset:1664
	v_mfma_f32_16x16x32_bf16 v[30:33], v[170:173], v[62:65], v[30:33]
	s_waitcnt vmcnt(8)
	ds_write_b128 v2, v[114:117] offset:20480
	v_mfma_f32_16x16x32_bf16 v[42:45], v[174:177], v[62:65], v[42:45]
	v_mfma_f32_16x16x32_bf16 v[14:17], v[182:185], v[62:65], v[14:17]
	v_mfma_f32_16x16x32_bf16 v[90:93], v[178:181], v[62:65], v[90:93]
	global_load_dwordx4 v[62:65], v226, s[0:1] offset:1664
	v_mfma_f32_16x16x32_bf16 v[34:37], v[170:173], v[106:109], v[34:37]
	s_waitcnt vmcnt(8)
	ds_write_b128 v2, v[98:101] offset:24576
	v_mfma_f32_16x16x32_bf16 v[46:49], v[174:177], v[106:109], v[46:49]
	v_mfma_f32_16x16x32_bf16 v[58:61], v[178:181], v[106:109], v[58:61]
	v_mfma_f32_16x16x32_bf16 v[18:21], v[182:185], v[106:109], v[18:21]
	global_load_dwordx4 v[98:101], v227, s[0:1] offset:1664
	v_mfma_f32_16x16x32_bf16 v[38:41], v[170:173], v[132:135], v[38:41]
	s_waitcnt vmcnt(8)
	ds_write_b128 v2, v[82:85] offset:28672
	v_mfma_f32_16x16x32_bf16 v[50:53], v[174:177], v[132:135], v[50:53]
	v_mfma_f32_16x16x32_bf16 v[54:57], v[178:181], v[132:135], v[54:57]
	v_mfma_f32_16x16x32_bf16 v[22:25], v[182:185], v[132:135], v[22:25]
	s_setprio 0
	s_waitcnt lgkmcnt(0)
	s_barrier
	ds_read_b128 v[82:85], v6
	ds_read_b128 v[106:109], v6 offset:2048
	ds_read_b128 v[114:117], v7 offset:16384
	ds_read_b128 v[126:129], v7 offset:18432
	ds_read_b128 v[132:135], v6 offset:4096
	ds_read_b128 v[150:153], v6 offset:6144
	ds_read_b128 v[154:157], v7 offset:20480
	ds_read_b128 v[158:161], v7 offset:22528
	s_setprio 2
	global_load_dwordx4 v[162:165], v8, s[36:37] offset:1792
	s_waitcnt vmcnt(8)
	ds_write_b128 v2, v[166:169] offset:32768
	ds_read_b128 v[166:169], v4
	ds_read_b128 v[170:173], v5 offset:16384
	s_waitcnt lgkmcnt(8)
	v_mfma_f32_16x16x32_bf16 v[26:29], v[114:117], v[82:85], v[26:29]
	s_waitcnt lgkmcnt(3)
	v_mfma_f32_16x16x32_bf16 v[10:13], v[158:161], v[82:85], v[10:13]
	v_mfma_f32_16x16x32_bf16 v[86:89], v[126:129], v[82:85], v[86:89]
	v_mfma_f32_16x16x32_bf16 v[94:97], v[154:157], v[82:85], v[94:97]
	global_load_dwordx4 v[82:85], v222, s[36:37] offset:1792
	v_mfma_f32_16x16x32_bf16 v[30:33], v[114:117], v[106:109], v[30:33]
	s_waitcnt vmcnt(8)
	ds_write_b128 v2, v[102:105] offset:36864
	v_mfma_f32_16x16x32_bf16 v[42:45], v[126:129], v[106:109], v[42:45]
	ds_read_b128 v[102:105], v4 offset:2048
	v_mfma_f32_16x16x32_bf16 v[14:17], v[158:161], v[106:109], v[14:17]
	ds_read_b128 v[174:177], v5 offset:18432
	v_mfma_f32_16x16x32_bf16 v[90:93], v[154:157], v[106:109], v[90:93]
	global_load_dwordx4 v[106:109], v223, s[36:37] offset:1792
	v_mfma_f32_16x16x32_bf16 v[34:37], v[114:117], v[132:135], v[34:37]
	s_waitcnt vmcnt(8)
; template <int MODE>
; __device__ __forceinline__ void gemm_tile(const Params& P, int tm, int tn, unsigned char* smem) {
;     ...
;     for (int kt = 0; kt < 16; ++kt) {
;         unsigned char* sA = (kt & 1) ? sA1 : sA0; unsigned char* sB = (kt & 1) ? sB1 : sB0;
;         unsigned char* nA = (kt & 1) ? sA0 : sA1; unsigned char* nB = (kt & 1) ? sB0 : sB1;
;         bf16x8 fa[4], fb[4], ga[4], gb[4];
;         const int ch0 = ((g ^ sw) << 4), ch1 = (((4 + g) ^ sw) << 4);
;         const unsigned ko = (unsigned)(kt + 2) * 128u;
;         const unsigned koa = ko + ((MODE == 2 && kt + 2 >= 8) ? (unsigned)(ZC_FQ - 512) * 2u : 0u);
;         const bool wr_ok = kt < 15, ld_ok = kt < 14;
; #pragma unroll
;         for (int i = 0; i < 4; ++i) { fa[i] = *(const bf16x8*)(sA + arow_off + i * 2048 + ch0); fb[i] = *(const bf16x8*)(sB + brow_off + i * 2048 + ch0); }
;         __builtin_amdgcn_sched_barrier(0);
;         __builtin_amdgcn_s_setprio(2);
;         if (wr_ok) *(uint4*)(nA + soff0) = ra0;
;         if (ld_ok) ra0 = *(const uint4*)(Ab + (aoff + 0u * LDA + koa));
;         ga[0] = *(const bf16x8*)(sA + arow_off + 0 * 2048 + ch1); gb[0] = *(const bf16x8*)(sB + brow_off + 0 * 2048 + ch1);
;         __builtin_amdgcn_sched_barrier(0);
; #pragma unroll
;         for (int j = 0; j < 4; ++j) acc[0][j] = __builtin_amdgcn_mfma_f32_16x16x32_bf16(fb[j], fa[0], acc[0][j], 0, 0, 0);
;         __builtin_amdgcn_sched_barrier(0);
;         if (wr_ok) *(uint4*)(nA + soff0 + 4096) = ra1;
;         if (ld_ok) ra1 = *(const uint4*)(Ab + (aoff + 32u * LDA + koa));
;         ga[1] = *(const bf16x8*)(sA + arow_off + 1 * 2048 + ch1); gb[1] = *(const bf16x8*)(sB + brow_off + 1 * 2048 + ch1);
;         __builtin_amdgcn_sched_barrier(0);
; #pragma unroll
;         for (int j = 0; j < 4; ++j) acc[1][j] = __builtin_amdgcn_mfma_f32_16x16x32_bf16(fb[j], fa[1], acc[1][j], 0, 0, 0);
;         __builtin_amdgcn_sched_barrier(0);
;         if (wr_ok) *(uint4*)(nA + soff0 + 8192) = ra2;
;         if (ld_ok) ra2 = *(const uint4*)(Ab + (aoff + 64u * LDA + koa));
;         ga[2] = *(const bf16x8*)(sA + arow_off + 2 * 2048 + ch1); gb[2] = *(const bf16x8*)(sB + brow_off + 2 * 2048 + ch1);
;         __builtin_amdgcn_sched_barrier(0);
; #pragma unroll
;         for (int j = 0; j < 4; ++j) acc[2][j] = __builtin_amdgcn_mfma_f32_16x16x32_bf16(fb[j], fa[2], acc[2][j], 0, 0, 0);
	ds_write_b128 v2, v[110:113] offset:40960
	v_mfma_f32_16x16x32_bf16 v[46:49], v[126:129], v[132:135], v[46:49]
	ds_read_b128 v[110:113], v4 offset:4096
	v_mfma_f32_16x16x32_bf16 v[58:61], v[154:157], v[132:135], v[58:61]
	ds_read_b128 v[178:181], v5 offset:20480
	v_mfma_f32_16x16x32_bf16 v[18:21], v[158:161], v[132:135], v[18:21]
	global_load_dwordx4 v[132:135], v224, s[36:37] offset:1792
	v_mfma_f32_16x16x32_bf16 v[38:41], v[114:117], v[150:153], v[38:41]
	s_waitcnt vmcnt(8)
	ds_write_b128 v2, v[146:149] offset:45056
	v_mfma_f32_16x16x32_bf16 v[50:53], v[126:129], v[150:153], v[50:53]
	ds_read_b128 v[146:149], v4 offset:6144
	v_mfma_f32_16x16x32_bf16 v[54:57], v[154:157], v[150:153], v[54:57]
	ds_read_b128 v[182:185], v5 offset:22528
	v_mfma_f32_16x16x32_bf16 v[22:25], v[158:161], v[150:153], v[22:25]
	global_load_dwordx4 v[114:117], v3, s[0:1] offset:1792
	s_waitcnt vmcnt(8)
	ds_write_b128 v2, v[122:125] offset:49152
	s_waitcnt lgkmcnt(10)
	v_mfma_f32_16x16x32_bf16 v[26:29], v[170:173], v[166:169], v[26:29]
	s_waitcnt lgkmcnt(1)
	v_mfma_f32_16x16x32_bf16 v[10:13], v[182:185], v[166:169], v[10:13]
	v_mfma_f32_16x16x32_bf16 v[86:89], v[174:177], v[166:169], v[86:89]
	v_mfma_f32_16x16x32_bf16 v[94:97], v[178:181], v[166:169], v[94:97]
	global_load_dwordx4 v[122:125], v225, s[0:1] offset:1792
	v_mfma_f32_16x16x32_bf16 v[30:33], v[170:173], v[102:105], v[30:33]
	s_waitcnt vmcnt(8)
	ds_write_b128 v2, v[118:121] offset:53248
	v_mfma_f32_16x16x32_bf16 v[42:45], v[174:177], v[102:105], v[42:45]
	v_mfma_f32_16x16x32_bf16 v[14:17], v[182:185], v[102:105], v[14:17]
	v_mfma_f32_16x16x32_bf16 v[90:93], v[178:181], v[102:105], v[90:93]
	global_load_dwordx4 v[102:105], v226, s[0:1] offset:1792
	v_mfma_f32_16x16x32_bf16 v[34:37], v[170:173], v[110:113], v[34:37]
	s_waitcnt vmcnt(8)
	ds_write_b128 v2, v[62:65] offset:57344
	v_mfma_f32_16x16x32_bf16 v[46:49], v[174:177], v[110:113], v[46:49]
	v_mfma_f32_16x16x32_bf16 v[58:61], v[178:181], v[110:113], v[58:61]
	v_mfma_f32_16x16x32_bf16 v[18:21], v[182:185], v[110:113], v[18:21]
	global_load_dwordx4 v[62:65], v227, s[0:1] offset:1792
	v_mfma_f32_16x16x32_bf16 v[38:41], v[170:173], v[146:149], v[38:41]
	s_waitcnt vmcnt(8)
	ds_write_b128 v2, v[98:101] offset:61440
	v_mfma_f32_16x16x32_bf16 v[50:53], v[174:177], v[146:149], v[50:53]
	v_mfma_f32_16x16x32_bf16 v[54:57], v[178:181], v[146:149], v[54:57]
	v_mfma_f32_16x16x32_bf16 v[22:25], v[182:185], v[146:149], v[22:25]
	s_setprio 0
	s_waitcnt lgkmcnt(0)
	s_barrier
	ds_read_b128 v[98:101], v6 offset:32768
	ds_read_b128 v[110:113], v6 offset:34816
	ds_read_b128 v[118:121], v7 offset:49152
	ds_read_b128 v[126:129], v7 offset:51200
	ds_read_b128 v[146:149], v6 offset:36864
	ds_read_b128 v[150:153], v6 offset:38912
	ds_read_b128 v[154:157], v7 offset:53248
	ds_read_b128 v[158:161], v7 offset:55296
	s_setprio 2
	global_load_dwordx4 v[166:169], v8, s[36:37] offset:1920
	s_waitcnt vmcnt(8)
	ds_write_b128 v2, v[162:165]
	ds_read_b128 v[162:165], v4 offset:32768
	ds_read_b128 v[170:173], v5 offset:49152
	s_waitcnt lgkmcnt(8)
	v_mfma_f32_16x16x32_bf16 v[26:29], v[118:121], v[98:101], v[26:29]
	s_waitcnt lgkmcnt(3)
	v_mfma_f32_16x16x32_bf16 v[10:13], v[158:161], v[98:101], v[10:13]
	v_mfma_f32_16x16x32_bf16 v[86:89], v[126:129], v[98:101], v[86:89]
	v_mfma_f32_16x16x32_bf16 v[94:97], v[154:157], v[98:101], v[94:97]
	global_load_dwordx4 v[98:101], v222, s[36:37] offset:1920
	v_mfma_f32_16x16x32_bf16 v[30:33], v[118:121], v[110:113], v[30:33]
	s_waitcnt vmcnt(8)
	ds_write_b128 v2, v[82:85] offset:4096
	v_mfma_f32_16x16x32_bf16 v[42:45], v[126:129], v[110:113], v[42:45]
	ds_read_b128 v[82:85], v4 offset:34816
	v_mfma_f32_16x16x32_bf16 v[14:17], v[158:161], v[110:113], v[14:17]
	ds_read_b128 v[174:177], v5 offset:51200
	v_mfma_f32_16x16x32_bf16 v[90:93], v[154:157], v[110:113], v[90:93]
	global_load_dwordx4 v[110:113], v223, s[36:37] offset:1920
	v_mfma_f32_16x16x32_bf16 v[34:37], v[118:121], v[146:149], v[34:37]
	s_waitcnt vmcnt(8)
	ds_write_b128 v2, v[106:109] offset:8192
	v_mfma_f32_16x16x32_bf16 v[46:49], v[126:129], v[146:149], v[46:49]
	ds_read_b128 v[106:109], v4 offset:36864
	v_mfma_f32_16x16x32_bf16 v[58:61], v[154:157], v[146:149], v[58:61]
	ds_read_b128 v[178:181], v5 offset:53248
	v_mfma_f32_16x16x32_bf16 v[18:21], v[158:161], v[146:149], v[18:21]
	v_add_u32_e32 v8, 0x30780, v8
	global_load_dwordx4 v[146:149], v8, s[36:37]
	s_waitcnt vmcnt(8)
	ds_write_b128 v2, v[132:135] offset:12288
	ds_read_b128 v[132:135], v4 offset:38912
	ds_read_b128 v[182:185], v5 offset:55296
	v_mfma_f32_16x16x32_bf16 v[38:41], v[118:121], v[150:153], v[38:41]
	v_mfma_f32_16x16x32_bf16 v[50:53], v[126:129], v[150:153], v[50:53]
	v_mfma_f32_16x16x32_bf16 v[54:57], v[154:157], v[150:153], v[54:57]
	v_mfma_f32_16x16x32_bf16 v[22:25], v[158:161], v[150:153], v[22:25]
	global_load_dwordx4 v[118:121], v3, s[0:1] offset:1920
	s_waitcnt vmcnt(8)
	ds_write_b128 v2, v[114:117] offset:16384
	s_waitcnt lgkmcnt(10)
	v_mfma_f32_16x16x32_bf16 v[26:29], v[170:173], v[162:165], v[26:29]
	s_waitcnt lgkmcnt(1)
	v_mfma_f32_16x16x32_bf16 v[8:11], v[182:185], v[162:165], v[10:13]
	v_mfma_f32_16x16x32_bf16 v[86:89], v[174:177], v[162:165], v[86:89]
	v_mfma_f32_16x16x32_bf16 v[94:97], v[178:181], v[162:165], v[94:97]
	s_nop 0
	global_load_dwordx4 v[114:117], v225, s[0:1] offset:1920
	s_waitcnt vmcnt(8)
	ds_write_b128 v2, v[122:125] offset:20480
	v_mfma_f32_16x16x32_bf16 v[30:33], v[170:173], v[82:85], v[30:33]
	v_mfma_f32_16x16x32_bf16 v[42:45], v[174:177], v[82:85], v[42:45]
	v_mfma_f32_16x16x32_bf16 v[12:15], v[182:185], v[82:85], v[14:17]
	v_mfma_f32_16x16x32_bf16 v[90:93], v[178:181], v[82:85], v[90:93]
	s_nop 1
	global_load_dwordx4 v[82:85], v226, s[0:1] offset:1920
	s_waitcnt vmcnt(8)
	ds_write_b128 v2, v[102:105] offset:24576
	v_mfma_f32_16x16x32_bf16 v[34:37], v[170:173], v[106:109], v[34:37]
	v_mfma_f32_16x16x32_bf16 v[46:49], v[174:177], v[106:109], v[46:49]
	v_mfma_f32_16x16x32_bf16 v[58:61], v[178:181], v[106:109], v[58:61]
	v_mfma_f32_16x16x32_bf16 v[16:19], v[182:185], v[106:109], v[18:21]
	v_add_u32_e32 v3, 0x30780, v3
	global_load_dwordx4 v[102:105], v3, s[0:1]
	s_waitcnt vmcnt(8)
	ds_write_b128 v2, v[62:65] offset:28672
	v_mfma_f32_16x16x32_bf16 v[38:41], v[170:173], v[132:135], v[38:41]
	v_mfma_f32_16x16x32_bf16 v[50:53], v[174:177], v[132:135], v[50:53]
	v_mfma_f32_16x16x32_bf16 v[54:57], v[178:181], v[132:135], v[54:57]
	v_mfma_f32_16x16x32_bf16 v[20:23], v[182:185], v[132:135], v[22:25]
	s_setprio 0
	s_waitcnt lgkmcnt(0)
	s_barrier
; template <int MODE>
; __device__ __forceinline__ void gemm_tile(const Params& P, int tm, int tn, unsigned char* smem) {
;     ...
; #pragma unroll
;         for (int i = 0; i < 4; ++i) { fa[i] = *(const bf16x8*)(sA + arow_off + i * 2048 + ch0); fb[i] = *(const bf16x8*)(sB + brow_off + i * 2048 + ch0); }
;         __builtin_amdgcn_sched_barrier(0);
;         __builtin_amdgcn_s_setprio(2);
;         if (wr_ok) *(uint4*)(nA + soff0) = ra0;
;         if (ld_ok) ra0 = *(const uint4*)(Ab + (aoff + 0u * LDA + koa));
;         ga[0] = *(const bf16x8*)(sA + arow_off + 0 * 2048 + ch1); gb[0] = *(const bf16x8*)(sB + brow_off + 0 * 2048 + ch1);
;         __builtin_amdgcn_sched_barrier(0);
; #pragma unroll
;         for (int j = 0; j < 4; ++j) acc[0][j] = __builtin_amdgcn_mfma_f32_16x16x32_bf16(fb[j], fa[0], acc[0][j], 0, 0, 0);
;         __builtin_amdgcn_sched_barrier(0);
;         if (wr_ok) *(uint4*)(nA + soff0 + 4096) = ra1;
;         if (ld_ok) ra1 = *(const uint4*)(Ab + (aoff + 32u * LDA + koa));
;         ga[1] = *(const bf16x8*)(sA + arow_off + 1 * 2048 + ch1); gb[1] = *(const bf16x8*)(sB + brow_off + 1 * 2048 + ch1);
;         __builtin_amdgcn_sched_barrier(0);
; #pragma unroll
;         for (int j = 0; j < 4; ++j) acc[1][j] = __builtin_amdgcn_mfma_f32_16x16x32_bf16(fb[j], fa[1], acc[1][j], 0, 0, 0);
;         __builtin_amdgcn_sched_barrier(0);
;         if (wr_ok) *(uint4*)(nA + soff0 + 8192) = ra2;
;         if (ld_ok) ra2 = *(const uint4*)(Ab + (aoff + 64u * LDA + koa));
;         ga[2] = *(const bf16x8*)(sA + arow_off + 2 * 2048 + ch1); gb[2] = *(const bf16x8*)(sB + brow_off + 2 * 2048 + ch1);
;         __builtin_amdgcn_sched_barrier(0);
; #pragma unroll
;         for (int j = 0; j < 4; ++j) acc[2][j] = __builtin_amdgcn_mfma_f32_16x16x32_bf16(fb[j], fa[2], acc[2][j], 0, 0, 0);
;         __builtin_amdgcn_sched_barrier(0);
;         if (wr_ok) *(uint4*)(nA + soff0 + 12288) = ra3;
;         if (ld_ok) ra3 = *(const uint4*)(Ab + (aoff + 96u * LDA + koa));
;         ga[3] = *(const bf16x8*)(sA + arow_off + 3 * 2048 + ch1); gb[3] = *(const bf16x8*)(sB + brow_off + 3 * 2048 + ch1);
;         __builtin_amdgcn_sched_barrier(0);
; #pragma unroll
;         for (int j = 0; j < 4; ++j) acc[3][j] = __builtin_amdgcn_mfma_f32_16x16x32_bf16(fb[j], fa[3], acc[3][j], 0, 0, 0);
;         __builtin_amdgcn_sched_barrier(0);
;         if (wr_ok) *(uint4*)(nB + soff0) = rb0;
	ds_read_b128 v[62:65], v6
	ds_read_b128 v[106:109], v6 offset:2048
	ds_read_b128 v[122:125], v7 offset:16384
	ds_read_b128 v[126:129], v7 offset:18432
	ds_read_b128 v[132:135], v6 offset:4096
	ds_read_b128 v[150:153], v6 offset:6144
	ds_read_b128 v[154:157], v7 offset:20480
	ds_read_b128 v[158:161], v7 offset:22528
	s_setprio 2
	s_waitcnt vmcnt(7)
	ds_write_b128 v2, v[166:169] offset:32768
	ds_read_b128 v[162:165], v4
	ds_read_b128 v[166:169], v5 offset:16384
	s_waitcnt lgkmcnt(8)
	v_mfma_f32_16x16x32_bf16 v[24:27], v[122:125], v[62:65], v[26:29]
	s_waitcnt lgkmcnt(3)
	v_mfma_f32_16x16x32_bf16 v[8:11], v[158:161], v[62:65], v[8:11]
	v_mfma_f32_16x16x32_bf16 v[86:89], v[126:129], v[62:65], v[86:89]
	v_mfma_f32_16x16x32_bf16 v[94:97], v[154:157], v[62:65], v[94:97]
	v_mfma_f32_16x16x32_bf16 v[28:31], v[122:125], v[106:109], v[30:33]
	s_waitcnt vmcnt(6)
	ds_write_b128 v2, v[98:101] offset:36864
	v_mfma_f32_16x16x32_bf16 v[42:45], v[126:129], v[106:109], v[42:45]
	ds_read_b128 v[62:65], v4 offset:2048
	v_mfma_f32_16x16x32_bf16 v[12:15], v[158:161], v[106:109], v[12:15]
	ds_read_b128 v[98:101], v5 offset:18432
	v_mfma_f32_16x16x32_bf16 v[90:93], v[154:157], v[106:109], v[90:93]
	v_mfma_f32_16x16x32_bf16 v[32:35], v[122:125], v[132:135], v[34:37]
	s_waitcnt vmcnt(5)
	ds_write_b128 v2, v[110:113] offset:40960
	v_mfma_f32_16x16x32_bf16 v[46:49], v[126:129], v[132:135], v[46:49]
	ds_read_b128 v[106:109], v4 offset:4096
	v_mfma_f32_16x16x32_bf16 v[58:61], v[154:157], v[132:135], v[58:61]
	ds_read_b128 v[110:113], v5 offset:20480
	v_mfma_f32_16x16x32_bf16 v[16:19], v[158:161], v[132:135], v[16:19]
	v_mfma_f32_16x16x32_bf16 v[36:39], v[122:125], v[150:153], v[38:41]
	s_waitcnt vmcnt(4)
	ds_write_b128 v2, v[146:149] offset:45056
	v_mfma_f32_16x16x32_bf16 v[50:53], v[126:129], v[150:153], v[50:53]
	ds_read_b128 v[132:135], v4 offset:6144
	v_mfma_f32_16x16x32_bf16 v[54:57], v[154:157], v[150:153], v[54:57]
	ds_read_b128 v[146:149], v5 offset:22528
	v_mfma_f32_16x16x32_bf16 v[20:23], v[158:161], v[150:153], v[20:23]
	s_waitcnt vmcnt(3)
	ds_write_b128 v2, v[118:121] offset:49152
	s_waitcnt lgkmcnt(10)
	v_mfma_f32_16x16x32_bf16 v[24:27], v[166:169], v[162:165], v[24:27]
	s_waitcnt lgkmcnt(1)
	v_mfma_f32_16x16x32_bf16 v[8:11], v[146:149], v[162:165], v[8:11]
	v_mfma_f32_16x16x32_bf16 v[86:89], v[98:101], v[162:165], v[86:89]
	v_mfma_f32_16x16x32_bf16 v[94:97], v[110:113], v[162:165], v[94:97]
	v_mfma_f32_16x16x32_bf16 v[28:31], v[166:169], v[62:65], v[28:31]
	s_waitcnt vmcnt(2)
	ds_write_b128 v2, v[114:117] offset:53248
	v_mfma_f32_16x16x32_bf16 v[40:43], v[98:101], v[62:65], v[42:45]
	v_mfma_f32_16x16x32_bf16 v[12:15], v[146:149], v[62:65], v[12:15]
	v_mfma_f32_16x16x32_bf16 v[90:93], v[110:113], v[62:65], v[90:93]
	v_mfma_f32_16x16x32_bf16 v[32:35], v[166:169], v[106:109], v[32:35]
	s_waitcnt vmcnt(1)
	ds_write_b128 v2, v[82:85] offset:57344
	v_mfma_f32_16x16x32_bf16 v[44:47], v[98:101], v[106:109], v[46:49]
	v_mfma_f32_16x16x32_bf16 v[58:61], v[110:113], v[106:109], v[58:61]
	v_mfma_f32_16x16x32_bf16 v[16:19], v[146:149], v[106:109], v[16:19]
	v_mfma_f32_16x16x32_bf16 v[36:39], v[166:169], v[132:135], v[36:39]
	s_waitcnt vmcnt(0)
	ds_write_b128 v2, v[102:105] offset:61440
	v_mfma_f32_16x16x32_bf16 v[48:51], v[98:101], v[132:135], v[50:53]
	v_mfma_f32_16x16x32_bf16 v[52:55], v[110:113], v[132:135], v[54:57]
	v_mfma_f32_16x16x32_bf16 v[20:23], v[146:149], v[132:135], v[20:23]
	s_setprio 0
	s_waitcnt lgkmcnt(0)
	s_barrier
	ds_read_b128 v[62:65], v6 offset:32768
	ds_read_b128 v[82:85], v6 offset:34816
	ds_read_b128 v[98:101], v7 offset:49152
	ds_read_b128 v[102:105], v7 offset:51200
	ds_read_b128 v[106:109], v6 offset:36864
	ds_read_b128 v[110:113], v6 offset:38912
	ds_read_b128 v[114:117], v7 offset:53248
	ds_read_b128 v[118:121], v7 offset:55296
	s_setprio 2
	ds_read_b128 v[122:125], v4 offset:32768
	ds_read_b128 v[126:129], v5 offset:49152
	s_waitcnt lgkmcnt(7)
	v_mfma_f32_16x16x32_bf16 v[24:27], v[98:101], v[62:65], v[24:27]
	s_waitcnt lgkmcnt(2)
	v_mfma_f32_16x16x32_bf16 v[6:9], v[118:121], v[62:65], v[8:11]
	v_mfma_f32_16x16x32_bf16 v[86:89], v[102:105], v[62:65], v[86:89]
	v_mfma_f32_16x16x32_bf16 v[94:97], v[114:117], v[62:65], v[94:97]
	v_mfma_f32_16x16x32_bf16 v[28:31], v[98:101], v[82:85], v[28:31]
	ds_read_b128 v[132:135], v4 offset:34816
	v_mfma_f32_16x16x32_bf16 v[40:43], v[102:105], v[82:85], v[40:43]
	ds_read_b128 v[146:149], v5 offset:51200
	v_mfma_f32_16x16x32_bf16 v[10:13], v[118:121], v[82:85], v[12:15]
	v_mfma_f32_16x16x32_bf16 v[90:93], v[114:117], v[82:85], v[90:93]
	v_mfma_f32_16x16x32_bf16 v[14:17], v[118:121], v[106:109], v[16:19]
	ds_read_b128 v[82:85], v4 offset:36864
	v_mfma_f32_16x16x32_bf16 v[154:157], v[98:101], v[106:109], v[32:35]
	ds_read_b128 v[150:153], v5 offset:53248
	v_mfma_f32_16x16x32_bf16 v[158:161], v[102:105], v[106:109], v[44:47]
	v_mfma_f32_16x16x32_bf16 v[162:165], v[114:117], v[106:109], v[58:61]
	v_mfma_f32_16x16x32_bf16 v[98:101], v[98:101], v[110:113], v[36:39]
	ds_read_b128 v[106:109], v4 offset:38912
	v_mfma_f32_16x16x32_bf16 v[102:105], v[102:105], v[110:113], v[48:51]
	ds_read_b128 v[2:5], v5 offset:55296
	v_mfma_f32_16x16x32_bf16 v[114:117], v[114:117], v[110:113], v[52:55]
	v_mfma_f32_16x16x32_bf16 v[110:113], v[118:121], v[110:113], v[20:23]
	s_waitcnt lgkmcnt(6)
	v_mfma_f32_16x16x32_bf16 v[62:65], v[126:129], v[122:125], v[24:27]
	s_waitcnt lgkmcnt(4)
	v_mfma_f32_16x16x32_bf16 v[58:61], v[146:149], v[122:125], v[86:89]
	s_waitcnt lgkmcnt(2)
	v_mfma_f32_16x16x32_bf16 v[54:57], v[150:153], v[122:125], v[94:97]
	s_waitcnt lgkmcnt(0)
	v_mfma_f32_16x16x32_bf16 v[50:53], v[2:5], v[122:125], v[6:9]
	v_mfma_f32_16x16x32_bf16 v[46:49], v[126:129], v[132:135], v[28:31]
	v_mfma_f32_16x16x32_bf16 v[42:45], v[146:149], v[132:135], v[40:43]
	v_mfma_f32_16x16x32_bf16 v[38:41], v[150:153], v[132:135], v[90:93]
	v_mfma_f32_16x16x32_bf16 v[34:37], v[2:5], v[132:135], v[10:13]
	v_mfma_f32_16x16x32_bf16 v[30:33], v[126:129], v[82:85], v[154:157]
	v_mfma_f32_16x16x32_bf16 v[26:29], v[146:149], v[82:85], v[158:161]
	v_mfma_f32_16x16x32_bf16 v[22:25], v[150:153], v[82:85], v[162:165]
	v_mfma_f32_16x16x32_bf16 v[18:21], v[2:5], v[82:85], v[14:17]
	v_mfma_f32_16x16x32_bf16 v[14:17], v[126:129], v[106:109], v[98:101]
	v_mfma_f32_16x16x32_bf16 v[10:13], v[146:149], v[106:109], v[102:105]
	v_mfma_f32_16x16x32_bf16 v[6:9], v[150:153], v[106:109], v[114:117]
	v_mfma_f32_16x16x32_bf16 v[2:5], v[2:5], v[106:109], v[110:113]
	s_setprio 0
	s_and_b32 s0, s7, -8
	s_cmp_lg_u32 s0, 16
	s_barrier
; template <int MODE>
; __device__ __forceinline__ void gemm_tile(const Params& P, int tm, int tn, unsigned char* smem) {
;     ...
;     if (MODE == 1) {
;         if (n0 >= ZC_FQ && n0 < ZC_FV) {
;             const bool isk = n0 >= ZC_FK;
;             const float* gain = isk ? P.f_k_norm : P.f_q_norm;
;             const float scl = isk ? 1.0f : 0.125f * LOG2E;
;             float gn[4][4];
; #pragma unroll
;             for (int j = 0; j < 4; ++j)
; #pragma unroll
;                 for (int r = 0; r < 4; ++r) gn[j][r] = gain[16 * j + 4 * g + r];
; #pragma unroll
;             for (int i = 0; i < 4; ++i) {
;                 float ss = 0.f;
; #pragma unroll
;                 for (int j = 0; j < 4; ++j)
; #pragma unroll
;                     for (int r = 0; r < 4; ++r) ss += acc[i][j][r] * acc[i][j][r];
;                 ss = x4_sum(ss);
;                 const float rstd = rsqrtf(ss * (1.0f / 64.0f) + EPS) * scl;
	s_cbranch_scc1 .LBB0_223
	v_mul_f32_e32 v68, v63, v63
	v_fmac_f32_e32 v68, v62, v62
	v_fmac_f32_e32 v68, v64, v64
	v_fmac_f32_e32 v68, v65, v65
	v_fmac_f32_e32 v68, v58, v58
	v_fmac_f32_e32 v68, v59, v59
	v_fmac_f32_e32 v68, v60, v60
	v_fmac_f32_e32 v68, v61, v61
	v_fmac_f32_e32 v68, v54, v54
	v_fmac_f32_e32 v68, v55, v55
	v_fmac_f32_e32 v68, v56, v56
	s_cmp_gt_u32 s7, 19
	v_fmac_f32_e32 v68, v57, v57
	v_pk_mul_f32 v[82:83], v[50:51], v[50:51]
	v_mov_b32_e32 v66, 0x3e38aa3b
	s_cselect_b64 s[0:1], -1, 0
	v_add_f32_e32 v68, v82, v68
	v_cndmask_b32_e64 v106, v66, 1.0, s[0:1]
	v_pk_mul_f32 v[66:67], v[52:53], v[52:53]
	v_add_f32_e32 v68, v83, v68
	v_add_f32_e32 v66, v66, v68
	v_add_f32_e32 v66, v67, v66
	v_mov_b32_e32 v67, v66
	s_nop 1
	v_permlane32_swap_b32_e32 v66, v67
	v_add_f32_e32 v67, v66, v67
	v_mul_f32_e32 v66, v47, v47
	v_fmac_f32_e32 v66, v46, v46
	v_fmac_f32_e32 v66, v48, v48
	v_fmac_f32_e32 v66, v49, v49
	v_fmac_f32_e32 v66, v42, v42
	v_fmac_f32_e32 v66, v43, v43
	v_fmac_f32_e32 v66, v44, v44
	v_fmac_f32_e32 v66, v45, v45
	v_fmac_f32_e32 v66, v38, v38
	v_fmac_f32_e32 v66, v39, v39
	v_fmac_f32_e32 v66, v40, v40
	v_fmac_f32_e32 v66, v41, v41
	v_pk_mul_f32 v[86:87], v[34:35], v[34:35]
	v_pk_mul_f32 v[84:85], v[36:37], v[36:37]
	v_add_f32_e32 v66, v86, v66
	v_add_f32_e32 v66, v87, v66
	v_add_f32_e32 v66, v84, v66
	v_add_f32_e32 v66, v85, v66
	v_mov_b32_e32 v68, v66
	s_nop 1
	v_permlane32_swap_b32_e32 v66, v68
	v_add_f32_e32 v66, v66, v68
	s_and_b64 s[0:1], s[0:1], exec
	v_mov_b32_e32 v83, v67
	v_mov_b32_e32 v82, v66
	s_nop 0
	v_permlane16_swap_b32_e32 v67, v83
	v_permlane16_swap_b32_e32 v66, v82
	s_mov_b32 s0, 0x358637bd
	v_pk_add_f32 v[82:83], v[66:67], v[82:83]
	s_mov_b32 s10, 0x3c800000
	v_mov_b64_e32 v[66:67], s[0:1]
	v_mul_f32_e32 v95, v31, v31
	v_pk_fma_f32 v[86:87], v[82:83], s[10:11], v[66:67] op_sel_hi:[1,0,0]
	s_mov_b32 s7, 0x800000
	v_fmac_f32_e32 v95, v30, v30
	v_mul_f32_e32 v68, 0x4b800000, v87
	v_cmp_gt_f32_e32 vcc, s7, v87
	v_fmac_f32_e32 v95, v32, v32
	v_fmac_f32_e32 v95, v33, v33
	v_cndmask_b32_e32 v68, v87, v68, vcc
	v_rsq_f32_e32 v68, v68
	v_mul_f32_e32 v70, 0x4b800000, v86
	v_cmp_gt_f32_e64 s[0:1], s7, v86
	v_fmac_f32_e32 v95, v26, v26
	v_fmac_f32_e32 v95, v27, v27
	v_cndmask_b32_e64 v70, v86, v70, s[0:1]
	v_rsq_f32_e32 v86, v70
	v_fmac_f32_e32 v95, v28, v28
	s_cselect_b32 s9, s41, s39
	s_cselect_b32 s8, s40, s38
	v_lshlrev_b32_e32 v94, 4, v81
	v_fmac_f32_e32 v95, v29, v29
	global_load_dwordx4 v[82:85], v94, s[8:9]
	v_mul_f32_e32 v70, 0x45800000, v68
	v_fmac_f32_e32 v95, v22, v22
	v_cndmask_b32_e32 v68, v68, v70, vcc
	v_fmac_f32_e32 v95, v23, v23
	v_mul_f32_e32 v70, v106, v68
	v_mul_f32_e32 v68, 0x45800000, v86
	v_fmac_f32_e32 v95, v24, v24
	v_cndmask_b32_e64 v68, v86, v68, s[0:1]
	global_load_dwordx4 v[86:89], v94, s[8:9] offset:64
	v_fmac_f32_e32 v95, v25, v25
	v_pk_mul_f32 v[92:93], v[18:19], v[18:19]
	v_pk_mul_f32 v[90:91], v[20:21], v[20:21]
	v_add_f32_e32 v92, v92, v95
	v_add_f32_e32 v92, v93, v92
	v_add_f32_e32 v90, v90, v92
	v_add_f32_e32 v95, v91, v90
	global_load_dwordx4 v[90:93], v94, s[8:9] offset:128
	v_mov_b32_e32 v96, v95
	s_nop 1
	v_permlane32_swap_b32_e32 v95, v96
	v_add_f32_e32 v99, v95, v96
	global_load_dwordx4 v[94:97], v94, s[8:9] offset:192
	v_mul_f32_e32 v98, v15, v15
	v_fmac_f32_e32 v98, v14, v14
	v_fmac_f32_e32 v98, v16, v16
	v_fmac_f32_e32 v98, v17, v17
	v_fmac_f32_e32 v98, v10, v10
	v_fmac_f32_e32 v98, v11, v11
	v_fmac_f32_e32 v98, v12, v12
	v_fmac_f32_e32 v98, v13, v13
	v_fmac_f32_e32 v98, v6, v6
	v_fmac_f32_e32 v98, v7, v7
	v_fmac_f32_e32 v98, v8, v8
	v_fmac_f32_e32 v98, v9, v9
	v_pk_mul_f32 v[104:105], v[2:3], v[2:3]
	v_pk_mul_f32 v[102:103], v[4:5], v[4:5]
	v_add_f32_e32 v98, v104, v98
	v_add_f32_e32 v98, v105, v98
	v_add_f32_e32 v98, v102, v98
	v_add_f32_e32 v98, v103, v98
	v_mov_b32_e32 v100, v98
	s_nop 1
	v_permlane32_swap_b32_e32 v98, v100
	v_add_f32_e32 v98, v98, v100
	v_mov_b32_e32 v101, v99
	v_mov_b32_e32 v100, v98
	s_nop 0
	v_permlane16_swap_b32_e32 v99, v101
	v_permlane16_swap_b32_e32 v98, v100
	v_pk_add_f32 v[98:99], v[98:99], v[100:101]
	v_mul_f32_e32 v68, v106, v68
	v_pk_fma_f32 v[66:67], v[98:99], s[10:11], v[66:67] op_sel_hi:[1,0,0]
	s_waitcnt vmcnt(3)
; template <int MODE>
; __device__ __forceinline__ void gemm_tile(const Params& P, int tm, int tn, unsigned char* smem) {
;     ...
;                 const float rstd = rsqrtf(ss * (1.0f / 64.0f) + EPS) * scl;
; #pragma unroll
;                 for (int j = 0; j < 4; ++j)
; #pragma unroll
;                     for (int r = 0; r < 4; ++r) acc[i][j][r] *= rstd * gn[j][r];
	v_pk_mul_f32 v[100:101], v[82:83], v[70:71] op_sel_hi:[1,0]
	v_mul_f32_e32 v98, 0x4b800000, v67
	v_cmp_gt_f32_e32 vcc, s7, v67
	v_cmp_gt_f32_e64 s[0:1], s7, v66
	v_pk_mul_f32 v[62:63], v[62:63], v[100:101]
	v_cndmask_b32_e32 v67, v67, v98, vcc
	v_mul_f32_e32 v98, 0x4b800000, v66
	v_rsq_f32_e32 v67, v67
	v_cndmask_b32_e64 v66, v66, v98, s[0:1]
	v_rsq_f32_e32 v98, v66
	v_pk_mul_f32 v[100:101], v[82:83], v[68:69] op_sel_hi:[1,0]
	v_mul_f32_e32 v66, 0x45800000, v67
	v_cndmask_b32_e32 v66, v67, v66, vcc
	v_mul_f32_e32 v67, 0x45800000, v98
	v_cndmask_b32_e64 v67, v98, v67, s[0:1]
	v_mul_f32_e32 v66, v106, v66
	v_mul_f32_e32 v98, v106, v67
	v_pk_mul_f32 v[102:103], v[84:85], v[70:71] op_sel_hi:[1,0]
	v_pk_mul_f32 v[46:47], v[46:47], v[100:101]
	v_pk_mul_f32 v[100:101], v[82:83], v[66:67] op_sel_hi:[1,0]
	v_pk_mul_f32 v[82:83], v[82:83], v[98:99] op_sel_hi:[1,0]
	v_pk_mul_f32 v[64:65], v[64:65], v[102:103]
	v_pk_mul_f32 v[102:103], v[84:85], v[68:69] op_sel_hi:[1,0]
	v_pk_mul_f32 v[14:15], v[14:15], v[82:83]
	s_waitcnt vmcnt(2)
	v_pk_mul_f32 v[82:83], v[86:87], v[70:71] op_sel_hi:[1,0]
	v_pk_mul_f32 v[48:49], v[48:49], v[102:103]
	v_pk_mul_f32 v[102:103], v[84:85], v[66:67] op_sel_hi:[1,0]
	v_pk_mul_f32 v[84:85], v[84:85], v[98:99] op_sel_hi:[1,0]
	v_pk_mul_f32 v[58:59], v[58:59], v[82:83]
	v_pk_mul_f32 v[82:83], v[86:87], v[68:69] op_sel_hi:[1,0]
	v_pk_mul_f32 v[16:17], v[16:17], v[84:85]
	v_pk_mul_f32 v[84:85], v[88:89], v[70:71] op_sel_hi:[1,0]
	v_pk_mul_f32 v[42:43], v[42:43], v[82:83]
	v_pk_mul_f32 v[82:83], v[86:87], v[66:67] op_sel_hi:[1,0]
	v_pk_mul_f32 v[60:61], v[60:61], v[84:85]
	v_pk_mul_f32 v[84:85], v[88:89], v[68:69] op_sel_hi:[1,0]
	v_pk_mul_f32 v[26:27], v[26:27], v[82:83]
	v_pk_mul_f32 v[82:83], v[86:87], v[98:99] op_sel_hi:[1,0]
	v_pk_mul_f32 v[44:45], v[44:45], v[84:85]
	v_pk_mul_f32 v[84:85], v[88:89], v[66:67] op_sel_hi:[1,0]
	v_pk_mul_f32 v[10:11], v[10:11], v[82:83]
	s_waitcnt vmcnt(1)
	v_pk_mul_f32 v[82:83], v[90:91], v[70:71] op_sel_hi:[1,0]
	v_pk_mul_f32 v[28:29], v[28:29], v[84:85]
	v_pk_mul_f32 v[84:85], v[88:89], v[98:99] op_sel_hi:[1,0]
	v_pk_mul_f32 v[54:55], v[54:55], v[82:83]
	v_pk_mul_f32 v[82:83], v[90:91], v[68:69] op_sel_hi:[1,0]
	v_pk_mul_f32 v[12:13], v[12:13], v[84:85]
	v_pk_mul_f32 v[84:85], v[92:93], v[70:71] op_sel_hi:[1,0]
	v_pk_mul_f32 v[38:39], v[38:39], v[82:83]
	v_pk_mul_f32 v[82:83], v[90:91], v[66:67] op_sel_hi:[1,0]
	v_pk_mul_f32 v[56:57], v[56:57], v[84:85]
	v_pk_mul_f32 v[84:85], v[92:93], v[68:69] op_sel_hi:[1,0]
	v_pk_mul_f32 v[22:23], v[22:23], v[82:83]
	v_pk_mul_f32 v[82:83], v[90:91], v[98:99] op_sel_hi:[1,0]
	v_pk_mul_f32 v[40:41], v[40:41], v[84:85]
	v_pk_mul_f32 v[84:85], v[92:93], v[66:67] op_sel_hi:[1,0]
	v_pk_mul_f32 v[6:7], v[6:7], v[82:83]
	s_waitcnt vmcnt(0)
	v_pk_mul_f32 v[82:83], v[94:95], v[70:71] op_sel_hi:[1,0]
	v_pk_mul_f32 v[24:25], v[24:25], v[84:85]
	v_pk_mul_f32 v[84:85], v[92:93], v[98:99] op_sel_hi:[1,0]
	v_pk_mul_f32 v[50:51], v[50:51], v[82:83]
	v_pk_mul_f32 v[82:83], v[94:95], v[68:69] op_sel_hi:[1,0]
	v_pk_mul_f32 v[8:9], v[8:9], v[84:85]
	v_pk_mul_f32 v[84:85], v[96:97], v[70:71] op_sel_hi:[1,0]
	v_pk_mul_f32 v[34:35], v[34:35], v[82:83]
	v_pk_mul_f32 v[82:83], v[94:95], v[66:67] op_sel_hi:[1,0]
	v_pk_mul_f32 v[66:67], v[96:97], v[66:67] op_sel_hi:[1,0]
	v_pk_mul_f32 v[52:53], v[52:53], v[84:85]
	v_pk_mul_f32 v[84:85], v[96:97], v[68:69] op_sel_hi:[1,0]
	v_pk_mul_f32 v[20:21], v[20:21], v[66:67]
	v_pk_mul_f32 v[18:19], v[18:19], v[82:83]
	v_pk_mul_f32 v[66:67], v[94:95], v[98:99] op_sel_hi:[1,0]
	v_pk_mul_f32 v[82:83], v[96:97], v[98:99] op_sel_hi:[1,0]
	v_pk_mul_f32 v[32:33], v[32:33], v[102:103]
	v_pk_mul_f32 v[30:31], v[30:31], v[100:101]
	v_pk_mul_f32 v[36:37], v[36:37], v[84:85]
	v_pk_mul_f32 v[4:5], v[4:5], v[82:83]
	v_pk_mul_f32 v[2:3], v[2:3], v[66:67]

; template <int MODE>
; __device__ __forceinline__ void gemm_tile(const Params& P, int tm, int tn, unsigned char* smem) {
;     ...
;     const int tid = opaque_tid(), lane = tid & 63, wave = tid >> 6, wr = wave >> 1, wc = wave & 1, g = lane >> 4, lr = lane & 15;
;     const int m0 = tm * 128, n0 = tn * 128;
;     const int srow = tid >> 3, sc = tid & 7;
;     constexpr unsigned LDA = (MODE == 2 ? NZ : 1024) * 2u;
;     unsigned aoff, boff; int soff0;
;     {
;         int ar = m0 + srow;
;         if (MODE == 2) { const int b = ar >> 11, t = ar & 2047; ar = b * L + NMETA + t; }
;         aoff = (unsigned)ar * LDA + (unsigned)sc * 16u;
;         boff = (unsigned)(n0 + srow) * 2048u + (unsigned)sc * 16u;
;         soff0 = srow * 128 + ((sc ^ (srow & 7)) << 4);
;     }
;     const unsigned char* Ab = (const unsigned char*)A; const unsigned char* Bb = (const unsigned char*)Bt;
;     float4 ssp0, ssp1, ssp2, ssp3;
;     if (MODE == 3) {
;         const float* ssq = (const float*)(P.ws + WS_SSQ) + (size_t)(m0 + wr * 64 + lr) * 16 + 4 * g;
;         ssp0 = *(const float4*)(ssq); ssp1 = *(const float4*)(ssq + 16 * 16); ssp2 = *(const float4*)(ssq + 32 * 16); ssp3 = *(const float4*)(ssq + 48 * 16);
;     }
;     f32x4 acc[4][4];
; #pragma unroll
;     for (int i = 0; i < 4; ++i)
; #pragma unroll
;         for (int j = 0; j < 4; ++j) acc[i][j] = (f32x4){0.f, 0.f, 0.f, 0.f};
;     uint4 ra0, ra1, ra2, ra3, rb0, rb1, rb2, rb3;
;     ...
;     unsigned char* sA0 = smem; unsigned char* sB0 = smem + 16384; unsigned char* sA1 = smem + 32768; unsigned char* sB1 = smem + 49152;
;     G_LOAD(0)
;     G_WRITE(sA0, sB0)
;     __syncthreads();
;     const int arow_off = (wr * 64 + lr) * 128, brow_off = (wc * 64 + lr) * 128, sw = lr & 7;
;     G_LOAD(1)
;     for (int kt = 0; kt < 16; ++kt) {
;         unsigned char* sA = (kt & 1) ? sA1 : sA0; unsigned char* sB = (kt & 1) ? sB1 : sB0;
;         unsigned char* nA = (kt & 1) ? sA0 : sA1; unsigned char* nB = (kt & 1) ? sB0 : sB1;
;         bf16x8 fa[4], fb[4], ga[4], gb[4];
;         const int ch0 = ((g ^ sw) << 4), ch1 = (((4 + g) ^ sw) << 4);
;         const unsigned ko = (unsigned)(kt + 2) * 128u;
;         const unsigned koa = ko + ((MODE == 2 && kt + 2 >= 8) ? (unsigned)(ZC_FQ - 512) * 2u : 0u);
;         const bool wr_ok = kt < 15, ld_ok = kt < 14;
; #pragma unroll
.LBB0_241:
	s_andn2_b64 vcc, exec, s[4:5]
	s_cbranch_vccnz .LBB0_245
	s_add_i32 s14, s14, s10
	s_mul_hi_i32 s0, s14, 0x92492493
	s_add_i32 s0, s0, s14
	s_lshr_b32 s1, s0, 31
	s_ashr_i32 s0, s0, 7
	s_add_i32 s0, s0, s1
	s_mul_i32 s1, s0, 0xffffff20
	s_lshl_b32 s0, s0, 3
	s_add_i32 s1, s1, s14
	s_sub_i32 s3, 0x81, s0
	s_cmpk_gt_i32 s14, 0xdff
	s_cselect_b32 s3, s3, 8
	s_abs_i32 s4, s3
	v_cvt_f32_u32_e32 v2, s4
	s_sub_i32 s7, 0, s4
	s_abs_i32 s5, s1
	s_xor_b32 s6, s1, s3
	v_rcp_iflag_f32_e32 v2, v2
	s_ashr_i32 s6, s6, 31
	v_mov_b32_e32 v69, v0
	v_mul_f32_e32 v2, 0x4f7ffffe, v2
	v_cvt_u32_f32_e32 v2, v2
	v_lshlrev_b32_e32 v3, 4, v69
	v_and_b32_e32 v5, 0x70, v3
	v_and_b32_e32 v78, 15, v69
	v_readfirstlane_b32 s8, v2
	s_mul_i32 s7, s7, s8
	s_mul_hi_u32 s7, s8, s7
	s_add_i32 s8, s8, s7
	s_mul_hi_u32 s7, s5, s8
	s_mul_i32 s8, s7, s4
	s_sub_i32 s5, s5, s8
	s_add_i32 s9, s7, 1
	s_sub_i32 s8, s5, s4
	s_cmp_ge_u32 s5, s4
	s_cselect_b32 s7, s9, s7
	s_cselect_b32 s5, s8, s5
	s_add_i32 s8, s7, 1
	s_cmp_ge_u32 s5, s4
	s_cselect_b32 s4, s8, s7
	s_xor_b32 s4, s4, s6
	s_sub_i32 s5, s4, s6
	s_mul_i32 s3, s5, s3
	s_add_i32 s1, s1, s0
	s_sub_i32 s0, s1, s3
	s_lshl_b32 s3, s0, 7
	v_ashrrev_i32_e32 v2, 3, v69
	s_lshl_b32 s4, s5, 7
	v_add_u32_e32 v4, s3, v2
	v_add_u32_e32 v3, s4, v2
	v_lshl_or_b32 v8, v4, 11, v5
	v_lshl_or_b32 v3, v3, 11, v5
	s_add_u32 s0, s28, 0xc075800
	v_add_u32_e32 v9, 0x10000, v8
	s_addc_u32 s1, s29, 0
	v_add_u32_e32 v22, 0x20000, v8
	global_load_dwordx4 v[4:7], v9, s[36:37]
	global_load_dwordx4 v[10:13], v22, s[36:37]
	global_load_dwordx4 v[14:17], v8, s[36:37]
	global_load_dwordx4 v[18:21], v3, s[0:1]
	v_add_u32_e32 v9, 0x20000, v3
	v_add_u32_e32 v30, 0x30000, v3
	global_load_dwordx4 v[22:25], v9, s[0:1]
	global_load_dwordx4 v[26:29], v30, s[0:1]
	v_add_u32_e32 v9, 0x30000, v8
	v_add_u32_e32 v38, 0x10000, v3
	global_load_dwordx4 v[30:33], v9, s[36:37]
	global_load_dwordx4 v[34:37], v38, s[0:1]
	v_xor_b32_e32 v9, v2, v69
	s_movk_i32 s6, 0x70
	v_lshlrev_b32_e32 v2, 7, v2
	v_lshlrev_b32_e32 v9, 4, v9
	v_and_or_b32 v2, v9, s6, v2
	v_add_u32_e32 v2, 0, v2
	v_or_b32_e32 v45, 0x80, v8
	v_or_b32_e32 v9, 0x80, v3
	v_add_u32_e32 v42, 0x10080, v3
	v_add_u32_e32 v43, 0x20080, v3
	v_add_u32_e32 v44, 0x30080, v3
	v_add_u32_e32 v46, 0x10080, v8
	v_add_u32_e32 v47, 0x20080, v8
	v_add_u32_e32 v48, 0x30080, v8
	v_ashrrev_i32_e32 v79, 7, v69
	v_bfe_u32 v80, v69, 6, 1
	v_bfe_u32 v81, v69, 4, 2
	s_waitcnt vmcnt(5)
	ds_write_b128 v2, v[14:17]
	s_waitcnt vmcnt(4)
	ds_write_b128 v2, v[18:21] offset:16384
	s_waitcnt vmcnt(3)
	ds_write_b128 v2, v[22:25] offset:24576
	s_waitcnt vmcnt(2)
	ds_write_b128 v2, v[26:29] offset:28672
	ds_write_b128 v2, v[4:7] offset:4096
	ds_write_b128 v2, v[10:13] offset:8192
	s_waitcnt vmcnt(1)
	ds_write_b128 v2, v[30:33] offset:12288
	s_waitcnt vmcnt(0)
	ds_write_b128 v2, v[34:37] offset:20480
	s_waitcnt lgkmcnt(0)
	s_barrier
	global_load_dwordx4 v[10:13], v45, s[36:37]
	global_load_dwordx4 v[14:17], v46, s[36:37]
	global_load_dwordx4 v[18:21], v47, s[36:37]
	global_load_dwordx4 v[22:25], v48, s[36:37]
	global_load_dwordx4 v[26:29], v9, s[0:1]
	global_load_dwordx4 v[30:33], v42, s[0:1]
	global_load_dwordx4 v[34:37], v43, s[0:1]
	global_load_dwordx4 v[38:41], v44, s[0:1]
	v_lshrrev_b32_e32 v4, 4, v69
	v_lshlrev_b32_e32 v5, 7, v78
	v_and_b32_e32 v9, 7, v69
	v_lshl_or_b32 v6, v79, 13, v5
	v_bitop3_b32 v4, v4, v9, 3 bitop3:0x6c
	v_lshl_or_b32 v5, v80, 13, v5
	v_lshlrev_b32_e32 v4, 4, v4
	v_add_u32_e32 v66, 0, v6
	v_add_u32_e32 v6, v66, v4
	v_add_u32_e32 v5, 0, v5
	v_add_u32_e32 v7, v5, v4
	ds_read_b128 v[42:45], v6
	ds_read_b128 v[46:49], v6 offset:2048
	ds_read_b128 v[50:53], v7 offset:16384
	ds_read_b128 v[54:57], v7 offset:18432
	ds_read_b128 v[58:61], v6 offset:4096
	ds_read_b128 v[62:65], v6 offset:6144
	ds_read_b128 v[82:85], v7 offset:20480
	ds_read_b128 v[86:89], v7 offset:22528
	v_bitop3_b32 v4, v81, v9, 4 bitop3:0x36
	v_lshlrev_b32_e32 v9, 4, v4
	s_setprio 2
	global_load_dwordx4 v[90:93], v8, s[36:37] offset:256
	s_waitcnt vmcnt(8)
	ds_write_b128 v2, v[10:13] offset:32768
	v_add_u32_e32 v4, v66, v9
	v_add_u32_e32 v5, v5, v9
	ds_read_b128 v[10:13], v4
	ds_read_b128 v[94:97], v5 offset:16384
	s_waitcnt lgkmcnt(8)
	v_mfma_f32_16x16x32_bf16 v[98:101], v[50:53], v[42:45], 0
	s_waitcnt lgkmcnt(7)
	v_mfma_f32_16x16x32_bf16 v[102:105], v[54:57], v[42:45], 0
	s_waitcnt lgkmcnt(4)
	v_mfma_f32_16x16x32_bf16 v[106:109], v[82:85], v[42:45], 0
	s_waitcnt lgkmcnt(3)
	v_mfma_f32_16x16x32_bf16 v[42:45], v[86:89], v[42:45], 0
	v_add_u32_e32 v228, 0x10000, v8
	global_load_dwordx4 v[110:113], v228, s[36:37] offset:256
	s_waitcnt vmcnt(8)
	ds_write_b128 v2, v[14:17] offset:36864
	ds_read_b128 v[14:17], v4 offset:2048
	ds_read_b128 v[114:117], v5 offset:18432
	v_mfma_f32_16x16x32_bf16 v[118:121], v[50:53], v[46:49], 0
	v_mfma_f32_16x16x32_bf16 v[122:125], v[54:57], v[46:49], 0
	v_mfma_f32_16x16x32_bf16 v[126:129], v[82:85], v[46:49], 0
	v_mfma_f32_16x16x32_bf16 v[46:49], v[86:89], v[46:49], 0
	v_add_u32_e32 v229, 0x20000, v8
	global_load_dwordx4 v[132:135], v229, s[36:37] offset:256
	s_waitcnt vmcnt(8)
	ds_write_b128 v2, v[18:21] offset:40960
	ds_read_b128 v[18:21], v4 offset:4096
	ds_read_b128 v[146:149], v5 offset:20480
	v_mfma_f32_16x16x32_bf16 v[150:153], v[50:53], v[58:61], 0
	v_mfma_f32_16x16x32_bf16 v[154:157], v[54:57], v[58:61], 0
	v_mfma_f32_16x16x32_bf16 v[158:161], v[82:85], v[58:61], 0
	v_mfma_f32_16x16x32_bf16 v[58:61], v[86:89], v[58:61], 0
	v_add_u32_e32 v230, 0x30000, v8
	global_load_dwordx4 v[162:165], v230, s[36:37] offset:256
	s_waitcnt vmcnt(8)
; template <int MODE>
; __device__ __forceinline__ void gemm_tile(const Params& P, int tm, int tn, unsigned char* smem) {
;     ...
; #pragma unroll
;         for (int i = 0; i < 4; ++i) { fa[i] = *(const bf16x8*)(sA + arow_off + i * 2048 + ch0); fb[i] = *(const bf16x8*)(sB + brow_off + i * 2048 + ch0); }
;         __builtin_amdgcn_sched_barrier(0);
;         __builtin_amdgcn_s_setprio(2);
;         if (wr_ok) *(uint4*)(nA + soff0) = ra0;
;         if (ld_ok) ra0 = *(const uint4*)(Ab + (aoff + 0u * LDA + koa));
;         ga[0] = *(const bf16x8*)(sA + arow_off + 0 * 2048 + ch1); gb[0] = *(const bf16x8*)(sB + brow_off + 0 * 2048 + ch1);
;         __builtin_amdgcn_sched_barrier(0);
; #pragma unroll
;         for (int j = 0; j < 4; ++j) acc[0][j] = __builtin_amdgcn_mfma_f32_16x16x32_bf16(fb[j], fa[0], acc[0][j], 0, 0, 0);
;         __builtin_amdgcn_sched_barrier(0);
;         if (wr_ok) *(uint4*)(nA + soff0 + 4096) = ra1;
;         if (ld_ok) ra1 = *(const uint4*)(Ab + (aoff + 32u * LDA + koa));
;         ga[1] = *(const bf16x8*)(sA + arow_off + 1 * 2048 + ch1); gb[1] = *(const bf16x8*)(sB + brow_off + 1 * 2048 + ch1);
;         __builtin_amdgcn_sched_barrier(0);
; #pragma unroll
;         for (int j = 0; j < 4; ++j) acc[1][j] = __builtin_amdgcn_mfma_f32_16x16x32_bf16(fb[j], fa[1], acc[1][j], 0, 0, 0);
;         __builtin_amdgcn_sched_barrier(0);
;         if (wr_ok) *(uint4*)(nA + soff0 + 8192) = ra2;
;         if (ld_ok) ra2 = *(const uint4*)(Ab + (aoff + 64u * LDA + koa));
;         ga[2] = *(const bf16x8*)(sA + arow_off + 2 * 2048 + ch1); gb[2] = *(const bf16x8*)(sB + brow_off + 2 * 2048 + ch1);
;         __builtin_amdgcn_sched_barrier(0);
; #pragma unroll
;         for (int j = 0; j < 4; ++j) acc[2][j] = __builtin_amdgcn_mfma_f32_16x16x32_bf16(fb[j], fa[2], acc[2][j], 0, 0, 0);
;         __builtin_amdgcn_sched_barrier(0);
;         if (wr_ok) *(uint4*)(nA + soff0 + 12288) = ra3;
;         if (ld_ok) ra3 = *(const uint4*)(Ab + (aoff + 96u * LDA + koa));
;         ga[3] = *(const bf16x8*)(sA + arow_off + 3 * 2048 + ch1); gb[3] = *(const bf16x8*)(sB + brow_off + 3 * 2048 + ch1);
;         __builtin_amdgcn_sched_barrier(0);
; #pragma unroll
;         for (int j = 0; j < 4; ++j) acc[3][j] = __builtin_amdgcn_mfma_f32_16x16x32_bf16(fb[j], fa[3], acc[3][j], 0, 0, 0);
;         __builtin_amdgcn_sched_barrier(0);
;         if (wr_ok) *(uint4*)(nB + soff0) = rb0;
	ds_write_b128 v2, v[22:25] offset:45056
	ds_read_b128 v[22:25], v4 offset:6144
	ds_read_b128 v[166:169], v5 offset:22528
	v_mfma_f32_16x16x32_bf16 v[50:53], v[50:53], v[62:65], 0
	v_mfma_f32_16x16x32_bf16 v[54:57], v[54:57], v[62:65], 0
	v_mfma_f32_16x16x32_bf16 v[82:85], v[82:85], v[62:65], 0
	v_mfma_f32_16x16x32_bf16 v[62:65], v[86:89], v[62:65], 0
	global_load_dwordx4 v[86:89], v3, s[0:1] offset:256
	s_waitcnt vmcnt(8)
	ds_write_b128 v2, v[26:29] offset:49152
	s_waitcnt lgkmcnt(10)
	v_mfma_f32_16x16x32_bf16 v[26:29], v[94:97], v[10:13], v[98:101]
	s_waitcnt lgkmcnt(7)
	v_mfma_f32_16x16x32_bf16 v[98:101], v[114:117], v[10:13], v[102:105]
	s_waitcnt lgkmcnt(4)
	v_mfma_f32_16x16x32_bf16 v[102:105], v[146:149], v[10:13], v[106:109]
	s_waitcnt lgkmcnt(1)
	v_mfma_f32_16x16x32_bf16 v[10:13], v[166:169], v[10:13], v[42:45]
	v_add_u32_e32 v231, 0x10000, v3
	global_load_dwordx4 v[42:45], v231, s[0:1] offset:256
	s_waitcnt vmcnt(8)
	ds_write_b128 v2, v[30:33] offset:53248
	v_mfma_f32_16x16x32_bf16 v[30:33], v[94:97], v[14:17], v[118:121]
	v_mfma_f32_16x16x32_bf16 v[106:109], v[114:117], v[14:17], v[122:125]
	v_mfma_f32_16x16x32_bf16 v[118:121], v[146:149], v[14:17], v[126:129]
	v_mfma_f32_16x16x32_bf16 v[14:17], v[166:169], v[14:17], v[46:49]
	v_add_u32_e32 v232, 0x20000, v3
	global_load_dwordx4 v[46:49], v232, s[0:1] offset:256
	s_waitcnt vmcnt(8)
	ds_write_b128 v2, v[34:37] offset:57344
	v_mfma_f32_16x16x32_bf16 v[34:37], v[94:97], v[18:21], v[150:153]
	v_mfma_f32_16x16x32_bf16 v[122:125], v[114:117], v[18:21], v[154:157]
	v_mfma_f32_16x16x32_bf16 v[126:129], v[146:149], v[18:21], v[158:161]
	v_mfma_f32_16x16x32_bf16 v[18:21], v[166:169], v[18:21], v[58:61]
	v_add_u32_e32 v233, 0x30000, v3
	global_load_dwordx4 v[58:61], v233, s[0:1] offset:256
	s_waitcnt vmcnt(8)
	ds_write_b128 v2, v[38:41] offset:61440
	v_mfma_f32_16x16x32_bf16 v[38:41], v[94:97], v[22:25], v[50:53]
	v_mfma_f32_16x16x32_bf16 v[50:53], v[114:117], v[22:25], v[54:57]
	v_mfma_f32_16x16x32_bf16 v[54:57], v[146:149], v[22:25], v[82:85]
	v_mfma_f32_16x16x32_bf16 v[22:25], v[166:169], v[22:25], v[62:65]
	s_setprio 0
	s_waitcnt lgkmcnt(0)
	s_barrier
	ds_read_b128 v[62:65], v6 offset:32768
	ds_read_b128 v[82:85], v6 offset:34816
	ds_read_b128 v[94:97], v7 offset:49152
	ds_read_b128 v[114:117], v7 offset:51200
	ds_read_b128 v[146:149], v6 offset:36864
	ds_read_b128 v[150:153], v6 offset:38912
	ds_read_b128 v[154:157], v7 offset:53248
	ds_read_b128 v[158:161], v7 offset:55296
	s_setprio 2
	global_load_dwordx4 v[166:169], v8, s[36:37] offset:384
	s_waitcnt vmcnt(8)
	ds_write_b128 v2, v[90:93]
	ds_read_b128 v[90:93], v4 offset:32768
	ds_read_b128 v[170:173], v5 offset:49152
	s_waitcnt lgkmcnt(8)
	v_mfma_f32_16x16x32_bf16 v[26:29], v[94:97], v[62:65], v[26:29]
	s_waitcnt lgkmcnt(3)
	v_mfma_f32_16x16x32_bf16 v[10:13], v[158:161], v[62:65], v[10:13]
	v_mfma_f32_16x16x32_bf16 v[98:101], v[114:117], v[62:65], v[98:101]
	v_mfma_f32_16x16x32_bf16 v[102:105], v[154:157], v[62:65], v[102:105]
	global_load_dwordx4 v[62:65], v228, s[36:37] offset:384
	v_mfma_f32_16x16x32_bf16 v[30:33], v[94:97], v[82:85], v[30:33]
	s_waitcnt vmcnt(8)
	ds_write_b128 v2, v[110:113] offset:4096
	v_mfma_f32_16x16x32_bf16 v[14:17], v[158:161], v[82:85], v[14:17]
	ds_read_b128 v[110:113], v4 offset:34816
	v_mfma_f32_16x16x32_bf16 v[106:109], v[114:117], v[82:85], v[106:109]
	ds_read_b128 v[174:177], v5 offset:51200
	v_mfma_f32_16x16x32_bf16 v[118:121], v[154:157], v[82:85], v[118:121]
	global_load_dwordx4 v[82:85], v229, s[36:37] offset:384
	v_mfma_f32_16x16x32_bf16 v[34:37], v[94:97], v[146:149], v[34:37]
	s_waitcnt vmcnt(8)
	ds_write_b128 v2, v[132:135] offset:8192
	v_mfma_f32_16x16x32_bf16 v[18:21], v[158:161], v[146:149], v[18:21]
	ds_read_b128 v[132:135], v4 offset:36864
	v_mfma_f32_16x16x32_bf16 v[122:125], v[114:117], v[146:149], v[122:125]
	ds_read_b128 v[178:181], v5 offset:53248
	v_mfma_f32_16x16x32_bf16 v[126:129], v[154:157], v[146:149], v[126:129]
	global_load_dwordx4 v[146:149], v230, s[36:37] offset:384
	v_mfma_f32_16x16x32_bf16 v[38:41], v[94:97], v[150:153], v[38:41]
	s_waitcnt vmcnt(8)
	ds_write_b128 v2, v[162:165] offset:12288
	v_mfma_f32_16x16x32_bf16 v[50:53], v[114:117], v[150:153], v[50:53]
	ds_read_b128 v[162:165], v4 offset:38912
	v_mfma_f32_16x16x32_bf16 v[54:57], v[154:157], v[150:153], v[54:57]
	ds_read_b128 v[182:185], v5 offset:55296
	v_mfma_f32_16x16x32_bf16 v[22:25], v[158:161], v[150:153], v[22:25]
	global_load_dwordx4 v[94:97], v3, s[0:1] offset:384
	s_waitcnt vmcnt(8)
	ds_write_b128 v2, v[86:89] offset:16384
	s_waitcnt lgkmcnt(10)
	v_mfma_f32_16x16x32_bf16 v[26:29], v[170:173], v[90:93], v[26:29]
	s_waitcnt lgkmcnt(1)
	v_mfma_f32_16x16x32_bf16 v[10:13], v[182:185], v[90:93], v[10:13]
	v_mfma_f32_16x16x32_bf16 v[86:89], v[174:177], v[90:93], v[98:101]
	v_mfma_f32_16x16x32_bf16 v[98:101], v[178:181], v[90:93], v[102:105]
	global_load_dwordx4 v[90:93], v231, s[0:1] offset:384
	s_waitcnt vmcnt(8)
	ds_write_b128 v2, v[42:45] offset:20480
	v_mfma_f32_16x16x32_bf16 v[30:33], v[170:173], v[110:113], v[30:33]
	v_mfma_f32_16x16x32_bf16 v[42:45], v[174:177], v[110:113], v[106:109]
	v_mfma_f32_16x16x32_bf16 v[14:17], v[182:185], v[110:113], v[14:17]
	v_mfma_f32_16x16x32_bf16 v[102:105], v[178:181], v[110:113], v[118:121]
	global_load_dwordx4 v[106:109], v232, s[0:1] offset:384
	s_waitcnt vmcnt(8)
	ds_write_b128 v2, v[46:49] offset:24576
	v_mfma_f32_16x16x32_bf16 v[34:37], v[170:173], v[132:135], v[34:37]
	v_mfma_f32_16x16x32_bf16 v[46:49], v[174:177], v[132:135], v[122:125]
	v_mfma_f32_16x16x32_bf16 v[18:21], v[182:185], v[132:135], v[18:21]
	v_mfma_f32_16x16x32_bf16 v[110:113], v[178:181], v[132:135], v[126:129]
	global_load_dwordx4 v[114:117], v233, s[0:1] offset:384
	v_mfma_f32_16x16x32_bf16 v[38:41], v[170:173], v[162:165], v[38:41]
	s_waitcnt vmcnt(8)
	ds_write_b128 v2, v[58:61] offset:28672
	v_mfma_f32_16x16x32_bf16 v[50:53], v[174:177], v[162:165], v[50:53]
	v_mfma_f32_16x16x32_bf16 v[54:57], v[178:181], v[162:165], v[54:57]
	v_mfma_f32_16x16x32_bf16 v[22:25], v[182:185], v[162:165], v[22:25]
	s_setprio 0
	s_waitcnt lgkmcnt(0)
	s_barrier
; template <int MODE>
; __device__ __forceinline__ void gemm_tile(const Params& P, int tm, int tn, unsigned char* smem) {
;     ...
; #pragma unroll
;         for (int i = 0; i < 4; ++i) { fa[i] = *(const bf16x8*)(sA + arow_off + i * 2048 + ch0); fb[i] = *(const bf16x8*)(sB + brow_off + i * 2048 + ch0); }
;         __builtin_amdgcn_sched_barrier(0);
;         __builtin_amdgcn_s_setprio(2);
;         if (wr_ok) *(uint4*)(nA + soff0) = ra0;
;         if (ld_ok) ra0 = *(const uint4*)(Ab + (aoff + 0u * LDA + koa));
;         ga[0] = *(const bf16x8*)(sA + arow_off + 0 * 2048 + ch1); gb[0] = *(const bf16x8*)(sB + brow_off + 0 * 2048 + ch1);
;         __builtin_amdgcn_sched_barrier(0);
; #pragma unroll
;         for (int j = 0; j < 4; ++j) acc[0][j] = __builtin_amdgcn_mfma_f32_16x16x32_bf16(fb[j], fa[0], acc[0][j], 0, 0, 0);
;         __builtin_amdgcn_sched_barrier(0);
;         if (wr_ok) *(uint4*)(nA + soff0 + 4096) = ra1;
;         if (ld_ok) ra1 = *(const uint4*)(Ab + (aoff + 32u * LDA + koa));
;         ga[1] = *(const bf16x8*)(sA + arow_off + 1 * 2048 + ch1); gb[1] = *(const bf16x8*)(sB + brow_off + 1 * 2048 + ch1);
;         __builtin_amdgcn_sched_barrier(0);
; #pragma unroll
;         for (int j = 0; j < 4; ++j) acc[1][j] = __builtin_amdgcn_mfma_f32_16x16x32_bf16(fb[j], fa[1], acc[1][j], 0, 0, 0);
;         __builtin_amdgcn_sched_barrier(0);
;         if (wr_ok) *(uint4*)(nA + soff0 + 8192) = ra2;
;         if (ld_ok) ra2 = *(const uint4*)(Ab + (aoff + 64u * LDA + koa));
;         ga[2] = *(const bf16x8*)(sA + arow_off + 2 * 2048 + ch1); gb[2] = *(const bf16x8*)(sB + brow_off + 2 * 2048 + ch1);
;         __builtin_amdgcn_sched_barrier(0);
; #pragma unroll
;         for (int j = 0; j < 4; ++j) acc[2][j] = __builtin_amdgcn_mfma_f32_16x16x32_bf16(fb[j], fa[2], acc[2][j], 0, 0, 0);
;         __builtin_amdgcn_sched_barrier(0);
;         if (wr_ok) *(uint4*)(nA + soff0 + 12288) = ra3;
;         if (ld_ok) ra3 = *(const uint4*)(Ab + (aoff + 96u * LDA + koa));
;         ga[3] = *(const bf16x8*)(sA + arow_off + 3 * 2048 + ch1); gb[3] = *(const bf16x8*)(sB + brow_off + 3 * 2048 + ch1);
;         __builtin_amdgcn_sched_barrier(0);
; #pragma unroll
;         for (int j = 0; j < 4; ++j) acc[3][j] = __builtin_amdgcn_mfma_f32_16x16x32_bf16(fb[j], fa[3], acc[3][j], 0, 0, 0);
;         __builtin_amdgcn_sched_barrier(0);
;         if (wr_ok) *(uint4*)(nB + soff0) = rb0;
	ds_read_b128 v[58:61], v6
	ds_read_b128 v[118:121], v6 offset:2048
	ds_read_b128 v[122:125], v7 offset:16384
	ds_read_b128 v[126:129], v7 offset:18432
	ds_read_b128 v[132:135], v6 offset:4096
	ds_read_b128 v[150:153], v6 offset:6144
	ds_read_b128 v[154:157], v7 offset:20480
	ds_read_b128 v[158:161], v7 offset:22528
	s_setprio 2
	global_load_dwordx4 v[162:165], v8, s[36:37] offset:512
	s_waitcnt vmcnt(8)
	ds_write_b128 v2, v[166:169] offset:32768
	ds_read_b128 v[166:169], v4
	ds_read_b128 v[170:173], v5 offset:16384
	s_waitcnt lgkmcnt(8)
	v_mfma_f32_16x16x32_bf16 v[26:29], v[122:125], v[58:61], v[26:29]
	s_waitcnt lgkmcnt(3)
	v_mfma_f32_16x16x32_bf16 v[10:13], v[158:161], v[58:61], v[10:13]
	v_mfma_f32_16x16x32_bf16 v[86:89], v[126:129], v[58:61], v[86:89]
	v_mfma_f32_16x16x32_bf16 v[98:101], v[154:157], v[58:61], v[98:101]
	global_load_dwordx4 v[58:61], v228, s[36:37] offset:512
	v_mfma_f32_16x16x32_bf16 v[30:33], v[122:125], v[118:121], v[30:33]
	s_waitcnt vmcnt(8)
	ds_write_b128 v2, v[62:65] offset:36864
	v_mfma_f32_16x16x32_bf16 v[42:45], v[126:129], v[118:121], v[42:45]
	ds_read_b128 v[62:65], v4 offset:2048
	v_mfma_f32_16x16x32_bf16 v[14:17], v[158:161], v[118:121], v[14:17]
	ds_read_b128 v[174:177], v5 offset:18432
	v_mfma_f32_16x16x32_bf16 v[102:105], v[154:157], v[118:121], v[102:105]
	global_load_dwordx4 v[118:121], v229, s[36:37] offset:512
	v_mfma_f32_16x16x32_bf16 v[34:37], v[122:125], v[132:135], v[34:37]
	s_waitcnt vmcnt(8)
	ds_write_b128 v2, v[82:85] offset:40960
	v_mfma_f32_16x16x32_bf16 v[46:49], v[126:129], v[132:135], v[46:49]
	ds_read_b128 v[82:85], v4 offset:4096
	v_mfma_f32_16x16x32_bf16 v[18:21], v[158:161], v[132:135], v[18:21]
	ds_read_b128 v[178:181], v5 offset:20480
	v_mfma_f32_16x16x32_bf16 v[110:113], v[154:157], v[132:135], v[110:113]
	global_load_dwordx4 v[132:135], v230, s[36:37] offset:512
	v_mfma_f32_16x16x32_bf16 v[38:41], v[122:125], v[150:153], v[38:41]
	s_waitcnt vmcnt(8)
	ds_write_b128 v2, v[146:149] offset:45056
	v_mfma_f32_16x16x32_bf16 v[50:53], v[126:129], v[150:153], v[50:53]
	ds_read_b128 v[146:149], v4 offset:6144
	v_mfma_f32_16x16x32_bf16 v[54:57], v[154:157], v[150:153], v[54:57]
	ds_read_b128 v[182:185], v5 offset:22528
	v_mfma_f32_16x16x32_bf16 v[22:25], v[158:161], v[150:153], v[22:25]
	global_load_dwordx4 v[122:125], v3, s[0:1] offset:512
	s_waitcnt vmcnt(8)
	ds_write_b128 v2, v[94:97] offset:49152
	s_waitcnt lgkmcnt(10)
	v_mfma_f32_16x16x32_bf16 v[26:29], v[170:173], v[166:169], v[26:29]
	s_waitcnt lgkmcnt(1)
	v_mfma_f32_16x16x32_bf16 v[10:13], v[182:185], v[166:169], v[10:13]
	v_mfma_f32_16x16x32_bf16 v[86:89], v[174:177], v[166:169], v[86:89]
	v_mfma_f32_16x16x32_bf16 v[94:97], v[178:181], v[166:169], v[98:101]
	global_load_dwordx4 v[98:101], v231, s[0:1] offset:512
	s_waitcnt vmcnt(8)
	ds_write_b128 v2, v[90:93] offset:53248
	v_mfma_f32_16x16x32_bf16 v[30:33], v[170:173], v[62:65], v[30:33]
	v_mfma_f32_16x16x32_bf16 v[42:45], v[174:177], v[62:65], v[42:45]
	v_mfma_f32_16x16x32_bf16 v[14:17], v[182:185], v[62:65], v[14:17]
	v_mfma_f32_16x16x32_bf16 v[90:93], v[178:181], v[62:65], v[102:105]
	global_load_dwordx4 v[62:65], v232, s[0:1] offset:512
	v_mfma_f32_16x16x32_bf16 v[34:37], v[170:173], v[82:85], v[34:37]
	s_waitcnt vmcnt(8)
	ds_write_b128 v2, v[106:109] offset:57344
	v_mfma_f32_16x16x32_bf16 v[46:49], v[174:177], v[82:85], v[46:49]
	v_mfma_f32_16x16x32_bf16 v[18:21], v[182:185], v[82:85], v[18:21]
	v_mfma_f32_16x16x32_bf16 v[102:105], v[178:181], v[82:85], v[110:113]
	global_load_dwordx4 v[82:85], v233, s[0:1] offset:512
	v_mfma_f32_16x16x32_bf16 v[38:41], v[170:173], v[146:149], v[38:41]
	s_waitcnt vmcnt(8)
	ds_write_b128 v2, v[114:117] offset:61440
	v_mfma_f32_16x16x32_bf16 v[50:53], v[174:177], v[146:149], v[50:53]
	v_mfma_f32_16x16x32_bf16 v[54:57], v[178:181], v[146:149], v[54:57]
	v_mfma_f32_16x16x32_bf16 v[22:25], v[182:185], v[146:149], v[22:25]
	s_setprio 0
	s_waitcnt lgkmcnt(0)
	s_barrier
	ds_read_b128 v[106:109], v6 offset:32768
	ds_read_b128 v[110:113], v6 offset:34816
	ds_read_b128 v[114:117], v7 offset:49152
	ds_read_b128 v[126:129], v7 offset:51200
	ds_read_b128 v[146:149], v6 offset:36864
	ds_read_b128 v[150:153], v6 offset:38912
	ds_read_b128 v[154:157], v7 offset:53248
	ds_read_b128 v[158:161], v7 offset:55296
	s_setprio 2
	global_load_dwordx4 v[166:169], v8, s[36:37] offset:640
	s_waitcnt vmcnt(8)
	ds_write_b128 v2, v[162:165]
	ds_read_b128 v[162:165], v4 offset:32768
	ds_read_b128 v[170:173], v5 offset:49152
	s_waitcnt lgkmcnt(8)
	v_mfma_f32_16x16x32_bf16 v[26:29], v[114:117], v[106:109], v[26:29]
	s_waitcnt lgkmcnt(3)
	v_mfma_f32_16x16x32_bf16 v[10:13], v[158:161], v[106:109], v[10:13]
	v_mfma_f32_16x16x32_bf16 v[86:89], v[126:129], v[106:109], v[86:89]
	v_mfma_f32_16x16x32_bf16 v[94:97], v[154:157], v[106:109], v[94:97]
	global_load_dwordx4 v[106:109], v228, s[36:37] offset:640
	v_mfma_f32_16x16x32_bf16 v[30:33], v[114:117], v[110:113], v[30:33]
	s_waitcnt vmcnt(8)
	ds_write_b128 v2, v[58:61] offset:4096
	v_mfma_f32_16x16x32_bf16 v[42:45], v[126:129], v[110:113], v[42:45]
	ds_read_b128 v[58:61], v4 offset:34816
	v_mfma_f32_16x16x32_bf16 v[14:17], v[158:161], v[110:113], v[14:17]
	ds_read_b128 v[174:177], v5 offset:51200
	v_mfma_f32_16x16x32_bf16 v[90:93], v[154:157], v[110:113], v[90:93]
	global_load_dwordx4 v[110:113], v229, s[36:37] offset:640
	v_mfma_f32_16x16x32_bf16 v[34:37], v[114:117], v[146:149], v[34:37]
	s_waitcnt vmcnt(8)
; template <int MODE>
; __device__ __forceinline__ void gemm_tile(const Params& P, int tm, int tn, unsigned char* smem) {
;     ...
; #pragma unroll
;         for (int i = 0; i < 4; ++i) { fa[i] = *(const bf16x8*)(sA + arow_off + i * 2048 + ch0); fb[i] = *(const bf16x8*)(sB + brow_off + i * 2048 + ch0); }
;         __builtin_amdgcn_sched_barrier(0);
;         __builtin_amdgcn_s_setprio(2);
;         if (wr_ok) *(uint4*)(nA + soff0) = ra0;
;         if (ld_ok) ra0 = *(const uint4*)(Ab + (aoff + 0u * LDA + koa));
;         ga[0] = *(const bf16x8*)(sA + arow_off + 0 * 2048 + ch1); gb[0] = *(const bf16x8*)(sB + brow_off + 0 * 2048 + ch1);
;         __builtin_amdgcn_sched_barrier(0);
; #pragma unroll
;         for (int j = 0; j < 4; ++j) acc[0][j] = __builtin_amdgcn_mfma_f32_16x16x32_bf16(fb[j], fa[0], acc[0][j], 0, 0, 0);
;         __builtin_amdgcn_sched_barrier(0);
;         if (wr_ok) *(uint4*)(nA + soff0 + 4096) = ra1;
;         if (ld_ok) ra1 = *(const uint4*)(Ab + (aoff + 32u * LDA + koa));
;         ga[1] = *(const bf16x8*)(sA + arow_off + 1 * 2048 + ch1); gb[1] = *(const bf16x8*)(sB + brow_off + 1 * 2048 + ch1);
;         __builtin_amdgcn_sched_barrier(0);
; #pragma unroll
;         for (int j = 0; j < 4; ++j) acc[1][j] = __builtin_amdgcn_mfma_f32_16x16x32_bf16(fb[j], fa[1], acc[1][j], 0, 0, 0);
;         __builtin_amdgcn_sched_barrier(0);
;         if (wr_ok) *(uint4*)(nA + soff0 + 8192) = ra2;
;         if (ld_ok) ra2 = *(const uint4*)(Ab + (aoff + 64u * LDA + koa));
;         ga[2] = *(const bf16x8*)(sA + arow_off + 2 * 2048 + ch1); gb[2] = *(const bf16x8*)(sB + brow_off + 2 * 2048 + ch1);
;         __builtin_amdgcn_sched_barrier(0);
; #pragma unroll
;         for (int j = 0; j < 4; ++j) acc[2][j] = __builtin_amdgcn_mfma_f32_16x16x32_bf16(fb[j], fa[2], acc[2][j], 0, 0, 0);
;         __builtin_amdgcn_sched_barrier(0);
;         if (wr_ok) *(uint4*)(nA + soff0 + 12288) = ra3;
;         if (ld_ok) ra3 = *(const uint4*)(Ab + (aoff + 96u * LDA + koa));
;         ga[3] = *(const bf16x8*)(sA + arow_off + 3 * 2048 + ch1); gb[3] = *(const bf16x8*)(sB + brow_off + 3 * 2048 + ch1);
;         __builtin_amdgcn_sched_barrier(0);
; #pragma unroll
;         for (int j = 0; j < 4; ++j) acc[3][j] = __builtin_amdgcn_mfma_f32_16x16x32_bf16(fb[j], fa[3], acc[3][j], 0, 0, 0);
;         __builtin_amdgcn_sched_barrier(0);
;         if (wr_ok) *(uint4*)(nB + soff0) = rb0;
	ds_write_b128 v2, v[118:121] offset:8192
	v_mfma_f32_16x16x32_bf16 v[46:49], v[126:129], v[146:149], v[46:49]
	ds_read_b128 v[118:121], v4 offset:36864
	v_mfma_f32_16x16x32_bf16 v[18:21], v[158:161], v[146:149], v[18:21]
	ds_read_b128 v[178:181], v5 offset:53248
	v_mfma_f32_16x16x32_bf16 v[102:105], v[154:157], v[146:149], v[102:105]
	global_load_dwordx4 v[146:149], v230, s[36:37] offset:640
	v_mfma_f32_16x16x32_bf16 v[38:41], v[114:117], v[150:153], v[38:41]
	s_waitcnt vmcnt(8)
	ds_write_b128 v2, v[132:135] offset:12288
	v_mfma_f32_16x16x32_bf16 v[50:53], v[126:129], v[150:153], v[50:53]
	ds_read_b128 v[132:135], v4 offset:38912
	v_mfma_f32_16x16x32_bf16 v[54:57], v[154:157], v[150:153], v[54:57]
	ds_read_b128 v[182:185], v5 offset:55296
	v_mfma_f32_16x16x32_bf16 v[22:25], v[158:161], v[150:153], v[22:25]
	global_load_dwordx4 v[114:117], v3, s[0:1] offset:640
	s_waitcnt vmcnt(8)
	ds_write_b128 v2, v[122:125] offset:16384
	s_waitcnt lgkmcnt(10)
	v_mfma_f32_16x16x32_bf16 v[26:29], v[170:173], v[162:165], v[26:29]
	s_waitcnt lgkmcnt(1)
	v_mfma_f32_16x16x32_bf16 v[10:13], v[182:185], v[162:165], v[10:13]
	v_mfma_f32_16x16x32_bf16 v[86:89], v[174:177], v[162:165], v[86:89]
	v_mfma_f32_16x16x32_bf16 v[94:97], v[178:181], v[162:165], v[94:97]
	global_load_dwordx4 v[122:125], v231, s[0:1] offset:640
	v_mfma_f32_16x16x32_bf16 v[30:33], v[170:173], v[58:61], v[30:33]
	s_waitcnt vmcnt(8)
	ds_write_b128 v2, v[98:101] offset:20480
	v_mfma_f32_16x16x32_bf16 v[42:45], v[174:177], v[58:61], v[42:45]
	v_mfma_f32_16x16x32_bf16 v[14:17], v[182:185], v[58:61], v[14:17]
	v_mfma_f32_16x16x32_bf16 v[90:93], v[178:181], v[58:61], v[90:93]
	global_load_dwordx4 v[58:61], v232, s[0:1] offset:640
	s_waitcnt vmcnt(8)
	ds_write_b128 v2, v[62:65] offset:24576
	v_mfma_f32_16x16x32_bf16 v[34:37], v[170:173], v[118:121], v[34:37]
	v_mfma_f32_16x16x32_bf16 v[46:49], v[174:177], v[118:121], v[46:49]
	v_mfma_f32_16x16x32_bf16 v[62:65], v[178:181], v[118:121], v[102:105]
	v_mfma_f32_16x16x32_bf16 v[18:21], v[182:185], v[118:121], v[18:21]
	global_load_dwordx4 v[98:101], v233, s[0:1] offset:640
	v_mfma_f32_16x16x32_bf16 v[38:41], v[170:173], v[132:135], v[38:41]
	s_waitcnt vmcnt(8)
	ds_write_b128 v2, v[82:85] offset:28672
	v_mfma_f32_16x16x32_bf16 v[50:53], v[174:177], v[132:135], v[50:53]
	v_mfma_f32_16x16x32_bf16 v[54:57], v[178:181], v[132:135], v[54:57]
	v_mfma_f32_16x16x32_bf16 v[22:25], v[182:185], v[132:135], v[22:25]
	s_setprio 0
	s_waitcnt lgkmcnt(0)
	s_barrier
	ds_read_b128 v[82:85], v6
	ds_read_b128 v[102:105], v6 offset:2048
	ds_read_b128 v[118:121], v7 offset:16384
	ds_read_b128 v[126:129], v7 offset:18432
	ds_read_b128 v[132:135], v6 offset:4096
	ds_read_b128 v[150:153], v6 offset:6144
	ds_read_b128 v[154:157], v7 offset:20480
	ds_read_b128 v[158:161], v7 offset:22528
	s_setprio 2
	global_load_dwordx4 v[162:165], v8, s[36:37] offset:768
	s_waitcnt vmcnt(8)
	ds_write_b128 v2, v[166:169] offset:32768
	ds_read_b128 v[166:169], v4
	ds_read_b128 v[170:173], v5 offset:16384
	s_waitcnt lgkmcnt(8)
	v_mfma_f32_16x16x32_bf16 v[26:29], v[118:121], v[82:85], v[26:29]
	s_waitcnt lgkmcnt(3)
	v_mfma_f32_16x16x32_bf16 v[10:13], v[158:161], v[82:85], v[10:13]
	v_mfma_f32_16x16x32_bf16 v[86:89], v[126:129], v[82:85], v[86:89]
	v_mfma_f32_16x16x32_bf16 v[94:97], v[154:157], v[82:85], v[94:97]
	global_load_dwordx4 v[82:85], v228, s[36:37] offset:768
	v_mfma_f32_16x16x32_bf16 v[30:33], v[118:121], v[102:105], v[30:33]
	s_waitcnt vmcnt(8)
	ds_write_b128 v2, v[106:109] offset:36864
	v_mfma_f32_16x16x32_bf16 v[42:45], v[126:129], v[102:105], v[42:45]
	ds_read_b128 v[106:109], v4 offset:2048
	v_mfma_f32_16x16x32_bf16 v[14:17], v[158:161], v[102:105], v[14:17]
	ds_read_b128 v[174:177], v5 offset:18432
	v_mfma_f32_16x16x32_bf16 v[90:93], v[154:157], v[102:105], v[90:93]
	global_load_dwordx4 v[102:105], v229, s[36:37] offset:768
	v_mfma_f32_16x16x32_bf16 v[34:37], v[118:121], v[132:135], v[34:37]
	s_waitcnt vmcnt(8)
	ds_write_b128 v2, v[110:113] offset:40960
	v_mfma_f32_16x16x32_bf16 v[46:49], v[126:129], v[132:135], v[46:49]
	ds_read_b128 v[110:113], v4 offset:4096
	v_mfma_f32_16x16x32_bf16 v[62:65], v[154:157], v[132:135], v[62:65]
	ds_read_b128 v[178:181], v5 offset:20480
	v_mfma_f32_16x16x32_bf16 v[18:21], v[158:161], v[132:135], v[18:21]
	global_load_dwordx4 v[132:135], v230, s[36:37] offset:768
	v_mfma_f32_16x16x32_bf16 v[38:41], v[118:121], v[150:153], v[38:41]
	s_waitcnt vmcnt(8)
	ds_write_b128 v2, v[146:149] offset:45056
	v_mfma_f32_16x16x32_bf16 v[50:53], v[126:129], v[150:153], v[50:53]
	ds_read_b128 v[146:149], v4 offset:6144
	v_mfma_f32_16x16x32_bf16 v[54:57], v[154:157], v[150:153], v[54:57]
	ds_read_b128 v[182:185], v5 offset:22528
	v_mfma_f32_16x16x32_bf16 v[22:25], v[158:161], v[150:153], v[22:25]
	global_load_dwordx4 v[118:121], v3, s[0:1] offset:768
	s_waitcnt vmcnt(8)
	ds_write_b128 v2, v[114:117] offset:49152
	s_waitcnt lgkmcnt(10)
	v_mfma_f32_16x16x32_bf16 v[26:29], v[170:173], v[166:169], v[26:29]
	s_waitcnt lgkmcnt(1)
	v_mfma_f32_16x16x32_bf16 v[10:13], v[182:185], v[166:169], v[10:13]
	v_mfma_f32_16x16x32_bf16 v[86:89], v[174:177], v[166:169], v[86:89]
	v_mfma_f32_16x16x32_bf16 v[94:97], v[178:181], v[166:169], v[94:97]
	global_load_dwordx4 v[114:117], v231, s[0:1] offset:768
	v_mfma_f32_16x16x32_bf16 v[30:33], v[170:173], v[106:109], v[30:33]
	s_waitcnt vmcnt(8)
	ds_write_b128 v2, v[122:125] offset:53248
	v_mfma_f32_16x16x32_bf16 v[42:45], v[174:177], v[106:109], v[42:45]
	v_mfma_f32_16x16x32_bf16 v[14:17], v[182:185], v[106:109], v[14:17]
	v_mfma_f32_16x16x32_bf16 v[90:93], v[178:181], v[106:109], v[90:93]
	global_load_dwordx4 v[106:109], v232, s[0:1] offset:768
	s_waitcnt vmcnt(8)
	ds_write_b128 v2, v[58:61] offset:57344
	v_mfma_f32_16x16x32_bf16 v[34:37], v[170:173], v[110:113], v[34:37]
	v_mfma_f32_16x16x32_bf16 v[46:49], v[174:177], v[110:113], v[46:49]
	v_mfma_f32_16x16x32_bf16 v[58:61], v[178:181], v[110:113], v[62:65]
	v_mfma_f32_16x16x32_bf16 v[18:21], v[182:185], v[110:113], v[18:21]
	global_load_dwordx4 v[62:65], v233, s[0:1] offset:768
	v_mfma_f32_16x16x32_bf16 v[38:41], v[170:173], v[146:149], v[38:41]
	s_waitcnt vmcnt(8)
	ds_write_b128 v2, v[98:101] offset:61440
	v_mfma_f32_16x16x32_bf16 v[50:53], v[174:177], v[146:149], v[50:53]
	v_mfma_f32_16x16x32_bf16 v[54:57], v[178:181], v[146:149], v[54:57]
	v_mfma_f32_16x16x32_bf16 v[22:25], v[182:185], v[146:149], v[22:25]
	s_setprio 0
	s_waitcnt lgkmcnt(0)
	s_barrier
; template <int MODE>
; __device__ __forceinline__ void gemm_tile(const Params& P, int tm, int tn, unsigned char* smem) {
;     ...
; #pragma unroll
;         for (int i = 0; i < 4; ++i) { fa[i] = *(const bf16x8*)(sA + arow_off + i * 2048 + ch0); fb[i] = *(const bf16x8*)(sB + brow_off + i * 2048 + ch0); }
;         __builtin_amdgcn_sched_barrier(0);
;         __builtin_amdgcn_s_setprio(2);
;         if (wr_ok) *(uint4*)(nA + soff0) = ra0;
;         if (ld_ok) ra0 = *(const uint4*)(Ab + (aoff + 0u * LDA + koa));
;         ga[0] = *(const bf16x8*)(sA + arow_off + 0 * 2048 + ch1); gb[0] = *(const bf16x8*)(sB + brow_off + 0 * 2048 + ch1);
;         __builtin_amdgcn_sched_barrier(0);
; #pragma unroll
;         for (int j = 0; j < 4; ++j) acc[0][j] = __builtin_amdgcn_mfma_f32_16x16x32_bf16(fb[j], fa[0], acc[0][j], 0, 0, 0);
;         __builtin_amdgcn_sched_barrier(0);
;         if (wr_ok) *(uint4*)(nA + soff0 + 4096) = ra1;
;         if (ld_ok) ra1 = *(const uint4*)(Ab + (aoff + 32u * LDA + koa));
;         ga[1] = *(const bf16x8*)(sA + arow_off + 1 * 2048 + ch1); gb[1] = *(const bf16x8*)(sB + brow_off + 1 * 2048 + ch1);
;         __builtin_amdgcn_sched_barrier(0);
; #pragma unroll
;         for (int j = 0; j < 4; ++j) acc[1][j] = __builtin_amdgcn_mfma_f32_16x16x32_bf16(fb[j], fa[1], acc[1][j], 0, 0, 0);
;         __builtin_amdgcn_sched_barrier(0);
;         if (wr_ok) *(uint4*)(nA + soff0 + 8192) = ra2;
;         if (ld_ok) ra2 = *(const uint4*)(Ab + (aoff + 64u * LDA + koa));
;         ga[2] = *(const bf16x8*)(sA + arow_off + 2 * 2048 + ch1); gb[2] = *(const bf16x8*)(sB + brow_off + 2 * 2048 + ch1);
;         __builtin_amdgcn_sched_barrier(0);
; #pragma unroll
;         for (int j = 0; j < 4; ++j) acc[2][j] = __builtin_amdgcn_mfma_f32_16x16x32_bf16(fb[j], fa[2], acc[2][j], 0, 0, 0);
;         __builtin_amdgcn_sched_barrier(0);
;         if (wr_ok) *(uint4*)(nA + soff0 + 12288) = ra3;
;         if (ld_ok) ra3 = *(const uint4*)(Ab + (aoff + 96u * LDA + koa));
;         ga[3] = *(const bf16x8*)(sA + arow_off + 3 * 2048 + ch1); gb[3] = *(const bf16x8*)(sB + brow_off + 3 * 2048 + ch1);
;         __builtin_amdgcn_sched_barrier(0);
; #pragma unroll
;         for (int j = 0; j < 4; ++j) acc[3][j] = __builtin_amdgcn_mfma_f32_16x16x32_bf16(fb[j], fa[3], acc[3][j], 0, 0, 0);
;         __builtin_amdgcn_sched_barrier(0);
;         if (wr_ok) *(uint4*)(nB + soff0) = rb0;
	ds_read_b128 v[98:101], v6 offset:32768
	ds_read_b128 v[110:113], v6 offset:34816
	ds_read_b128 v[122:125], v7 offset:49152
	ds_read_b128 v[126:129], v7 offset:51200
	ds_read_b128 v[146:149], v6 offset:36864
	ds_read_b128 v[150:153], v6 offset:38912
	ds_read_b128 v[154:157], v7 offset:53248
	ds_read_b128 v[158:161], v7 offset:55296
	s_setprio 2
	global_load_dwordx4 v[166:169], v8, s[36:37] offset:896
	s_waitcnt vmcnt(8)
	ds_write_b128 v2, v[162:165]
	ds_read_b128 v[162:165], v4 offset:32768
	ds_read_b128 v[170:173], v5 offset:49152
	s_waitcnt lgkmcnt(8)
	v_mfma_f32_16x16x32_bf16 v[26:29], v[122:125], v[98:101], v[26:29]
	s_waitcnt lgkmcnt(3)
	v_mfma_f32_16x16x32_bf16 v[10:13], v[158:161], v[98:101], v[10:13]
	v_mfma_f32_16x16x32_bf16 v[86:89], v[126:129], v[98:101], v[86:89]
	v_mfma_f32_16x16x32_bf16 v[94:97], v[154:157], v[98:101], v[94:97]
	global_load_dwordx4 v[98:101], v228, s[36:37] offset:896
	v_mfma_f32_16x16x32_bf16 v[30:33], v[122:125], v[110:113], v[30:33]
	s_waitcnt vmcnt(8)
	ds_write_b128 v2, v[82:85] offset:4096
	v_mfma_f32_16x16x32_bf16 v[42:45], v[126:129], v[110:113], v[42:45]
	ds_read_b128 v[82:85], v4 offset:34816
	v_mfma_f32_16x16x32_bf16 v[14:17], v[158:161], v[110:113], v[14:17]
	ds_read_b128 v[174:177], v5 offset:51200
	v_mfma_f32_16x16x32_bf16 v[90:93], v[154:157], v[110:113], v[90:93]
	global_load_dwordx4 v[110:113], v229, s[36:37] offset:896
	v_mfma_f32_16x16x32_bf16 v[34:37], v[122:125], v[146:149], v[34:37]
	s_waitcnt vmcnt(8)
	ds_write_b128 v2, v[102:105] offset:8192
	v_mfma_f32_16x16x32_bf16 v[46:49], v[126:129], v[146:149], v[46:49]
	ds_read_b128 v[102:105], v4 offset:36864
	v_mfma_f32_16x16x32_bf16 v[58:61], v[154:157], v[146:149], v[58:61]
	ds_read_b128 v[178:181], v5 offset:53248
	v_mfma_f32_16x16x32_bf16 v[18:21], v[158:161], v[146:149], v[18:21]
	global_load_dwordx4 v[146:149], v230, s[36:37] offset:896
	v_mfma_f32_16x16x32_bf16 v[38:41], v[122:125], v[150:153], v[38:41]
	s_waitcnt vmcnt(8)
	ds_write_b128 v2, v[132:135] offset:12288
	v_mfma_f32_16x16x32_bf16 v[50:53], v[126:129], v[150:153], v[50:53]
	ds_read_b128 v[132:135], v4 offset:38912
	v_mfma_f32_16x16x32_bf16 v[54:57], v[154:157], v[150:153], v[54:57]
	ds_read_b128 v[182:185], v5 offset:55296
	v_mfma_f32_16x16x32_bf16 v[22:25], v[158:161], v[150:153], v[22:25]
	global_load_dwordx4 v[122:125], v3, s[0:1] offset:896
	s_waitcnt vmcnt(8)
	ds_write_b128 v2, v[118:121] offset:16384
	s_waitcnt lgkmcnt(10)
	v_mfma_f32_16x16x32_bf16 v[26:29], v[170:173], v[162:165], v[26:29]
	s_waitcnt lgkmcnt(1)
	v_mfma_f32_16x16x32_bf16 v[10:13], v[182:185], v[162:165], v[10:13]
	v_mfma_f32_16x16x32_bf16 v[86:89], v[174:177], v[162:165], v[86:89]
	v_mfma_f32_16x16x32_bf16 v[94:97], v[178:181], v[162:165], v[94:97]
	global_load_dwordx4 v[118:121], v231, s[0:1] offset:896
	v_mfma_f32_16x16x32_bf16 v[30:33], v[170:173], v[82:85], v[30:33]
	s_waitcnt vmcnt(8)
	ds_write_b128 v2, v[114:117] offset:20480
	v_mfma_f32_16x16x32_bf16 v[42:45], v[174:177], v[82:85], v[42:45]
	v_mfma_f32_16x16x32_bf16 v[14:17], v[182:185], v[82:85], v[14:17]
	v_mfma_f32_16x16x32_bf16 v[90:93], v[178:181], v[82:85], v[90:93]
	global_load_dwordx4 v[82:85], v232, s[0:1] offset:896
	v_mfma_f32_16x16x32_bf16 v[34:37], v[170:173], v[102:105], v[34:37]
	s_waitcnt vmcnt(8)
	ds_write_b128 v2, v[106:109] offset:24576
	v_mfma_f32_16x16x32_bf16 v[46:49], v[174:177], v[102:105], v[46:49]
	v_mfma_f32_16x16x32_bf16 v[58:61], v[178:181], v[102:105], v[58:61]
	v_mfma_f32_16x16x32_bf16 v[18:21], v[182:185], v[102:105], v[18:21]
	global_load_dwordx4 v[102:105], v233, s[0:1] offset:896
	v_mfma_f32_16x16x32_bf16 v[38:41], v[170:173], v[132:135], v[38:41]
	s_waitcnt vmcnt(8)
	ds_write_b128 v2, v[62:65] offset:28672
	v_mfma_f32_16x16x32_bf16 v[50:53], v[174:177], v[132:135], v[50:53]
	v_mfma_f32_16x16x32_bf16 v[54:57], v[178:181], v[132:135], v[54:57]
	v_mfma_f32_16x16x32_bf16 v[22:25], v[182:185], v[132:135], v[22:25]
	s_setprio 0
	s_waitcnt lgkmcnt(0)
	s_barrier
	ds_read_b128 v[62:65], v6
	ds_read_b128 v[106:109], v6 offset:2048
	ds_read_b128 v[114:117], v7 offset:16384
	ds_read_b128 v[126:129], v7 offset:18432
	ds_read_b128 v[132:135], v6 offset:4096
	ds_read_b128 v[150:153], v6 offset:6144
	ds_read_b128 v[154:157], v7 offset:20480
	ds_read_b128 v[158:161], v7 offset:22528
	s_setprio 2
	global_load_dwordx4 v[162:165], v8, s[36:37] offset:1024
	s_waitcnt vmcnt(8)
	ds_write_b128 v2, v[166:169] offset:32768
	ds_read_b128 v[166:169], v4
	ds_read_b128 v[170:173], v5 offset:16384
	s_waitcnt lgkmcnt(8)
	v_mfma_f32_16x16x32_bf16 v[26:29], v[114:117], v[62:65], v[26:29]
	s_waitcnt lgkmcnt(3)
	v_mfma_f32_16x16x32_bf16 v[10:13], v[158:161], v[62:65], v[10:13]
	v_mfma_f32_16x16x32_bf16 v[86:89], v[126:129], v[62:65], v[86:89]
	v_mfma_f32_16x16x32_bf16 v[94:97], v[154:157], v[62:65], v[94:97]
	global_load_dwordx4 v[62:65], v228, s[36:37] offset:1024
	v_mfma_f32_16x16x32_bf16 v[30:33], v[114:117], v[106:109], v[30:33]
	s_waitcnt vmcnt(8)
	ds_write_b128 v2, v[98:101] offset:36864
	v_mfma_f32_16x16x32_bf16 v[42:45], v[126:129], v[106:109], v[42:45]
	ds_read_b128 v[98:101], v4 offset:2048
	v_mfma_f32_16x16x32_bf16 v[14:17], v[158:161], v[106:109], v[14:17]
	ds_read_b128 v[174:177], v5 offset:18432
	v_mfma_f32_16x16x32_bf16 v[90:93], v[154:157], v[106:109], v[90:93]
	global_load_dwordx4 v[106:109], v229, s[36:37] offset:1024
	v_mfma_f32_16x16x32_bf16 v[34:37], v[114:117], v[132:135], v[34:37]
	s_waitcnt vmcnt(8)
; template <int MODE>
; __device__ __forceinline__ void gemm_tile(const Params& P, int tm, int tn, unsigned char* smem) {
;     ...
; #pragma unroll
;         for (int i = 0; i < 4; ++i) { fa[i] = *(const bf16x8*)(sA + arow_off + i * 2048 + ch0); fb[i] = *(const bf16x8*)(sB + brow_off + i * 2048 + ch0); }
;         __builtin_amdgcn_sched_barrier(0);
;         __builtin_amdgcn_s_setprio(2);
;         if (wr_ok) *(uint4*)(nA + soff0) = ra0;
;         if (ld_ok) ra0 = *(const uint4*)(Ab + (aoff + 0u * LDA + koa));
;         ga[0] = *(const bf16x8*)(sA + arow_off + 0 * 2048 + ch1); gb[0] = *(const bf16x8*)(sB + brow_off + 0 * 2048 + ch1);
;         __builtin_amdgcn_sched_barrier(0);
; #pragma unroll
;         for (int j = 0; j < 4; ++j) acc[0][j] = __builtin_amdgcn_mfma_f32_16x16x32_bf16(fb[j], fa[0], acc[0][j], 0, 0, 0);
;         __builtin_amdgcn_sched_barrier(0);
;         if (wr_ok) *(uint4*)(nA + soff0 + 4096) = ra1;
;         if (ld_ok) ra1 = *(const uint4*)(Ab + (aoff + 32u * LDA + koa));
;         ga[1] = *(const bf16x8*)(sA + arow_off + 1 * 2048 + ch1); gb[1] = *(const bf16x8*)(sB + brow_off + 1 * 2048 + ch1);
;         __builtin_amdgcn_sched_barrier(0);
; #pragma unroll
;         for (int j = 0; j < 4; ++j) acc[1][j] = __builtin_amdgcn_mfma_f32_16x16x32_bf16(fb[j], fa[1], acc[1][j], 0, 0, 0);
;         __builtin_amdgcn_sched_barrier(0);
;         if (wr_ok) *(uint4*)(nA + soff0 + 8192) = ra2;
;         if (ld_ok) ra2 = *(const uint4*)(Ab + (aoff + 64u * LDA + koa));
;         ga[2] = *(const bf16x8*)(sA + arow_off + 2 * 2048 + ch1); gb[2] = *(const bf16x8*)(sB + brow_off + 2 * 2048 + ch1);
;         __builtin_amdgcn_sched_barrier(0);
; #pragma unroll
;         for (int j = 0; j < 4; ++j) acc[2][j] = __builtin_amdgcn_mfma_f32_16x16x32_bf16(fb[j], fa[2], acc[2][j], 0, 0, 0);
;         __builtin_amdgcn_sched_barrier(0);
;         if (wr_ok) *(uint4*)(nA + soff0 + 12288) = ra3;
;         if (ld_ok) ra3 = *(const uint4*)(Ab + (aoff + 96u * LDA + koa));
;         ga[3] = *(const bf16x8*)(sA + arow_off + 3 * 2048 + ch1); gb[3] = *(const bf16x8*)(sB + brow_off + 3 * 2048 + ch1);
;         __builtin_amdgcn_sched_barrier(0);
; #pragma unroll
;         for (int j = 0; j < 4; ++j) acc[3][j] = __builtin_amdgcn_mfma_f32_16x16x32_bf16(fb[j], fa[3], acc[3][j], 0, 0, 0);
;         __builtin_amdgcn_sched_barrier(0);
;         if (wr_ok) *(uint4*)(nB + soff0) = rb0;
	ds_write_b128 v2, v[110:113] offset:40960
	v_mfma_f32_16x16x32_bf16 v[46:49], v[126:129], v[132:135], v[46:49]
	ds_read_b128 v[110:113], v4 offset:4096
	v_mfma_f32_16x16x32_bf16 v[58:61], v[154:157], v[132:135], v[58:61]
	ds_read_b128 v[178:181], v5 offset:20480
	v_mfma_f32_16x16x32_bf16 v[18:21], v[158:161], v[132:135], v[18:21]
	global_load_dwordx4 v[132:135], v230, s[36:37] offset:1024
	v_mfma_f32_16x16x32_bf16 v[38:41], v[114:117], v[150:153], v[38:41]
	s_waitcnt vmcnt(8)
	ds_write_b128 v2, v[146:149] offset:45056
	v_mfma_f32_16x16x32_bf16 v[50:53], v[126:129], v[150:153], v[50:53]
	ds_read_b128 v[146:149], v4 offset:6144
	v_mfma_f32_16x16x32_bf16 v[54:57], v[154:157], v[150:153], v[54:57]
	ds_read_b128 v[182:185], v5 offset:22528
	v_mfma_f32_16x16x32_bf16 v[22:25], v[158:161], v[150:153], v[22:25]
	global_load_dwordx4 v[114:117], v3, s[0:1] offset:1024
	s_waitcnt vmcnt(8)
	ds_write_b128 v2, v[122:125] offset:49152
	s_waitcnt lgkmcnt(10)
	v_mfma_f32_16x16x32_bf16 v[26:29], v[170:173], v[166:169], v[26:29]
	s_waitcnt lgkmcnt(1)
	v_mfma_f32_16x16x32_bf16 v[10:13], v[182:185], v[166:169], v[10:13]
	v_mfma_f32_16x16x32_bf16 v[86:89], v[174:177], v[166:169], v[86:89]
	v_mfma_f32_16x16x32_bf16 v[94:97], v[178:181], v[166:169], v[94:97]
	global_load_dwordx4 v[122:125], v231, s[0:1] offset:1024
	v_mfma_f32_16x16x32_bf16 v[30:33], v[170:173], v[98:101], v[30:33]
	s_waitcnt vmcnt(8)
	ds_write_b128 v2, v[118:121] offset:53248
	v_mfma_f32_16x16x32_bf16 v[42:45], v[174:177], v[98:101], v[42:45]
	v_mfma_f32_16x16x32_bf16 v[14:17], v[182:185], v[98:101], v[14:17]
	v_mfma_f32_16x16x32_bf16 v[90:93], v[178:181], v[98:101], v[90:93]
	global_load_dwordx4 v[98:101], v232, s[0:1] offset:1024
	v_mfma_f32_16x16x32_bf16 v[34:37], v[170:173], v[110:113], v[34:37]
	s_waitcnt vmcnt(8)
	ds_write_b128 v2, v[82:85] offset:57344
	v_mfma_f32_16x16x32_bf16 v[46:49], v[174:177], v[110:113], v[46:49]
	v_mfma_f32_16x16x32_bf16 v[58:61], v[178:181], v[110:113], v[58:61]
	v_mfma_f32_16x16x32_bf16 v[18:21], v[182:185], v[110:113], v[18:21]
	global_load_dwordx4 v[82:85], v233, s[0:1] offset:1024
	v_mfma_f32_16x16x32_bf16 v[38:41], v[170:173], v[146:149], v[38:41]
	s_waitcnt vmcnt(8)
	ds_write_b128 v2, v[102:105] offset:61440
	v_mfma_f32_16x16x32_bf16 v[50:53], v[174:177], v[146:149], v[50:53]
	v_mfma_f32_16x16x32_bf16 v[54:57], v[178:181], v[146:149], v[54:57]
	v_mfma_f32_16x16x32_bf16 v[22:25], v[182:185], v[146:149], v[22:25]
	s_setprio 0
	s_waitcnt lgkmcnt(0)
	s_barrier
	ds_read_b128 v[102:105], v6 offset:32768
	ds_read_b128 v[110:113], v6 offset:34816
	ds_read_b128 v[118:121], v7 offset:49152
	ds_read_b128 v[126:129], v7 offset:51200
	ds_read_b128 v[146:149], v6 offset:36864
	ds_read_b128 v[150:153], v6 offset:38912
	ds_read_b128 v[154:157], v7 offset:53248
	ds_read_b128 v[158:161], v7 offset:55296
	s_setprio 2
	global_load_dwordx4 v[166:169], v8, s[36:37] offset:1152
	s_waitcnt vmcnt(8)
	ds_write_b128 v2, v[162:165]
	ds_read_b128 v[162:165], v4 offset:32768
	ds_read_b128 v[170:173], v5 offset:49152
	s_waitcnt lgkmcnt(8)
	v_mfma_f32_16x16x32_bf16 v[26:29], v[118:121], v[102:105], v[26:29]
	s_waitcnt lgkmcnt(3)
	v_mfma_f32_16x16x32_bf16 v[10:13], v[158:161], v[102:105], v[10:13]
	v_mfma_f32_16x16x32_bf16 v[86:89], v[126:129], v[102:105], v[86:89]
	v_mfma_f32_16x16x32_bf16 v[94:97], v[154:157], v[102:105], v[94:97]
	global_load_dwordx4 v[102:105], v228, s[36:37] offset:1152
	v_mfma_f32_16x16x32_bf16 v[30:33], v[118:121], v[110:113], v[30:33]
	s_waitcnt vmcnt(8)
	ds_write_b128 v2, v[62:65] offset:4096
	v_mfma_f32_16x16x32_bf16 v[42:45], v[126:129], v[110:113], v[42:45]
	ds_read_b128 v[62:65], v4 offset:34816
	v_mfma_f32_16x16x32_bf16 v[14:17], v[158:161], v[110:113], v[14:17]
	ds_read_b128 v[174:177], v5 offset:51200
	v_mfma_f32_16x16x32_bf16 v[90:93], v[154:157], v[110:113], v[90:93]
	global_load_dwordx4 v[110:113], v229, s[36:37] offset:1152
	v_mfma_f32_16x16x32_bf16 v[34:37], v[118:121], v[146:149], v[34:37]
	s_waitcnt vmcnt(8)
	ds_write_b128 v2, v[106:109] offset:8192
	v_mfma_f32_16x16x32_bf16 v[46:49], v[126:129], v[146:149], v[46:49]
	ds_read_b128 v[106:109], v4 offset:36864
	v_mfma_f32_16x16x32_bf16 v[58:61], v[154:157], v[146:149], v[58:61]
	ds_read_b128 v[178:181], v5 offset:53248
	v_mfma_f32_16x16x32_bf16 v[18:21], v[158:161], v[146:149], v[18:21]
	global_load_dwordx4 v[146:149], v230, s[36:37] offset:1152
	v_mfma_f32_16x16x32_bf16 v[38:41], v[118:121], v[150:153], v[38:41]
	s_waitcnt vmcnt(8)
	ds_write_b128 v2, v[132:135] offset:12288
	v_mfma_f32_16x16x32_bf16 v[50:53], v[126:129], v[150:153], v[50:53]
	ds_read_b128 v[132:135], v4 offset:38912
	v_mfma_f32_16x16x32_bf16 v[54:57], v[154:157], v[150:153], v[54:57]
	ds_read_b128 v[182:185], v5 offset:55296
	v_mfma_f32_16x16x32_bf16 v[22:25], v[158:161], v[150:153], v[22:25]
	global_load_dwordx4 v[118:121], v3, s[0:1] offset:1152
	s_waitcnt vmcnt(8)
	ds_write_b128 v2, v[114:117] offset:16384
	s_waitcnt lgkmcnt(10)
	v_mfma_f32_16x16x32_bf16 v[26:29], v[170:173], v[162:165], v[26:29]
	s_waitcnt lgkmcnt(1)
	v_mfma_f32_16x16x32_bf16 v[10:13], v[182:185], v[162:165], v[10:13]
	v_mfma_f32_16x16x32_bf16 v[86:89], v[174:177], v[162:165], v[86:89]
	v_mfma_f32_16x16x32_bf16 v[94:97], v[178:181], v[162:165], v[94:97]
	global_load_dwordx4 v[114:117], v231, s[0:1] offset:1152
	v_mfma_f32_16x16x32_bf16 v[30:33], v[170:173], v[62:65], v[30:33]
	s_waitcnt vmcnt(8)
	ds_write_b128 v2, v[122:125] offset:20480
	v_mfma_f32_16x16x32_bf16 v[42:45], v[174:177], v[62:65], v[42:45]
	v_mfma_f32_16x16x32_bf16 v[14:17], v[182:185], v[62:65], v[14:17]
	v_mfma_f32_16x16x32_bf16 v[90:93], v[178:181], v[62:65], v[90:93]
	global_load_dwordx4 v[62:65], v232, s[0:1] offset:1152
	v_mfma_f32_16x16x32_bf16 v[34:37], v[170:173], v[106:109], v[34:37]
	s_waitcnt vmcnt(8)
	ds_write_b128 v2, v[98:101] offset:24576
	v_mfma_f32_16x16x32_bf16 v[46:49], v[174:177], v[106:109], v[46:49]
	v_mfma_f32_16x16x32_bf16 v[58:61], v[178:181], v[106:109], v[58:61]
	v_mfma_f32_16x16x32_bf16 v[18:21], v[182:185], v[106:109], v[18:21]
	global_load_dwordx4 v[98:101], v233, s[0:1] offset:1152
	v_mfma_f32_16x16x32_bf16 v[38:41], v[170:173], v[132:135], v[38:41]
	s_waitcnt vmcnt(8)
	ds_write_b128 v2, v[82:85] offset:28672
	v_mfma_f32_16x16x32_bf16 v[50:53], v[174:177], v[132:135], v[50:53]
	v_mfma_f32_16x16x32_bf16 v[54:57], v[178:181], v[132:135], v[54:57]
	v_mfma_f32_16x16x32_bf16 v[22:25], v[182:185], v[132:135], v[22:25]
	s_setprio 0
	s_waitcnt lgkmcnt(0)
	s_barrier
; template <int MODE>
; __device__ __forceinline__ void gemm_tile(const Params& P, int tm, int tn, unsigned char* smem) {
;     ...
; #pragma unroll
;         for (int i = 0; i < 4; ++i) { fa[i] = *(const bf16x8*)(sA + arow_off + i * 2048 + ch0); fb[i] = *(const bf16x8*)(sB + brow_off + i * 2048 + ch0); }
;         __builtin_amdgcn_sched_barrier(0);
;         __builtin_amdgcn_s_setprio(2);
;         if (wr_ok) *(uint4*)(nA + soff0) = ra0;
;         if (ld_ok) ra0 = *(const uint4*)(Ab + (aoff + 0u * LDA + koa));
;         ga[0] = *(const bf16x8*)(sA + arow_off + 0 * 2048 + ch1); gb[0] = *(const bf16x8*)(sB + brow_off + 0 * 2048 + ch1);
;         __builtin_amdgcn_sched_barrier(0);
; #pragma unroll
;         for (int j = 0; j < 4; ++j) acc[0][j] = __builtin_amdgcn_mfma_f32_16x16x32_bf16(fb[j], fa[0], acc[0][j], 0, 0, 0);
;         __builtin_amdgcn_sched_barrier(0);
;         if (wr_ok) *(uint4*)(nA + soff0 + 4096) = ra1;
;         if (ld_ok) ra1 = *(const uint4*)(Ab + (aoff + 32u * LDA + koa));
;         ga[1] = *(const bf16x8*)(sA + arow_off + 1 * 2048 + ch1); gb[1] = *(const bf16x8*)(sB + brow_off + 1 * 2048 + ch1);
;         __builtin_amdgcn_sched_barrier(0);
; #pragma unroll
;         for (int j = 0; j < 4; ++j) acc[1][j] = __builtin_amdgcn_mfma_f32_16x16x32_bf16(fb[j], fa[1], acc[1][j], 0, 0, 0);
;         __builtin_amdgcn_sched_barrier(0);
;         if (wr_ok) *(uint4*)(nA + soff0 + 8192) = ra2;
;         if (ld_ok) ra2 = *(const uint4*)(Ab + (aoff + 64u * LDA + koa));
;         ga[2] = *(const bf16x8*)(sA + arow_off + 2 * 2048 + ch1); gb[2] = *(const bf16x8*)(sB + brow_off + 2 * 2048 + ch1);
;         __builtin_amdgcn_sched_barrier(0);
; #pragma unroll
;         for (int j = 0; j < 4; ++j) acc[2][j] = __builtin_amdgcn_mfma_f32_16x16x32_bf16(fb[j], fa[2], acc[2][j], 0, 0, 0);
;         __builtin_amdgcn_sched_barrier(0);
;         if (wr_ok) *(uint4*)(nA + soff0 + 12288) = ra3;
;         if (ld_ok) ra3 = *(const uint4*)(Ab + (aoff + 96u * LDA + koa));
;         ga[3] = *(const bf16x8*)(sA + arow_off + 3 * 2048 + ch1); gb[3] = *(const bf16x8*)(sB + brow_off + 3 * 2048 + ch1);
;         __builtin_amdgcn_sched_barrier(0);
; #pragma unroll
;         for (int j = 0; j < 4; ++j) acc[3][j] = __builtin_amdgcn_mfma_f32_16x16x32_bf16(fb[j], fa[3], acc[3][j], 0, 0, 0);
;         __builtin_amdgcn_sched_barrier(0);
;         if (wr_ok) *(uint4*)(nB + soff0) = rb0;
	ds_read_b128 v[82:85], v6
	ds_read_b128 v[106:109], v6 offset:2048
	ds_read_b128 v[122:125], v7 offset:16384
	ds_read_b128 v[126:129], v7 offset:18432
	ds_read_b128 v[132:135], v6 offset:4096
	ds_read_b128 v[150:153], v6 offset:6144
	ds_read_b128 v[154:157], v7 offset:20480
	ds_read_b128 v[158:161], v7 offset:22528
	s_setprio 2
	global_load_dwordx4 v[162:165], v8, s[36:37] offset:1280
	s_waitcnt vmcnt(8)
	ds_write_b128 v2, v[166:169] offset:32768
	ds_read_b128 v[166:169], v4
	ds_read_b128 v[170:173], v5 offset:16384
	s_waitcnt lgkmcnt(8)
	v_mfma_f32_16x16x32_bf16 v[26:29], v[122:125], v[82:85], v[26:29]
	s_waitcnt lgkmcnt(3)
	v_mfma_f32_16x16x32_bf16 v[10:13], v[158:161], v[82:85], v[10:13]
	v_mfma_f32_16x16x32_bf16 v[86:89], v[126:129], v[82:85], v[86:89]
	v_mfma_f32_16x16x32_bf16 v[94:97], v[154:157], v[82:85], v[94:97]
	global_load_dwordx4 v[82:85], v228, s[36:37] offset:1280
	v_mfma_f32_16x16x32_bf16 v[30:33], v[122:125], v[106:109], v[30:33]
	s_waitcnt vmcnt(8)
	ds_write_b128 v2, v[102:105] offset:36864
	v_mfma_f32_16x16x32_bf16 v[42:45], v[126:129], v[106:109], v[42:45]
	ds_read_b128 v[102:105], v4 offset:2048
	v_mfma_f32_16x16x32_bf16 v[14:17], v[158:161], v[106:109], v[14:17]
	ds_read_b128 v[174:177], v5 offset:18432
	v_mfma_f32_16x16x32_bf16 v[90:93], v[154:157], v[106:109], v[90:93]
	global_load_dwordx4 v[106:109], v229, s[36:37] offset:1280
	v_mfma_f32_16x16x32_bf16 v[34:37], v[122:125], v[132:135], v[34:37]
	s_waitcnt vmcnt(8)
	ds_write_b128 v2, v[110:113] offset:40960
	v_mfma_f32_16x16x32_bf16 v[46:49], v[126:129], v[132:135], v[46:49]
	ds_read_b128 v[110:113], v4 offset:4096
	v_mfma_f32_16x16x32_bf16 v[58:61], v[154:157], v[132:135], v[58:61]
	ds_read_b128 v[178:181], v5 offset:20480
	v_mfma_f32_16x16x32_bf16 v[18:21], v[158:161], v[132:135], v[18:21]
	global_load_dwordx4 v[132:135], v230, s[36:37] offset:1280
	v_mfma_f32_16x16x32_bf16 v[38:41], v[122:125], v[150:153], v[38:41]
	s_waitcnt vmcnt(8)
	ds_write_b128 v2, v[146:149] offset:45056
	v_mfma_f32_16x16x32_bf16 v[50:53], v[126:129], v[150:153], v[50:53]
	ds_read_b128 v[146:149], v4 offset:6144
	v_mfma_f32_16x16x32_bf16 v[54:57], v[154:157], v[150:153], v[54:57]
	ds_read_b128 v[182:185], v5 offset:22528
	v_mfma_f32_16x16x32_bf16 v[22:25], v[158:161], v[150:153], v[22:25]
	global_load_dwordx4 v[122:125], v3, s[0:1] offset:1280
	s_waitcnt vmcnt(8)
	ds_write_b128 v2, v[118:121] offset:49152
	s_waitcnt lgkmcnt(10)
	v_mfma_f32_16x16x32_bf16 v[26:29], v[170:173], v[166:169], v[26:29]
	s_waitcnt lgkmcnt(1)
	v_mfma_f32_16x16x32_bf16 v[10:13], v[182:185], v[166:169], v[10:13]
	v_mfma_f32_16x16x32_bf16 v[86:89], v[174:177], v[166:169], v[86:89]
	v_mfma_f32_16x16x32_bf16 v[94:97], v[178:181], v[166:169], v[94:97]
	global_load_dwordx4 v[118:121], v231, s[0:1] offset:1280
	v_mfma_f32_16x16x32_bf16 v[30:33], v[170:173], v[102:105], v[30:33]
	s_waitcnt vmcnt(8)
	ds_write_b128 v2, v[114:117] offset:53248
	v_mfma_f32_16x16x32_bf16 v[42:45], v[174:177], v[102:105], v[42:45]
	v_mfma_f32_16x16x32_bf16 v[14:17], v[182:185], v[102:105], v[14:17]
	v_mfma_f32_16x16x32_bf16 v[90:93], v[178:181], v[102:105], v[90:93]
	global_load_dwordx4 v[102:105], v232, s[0:1] offset:1280
	v_mfma_f32_16x16x32_bf16 v[34:37], v[170:173], v[110:113], v[34:37]
	s_waitcnt vmcnt(8)
	ds_write_b128 v2, v[62:65] offset:57344
	v_mfma_f32_16x16x32_bf16 v[46:49], v[174:177], v[110:113], v[46:49]
	v_mfma_f32_16x16x32_bf16 v[58:61], v[178:181], v[110:113], v[58:61]
	v_mfma_f32_16x16x32_bf16 v[18:21], v[182:185], v[110:113], v[18:21]
	global_load_dwordx4 v[62:65], v233, s[0:1] offset:1280
	v_mfma_f32_16x16x32_bf16 v[38:41], v[170:173], v[146:149], v[38:41]
	s_waitcnt vmcnt(8)
	ds_write_b128 v2, v[98:101] offset:61440
	v_mfma_f32_16x16x32_bf16 v[50:53], v[174:177], v[146:149], v[50:53]
	v_mfma_f32_16x16x32_bf16 v[54:57], v[178:181], v[146:149], v[54:57]
	v_mfma_f32_16x16x32_bf16 v[22:25], v[182:185], v[146:149], v[22:25]
	s_setprio 0
	s_waitcnt lgkmcnt(0)
	s_barrier
	ds_read_b128 v[98:101], v6 offset:32768
	ds_read_b128 v[110:113], v6 offset:34816
	ds_read_b128 v[114:117], v7 offset:49152
	ds_read_b128 v[126:129], v7 offset:51200
	ds_read_b128 v[146:149], v6 offset:36864
	ds_read_b128 v[150:153], v6 offset:38912
	ds_read_b128 v[154:157], v7 offset:53248
	ds_read_b128 v[158:161], v7 offset:55296
	s_setprio 2
	global_load_dwordx4 v[166:169], v8, s[36:37] offset:1408
	s_waitcnt vmcnt(8)
	ds_write_b128 v2, v[162:165]
	ds_read_b128 v[162:165], v4 offset:32768
	ds_read_b128 v[170:173], v5 offset:49152
	s_waitcnt lgkmcnt(8)
	v_mfma_f32_16x16x32_bf16 v[26:29], v[114:117], v[98:101], v[26:29]
	s_waitcnt lgkmcnt(3)
	v_mfma_f32_16x16x32_bf16 v[10:13], v[158:161], v[98:101], v[10:13]
	v_mfma_f32_16x16x32_bf16 v[86:89], v[126:129], v[98:101], v[86:89]
	v_mfma_f32_16x16x32_bf16 v[94:97], v[154:157], v[98:101], v[94:97]
	global_load_dwordx4 v[98:101], v228, s[36:37] offset:1408
	v_mfma_f32_16x16x32_bf16 v[30:33], v[114:117], v[110:113], v[30:33]
	s_waitcnt vmcnt(8)
	ds_write_b128 v2, v[82:85] offset:4096
	v_mfma_f32_16x16x32_bf16 v[42:45], v[126:129], v[110:113], v[42:45]
	ds_read_b128 v[82:85], v4 offset:34816
	v_mfma_f32_16x16x32_bf16 v[14:17], v[158:161], v[110:113], v[14:17]
	ds_read_b128 v[174:177], v5 offset:51200
	v_mfma_f32_16x16x32_bf16 v[90:93], v[154:157], v[110:113], v[90:93]
	global_load_dwordx4 v[110:113], v229, s[36:37] offset:1408
	v_mfma_f32_16x16x32_bf16 v[34:37], v[114:117], v[146:149], v[34:37]
	s_waitcnt vmcnt(8)
; template <int MODE>
; __device__ __forceinline__ void gemm_tile(const Params& P, int tm, int tn, unsigned char* smem) {
;     ...
; #pragma unroll
;         for (int i = 0; i < 4; ++i) { fa[i] = *(const bf16x8*)(sA + arow_off + i * 2048 + ch0); fb[i] = *(const bf16x8*)(sB + brow_off + i * 2048 + ch0); }
;         __builtin_amdgcn_sched_barrier(0);
;         __builtin_amdgcn_s_setprio(2);
;         if (wr_ok) *(uint4*)(nA + soff0) = ra0;
;         if (ld_ok) ra0 = *(const uint4*)(Ab + (aoff + 0u * LDA + koa));
;         ga[0] = *(const bf16x8*)(sA + arow_off + 0 * 2048 + ch1); gb[0] = *(const bf16x8*)(sB + brow_off + 0 * 2048 + ch1);
;         __builtin_amdgcn_sched_barrier(0);
; #pragma unroll
;         for (int j = 0; j < 4; ++j) acc[0][j] = __builtin_amdgcn_mfma_f32_16x16x32_bf16(fb[j], fa[0], acc[0][j], 0, 0, 0);
;         __builtin_amdgcn_sched_barrier(0);
;         if (wr_ok) *(uint4*)(nA + soff0 + 4096) = ra1;
;         if (ld_ok) ra1 = *(const uint4*)(Ab + (aoff + 32u * LDA + koa));
;         ga[1] = *(const bf16x8*)(sA + arow_off + 1 * 2048 + ch1); gb[1] = *(const bf16x8*)(sB + brow_off + 1 * 2048 + ch1);
;         __builtin_amdgcn_sched_barrier(0);
; #pragma unroll
;         for (int j = 0; j < 4; ++j) acc[1][j] = __builtin_amdgcn_mfma_f32_16x16x32_bf16(fb[j], fa[1], acc[1][j], 0, 0, 0);
;         __builtin_amdgcn_sched_barrier(0);
;         if (wr_ok) *(uint4*)(nA + soff0 + 8192) = ra2;
;         if (ld_ok) ra2 = *(const uint4*)(Ab + (aoff + 64u * LDA + koa));
;         ga[2] = *(const bf16x8*)(sA + arow_off + 2 * 2048 + ch1); gb[2] = *(const bf16x8*)(sB + brow_off + 2 * 2048 + ch1);
;         __builtin_amdgcn_sched_barrier(0);
; #pragma unroll
;         for (int j = 0; j < 4; ++j) acc[2][j] = __builtin_amdgcn_mfma_f32_16x16x32_bf16(fb[j], fa[2], acc[2][j], 0, 0, 0);
;         __builtin_amdgcn_sched_barrier(0);
;         if (wr_ok) *(uint4*)(nA + soff0 + 12288) = ra3;
;         if (ld_ok) ra3 = *(const uint4*)(Ab + (aoff + 96u * LDA + koa));
;         ga[3] = *(const bf16x8*)(sA + arow_off + 3 * 2048 + ch1); gb[3] = *(const bf16x8*)(sB + brow_off + 3 * 2048 + ch1);
;         __builtin_amdgcn_sched_barrier(0);
; #pragma unroll
;         for (int j = 0; j < 4; ++j) acc[3][j] = __builtin_amdgcn_mfma_f32_16x16x32_bf16(fb[j], fa[3], acc[3][j], 0, 0, 0);
;         __builtin_amdgcn_sched_barrier(0);
;         if (wr_ok) *(uint4*)(nB + soff0) = rb0;
	ds_write_b128 v2, v[106:109] offset:8192
	v_mfma_f32_16x16x32_bf16 v[46:49], v[126:129], v[146:149], v[46:49]
	ds_read_b128 v[106:109], v4 offset:36864
	v_mfma_f32_16x16x32_bf16 v[58:61], v[154:157], v[146:149], v[58:61]
	ds_read_b128 v[178:181], v5 offset:53248
	v_mfma_f32_16x16x32_bf16 v[18:21], v[158:161], v[146:149], v[18:21]
	global_load_dwordx4 v[146:149], v230, s[36:37] offset:1408
	v_mfma_f32_16x16x32_bf16 v[38:41], v[114:117], v[150:153], v[38:41]
	s_waitcnt vmcnt(8)
	ds_write_b128 v2, v[132:135] offset:12288
	v_mfma_f32_16x16x32_bf16 v[50:53], v[126:129], v[150:153], v[50:53]
	ds_read_b128 v[132:135], v4 offset:38912
	v_mfma_f32_16x16x32_bf16 v[54:57], v[154:157], v[150:153], v[54:57]
	ds_read_b128 v[182:185], v5 offset:55296
	v_mfma_f32_16x16x32_bf16 v[22:25], v[158:161], v[150:153], v[22:25]
	global_load_dwordx4 v[114:117], v3, s[0:1] offset:1408
	s_waitcnt vmcnt(8)
	ds_write_b128 v2, v[122:125] offset:16384
	s_waitcnt lgkmcnt(10)
	v_mfma_f32_16x16x32_bf16 v[26:29], v[170:173], v[162:165], v[26:29]
	s_waitcnt lgkmcnt(1)
	v_mfma_f32_16x16x32_bf16 v[10:13], v[182:185], v[162:165], v[10:13]
	v_mfma_f32_16x16x32_bf16 v[86:89], v[174:177], v[162:165], v[86:89]
	v_mfma_f32_16x16x32_bf16 v[94:97], v[178:181], v[162:165], v[94:97]
	global_load_dwordx4 v[122:125], v231, s[0:1] offset:1408
	v_mfma_f32_16x16x32_bf16 v[30:33], v[170:173], v[82:85], v[30:33]
	s_waitcnt vmcnt(8)
	ds_write_b128 v2, v[118:121] offset:20480
	v_mfma_f32_16x16x32_bf16 v[42:45], v[174:177], v[82:85], v[42:45]
	v_mfma_f32_16x16x32_bf16 v[14:17], v[182:185], v[82:85], v[14:17]
	v_mfma_f32_16x16x32_bf16 v[90:93], v[178:181], v[82:85], v[90:93]
	global_load_dwordx4 v[82:85], v232, s[0:1] offset:1408
	v_mfma_f32_16x16x32_bf16 v[34:37], v[170:173], v[106:109], v[34:37]
	s_waitcnt vmcnt(8)
	ds_write_b128 v2, v[102:105] offset:24576
	v_mfma_f32_16x16x32_bf16 v[46:49], v[174:177], v[106:109], v[46:49]
	v_mfma_f32_16x16x32_bf16 v[58:61], v[178:181], v[106:109], v[58:61]
	v_mfma_f32_16x16x32_bf16 v[18:21], v[182:185], v[106:109], v[18:21]
	global_load_dwordx4 v[102:105], v233, s[0:1] offset:1408
	v_mfma_f32_16x16x32_bf16 v[38:41], v[170:173], v[132:135], v[38:41]
	s_waitcnt vmcnt(8)
	ds_write_b128 v2, v[62:65] offset:28672
	v_mfma_f32_16x16x32_bf16 v[50:53], v[174:177], v[132:135], v[50:53]
	v_mfma_f32_16x16x32_bf16 v[54:57], v[178:181], v[132:135], v[54:57]
	v_mfma_f32_16x16x32_bf16 v[22:25], v[182:185], v[132:135], v[22:25]
	s_setprio 0
	s_waitcnt lgkmcnt(0)
	s_barrier
	ds_read_b128 v[62:65], v6
	ds_read_b128 v[106:109], v6 offset:2048
	ds_read_b128 v[118:121], v7 offset:16384
	ds_read_b128 v[126:129], v7 offset:18432
	ds_read_b128 v[132:135], v6 offset:4096
	ds_read_b128 v[150:153], v6 offset:6144
	ds_read_b128 v[154:157], v7 offset:20480
	ds_read_b128 v[158:161], v7 offset:22528
	s_setprio 2
	global_load_dwordx4 v[162:165], v8, s[36:37] offset:1536
	s_waitcnt vmcnt(8)
	ds_write_b128 v2, v[166:169] offset:32768
	ds_read_b128 v[166:169], v4
	ds_read_b128 v[170:173], v5 offset:16384
	s_waitcnt lgkmcnt(8)
	v_mfma_f32_16x16x32_bf16 v[26:29], v[118:121], v[62:65], v[26:29]
	s_waitcnt lgkmcnt(3)
	v_mfma_f32_16x16x32_bf16 v[10:13], v[158:161], v[62:65], v[10:13]
	v_mfma_f32_16x16x32_bf16 v[86:89], v[126:129], v[62:65], v[86:89]
	v_mfma_f32_16x16x32_bf16 v[94:97], v[154:157], v[62:65], v[94:97]
	global_load_dwordx4 v[62:65], v228, s[36:37] offset:1536
	v_mfma_f32_16x16x32_bf16 v[30:33], v[118:121], v[106:109], v[30:33]
	s_waitcnt vmcnt(8)
	ds_write_b128 v2, v[98:101] offset:36864
	v_mfma_f32_16x16x32_bf16 v[42:45], v[126:129], v[106:109], v[42:45]
	ds_read_b128 v[98:101], v4 offset:2048
	v_mfma_f32_16x16x32_bf16 v[14:17], v[158:161], v[106:109], v[14:17]
	ds_read_b128 v[174:177], v5 offset:18432
	v_mfma_f32_16x16x32_bf16 v[90:93], v[154:157], v[106:109], v[90:93]
	global_load_dwordx4 v[106:109], v229, s[36:37] offset:1536
	v_mfma_f32_16x16x32_bf16 v[34:37], v[118:121], v[132:135], v[34:37]
	s_waitcnt vmcnt(8)
	ds_write_b128 v2, v[110:113] offset:40960
	v_mfma_f32_16x16x32_bf16 v[46:49], v[126:129], v[132:135], v[46:49]
	ds_read_b128 v[110:113], v4 offset:4096
	v_mfma_f32_16x16x32_bf16 v[58:61], v[154:157], v[132:135], v[58:61]
	ds_read_b128 v[178:181], v5 offset:20480
	v_mfma_f32_16x16x32_bf16 v[18:21], v[158:161], v[132:135], v[18:21]
	global_load_dwordx4 v[132:135], v230, s[36:37] offset:1536
	v_mfma_f32_16x16x32_bf16 v[38:41], v[118:121], v[150:153], v[38:41]
	s_waitcnt vmcnt(8)
	ds_write_b128 v2, v[146:149] offset:45056
	v_mfma_f32_16x16x32_bf16 v[50:53], v[126:129], v[150:153], v[50:53]
	ds_read_b128 v[146:149], v4 offset:6144
	v_mfma_f32_16x16x32_bf16 v[54:57], v[154:157], v[150:153], v[54:57]
	ds_read_b128 v[182:185], v5 offset:22528
	v_mfma_f32_16x16x32_bf16 v[22:25], v[158:161], v[150:153], v[22:25]
	global_load_dwordx4 v[118:121], v3, s[0:1] offset:1536
	s_waitcnt vmcnt(8)
	ds_write_b128 v2, v[114:117] offset:49152
	s_waitcnt lgkmcnt(10)
	v_mfma_f32_16x16x32_bf16 v[26:29], v[170:173], v[166:169], v[26:29]
	s_waitcnt lgkmcnt(1)
	v_mfma_f32_16x16x32_bf16 v[10:13], v[182:185], v[166:169], v[10:13]
	v_mfma_f32_16x16x32_bf16 v[86:89], v[174:177], v[166:169], v[86:89]
	v_mfma_f32_16x16x32_bf16 v[94:97], v[178:181], v[166:169], v[94:97]
	global_load_dwordx4 v[114:117], v231, s[0:1] offset:1536
	v_mfma_f32_16x16x32_bf16 v[30:33], v[170:173], v[98:101], v[30:33]
	s_waitcnt vmcnt(8)
	ds_write_b128 v2, v[122:125] offset:53248
	v_mfma_f32_16x16x32_bf16 v[42:45], v[174:177], v[98:101], v[42:45]
	v_mfma_f32_16x16x32_bf16 v[14:17], v[182:185], v[98:101], v[14:17]
	v_mfma_f32_16x16x32_bf16 v[90:93], v[178:181], v[98:101], v[90:93]
	global_load_dwordx4 v[98:101], v232, s[0:1] offset:1536
	v_mfma_f32_16x16x32_bf16 v[34:37], v[170:173], v[110:113], v[34:37]
	s_waitcnt vmcnt(8)
	ds_write_b128 v2, v[82:85] offset:57344
	v_mfma_f32_16x16x32_bf16 v[46:49], v[174:177], v[110:113], v[46:49]
	v_mfma_f32_16x16x32_bf16 v[58:61], v[178:181], v[110:113], v[58:61]
	v_mfma_f32_16x16x32_bf16 v[18:21], v[182:185], v[110:113], v[18:21]
	global_load_dwordx4 v[82:85], v233, s[0:1] offset:1536
	v_mfma_f32_16x16x32_bf16 v[38:41], v[170:173], v[146:149], v[38:41]
	s_waitcnt vmcnt(8)
	ds_write_b128 v2, v[102:105] offset:61440
	v_mfma_f32_16x16x32_bf16 v[50:53], v[174:177], v[146:149], v[50:53]
	v_mfma_f32_16x16x32_bf16 v[54:57], v[178:181], v[146:149], v[54:57]
	v_mfma_f32_16x16x32_bf16 v[22:25], v[182:185], v[146:149], v[22:25]
	s_setprio 0
	s_waitcnt lgkmcnt(0)
	s_barrier
; template <int MODE>
; __device__ __forceinline__ void gemm_tile(const Params& P, int tm, int tn, unsigned char* smem) {
;     ...
; #pragma unroll
;         for (int i = 0; i < 4; ++i) { fa[i] = *(const bf16x8*)(sA + arow_off + i * 2048 + ch0); fb[i] = *(const bf16x8*)(sB + brow_off + i * 2048 + ch0); }
;         __builtin_amdgcn_sched_barrier(0);
;         __builtin_amdgcn_s_setprio(2);
;         if (wr_ok) *(uint4*)(nA + soff0) = ra0;
;         if (ld_ok) ra0 = *(const uint4*)(Ab + (aoff + 0u * LDA + koa));
;         ga[0] = *(const bf16x8*)(sA + arow_off + 0 * 2048 + ch1); gb[0] = *(const bf16x8*)(sB + brow_off + 0 * 2048 + ch1);
;         __builtin_amdgcn_sched_barrier(0);
; #pragma unroll
;         for (int j = 0; j < 4; ++j) acc[0][j] = __builtin_amdgcn_mfma_f32_16x16x32_bf16(fb[j], fa[0], acc[0][j], 0, 0, 0);
;         __builtin_amdgcn_sched_barrier(0);
;         if (wr_ok) *(uint4*)(nA + soff0 + 4096) = ra1;
;         if (ld_ok) ra1 = *(const uint4*)(Ab + (aoff + 32u * LDA + koa));
;         ga[1] = *(const bf16x8*)(sA + arow_off + 1 * 2048 + ch1); gb[1] = *(const bf16x8*)(sB + brow_off + 1 * 2048 + ch1);
;         __builtin_amdgcn_sched_barrier(0);
; #pragma unroll
;         for (int j = 0; j < 4; ++j) acc[1][j] = __builtin_amdgcn_mfma_f32_16x16x32_bf16(fb[j], fa[1], acc[1][j], 0, 0, 0);
;         __builtin_amdgcn_sched_barrier(0);
;         if (wr_ok) *(uint4*)(nA + soff0 + 8192) = ra2;
;         if (ld_ok) ra2 = *(const uint4*)(Ab + (aoff + 64u * LDA + koa));
;         ga[2] = *(const bf16x8*)(sA + arow_off + 2 * 2048 + ch1); gb[2] = *(const bf16x8*)(sB + brow_off + 2 * 2048 + ch1);
;         __builtin_amdgcn_sched_barrier(0);
; #pragma unroll
;         for (int j = 0; j < 4; ++j) acc[2][j] = __builtin_amdgcn_mfma_f32_16x16x32_bf16(fb[j], fa[2], acc[2][j], 0, 0, 0);
;         __builtin_amdgcn_sched_barrier(0);
;         if (wr_ok) *(uint4*)(nA + soff0 + 12288) = ra3;
;         if (ld_ok) ra3 = *(const uint4*)(Ab + (aoff + 96u * LDA + koa));
;         ga[3] = *(const bf16x8*)(sA + arow_off + 3 * 2048 + ch1); gb[3] = *(const bf16x8*)(sB + brow_off + 3 * 2048 + ch1);
;         __builtin_amdgcn_sched_barrier(0);
; #pragma unroll
;         for (int j = 0; j < 4; ++j) acc[3][j] = __builtin_amdgcn_mfma_f32_16x16x32_bf16(fb[j], fa[3], acc[3][j], 0, 0, 0);
;         __builtin_amdgcn_sched_barrier(0);
;         if (wr_ok) *(uint4*)(nB + soff0) = rb0;
	ds_read_b128 v[102:105], v6 offset:32768
	ds_read_b128 v[110:113], v6 offset:34816
	ds_read_b128 v[122:125], v7 offset:49152
	ds_read_b128 v[126:129], v7 offset:51200
	ds_read_b128 v[146:149], v6 offset:36864
	ds_read_b128 v[150:153], v6 offset:38912
	ds_read_b128 v[154:157], v7 offset:53248
	ds_read_b128 v[158:161], v7 offset:55296
	s_setprio 2
	global_load_dwordx4 v[166:169], v8, s[36:37] offset:1664
	s_waitcnt vmcnt(8)
	ds_write_b128 v2, v[162:165]
	ds_read_b128 v[162:165], v4 offset:32768
	ds_read_b128 v[170:173], v5 offset:49152
	s_waitcnt lgkmcnt(8)
	v_mfma_f32_16x16x32_bf16 v[26:29], v[122:125], v[102:105], v[26:29]
	s_waitcnt lgkmcnt(3)
	v_mfma_f32_16x16x32_bf16 v[10:13], v[158:161], v[102:105], v[10:13]
	v_mfma_f32_16x16x32_bf16 v[86:89], v[126:129], v[102:105], v[86:89]
	v_mfma_f32_16x16x32_bf16 v[94:97], v[154:157], v[102:105], v[94:97]
	global_load_dwordx4 v[102:105], v228, s[36:37] offset:1664
	v_mfma_f32_16x16x32_bf16 v[30:33], v[122:125], v[110:113], v[30:33]
	s_waitcnt vmcnt(8)
	ds_write_b128 v2, v[62:65] offset:4096
	v_mfma_f32_16x16x32_bf16 v[42:45], v[126:129], v[110:113], v[42:45]
	ds_read_b128 v[62:65], v4 offset:34816
	v_mfma_f32_16x16x32_bf16 v[14:17], v[158:161], v[110:113], v[14:17]
	ds_read_b128 v[174:177], v5 offset:51200
	v_mfma_f32_16x16x32_bf16 v[90:93], v[154:157], v[110:113], v[90:93]
	global_load_dwordx4 v[110:113], v229, s[36:37] offset:1664
	v_mfma_f32_16x16x32_bf16 v[34:37], v[122:125], v[146:149], v[34:37]
	s_waitcnt vmcnt(8)
	ds_write_b128 v2, v[106:109] offset:8192
	v_mfma_f32_16x16x32_bf16 v[46:49], v[126:129], v[146:149], v[46:49]
	ds_read_b128 v[106:109], v4 offset:36864
	v_mfma_f32_16x16x32_bf16 v[58:61], v[154:157], v[146:149], v[58:61]
	ds_read_b128 v[178:181], v5 offset:53248
	v_mfma_f32_16x16x32_bf16 v[18:21], v[158:161], v[146:149], v[18:21]
	global_load_dwordx4 v[146:149], v230, s[36:37] offset:1664
	v_mfma_f32_16x16x32_bf16 v[38:41], v[122:125], v[150:153], v[38:41]
	s_waitcnt vmcnt(8)
	ds_write_b128 v2, v[132:135] offset:12288
	v_mfma_f32_16x16x32_bf16 v[50:53], v[126:129], v[150:153], v[50:53]
	ds_read_b128 v[132:135], v4 offset:38912
	v_mfma_f32_16x16x32_bf16 v[54:57], v[154:157], v[150:153], v[54:57]
	ds_read_b128 v[182:185], v5 offset:55296
	v_mfma_f32_16x16x32_bf16 v[22:25], v[158:161], v[150:153], v[22:25]
	global_load_dwordx4 v[122:125], v3, s[0:1] offset:1664
	s_waitcnt vmcnt(8)
	ds_write_b128 v2, v[118:121] offset:16384
	s_waitcnt lgkmcnt(10)
	v_mfma_f32_16x16x32_bf16 v[26:29], v[170:173], v[162:165], v[26:29]
	s_waitcnt lgkmcnt(1)
	v_mfma_f32_16x16x32_bf16 v[10:13], v[182:185], v[162:165], v[10:13]
	v_mfma_f32_16x16x32_bf16 v[86:89], v[174:177], v[162:165], v[86:89]
	v_mfma_f32_16x16x32_bf16 v[94:97], v[178:181], v[162:165], v[94:97]
	global_load_dwordx4 v[118:121], v231, s[0:1] offset:1664
	v_mfma_f32_16x16x32_bf16 v[30:33], v[170:173], v[62:65], v[30:33]
	s_waitcnt vmcnt(8)
	ds_write_b128 v2, v[114:117] offset:20480
	v_mfma_f32_16x16x32_bf16 v[42:45], v[174:177], v[62:65], v[42:45]
	v_mfma_f32_16x16x32_bf16 v[14:17], v[182:185], v[62:65], v[14:17]
	v_mfma_f32_16x16x32_bf16 v[90:93], v[178:181], v[62:65], v[90:93]
	global_load_dwordx4 v[62:65], v232, s[0:1] offset:1664
	v_mfma_f32_16x16x32_bf16 v[34:37], v[170:173], v[106:109], v[34:37]
	s_waitcnt vmcnt(8)
	ds_write_b128 v2, v[98:101] offset:24576
	v_mfma_f32_16x16x32_bf16 v[46:49], v[174:177], v[106:109], v[46:49]
	v_mfma_f32_16x16x32_bf16 v[58:61], v[178:181], v[106:109], v[58:61]
	v_mfma_f32_16x16x32_bf16 v[18:21], v[182:185], v[106:109], v[18:21]
	global_load_dwordx4 v[98:101], v233, s[0:1] offset:1664
	v_mfma_f32_16x16x32_bf16 v[38:41], v[170:173], v[132:135], v[38:41]
	s_waitcnt vmcnt(8)
	ds_write_b128 v2, v[82:85] offset:28672
	v_mfma_f32_16x16x32_bf16 v[50:53], v[174:177], v[132:135], v[50:53]
	v_mfma_f32_16x16x32_bf16 v[54:57], v[178:181], v[132:135], v[54:57]
	v_mfma_f32_16x16x32_bf16 v[22:25], v[182:185], v[132:135], v[22:25]
	s_setprio 0
	s_waitcnt lgkmcnt(0)
	s_barrier
	ds_read_b128 v[82:85], v6
	ds_read_b128 v[106:109], v6 offset:2048
	ds_read_b128 v[114:117], v7 offset:16384
	ds_read_b128 v[126:129], v7 offset:18432
	ds_read_b128 v[132:135], v6 offset:4096
	ds_read_b128 v[150:153], v6 offset:6144
	ds_read_b128 v[154:157], v7 offset:20480
	ds_read_b128 v[158:161], v7 offset:22528
	s_setprio 2
	global_load_dwordx4 v[162:165], v8, s[36:37] offset:1792
	s_waitcnt vmcnt(8)
	ds_write_b128 v2, v[166:169] offset:32768
	ds_read_b128 v[166:169], v4
	ds_read_b128 v[170:173], v5 offset:16384
	s_waitcnt lgkmcnt(8)
	v_mfma_f32_16x16x32_bf16 v[26:29], v[114:117], v[82:85], v[26:29]
	s_waitcnt lgkmcnt(3)
	v_mfma_f32_16x16x32_bf16 v[10:13], v[158:161], v[82:85], v[10:13]
	v_mfma_f32_16x16x32_bf16 v[86:89], v[126:129], v[82:85], v[86:89]
	v_mfma_f32_16x16x32_bf16 v[94:97], v[154:157], v[82:85], v[94:97]
	global_load_dwordx4 v[82:85], v228, s[36:37] offset:1792
	v_mfma_f32_16x16x32_bf16 v[30:33], v[114:117], v[106:109], v[30:33]
	s_waitcnt vmcnt(8)
	ds_write_b128 v2, v[102:105] offset:36864
	v_mfma_f32_16x16x32_bf16 v[42:45], v[126:129], v[106:109], v[42:45]
	ds_read_b128 v[102:105], v4 offset:2048
	v_mfma_f32_16x16x32_bf16 v[14:17], v[158:161], v[106:109], v[14:17]
	ds_read_b128 v[174:177], v5 offset:18432
	v_mfma_f32_16x16x32_bf16 v[90:93], v[154:157], v[106:109], v[90:93]
	global_load_dwordx4 v[106:109], v229, s[36:37] offset:1792
	v_mfma_f32_16x16x32_bf16 v[34:37], v[114:117], v[132:135], v[34:37]
	s_waitcnt vmcnt(8)
; template <int MODE>
; __device__ __forceinline__ void gemm_tile(const Params& P, int tm, int tn, unsigned char* smem) {
;     ...
; #pragma unroll
;         for (int i = 0; i < 4; ++i) { fa[i] = *(const bf16x8*)(sA + arow_off + i * 2048 + ch0); fb[i] = *(const bf16x8*)(sB + brow_off + i * 2048 + ch0); }
;         __builtin_amdgcn_sched_barrier(0);
;         __builtin_amdgcn_s_setprio(2);
;         if (wr_ok) *(uint4*)(nA + soff0) = ra0;
;         if (ld_ok) ra0 = *(const uint4*)(Ab + (aoff + 0u * LDA + koa));
;         ga[0] = *(const bf16x8*)(sA + arow_off + 0 * 2048 + ch1); gb[0] = *(const bf16x8*)(sB + brow_off + 0 * 2048 + ch1);
;         __builtin_amdgcn_sched_barrier(0);
; #pragma unroll
;         for (int j = 0; j < 4; ++j) acc[0][j] = __builtin_amdgcn_mfma_f32_16x16x32_bf16(fb[j], fa[0], acc[0][j], 0, 0, 0);
;         __builtin_amdgcn_sched_barrier(0);
;         if (wr_ok) *(uint4*)(nA + soff0 + 4096) = ra1;
;         if (ld_ok) ra1 = *(const uint4*)(Ab + (aoff + 32u * LDA + koa));
;         ga[1] = *(const bf16x8*)(sA + arow_off + 1 * 2048 + ch1); gb[1] = *(const bf16x8*)(sB + brow_off + 1 * 2048 + ch1);
;         __builtin_amdgcn_sched_barrier(0);
; #pragma unroll
;         for (int j = 0; j < 4; ++j) acc[1][j] = __builtin_amdgcn_mfma_f32_16x16x32_bf16(fb[j], fa[1], acc[1][j], 0, 0, 0);
;         __builtin_amdgcn_sched_barrier(0);
;         if (wr_ok) *(uint4*)(nA + soff0 + 8192) = ra2;
;         if (ld_ok) ra2 = *(const uint4*)(Ab + (aoff + 64u * LDA + koa));
;         ga[2] = *(const bf16x8*)(sA + arow_off + 2 * 2048 + ch1); gb[2] = *(const bf16x8*)(sB + brow_off + 2 * 2048 + ch1);
;         __builtin_amdgcn_sched_barrier(0);
; #pragma unroll
;         for (int j = 0; j < 4; ++j) acc[2][j] = __builtin_amdgcn_mfma_f32_16x16x32_bf16(fb[j], fa[2], acc[2][j], 0, 0, 0);
;         __builtin_amdgcn_sched_barrier(0);
;         if (wr_ok) *(uint4*)(nA + soff0 + 12288) = ra3;
;         if (ld_ok) ra3 = *(const uint4*)(Ab + (aoff + 96u * LDA + koa));
;         ga[3] = *(const bf16x8*)(sA + arow_off + 3 * 2048 + ch1); gb[3] = *(const bf16x8*)(sB + brow_off + 3 * 2048 + ch1);
;         __builtin_amdgcn_sched_barrier(0);
; #pragma unroll
;         for (int j = 0; j < 4; ++j) acc[3][j] = __builtin_amdgcn_mfma_f32_16x16x32_bf16(fb[j], fa[3], acc[3][j], 0, 0, 0);
;         __builtin_amdgcn_sched_barrier(0);
;         if (wr_ok) *(uint4*)(nB + soff0) = rb0;
	ds_write_b128 v2, v[110:113] offset:40960
	v_mfma_f32_16x16x32_bf16 v[46:49], v[126:129], v[132:135], v[46:49]
	ds_read_b128 v[110:113], v4 offset:4096
	v_mfma_f32_16x16x32_bf16 v[58:61], v[154:157], v[132:135], v[58:61]
	ds_read_b128 v[178:181], v5 offset:20480
	v_mfma_f32_16x16x32_bf16 v[18:21], v[158:161], v[132:135], v[18:21]
	global_load_dwordx4 v[132:135], v230, s[36:37] offset:1792
	v_mfma_f32_16x16x32_bf16 v[38:41], v[114:117], v[150:153], v[38:41]
	s_waitcnt vmcnt(8)
	ds_write_b128 v2, v[146:149] offset:45056
	v_mfma_f32_16x16x32_bf16 v[50:53], v[126:129], v[150:153], v[50:53]
	ds_read_b128 v[146:149], v4 offset:6144
	v_mfma_f32_16x16x32_bf16 v[54:57], v[154:157], v[150:153], v[54:57]
	ds_read_b128 v[182:185], v5 offset:22528
	v_mfma_f32_16x16x32_bf16 v[22:25], v[158:161], v[150:153], v[22:25]
	global_load_dwordx4 v[114:117], v3, s[0:1] offset:1792
	s_waitcnt vmcnt(8)
	ds_write_b128 v2, v[122:125] offset:49152
	s_waitcnt lgkmcnt(10)
	v_mfma_f32_16x16x32_bf16 v[26:29], v[170:173], v[166:169], v[26:29]
	s_waitcnt lgkmcnt(1)
	v_mfma_f32_16x16x32_bf16 v[10:13], v[182:185], v[166:169], v[10:13]
	v_mfma_f32_16x16x32_bf16 v[86:89], v[174:177], v[166:169], v[86:89]
	v_mfma_f32_16x16x32_bf16 v[94:97], v[178:181], v[166:169], v[94:97]
	global_load_dwordx4 v[122:125], v231, s[0:1] offset:1792
	v_mfma_f32_16x16x32_bf16 v[30:33], v[170:173], v[102:105], v[30:33]
	s_waitcnt vmcnt(8)
	ds_write_b128 v2, v[118:121] offset:53248
	v_mfma_f32_16x16x32_bf16 v[42:45], v[174:177], v[102:105], v[42:45]
	v_mfma_f32_16x16x32_bf16 v[14:17], v[182:185], v[102:105], v[14:17]
	v_mfma_f32_16x16x32_bf16 v[90:93], v[178:181], v[102:105], v[90:93]
	global_load_dwordx4 v[102:105], v232, s[0:1] offset:1792
	v_mfma_f32_16x16x32_bf16 v[34:37], v[170:173], v[110:113], v[34:37]
	s_waitcnt vmcnt(8)
	ds_write_b128 v2, v[62:65] offset:57344
	v_mfma_f32_16x16x32_bf16 v[46:49], v[174:177], v[110:113], v[46:49]
	v_mfma_f32_16x16x32_bf16 v[58:61], v[178:181], v[110:113], v[58:61]
	v_mfma_f32_16x16x32_bf16 v[18:21], v[182:185], v[110:113], v[18:21]
	global_load_dwordx4 v[62:65], v233, s[0:1] offset:1792
	v_mfma_f32_16x16x32_bf16 v[38:41], v[170:173], v[146:149], v[38:41]
	s_waitcnt vmcnt(8)
	ds_write_b128 v2, v[98:101] offset:61440
	v_mfma_f32_16x16x32_bf16 v[50:53], v[174:177], v[146:149], v[50:53]
	v_mfma_f32_16x16x32_bf16 v[54:57], v[178:181], v[146:149], v[54:57]
	v_mfma_f32_16x16x32_bf16 v[22:25], v[182:185], v[146:149], v[22:25]
	s_setprio 0
	s_waitcnt lgkmcnt(0)
	s_barrier
	ds_read_b128 v[98:101], v6 offset:32768
	ds_read_b128 v[110:113], v6 offset:34816
	ds_read_b128 v[118:121], v7 offset:49152
	ds_read_b128 v[126:129], v7 offset:51200
	ds_read_b128 v[146:149], v6 offset:36864
	ds_read_b128 v[150:153], v6 offset:38912
	ds_read_b128 v[154:157], v7 offset:53248
	ds_read_b128 v[158:161], v7 offset:55296
	s_setprio 2
	global_load_dwordx4 v[166:169], v8, s[36:37] offset:1920
	s_waitcnt vmcnt(8)
	ds_write_b128 v2, v[162:165]
	ds_read_b128 v[162:165], v4 offset:32768
	ds_read_b128 v[170:173], v5 offset:49152
	s_waitcnt lgkmcnt(8)
	v_mfma_f32_16x16x32_bf16 v[26:29], v[118:121], v[98:101], v[26:29]
	s_waitcnt lgkmcnt(3)
	v_mfma_f32_16x16x32_bf16 v[10:13], v[158:161], v[98:101], v[10:13]
	v_mfma_f32_16x16x32_bf16 v[86:89], v[126:129], v[98:101], v[86:89]
	v_mfma_f32_16x16x32_bf16 v[94:97], v[154:157], v[98:101], v[94:97]
	global_load_dwordx4 v[98:101], v228, s[36:37] offset:1920
	v_mfma_f32_16x16x32_bf16 v[30:33], v[118:121], v[110:113], v[30:33]
	s_waitcnt vmcnt(8)
	ds_write_b128 v2, v[82:85] offset:4096
	v_mfma_f32_16x16x32_bf16 v[42:45], v[126:129], v[110:113], v[42:45]
	ds_read_b128 v[82:85], v4 offset:34816
	v_mfma_f32_16x16x32_bf16 v[14:17], v[158:161], v[110:113], v[14:17]
	ds_read_b128 v[174:177], v5 offset:51200
	v_mfma_f32_16x16x32_bf16 v[90:93], v[154:157], v[110:113], v[90:93]
	global_load_dwordx4 v[110:113], v229, s[36:37] offset:1920
	v_mfma_f32_16x16x32_bf16 v[34:37], v[118:121], v[146:149], v[34:37]
	s_waitcnt vmcnt(8)
	ds_write_b128 v2, v[106:109] offset:8192
	v_mfma_f32_16x16x32_bf16 v[46:49], v[126:129], v[146:149], v[46:49]
	ds_read_b128 v[106:109], v4 offset:36864
	v_mfma_f32_16x16x32_bf16 v[58:61], v[154:157], v[146:149], v[58:61]
	ds_read_b128 v[178:181], v5 offset:53248
	v_mfma_f32_16x16x32_bf16 v[18:21], v[158:161], v[146:149], v[18:21]
	v_add_u32_e32 v8, 0x30780, v8
	global_load_dwordx4 v[146:149], v8, s[36:37]
	s_waitcnt vmcnt(8)
	ds_write_b128 v2, v[132:135] offset:12288
	ds_read_b128 v[132:135], v4 offset:38912
	ds_read_b128 v[182:185], v5 offset:55296
	v_mfma_f32_16x16x32_bf16 v[38:41], v[118:121], v[150:153], v[38:41]
	v_mfma_f32_16x16x32_bf16 v[50:53], v[126:129], v[150:153], v[50:53]
	v_mfma_f32_16x16x32_bf16 v[54:57], v[154:157], v[150:153], v[54:57]
	v_mfma_f32_16x16x32_bf16 v[22:25], v[158:161], v[150:153], v[22:25]
	global_load_dwordx4 v[118:121], v3, s[0:1] offset:1920
	s_waitcnt vmcnt(8)
	ds_write_b128 v2, v[114:117] offset:16384
	s_waitcnt lgkmcnt(10)
	v_mfma_f32_16x16x32_bf16 v[26:29], v[170:173], v[162:165], v[26:29]
	s_waitcnt lgkmcnt(1)
	v_mfma_f32_16x16x32_bf16 v[8:11], v[182:185], v[162:165], v[10:13]
	v_mfma_f32_16x16x32_bf16 v[86:89], v[174:177], v[162:165], v[86:89]
	v_mfma_f32_16x16x32_bf16 v[94:97], v[178:181], v[162:165], v[94:97]
	s_nop 0
	global_load_dwordx4 v[114:117], v231, s[0:1] offset:1920
	s_waitcnt vmcnt(8)
	ds_write_b128 v2, v[122:125] offset:20480
	v_mfma_f32_16x16x32_bf16 v[30:33], v[170:173], v[82:85], v[30:33]
	v_mfma_f32_16x16x32_bf16 v[42:45], v[174:177], v[82:85], v[42:45]
	v_mfma_f32_16x16x32_bf16 v[12:15], v[182:185], v[82:85], v[14:17]
	v_mfma_f32_16x16x32_bf16 v[90:93], v[178:181], v[82:85], v[90:93]
	s_nop 1
	global_load_dwordx4 v[82:85], v232, s[0:1] offset:1920
	s_waitcnt vmcnt(8)
	ds_write_b128 v2, v[102:105] offset:24576
	v_mfma_f32_16x16x32_bf16 v[34:37], v[170:173], v[106:109], v[34:37]
	v_mfma_f32_16x16x32_bf16 v[46:49], v[174:177], v[106:109], v[46:49]
	v_mfma_f32_16x16x32_bf16 v[58:61], v[178:181], v[106:109], v[58:61]
	v_mfma_f32_16x16x32_bf16 v[16:19], v[182:185], v[106:109], v[18:21]
	v_add_u32_e32 v3, 0x30780, v3
	global_load_dwordx4 v[102:105], v3, s[0:1]
	s_waitcnt vmcnt(8)
	ds_write_b128 v2, v[62:65] offset:28672
	v_mfma_f32_16x16x32_bf16 v[38:41], v[170:173], v[132:135], v[38:41]
	v_mfma_f32_16x16x32_bf16 v[50:53], v[174:177], v[132:135], v[50:53]
	v_mfma_f32_16x16x32_bf16 v[54:57], v[178:181], v[132:135], v[54:57]
	v_mfma_f32_16x16x32_bf16 v[20:23], v[182:185], v[132:135], v[22:25]
	s_setprio 0
	s_waitcnt lgkmcnt(0)
	s_barrier
; template <int MODE>
; __device__ __forceinline__ void gemm_tile(const Params& P, int tm, int tn, unsigned char* smem) {
;     ...
; #pragma unroll
;         for (int i = 0; i < 4; ++i) { fa[i] = *(const bf16x8*)(sA + arow_off + i * 2048 + ch0); fb[i] = *(const bf16x8*)(sB + brow_off + i * 2048 + ch0); }
;         __builtin_amdgcn_sched_barrier(0);
;         __builtin_amdgcn_s_setprio(2);
;         if (wr_ok) *(uint4*)(nA + soff0) = ra0;
;         if (ld_ok) ra0 = *(const uint4*)(Ab + (aoff + 0u * LDA + koa));
;         ga[0] = *(const bf16x8*)(sA + arow_off + 0 * 2048 + ch1); gb[0] = *(const bf16x8*)(sB + brow_off + 0 * 2048 + ch1);
;         __builtin_amdgcn_sched_barrier(0);
; #pragma unroll
;         for (int j = 0; j < 4; ++j) acc[0][j] = __builtin_amdgcn_mfma_f32_16x16x32_bf16(fb[j], fa[0], acc[0][j], 0, 0, 0);
;         __builtin_amdgcn_sched_barrier(0);
;         if (wr_ok) *(uint4*)(nA + soff0 + 4096) = ra1;
;         if (ld_ok) ra1 = *(const uint4*)(Ab + (aoff + 32u * LDA + koa));
;         ga[1] = *(const bf16x8*)(sA + arow_off + 1 * 2048 + ch1); gb[1] = *(const bf16x8*)(sB + brow_off + 1 * 2048 + ch1);
;         __builtin_amdgcn_sched_barrier(0);
; #pragma unroll
;         for (int j = 0; j < 4; ++j) acc[1][j] = __builtin_amdgcn_mfma_f32_16x16x32_bf16(fb[j], fa[1], acc[1][j], 0, 0, 0);
;         __builtin_amdgcn_sched_barrier(0);
;         if (wr_ok) *(uint4*)(nA + soff0 + 8192) = ra2;
;         if (ld_ok) ra2 = *(const uint4*)(Ab + (aoff + 64u * LDA + koa));
;         ga[2] = *(const bf16x8*)(sA + arow_off + 2 * 2048 + ch1); gb[2] = *(const bf16x8*)(sB + brow_off + 2 * 2048 + ch1);
;         __builtin_amdgcn_sched_barrier(0);
; #pragma unroll
;         for (int j = 0; j < 4; ++j) acc[2][j] = __builtin_amdgcn_mfma_f32_16x16x32_bf16(fb[j], fa[2], acc[2][j], 0, 0, 0);
;         __builtin_amdgcn_sched_barrier(0);
;         if (wr_ok) *(uint4*)(nA + soff0 + 12288) = ra3;
;         if (ld_ok) ra3 = *(const uint4*)(Ab + (aoff + 96u * LDA + koa));
;         ga[3] = *(const bf16x8*)(sA + arow_off + 3 * 2048 + ch1); gb[3] = *(const bf16x8*)(sB + brow_off + 3 * 2048 + ch1);
;         __builtin_amdgcn_sched_barrier(0);
; #pragma unroll
;         for (int j = 0; j < 4; ++j) acc[3][j] = __builtin_amdgcn_mfma_f32_16x16x32_bf16(fb[j], fa[3], acc[3][j], 0, 0, 0);
;         __builtin_amdgcn_sched_barrier(0);
;         if (wr_ok) *(uint4*)(nB + soff0) = rb0;
	ds_read_b128 v[62:65], v6
	ds_read_b128 v[106:109], v6 offset:2048
	ds_read_b128 v[122:125], v7 offset:16384
	ds_read_b128 v[126:129], v7 offset:18432
	ds_read_b128 v[132:135], v6 offset:4096
	ds_read_b128 v[150:153], v6 offset:6144
	ds_read_b128 v[154:157], v7 offset:20480
	ds_read_b128 v[158:161], v7 offset:22528
	s_setprio 2
	s_waitcnt vmcnt(7)
	ds_write_b128 v2, v[166:169] offset:32768
	ds_read_b128 v[162:165], v4
	ds_read_b128 v[166:169], v5 offset:16384
	s_waitcnt lgkmcnt(8)
	v_mfma_f32_16x16x32_bf16 v[24:27], v[122:125], v[62:65], v[26:29]
	s_waitcnt lgkmcnt(3)
	v_mfma_f32_16x16x32_bf16 v[8:11], v[158:161], v[62:65], v[8:11]
	v_mfma_f32_16x16x32_bf16 v[86:89], v[126:129], v[62:65], v[86:89]
	v_mfma_f32_16x16x32_bf16 v[94:97], v[154:157], v[62:65], v[94:97]
	v_mfma_f32_16x16x32_bf16 v[28:31], v[122:125], v[106:109], v[30:33]
	s_waitcnt vmcnt(6)
	ds_write_b128 v2, v[98:101] offset:36864
	v_mfma_f32_16x16x32_bf16 v[42:45], v[126:129], v[106:109], v[42:45]
	ds_read_b128 v[62:65], v4 offset:2048
	v_mfma_f32_16x16x32_bf16 v[12:15], v[158:161], v[106:109], v[12:15]
	ds_read_b128 v[98:101], v5 offset:18432
	v_mfma_f32_16x16x32_bf16 v[90:93], v[154:157], v[106:109], v[90:93]
	v_mfma_f32_16x16x32_bf16 v[32:35], v[122:125], v[132:135], v[34:37]
	s_waitcnt vmcnt(5)
	ds_write_b128 v2, v[110:113] offset:40960
	v_mfma_f32_16x16x32_bf16 v[46:49], v[126:129], v[132:135], v[46:49]
	ds_read_b128 v[106:109], v4 offset:4096
	v_mfma_f32_16x16x32_bf16 v[58:61], v[154:157], v[132:135], v[58:61]
	ds_read_b128 v[110:113], v5 offset:20480
	v_mfma_f32_16x16x32_bf16 v[16:19], v[158:161], v[132:135], v[16:19]
	v_mfma_f32_16x16x32_bf16 v[36:39], v[122:125], v[150:153], v[38:41]
	s_waitcnt vmcnt(4)
	ds_write_b128 v2, v[146:149] offset:45056
	v_mfma_f32_16x16x32_bf16 v[50:53], v[126:129], v[150:153], v[50:53]
	ds_read_b128 v[132:135], v4 offset:6144
	v_mfma_f32_16x16x32_bf16 v[54:57], v[154:157], v[150:153], v[54:57]
	ds_read_b128 v[146:149], v5 offset:22528
	v_mfma_f32_16x16x32_bf16 v[20:23], v[158:161], v[150:153], v[20:23]
	s_waitcnt vmcnt(3)
	ds_write_b128 v2, v[118:121] offset:49152
	s_waitcnt lgkmcnt(10)
	v_mfma_f32_16x16x32_bf16 v[24:27], v[166:169], v[162:165], v[24:27]
	s_waitcnt lgkmcnt(1)
	v_mfma_f32_16x16x32_bf16 v[8:11], v[146:149], v[162:165], v[8:11]
	v_mfma_f32_16x16x32_bf16 v[86:89], v[98:101], v[162:165], v[86:89]
	v_mfma_f32_16x16x32_bf16 v[94:97], v[110:113], v[162:165], v[94:97]
	v_mfma_f32_16x16x32_bf16 v[28:31], v[166:169], v[62:65], v[28:31]
	s_waitcnt vmcnt(2)
	ds_write_b128 v2, v[114:117] offset:53248
	v_mfma_f32_16x16x32_bf16 v[40:43], v[98:101], v[62:65], v[42:45]
	v_mfma_f32_16x16x32_bf16 v[12:15], v[146:149], v[62:65], v[12:15]
	v_mfma_f32_16x16x32_bf16 v[90:93], v[110:113], v[62:65], v[90:93]
	v_mfma_f32_16x16x32_bf16 v[32:35], v[166:169], v[106:109], v[32:35]
	s_waitcnt vmcnt(1)
	ds_write_b128 v2, v[82:85] offset:57344
	v_mfma_f32_16x16x32_bf16 v[44:47], v[98:101], v[106:109], v[46:49]
	v_mfma_f32_16x16x32_bf16 v[58:61], v[110:113], v[106:109], v[58:61]
	v_mfma_f32_16x16x32_bf16 v[16:19], v[146:149], v[106:109], v[16:19]
	v_mfma_f32_16x16x32_bf16 v[36:39], v[166:169], v[132:135], v[36:39]
	s_waitcnt vmcnt(0)
	ds_write_b128 v2, v[102:105] offset:61440
	v_mfma_f32_16x16x32_bf16 v[48:51], v[98:101], v[132:135], v[50:53]
	v_mfma_f32_16x16x32_bf16 v[52:55], v[110:113], v[132:135], v[54:57]
	v_mfma_f32_16x16x32_bf16 v[20:23], v[146:149], v[132:135], v[20:23]
	s_setprio 0
	s_waitcnt lgkmcnt(0)
	s_barrier
	ds_read_b128 v[62:65], v6 offset:32768
	ds_read_b128 v[82:85], v6 offset:34816
	ds_read_b128 v[98:101], v7 offset:49152
	ds_read_b128 v[102:105], v7 offset:51200
	ds_read_b128 v[106:109], v6 offset:36864
	ds_read_b128 v[110:113], v6 offset:38912
	ds_read_b128 v[114:117], v7 offset:53248
	ds_read_b128 v[118:121], v7 offset:55296
	s_setprio 2
	ds_read_b128 v[122:125], v4 offset:32768
	ds_read_b128 v[126:129], v5 offset:49152
	s_waitcnt lgkmcnt(7)
	v_mfma_f32_16x16x32_bf16 v[24:27], v[98:101], v[62:65], v[24:27]
	s_waitcnt lgkmcnt(2)
	v_mfma_f32_16x16x32_bf16 v[6:9], v[118:121], v[62:65], v[8:11]
	v_mfma_f32_16x16x32_bf16 v[86:89], v[102:105], v[62:65], v[86:89]
	v_mfma_f32_16x16x32_bf16 v[94:97], v[114:117], v[62:65], v[94:97]
	v_mfma_f32_16x16x32_bf16 v[28:31], v[98:101], v[82:85], v[28:31]
	ds_read_b128 v[132:135], v4 offset:34816
	v_mfma_f32_16x16x32_bf16 v[40:43], v[102:105], v[82:85], v[40:43]
	ds_read_b128 v[146:149], v5 offset:51200
	v_mfma_f32_16x16x32_bf16 v[10:13], v[118:121], v[82:85], v[12:15]
	v_mfma_f32_16x16x32_bf16 v[90:93], v[114:117], v[82:85], v[90:93]
	v_mfma_f32_16x16x32_bf16 v[14:17], v[118:121], v[106:109], v[16:19]
	ds_read_b128 v[82:85], v4 offset:36864
	v_mfma_f32_16x16x32_bf16 v[154:157], v[98:101], v[106:109], v[32:35]
	ds_read_b128 v[150:153], v5 offset:53248
	v_mfma_f32_16x16x32_bf16 v[158:161], v[102:105], v[106:109], v[44:47]
	v_mfma_f32_16x16x32_bf16 v[162:165], v[114:117], v[106:109], v[58:61]
	v_mfma_f32_16x16x32_bf16 v[98:101], v[98:101], v[110:113], v[36:39]
	ds_read_b128 v[106:109], v4 offset:38912
	v_mfma_f32_16x16x32_bf16 v[102:105], v[102:105], v[110:113], v[48:51]
	ds_read_b128 v[2:5], v5 offset:55296
	v_mfma_f32_16x16x32_bf16 v[114:117], v[114:117], v[110:113], v[52:55]
	v_mfma_f32_16x16x32_bf16 v[110:113], v[118:121], v[110:113], v[20:23]
	s_waitcnt lgkmcnt(6)
	v_mfma_f32_16x16x32_bf16 v[62:65], v[126:129], v[122:125], v[24:27]
	s_waitcnt lgkmcnt(4)
	v_mfma_f32_16x16x32_bf16 v[58:61], v[146:149], v[122:125], v[86:89]
	s_waitcnt lgkmcnt(2)
	v_mfma_f32_16x16x32_bf16 v[54:57], v[150:153], v[122:125], v[94:97]
	s_waitcnt lgkmcnt(0)
	v_mfma_f32_16x16x32_bf16 v[50:53], v[2:5], v[122:125], v[6:9]
	v_mfma_f32_16x16x32_bf16 v[46:49], v[126:129], v[132:135], v[28:31]
	v_mfma_f32_16x16x32_bf16 v[42:45], v[146:149], v[132:135], v[40:43]
	v_mfma_f32_16x16x32_bf16 v[38:41], v[150:153], v[132:135], v[90:93]
	v_mfma_f32_16x16x32_bf16 v[34:37], v[2:5], v[132:135], v[10:13]
	v_mfma_f32_16x16x32_bf16 v[30:33], v[126:129], v[82:85], v[154:157]
	v_mfma_f32_16x16x32_bf16 v[26:29], v[146:149], v[82:85], v[158:161]
	v_mfma_f32_16x16x32_bf16 v[22:25], v[150:153], v[82:85], v[162:165]
	v_mfma_f32_16x16x32_bf16 v[18:21], v[2:5], v[82:85], v[14:17]
	v_mfma_f32_16x16x32_bf16 v[14:17], v[126:129], v[106:109], v[98:101]
	v_mfma_f32_16x16x32_bf16 v[10:13], v[146:149], v[106:109], v[102:105]
	v_mfma_f32_16x16x32_bf16 v[6:9], v[150:153], v[106:109], v[114:117]
	v_mfma_f32_16x16x32_bf16 v[2:5], v[2:5], v[106:109], v[110:113]
	s_setprio 0
	s_and_b32 s0, s5, -8
	s_cmp_lg_u32 s0, 16
	s_barrier
; template <int MODE>
; __device__ __forceinline__ void gemm_tile(const Params& P, int tm, int tn, unsigned char* smem) {
;     ...
;     if (MODE == 1) {
;         if (n0 >= ZC_FQ && n0 < ZC_FV) {
;             const bool isk = n0 >= ZC_FK;
;             const float* gain = isk ? P.f_k_norm : P.f_q_norm;
;             const float scl = isk ? 1.0f : 0.125f * LOG2E;
;             float gn[4][4];
; #pragma unroll
;             for (int j = 0; j < 4; ++j)
; #pragma unroll
;                 for (int r = 0; r < 4; ++r) gn[j][r] = gain[16 * j + 4 * g + r];
; #pragma unroll
;             for (int i = 0; i < 4; ++i) {
;                 float ss = 0.f;
; #pragma unroll
;                 for (int j = 0; j < 4; ++j)
; #pragma unroll
;                     for (int r = 0; r < 4; ++r) ss += acc[i][j][r] * acc[i][j][r];
;                 ss = x4_sum(ss);
;                 const float rstd = rsqrtf(ss * (1.0f / 64.0f) + EPS) * scl;
	s_cbranch_scc1 .LBB0_244
	v_mul_f32_e32 v68, v63, v63
	v_fmac_f32_e32 v68, v62, v62
	v_fmac_f32_e32 v68, v64, v64
	v_fmac_f32_e32 v68, v65, v65
	v_fmac_f32_e32 v68, v58, v58
	v_fmac_f32_e32 v68, v59, v59
	v_fmac_f32_e32 v68, v60, v60
	v_fmac_f32_e32 v68, v61, v61
	v_fmac_f32_e32 v68, v54, v54
	v_fmac_f32_e32 v68, v55, v55
	v_fmac_f32_e32 v68, v56, v56
	s_cmp_gt_u32 s5, 19
	v_fmac_f32_e32 v68, v57, v57
	v_pk_mul_f32 v[82:83], v[50:51], v[50:51]
	v_mov_b32_e32 v66, 0x3e38aa3b
	s_cselect_b64 s[0:1], -1, 0
	v_add_f32_e32 v68, v82, v68
	v_cndmask_b32_e64 v106, v66, 1.0, s[0:1]
	v_pk_mul_f32 v[66:67], v[52:53], v[52:53]
	v_add_f32_e32 v68, v83, v68
	v_add_f32_e32 v66, v66, v68
	v_add_f32_e32 v66, v67, v66
	v_mov_b32_e32 v67, v66
	s_nop 1
	v_permlane32_swap_b32_e32 v66, v67
	v_add_f32_e32 v67, v66, v67
	v_mul_f32_e32 v66, v47, v47
	v_fmac_f32_e32 v66, v46, v46
	v_fmac_f32_e32 v66, v48, v48
	v_fmac_f32_e32 v66, v49, v49
	v_fmac_f32_e32 v66, v42, v42
	v_fmac_f32_e32 v66, v43, v43
	v_fmac_f32_e32 v66, v44, v44
	v_fmac_f32_e32 v66, v45, v45
	v_fmac_f32_e32 v66, v38, v38
	v_fmac_f32_e32 v66, v39, v39
	v_fmac_f32_e32 v66, v40, v40
	v_fmac_f32_e32 v66, v41, v41
	v_pk_mul_f32 v[86:87], v[34:35], v[34:35]
	v_pk_mul_f32 v[84:85], v[36:37], v[36:37]
	v_add_f32_e32 v66, v86, v66
	v_add_f32_e32 v66, v87, v66
	v_add_f32_e32 v66, v84, v66
	v_add_f32_e32 v66, v85, v66
	v_mov_b32_e32 v68, v66
	s_nop 1
	v_permlane32_swap_b32_e32 v66, v68
	v_add_f32_e32 v66, v66, v68
	s_and_b64 s[0:1], s[0:1], exec
	v_mov_b32_e32 v83, v67
	v_mov_b32_e32 v82, v66
	s_nop 0
	v_permlane16_swap_b32_e32 v67, v83
	v_permlane16_swap_b32_e32 v66, v82
	s_mov_b32 s0, 0x358637bd
	v_pk_add_f32 v[82:83], v[66:67], v[82:83]
	s_mov_b32 s8, 0x3c800000
	v_mov_b64_e32 v[66:67], s[0:1]
	v_mul_f32_e32 v95, v31, v31
	v_pk_fma_f32 v[86:87], v[82:83], s[8:9], v[66:67] op_sel_hi:[1,0,0]
	s_mov_b32 s5, 0x800000
	v_fmac_f32_e32 v95, v30, v30
	v_mul_f32_e32 v68, 0x4b800000, v87
	v_cmp_gt_f32_e32 vcc, s5, v87
	v_fmac_f32_e32 v95, v32, v32
	v_fmac_f32_e32 v95, v33, v33
	v_cndmask_b32_e32 v68, v87, v68, vcc
	v_rsq_f32_e32 v68, v68
	v_mul_f32_e32 v70, 0x4b800000, v86
	v_cmp_gt_f32_e64 s[0:1], s5, v86
	v_fmac_f32_e32 v95, v26, v26
	v_fmac_f32_e32 v95, v27, v27
	v_cndmask_b32_e64 v70, v86, v70, s[0:1]
	v_rsq_f32_e32 v86, v70
	v_fmac_f32_e32 v95, v28, v28
	s_cselect_b32 s7, s41, s39
	s_cselect_b32 s6, s40, s38
	v_lshlrev_b32_e32 v94, 4, v81
	v_fmac_f32_e32 v95, v29, v29
	global_load_dwordx4 v[82:85], v94, s[6:7]
	v_mul_f32_e32 v70, 0x45800000, v68
	v_fmac_f32_e32 v95, v22, v22
	v_cndmask_b32_e32 v68, v68, v70, vcc
	v_fmac_f32_e32 v95, v23, v23
	v_mul_f32_e32 v70, v106, v68
	v_mul_f32_e32 v68, 0x45800000, v86
	v_fmac_f32_e32 v95, v24, v24
	v_cndmask_b32_e64 v68, v86, v68, s[0:1]
	global_load_dwordx4 v[86:89], v94, s[6:7] offset:64
	v_fmac_f32_e32 v95, v25, v25
	v_pk_mul_f32 v[92:93], v[18:19], v[18:19]
	v_pk_mul_f32 v[90:91], v[20:21], v[20:21]
	v_add_f32_e32 v92, v92, v95
	v_add_f32_e32 v92, v93, v92
	v_add_f32_e32 v90, v90, v92
	v_add_f32_e32 v95, v91, v90
	global_load_dwordx4 v[90:93], v94, s[6:7] offset:128
	v_mov_b32_e32 v96, v95
	s_nop 1
	v_permlane32_swap_b32_e32 v95, v96
	v_add_f32_e32 v99, v95, v96
	global_load_dwordx4 v[94:97], v94, s[6:7] offset:192
	v_mul_f32_e32 v98, v15, v15
	v_fmac_f32_e32 v98, v14, v14
	v_fmac_f32_e32 v98, v16, v16
	v_fmac_f32_e32 v98, v17, v17
	v_fmac_f32_e32 v98, v10, v10
	v_fmac_f32_e32 v98, v11, v11
	v_fmac_f32_e32 v98, v12, v12
	v_fmac_f32_e32 v98, v13, v13
	v_fmac_f32_e32 v98, v6, v6
	v_fmac_f32_e32 v98, v7, v7
	v_fmac_f32_e32 v98, v8, v8
	v_fmac_f32_e32 v98, v9, v9
	v_pk_mul_f32 v[104:105], v[2:3], v[2:3]
	v_pk_mul_f32 v[102:103], v[4:5], v[4:5]
	v_add_f32_e32 v98, v104, v98
	v_add_f32_e32 v98, v105, v98
	v_add_f32_e32 v98, v102, v98
	v_add_f32_e32 v98, v103, v98
	v_mov_b32_e32 v100, v98
	s_nop 1
	v_permlane32_swap_b32_e32 v98, v100
	v_add_f32_e32 v98, v98, v100
	v_mov_b32_e32 v101, v99
	v_mov_b32_e32 v100, v98
	s_nop 0
	v_permlane16_swap_b32_e32 v99, v101
	v_permlane16_swap_b32_e32 v98, v100
	v_pk_add_f32 v[98:99], v[98:99], v[100:101]
	v_mul_f32_e32 v68, v106, v68
	v_pk_fma_f32 v[66:67], v[98:99], s[8:9], v[66:67] op_sel_hi:[1,0,0]
	s_waitcnt vmcnt(3)
; template <int MODE>
; __device__ __forceinline__ void gemm_tile(const Params& P, int tm, int tn, unsigned char* smem) {
;     ...
;                 const float rstd = rsqrtf(ss * (1.0f / 64.0f) + EPS) * scl;
; #pragma unroll
;                 for (int j = 0; j < 4; ++j)
; #pragma unroll
;                     for (int r = 0; r < 4; ++r) acc[i][j][r] *= rstd * gn[j][r];
	v_pk_mul_f32 v[100:101], v[82:83], v[70:71] op_sel_hi:[1,0]
	v_mul_f32_e32 v98, 0x4b800000, v67
	v_cmp_gt_f32_e32 vcc, s5, v67
	v_cmp_gt_f32_e64 s[0:1], s5, v66
	v_pk_mul_f32 v[62:63], v[62:63], v[100:101]
	v_cndmask_b32_e32 v67, v67, v98, vcc
	v_mul_f32_e32 v98, 0x4b800000, v66
	v_rsq_f32_e32 v67, v67
	v_cndmask_b32_e64 v66, v66, v98, s[0:1]
	v_rsq_f32_e32 v98, v66
	v_pk_mul_f32 v[100:101], v[82:83], v[68:69] op_sel_hi:[1,0]
	v_mul_f32_e32 v66, 0x45800000, v67
	v_cndmask_b32_e32 v66, v67, v66, vcc
	v_mul_f32_e32 v67, 0x45800000, v98
	v_cndmask_b32_e64 v67, v98, v67, s[0:1]
	v_mul_f32_e32 v66, v106, v66
	v_mul_f32_e32 v98, v106, v67
	v_pk_mul_f32 v[102:103], v[84:85], v[70:71] op_sel_hi:[1,0]
	v_pk_mul_f32 v[46:47], v[46:47], v[100:101]
	v_pk_mul_f32 v[100:101], v[82:83], v[66:67] op_sel_hi:[1,0]
	v_pk_mul_f32 v[82:83], v[82:83], v[98:99] op_sel_hi:[1,0]
	v_pk_mul_f32 v[64:65], v[64:65], v[102:103]
	v_pk_mul_f32 v[102:103], v[84:85], v[68:69] op_sel_hi:[1,0]
	v_pk_mul_f32 v[14:15], v[14:15], v[82:83]
	s_waitcnt vmcnt(2)
	v_pk_mul_f32 v[82:83], v[86:87], v[70:71] op_sel_hi:[1,0]
	v_pk_mul_f32 v[48:49], v[48:49], v[102:103]
	v_pk_mul_f32 v[102:103], v[84:85], v[66:67] op_sel_hi:[1,0]
	v_pk_mul_f32 v[84:85], v[84:85], v[98:99] op_sel_hi:[1,0]
	v_pk_mul_f32 v[58:59], v[58:59], v[82:83]
	v_pk_mul_f32 v[82:83], v[86:87], v[68:69] op_sel_hi:[1,0]
	v_pk_mul_f32 v[16:17], v[16:17], v[84:85]
	v_pk_mul_f32 v[84:85], v[88:89], v[70:71] op_sel_hi:[1,0]
	v_pk_mul_f32 v[42:43], v[42:43], v[82:83]
	v_pk_mul_f32 v[82:83], v[86:87], v[66:67] op_sel_hi:[1,0]
	v_pk_mul_f32 v[60:61], v[60:61], v[84:85]
	v_pk_mul_f32 v[84:85], v[88:89], v[68:69] op_sel_hi:[1,0]
	v_pk_mul_f32 v[26:27], v[26:27], v[82:83]
	v_pk_mul_f32 v[82:83], v[86:87], v[98:99] op_sel_hi:[1,0]
	v_pk_mul_f32 v[44:45], v[44:45], v[84:85]
	v_pk_mul_f32 v[84:85], v[88:89], v[66:67] op_sel_hi:[1,0]
	v_pk_mul_f32 v[10:11], v[10:11], v[82:83]
	s_waitcnt vmcnt(1)
	v_pk_mul_f32 v[82:83], v[90:91], v[70:71] op_sel_hi:[1,0]
	v_pk_mul_f32 v[28:29], v[28:29], v[84:85]
	v_pk_mul_f32 v[84:85], v[88:89], v[98:99] op_sel_hi:[1,0]
	v_pk_mul_f32 v[54:55], v[54:55], v[82:83]
	v_pk_mul_f32 v[82:83], v[90:91], v[68:69] op_sel_hi:[1,0]
	v_pk_mul_f32 v[12:13], v[12:13], v[84:85]
	v_pk_mul_f32 v[84:85], v[92:93], v[70:71] op_sel_hi:[1,0]
	v_pk_mul_f32 v[38:39], v[38:39], v[82:83]
	v_pk_mul_f32 v[82:83], v[90:91], v[66:67] op_sel_hi:[1,0]
	v_pk_mul_f32 v[56:57], v[56:57], v[84:85]
	v_pk_mul_f32 v[84:85], v[92:93], v[68:69] op_sel_hi:[1,0]
	v_pk_mul_f32 v[22:23], v[22:23], v[82:83]
	v_pk_mul_f32 v[82:83], v[90:91], v[98:99] op_sel_hi:[1,0]
	v_pk_mul_f32 v[40:41], v[40:41], v[84:85]
	v_pk_mul_f32 v[84:85], v[92:93], v[66:67] op_sel_hi:[1,0]
	v_pk_mul_f32 v[6:7], v[6:7], v[82:83]
	s_waitcnt vmcnt(0)
	v_pk_mul_f32 v[82:83], v[94:95], v[70:71] op_sel_hi:[1,0]
	v_pk_mul_f32 v[24:25], v[24:25], v[84:85]
	v_pk_mul_f32 v[84:85], v[92:93], v[98:99] op_sel_hi:[1,0]
	v_pk_mul_f32 v[50:51], v[50:51], v[82:83]
	v_pk_mul_f32 v[82:83], v[94:95], v[68:69] op_sel_hi:[1,0]
	v_pk_mul_f32 v[8:9], v[8:9], v[84:85]
	v_pk_mul_f32 v[84:85], v[96:97], v[70:71] op_sel_hi:[1,0]
	v_pk_mul_f32 v[34:35], v[34:35], v[82:83]
	v_pk_mul_f32 v[82:83], v[94:95], v[66:67] op_sel_hi:[1,0]
	v_pk_mul_f32 v[66:67], v[96:97], v[66:67] op_sel_hi:[1,0]
	v_pk_mul_f32 v[52:53], v[52:53], v[84:85]
	v_pk_mul_f32 v[84:85], v[96:97], v[68:69] op_sel_hi:[1,0]
	v_pk_mul_f32 v[20:21], v[20:21], v[66:67]
	v_pk_mul_f32 v[18:19], v[18:19], v[82:83]
	v_pk_mul_f32 v[66:67], v[94:95], v[98:99] op_sel_hi:[1,0]
	v_pk_mul_f32 v[82:83], v[96:97], v[98:99] op_sel_hi:[1,0]
	v_pk_mul_f32 v[32:33], v[32:33], v[102:103]
	v_pk_mul_f32 v[30:31], v[30:31], v[100:101]
	v_pk_mul_f32 v[36:37], v[36:37], v[84:85]
	v_pk_mul_f32 v[4:5], v[4:5], v[82:83]
	v_pk_mul_f32 v[2:3], v[2:3], v[66:67]

; template <int MODE>
; __device__ __forceinline__ void gemm_tile(const Params& P, int tm, int tn, unsigned char* smem) {
;     ...
;     const int tid = opaque_tid(), lane = tid & 63, wave = tid >> 6, wr = wave >> 1, wc = wave & 1, g = lane >> 4, lr = lane & 15;
;     const int m0 = tm * 128, n0 = tn * 128;
;     const int srow = tid >> 3, sc = tid & 7;
;     constexpr unsigned LDA = (MODE == 2 ? NZ : 1024) * 2u;
;     unsigned aoff, boff; int soff0;
;     {
;         int ar = m0 + srow;
;         if (MODE == 2) { const int b = ar >> 11, t = ar & 2047; ar = b * L + NMETA + t; }
;         aoff = (unsigned)ar * LDA + (unsigned)sc * 16u;
;         boff = (unsigned)(n0 + srow) * 2048u + (unsigned)sc * 16u;
;         soff0 = srow * 128 + ((sc ^ (srow & 7)) << 4);
;     }
;     const unsigned char* Ab = (const unsigned char*)A; const unsigned char* Bb = (const unsigned char*)Bt;
;     float4 ssp0, ssp1, ssp2, ssp3;
;     if (MODE == 3) {
;         const float* ssq = (const float*)(P.ws + WS_SSQ) + (size_t)(m0 + wr * 64 + lr) * 16 + 4 * g;
;         ssp0 = *(const float4*)(ssq); ssp1 = *(const float4*)(ssq + 16 * 16); ssp2 = *(const float4*)(ssq + 32 * 16); ssp3 = *(const float4*)(ssq + 48 * 16);
;     }
;     f32x4 acc[4][4];
; #pragma unroll
;     for (int i = 0; i < 4; ++i)
; #pragma unroll
;         for (int j = 0; j < 4; ++j) acc[i][j] = (f32x4){0.f, 0.f, 0.f, 0.f};
;     uint4 ra0, ra1, ra2, ra3, rb0, rb1, rb2, rb3;
;     ...
;     unsigned char* sA0 = smem; unsigned char* sB0 = smem + 16384; unsigned char* sA1 = smem + 32768; unsigned char* sB1 = smem + 49152;
;     G_LOAD(0)
;     G_WRITE(sA0, sB0)
;     __syncthreads();
;     const int arow_off = (wr * 64 + lr) * 128, brow_off = (wc * 64 + lr) * 128, sw = lr & 7;
;     G_LOAD(1)
;     for (int kt = 0; kt < 16; ++kt) {
;         unsigned char* sA = (kt & 1) ? sA1 : sA0; unsigned char* sB = (kt & 1) ? sB1 : sB0;
;         unsigned char* nA = (kt & 1) ? sA0 : sA1; unsigned char* nB = (kt & 1) ? sB0 : sB1;
;         bf16x8 fa[4], fb[4], ga[4], gb[4];
;         const int ch0 = ((g ^ sw) << 4), ch1 = (((4 + g) ^ sw) << 4);
;         const unsigned ko = (unsigned)(kt + 2) * 128u;
;         const unsigned koa = ko + ((MODE == 2 && kt + 2 >= 8) ? (unsigned)(ZC_FQ - 512) * 2u : 0u);
;         const bool wr_ok = kt < 15, ld_ok = kt < 14;
; #pragma unroll
.LBB0_1154:
	v_mov_b32_e32 v142, v0
	s_and_b32 s15, s9, 0xffffff80
	v_ashrrev_i32_e32 v2, 3, v142
	v_add_u32_e32 v3, s15, v2
	v_ashrrev_i32_e32 v4, 11, v3
	v_and_b32_e32 v3, 0x7ff, v3
	s_and_b32 s4, s6, 7
	v_mad_i32_i24 v3, v4, s11, v3
	v_lshlrev_b32_e32 v4, 4, v142
	s_lshl_b32 s18, s4, 7
	v_mul_lo_u32 v3, v3, s12
	v_and_b32_e32 v5, 0x70, v4
	v_add_u32_e32 v4, s18, v2
	v_or_b32_e32 v9, v3, v5
	v_lshl_or_b32 v4, v4, 11, v5
	v_add_u32_e32 v234, 0x1c000, v9
	global_load_dwordx4 v[10:13], v234, s[0:1]
	v_add_u32_e32 v3, 0x54000, v9
	v_add_u32_e32 v6, 0x20000, v4
	v_add_u32_e32 v5, 0x8c000, v9
	v_add_u32_e32 v7, 0x30000, v4
	global_load_dwordx4 v[14:17], v6, s[2:3]
	global_load_dwordx4 v[18:21], v7, s[2:3]
	global_load_dwordx4 v[22:25], v3, s[0:1]
	global_load_dwordx4 v[26:29], v5, s[0:1]
	v_add_u32_e32 v235, 0xc4000, v9
	global_load_dwordx4 v[30:33], v235, s[0:1]
	global_load_dwordx4 v[34:37], v4, s[2:3]
	v_add_u32_e32 v236, 0x10000, v4
	global_load_dwordx4 v[38:41], v236, s[2:3]
	v_xor_b32_e32 v3, v2, v142
	v_lshlrev_b32_e32 v2, 7, v2
	v_lshlrev_b32_e32 v3, 4, v3
	v_and_or_b32 v2, v3, s13, v2
	v_add_u32_e32 v3, 0, v2
	v_add_u32_e32 v2, 0x1c080, v9
	v_or_b32_e32 v5, 0x80, v4
	v_add_u32_e32 v6, 0x10080, v4
	v_add_u32_e32 v7, 0x20080, v4
	v_add_u32_e32 v8, 0x30080, v4
	v_add_u32_e32 v44, 0x54080, v9
	v_add_u32_e32 v45, 0x8c080, v9
	v_add_u32_e32 v46, 0xc4080, v9
	v_bfe_u32 v144, v142, 6, 1
	v_and_b32_e32 v143, 15, v142
	v_bfe_u32 v146, v142, 4, 2
	s_waitcnt vmcnt(6)
	ds_write_b128 v3, v[14:17] offset:24576
	s_waitcnt vmcnt(5)
	ds_write_b128 v3, v[18:21] offset:28672
	ds_write_b128 v3, v[10:13]
	s_waitcnt vmcnt(4)
	ds_write_b128 v3, v[22:25] offset:4096
	s_waitcnt vmcnt(3)
	ds_write_b128 v3, v[26:29] offset:8192
	s_waitcnt vmcnt(2)
	ds_write_b128 v3, v[30:33] offset:12288
	s_waitcnt vmcnt(1)
	ds_write_b128 v3, v[34:37] offset:16384
	s_waitcnt vmcnt(0)
	ds_write_b128 v3, v[38:41] offset:20480
	s_waitcnt lgkmcnt(0)
	s_barrier
	global_load_dwordx4 v[12:15], v2, s[0:1]
	global_load_dwordx4 v[16:19], v44, s[0:1]
	global_load_dwordx4 v[20:23], v45, s[0:1]
	global_load_dwordx4 v[24:27], v46, s[0:1]
	global_load_dwordx4 v[28:31], v5, s[2:3]
	global_load_dwordx4 v[32:35], v6, s[2:3]
	global_load_dwordx4 v[36:39], v7, s[2:3]
	global_load_dwordx4 v[40:43], v8, s[2:3]
	v_ashrrev_i32_e32 v2, 1, v142
	v_lshrrev_b32_e32 v5, 4, v142
	v_and_b32_e32 v10, 0xffffffc0, v2
	v_and_b32_e32 v11, 7, v142
	v_or_b32_e32 v145, v10, v143
	v_lshlrev_b32_e32 v2, 6, v144
	v_bitop3_b32 v5, v5, v11, 3 bitop3:0x6c
	v_or_b32_e32 v6, v2, v143
	v_lshlrev_b32_e32 v5, 4, v5
	v_lshl_add_u32 v80, v145, 7, 0
	v_add_u32_e32 v7, v80, v5
	v_lshl_add_u32 v6, v6, 7, 0
	v_add_u32_e32 v8, v6, v5
	ds_read_b128 v[44:47], v7
	ds_read_b128 v[48:51], v7 offset:2048
	ds_read_b128 v[52:55], v8 offset:16384
	ds_read_b128 v[56:59], v8 offset:18432
	ds_read_b128 v[60:63], v7 offset:4096
	ds_read_b128 v[64:67], v7 offset:6144
	ds_read_b128 v[68:71], v8 offset:20480
	ds_read_b128 v[72:75], v8 offset:22528
	v_bitop3_b32 v5, v146, v11, 4 bitop3:0x36
	v_lshlrev_b32_e32 v11, 4, v5
	s_setprio 2
	global_load_dwordx4 v[76:79], v234, s[0:1] offset:256
	s_waitcnt vmcnt(8)
	ds_write_b128 v3, v[12:15] offset:32768
	v_add_u32_e32 v5, v80, v11
	v_add_u32_e32 v6, v6, v11
	ds_read_b128 v[12:15], v5
	ds_read_b128 v[80:83], v6 offset:16384
	s_waitcnt lgkmcnt(8)
	v_mfma_f32_16x16x32_bf16 v[84:87], v[52:55], v[44:47], 0
	s_waitcnt lgkmcnt(7)
	v_mfma_f32_16x16x32_bf16 v[88:91], v[56:59], v[44:47], 0
	s_waitcnt lgkmcnt(4)
	v_mfma_f32_16x16x32_bf16 v[92:95], v[68:71], v[44:47], 0
	s_waitcnt lgkmcnt(3)
	v_mfma_f32_16x16x32_bf16 v[44:47], v[72:75], v[44:47], 0
	v_add_u32_e32 v237, 0x54000, v9
	global_load_dwordx4 v[100:103], v237, s[0:1] offset:256
	s_waitcnt vmcnt(8)
	ds_write_b128 v3, v[16:19] offset:36864
	ds_read_b128 v[16:19], v5 offset:2048
	ds_read_b128 v[104:107], v6 offset:18432
	v_mfma_f32_16x16x32_bf16 v[108:111], v[52:55], v[48:51], 0
	v_mfma_f32_16x16x32_bf16 v[112:115], v[56:59], v[48:51], 0
	v_mfma_f32_16x16x32_bf16 v[116:119], v[68:71], v[48:51], 0
	v_mfma_f32_16x16x32_bf16 v[48:51], v[72:75], v[48:51], 0
	v_add_u32_e32 v238, 0x8c000, v9
	global_load_dwordx4 v[120:123], v238, s[0:1] offset:256
	s_waitcnt vmcnt(8)
	ds_write_b128 v3, v[20:23] offset:40960
	ds_read_b128 v[20:23], v5 offset:4096
	ds_read_b128 v[124:127], v6 offset:20480
	v_mfma_f32_16x16x32_bf16 v[132:135], v[52:55], v[60:63], 0
	v_mfma_f32_16x16x32_bf16 v[136:139], v[56:59], v[60:63], 0
	v_mfma_f32_16x16x32_bf16 v[148:151], v[68:71], v[60:63], 0
	v_mfma_f32_16x16x32_bf16 v[60:63], v[72:75], v[60:63], 0
	global_load_dwordx4 v[152:155], v235, s[0:1] offset:256
	v_mfma_f32_16x16x32_bf16 v[52:55], v[52:55], v[64:67], 0
	s_waitcnt vmcnt(8)
	ds_write_b128 v3, v[24:27] offset:45056
	v_mfma_f32_16x16x32_bf16 v[56:59], v[56:59], v[64:67], 0
	ds_read_b128 v[24:27], v5 offset:6144
	v_mfma_f32_16x16x32_bf16 v[68:71], v[68:71], v[64:67], 0
	ds_read_b128 v[156:159], v6 offset:22528
	v_mfma_f32_16x16x32_bf16 v[64:67], v[72:75], v[64:67], 0
	global_load_dwordx4 v[72:75], v4, s[2:3] offset:256
	s_waitcnt vmcnt(8)
	ds_write_b128 v3, v[28:31] offset:49152
	s_waitcnt lgkmcnt(10)
	v_mfma_f32_16x16x32_bf16 v[28:31], v[80:83], v[12:15], v[84:87]
	s_waitcnt lgkmcnt(7)
	v_mfma_f32_16x16x32_bf16 v[84:87], v[104:107], v[12:15], v[88:91]
	s_waitcnt lgkmcnt(4)
	v_mfma_f32_16x16x32_bf16 v[88:91], v[124:127], v[12:15], v[92:95]
	s_waitcnt lgkmcnt(1)
	v_mfma_f32_16x16x32_bf16 v[12:15], v[156:159], v[12:15], v[44:47]
	global_load_dwordx4 v[44:47], v236, s[2:3] offset:256
	s_waitcnt vmcnt(8)
	ds_write_b128 v3, v[32:35] offset:53248
	v_mfma_f32_16x16x32_bf16 v[32:35], v[80:83], v[16:19], v[108:111]
	v_mfma_f32_16x16x32_bf16 v[92:95], v[104:107], v[16:19], v[112:115]
	v_mfma_f32_16x16x32_bf16 v[108:111], v[124:127], v[16:19], v[116:119]
	v_mfma_f32_16x16x32_bf16 v[16:19], v[156:159], v[16:19], v[48:51]
	v_add_u32_e32 v239, 0x20000, v4
	global_load_dwordx4 v[48:51], v239, s[2:3] offset:256
	s_waitcnt vmcnt(8)
	ds_write_b128 v3, v[36:39] offset:57344
	v_mfma_f32_16x16x32_bf16 v[36:39], v[80:83], v[20:23], v[132:135]
	v_mfma_f32_16x16x32_bf16 v[112:115], v[104:107], v[20:23], v[136:139]
	v_mfma_f32_16x16x32_bf16 v[116:119], v[124:127], v[20:23], v[148:151]
	v_mfma_f32_16x16x32_bf16 v[20:23], v[156:159], v[20:23], v[60:63]
	v_add_u32_e32 v240, 0x30000, v4
	global_load_dwordx4 v[60:63], v240, s[2:3] offset:256
	s_waitcnt vmcnt(8)
	ds_write_b128 v3, v[40:43] offset:61440
	v_mfma_f32_16x16x32_bf16 v[40:43], v[80:83], v[24:27], v[52:55]
	v_mfma_f32_16x16x32_bf16 v[52:55], v[104:107], v[24:27], v[56:59]
	v_mfma_f32_16x16x32_bf16 v[56:59], v[124:127], v[24:27], v[68:71]
	v_mfma_f32_16x16x32_bf16 v[24:27], v[156:159], v[24:27], v[64:67]
	s_setprio 0
	s_waitcnt lgkmcnt(0)
	s_barrier
; template <int MODE>
; __device__ __forceinline__ void gemm_tile(const Params& P, int tm, int tn, unsigned char* smem) {
;     ...
; #pragma unroll
;         for (int i = 0; i < 4; ++i) { fa[i] = *(const bf16x8*)(sA + arow_off + i * 2048 + ch0); fb[i] = *(const bf16x8*)(sB + brow_off + i * 2048 + ch0); }
;         __builtin_amdgcn_sched_barrier(0);
;         __builtin_amdgcn_s_setprio(2);
;         if (wr_ok) *(uint4*)(nA + soff0) = ra0;
;         if (ld_ok) ra0 = *(const uint4*)(Ab + (aoff + 0u * LDA + koa));
;         ga[0] = *(const bf16x8*)(sA + arow_off + 0 * 2048 + ch1); gb[0] = *(const bf16x8*)(sB + brow_off + 0 * 2048 + ch1);
;         __builtin_amdgcn_sched_barrier(0);
; #pragma unroll
;         for (int j = 0; j < 4; ++j) acc[0][j] = __builtin_amdgcn_mfma_f32_16x16x32_bf16(fb[j], fa[0], acc[0][j], 0, 0, 0);
;         __builtin_amdgcn_sched_barrier(0);
;         if (wr_ok) *(uint4*)(nA + soff0 + 4096) = ra1;
;         if (ld_ok) ra1 = *(const uint4*)(Ab + (aoff + 32u * LDA + koa));
;         ga[1] = *(const bf16x8*)(sA + arow_off + 1 * 2048 + ch1); gb[1] = *(const bf16x8*)(sB + brow_off + 1 * 2048 + ch1);
;         __builtin_amdgcn_sched_barrier(0);
; #pragma unroll
;         for (int j = 0; j < 4; ++j) acc[1][j] = __builtin_amdgcn_mfma_f32_16x16x32_bf16(fb[j], fa[1], acc[1][j], 0, 0, 0);
;         __builtin_amdgcn_sched_barrier(0);
;         if (wr_ok) *(uint4*)(nA + soff0 + 8192) = ra2;
;         if (ld_ok) ra2 = *(const uint4*)(Ab + (aoff + 64u * LDA + koa));
;         ga[2] = *(const bf16x8*)(sA + arow_off + 2 * 2048 + ch1); gb[2] = *(const bf16x8*)(sB + brow_off + 2 * 2048 + ch1);
;         __builtin_amdgcn_sched_barrier(0);
; #pragma unroll
;         for (int j = 0; j < 4; ++j) acc[2][j] = __builtin_amdgcn_mfma_f32_16x16x32_bf16(fb[j], fa[2], acc[2][j], 0, 0, 0);
;         __builtin_amdgcn_sched_barrier(0);
;         if (wr_ok) *(uint4*)(nA + soff0 + 12288) = ra3;
;         if (ld_ok) ra3 = *(const uint4*)(Ab + (aoff + 96u * LDA + koa));
;         ga[3] = *(const bf16x8*)(sA + arow_off + 3 * 2048 + ch1); gb[3] = *(const bf16x8*)(sB + brow_off + 3 * 2048 + ch1);
;         __builtin_amdgcn_sched_barrier(0);
; #pragma unroll
;         for (int j = 0; j < 4; ++j) acc[3][j] = __builtin_amdgcn_mfma_f32_16x16x32_bf16(fb[j], fa[3], acc[3][j], 0, 0, 0);
;         __builtin_amdgcn_sched_barrier(0);
;         if (wr_ok) *(uint4*)(nB + soff0) = rb0;
	ds_read_b128 v[64:67], v7 offset:32768
	ds_read_b128 v[68:71], v7 offset:34816
	ds_read_b128 v[80:83], v8 offset:49152
	ds_read_b128 v[104:107], v8 offset:51200
	ds_read_b128 v[124:127], v7 offset:36864
	ds_read_b128 v[132:135], v7 offset:38912
	ds_read_b128 v[136:139], v8 offset:53248
	ds_read_b128 v[148:151], v8 offset:55296
	s_setprio 2
	global_load_dwordx4 v[156:159], v234, s[0:1] offset:384
	s_waitcnt vmcnt(8)
	ds_write_b128 v3, v[76:79]
	ds_read_b128 v[76:79], v5 offset:32768
	ds_read_b128 v[160:163], v6 offset:49152
	s_waitcnt lgkmcnt(8)
	v_mfma_f32_16x16x32_bf16 v[28:31], v[80:83], v[64:67], v[28:31]
	s_waitcnt lgkmcnt(7)
	v_mfma_f32_16x16x32_bf16 v[84:87], v[104:107], v[64:67], v[84:87]
	s_waitcnt lgkmcnt(4)
	v_mfma_f32_16x16x32_bf16 v[88:91], v[136:139], v[64:67], v[88:91]
	s_waitcnt lgkmcnt(3)
	v_mfma_f32_16x16x32_bf16 v[12:15], v[148:151], v[64:67], v[12:15]
	global_load_dwordx4 v[64:67], v237, s[0:1] offset:384
	v_mfma_f32_16x16x32_bf16 v[32:35], v[80:83], v[68:71], v[32:35]
	s_waitcnt vmcnt(8)
	ds_write_b128 v3, v[100:103] offset:4096
	v_mfma_f32_16x16x32_bf16 v[92:95], v[104:107], v[68:71], v[92:95]
	ds_read_b128 v[100:103], v5 offset:34816
	v_mfma_f32_16x16x32_bf16 v[108:111], v[136:139], v[68:71], v[108:111]
	ds_read_b128 v[164:167], v6 offset:51200
	v_mfma_f32_16x16x32_bf16 v[16:19], v[148:151], v[68:71], v[16:19]
	global_load_dwordx4 v[68:71], v238, s[0:1] offset:384
	v_mfma_f32_16x16x32_bf16 v[36:39], v[80:83], v[124:127], v[36:39]
	s_waitcnt vmcnt(8)
	ds_write_b128 v3, v[120:123] offset:8192
	v_mfma_f32_16x16x32_bf16 v[112:115], v[104:107], v[124:127], v[112:115]
	ds_read_b128 v[120:123], v5 offset:36864
	v_mfma_f32_16x16x32_bf16 v[116:119], v[136:139], v[124:127], v[116:119]
	ds_read_b128 v[168:171], v6 offset:53248
	v_mfma_f32_16x16x32_bf16 v[20:23], v[148:151], v[124:127], v[20:23]
	global_load_dwordx4 v[124:127], v235, s[0:1] offset:384
	v_mfma_f32_16x16x32_bf16 v[40:43], v[80:83], v[132:135], v[40:43]
	s_waitcnt vmcnt(8)
	ds_write_b128 v3, v[152:155] offset:12288
	v_mfma_f32_16x16x32_bf16 v[52:55], v[104:107], v[132:135], v[52:55]
	ds_read_b128 v[152:155], v5 offset:38912
	v_mfma_f32_16x16x32_bf16 v[56:59], v[136:139], v[132:135], v[56:59]
	ds_read_b128 v[172:175], v6 offset:55296
	v_mfma_f32_16x16x32_bf16 v[24:27], v[148:151], v[132:135], v[24:27]
	global_load_dwordx4 v[80:83], v4, s[2:3] offset:384
	s_waitcnt vmcnt(8)
	ds_write_b128 v3, v[72:75] offset:16384
	s_waitcnt lgkmcnt(10)
	v_mfma_f32_16x16x32_bf16 v[28:31], v[160:163], v[76:79], v[28:31]
	s_waitcnt lgkmcnt(7)
	v_mfma_f32_16x16x32_bf16 v[72:75], v[164:167], v[76:79], v[84:87]
	s_waitcnt lgkmcnt(4)
	v_mfma_f32_16x16x32_bf16 v[84:87], v[168:171], v[76:79], v[88:91]
	s_waitcnt lgkmcnt(1)
	v_mfma_f32_16x16x32_bf16 v[12:15], v[172:175], v[76:79], v[12:15]
	global_load_dwordx4 v[76:79], v236, s[2:3] offset:384
	s_waitcnt vmcnt(8)
	ds_write_b128 v3, v[44:47] offset:20480
	v_mfma_f32_16x16x32_bf16 v[32:35], v[160:163], v[100:103], v[32:35]
	v_mfma_f32_16x16x32_bf16 v[44:47], v[164:167], v[100:103], v[92:95]
	v_mfma_f32_16x16x32_bf16 v[88:91], v[168:171], v[100:103], v[108:111]
	v_mfma_f32_16x16x32_bf16 v[16:19], v[172:175], v[100:103], v[16:19]
	global_load_dwordx4 v[92:95], v239, s[2:3] offset:384
	s_waitcnt vmcnt(8)
	ds_write_b128 v3, v[48:51] offset:24576
	v_mfma_f32_16x16x32_bf16 v[36:39], v[160:163], v[120:123], v[36:39]
	v_mfma_f32_16x16x32_bf16 v[48:51], v[164:167], v[120:123], v[112:115]
	v_mfma_f32_16x16x32_bf16 v[100:103], v[168:171], v[120:123], v[116:119]
	v_mfma_f32_16x16x32_bf16 v[20:23], v[172:175], v[120:123], v[20:23]
	global_load_dwordx4 v[104:107], v240, s[2:3] offset:384
	v_mfma_f32_16x16x32_bf16 v[40:43], v[160:163], v[152:155], v[40:43]
	s_waitcnt vmcnt(8)
	ds_write_b128 v3, v[60:63] offset:28672
	v_mfma_f32_16x16x32_bf16 v[52:55], v[164:167], v[152:155], v[52:55]
	v_mfma_f32_16x16x32_bf16 v[56:59], v[168:171], v[152:155], v[56:59]
	v_mfma_f32_16x16x32_bf16 v[24:27], v[172:175], v[152:155], v[24:27]
	s_setprio 0
	s_waitcnt lgkmcnt(0)
	s_barrier
	ds_read_b128 v[60:63], v7
	ds_read_b128 v[108:111], v7 offset:2048
	ds_read_b128 v[112:115], v8 offset:16384
	ds_read_b128 v[116:119], v8 offset:18432
	ds_read_b128 v[120:123], v7 offset:4096
	ds_read_b128 v[132:135], v7 offset:6144
	ds_read_b128 v[136:139], v8 offset:20480
	ds_read_b128 v[148:151], v8 offset:22528
	s_setprio 2
	global_load_dwordx4 v[152:155], v234, s[0:1] offset:512
	s_waitcnt vmcnt(8)
	ds_write_b128 v3, v[156:159] offset:32768
	ds_read_b128 v[156:159], v5
	ds_read_b128 v[160:163], v6 offset:16384
	s_waitcnt lgkmcnt(8)
	v_mfma_f32_16x16x32_bf16 v[28:31], v[112:115], v[60:63], v[28:31]
	s_waitcnt lgkmcnt(4)
	v_mfma_f32_16x16x32_bf16 v[84:87], v[136:139], v[60:63], v[84:87]
	s_waitcnt lgkmcnt(3)
	v_mfma_f32_16x16x32_bf16 v[12:15], v[148:151], v[60:63], v[12:15]
	v_mfma_f32_16x16x32_bf16 v[72:75], v[116:119], v[60:63], v[72:75]
	global_load_dwordx4 v[60:63], v237, s[0:1] offset:512
	v_mfma_f32_16x16x32_bf16 v[32:35], v[112:115], v[108:111], v[32:35]
	s_waitcnt vmcnt(8)
	ds_write_b128 v3, v[64:67] offset:36864
	v_mfma_f32_16x16x32_bf16 v[44:47], v[116:119], v[108:111], v[44:47]
	ds_read_b128 v[64:67], v5 offset:2048
	v_mfma_f32_16x16x32_bf16 v[88:91], v[136:139], v[108:111], v[88:91]
	ds_read_b128 v[164:167], v6 offset:18432
	v_mfma_f32_16x16x32_bf16 v[16:19], v[148:151], v[108:111], v[16:19]
	global_load_dwordx4 v[108:111], v238, s[0:1] offset:512
	v_mfma_f32_16x16x32_bf16 v[36:39], v[112:115], v[120:123], v[36:39]
	s_waitcnt vmcnt(8)
; template <int MODE>
; __device__ __forceinline__ void gemm_tile(const Params& P, int tm, int tn, unsigned char* smem) {
;     ...
; #pragma unroll
;         for (int i = 0; i < 4; ++i) { fa[i] = *(const bf16x8*)(sA + arow_off + i * 2048 + ch0); fb[i] = *(const bf16x8*)(sB + brow_off + i * 2048 + ch0); }
;         __builtin_amdgcn_sched_barrier(0);
;         __builtin_amdgcn_s_setprio(2);
;         if (wr_ok) *(uint4*)(nA + soff0) = ra0;
;         if (ld_ok) ra0 = *(const uint4*)(Ab + (aoff + 0u * LDA + koa));
;         ga[0] = *(const bf16x8*)(sA + arow_off + 0 * 2048 + ch1); gb[0] = *(const bf16x8*)(sB + brow_off + 0 * 2048 + ch1);
;         __builtin_amdgcn_sched_barrier(0);
; #pragma unroll
;         for (int j = 0; j < 4; ++j) acc[0][j] = __builtin_amdgcn_mfma_f32_16x16x32_bf16(fb[j], fa[0], acc[0][j], 0, 0, 0);
;         __builtin_amdgcn_sched_barrier(0);
;         if (wr_ok) *(uint4*)(nA + soff0 + 4096) = ra1;
;         if (ld_ok) ra1 = *(const uint4*)(Ab + (aoff + 32u * LDA + koa));
;         ga[1] = *(const bf16x8*)(sA + arow_off + 1 * 2048 + ch1); gb[1] = *(const bf16x8*)(sB + brow_off + 1 * 2048 + ch1);
;         __builtin_amdgcn_sched_barrier(0);
; #pragma unroll
;         for (int j = 0; j < 4; ++j) acc[1][j] = __builtin_amdgcn_mfma_f32_16x16x32_bf16(fb[j], fa[1], acc[1][j], 0, 0, 0);
;         __builtin_amdgcn_sched_barrier(0);
;         if (wr_ok) *(uint4*)(nA + soff0 + 8192) = ra2;
;         if (ld_ok) ra2 = *(const uint4*)(Ab + (aoff + 64u * LDA + koa));
;         ga[2] = *(const bf16x8*)(sA + arow_off + 2 * 2048 + ch1); gb[2] = *(const bf16x8*)(sB + brow_off + 2 * 2048 + ch1);
;         __builtin_amdgcn_sched_barrier(0);
; #pragma unroll
;         for (int j = 0; j < 4; ++j) acc[2][j] = __builtin_amdgcn_mfma_f32_16x16x32_bf16(fb[j], fa[2], acc[2][j], 0, 0, 0);
;         __builtin_amdgcn_sched_barrier(0);
;         if (wr_ok) *(uint4*)(nA + soff0 + 12288) = ra3;
;         if (ld_ok) ra3 = *(const uint4*)(Ab + (aoff + 96u * LDA + koa));
;         ga[3] = *(const bf16x8*)(sA + arow_off + 3 * 2048 + ch1); gb[3] = *(const bf16x8*)(sB + brow_off + 3 * 2048 + ch1);
;         __builtin_amdgcn_sched_barrier(0);
; #pragma unroll
;         for (int j = 0; j < 4; ++j) acc[3][j] = __builtin_amdgcn_mfma_f32_16x16x32_bf16(fb[j], fa[3], acc[3][j], 0, 0, 0);
;         __builtin_amdgcn_sched_barrier(0);
;         if (wr_ok) *(uint4*)(nB + soff0) = rb0;
	ds_write_b128 v3, v[68:71] offset:40960
	v_mfma_f32_16x16x32_bf16 v[48:51], v[116:119], v[120:123], v[48:51]
	ds_read_b128 v[68:71], v5 offset:4096
	v_mfma_f32_16x16x32_bf16 v[100:103], v[136:139], v[120:123], v[100:103]
	ds_read_b128 v[168:171], v6 offset:20480
	v_mfma_f32_16x16x32_bf16 v[20:23], v[148:151], v[120:123], v[20:23]
	global_load_dwordx4 v[120:123], v235, s[0:1] offset:512
	v_mfma_f32_16x16x32_bf16 v[40:43], v[112:115], v[132:135], v[40:43]
	s_waitcnt vmcnt(8)
	ds_write_b128 v3, v[124:127] offset:45056
	v_mfma_f32_16x16x32_bf16 v[52:55], v[116:119], v[132:135], v[52:55]
	ds_read_b128 v[124:127], v5 offset:6144
	v_mfma_f32_16x16x32_bf16 v[56:59], v[136:139], v[132:135], v[56:59]
	ds_read_b128 v[172:175], v6 offset:22528
	v_mfma_f32_16x16x32_bf16 v[24:27], v[148:151], v[132:135], v[24:27]
	global_load_dwordx4 v[112:115], v4, s[2:3] offset:512
	s_waitcnt vmcnt(8)
	ds_write_b128 v3, v[80:83] offset:49152
	s_waitcnt lgkmcnt(10)
	v_mfma_f32_16x16x32_bf16 v[28:31], v[160:163], v[156:159], v[28:31]
	s_waitcnt lgkmcnt(4)
	v_mfma_f32_16x16x32_bf16 v[80:83], v[168:171], v[156:159], v[84:87]
	s_waitcnt lgkmcnt(1)
	v_mfma_f32_16x16x32_bf16 v[12:15], v[172:175], v[156:159], v[12:15]
	v_mfma_f32_16x16x32_bf16 v[72:75], v[164:167], v[156:159], v[72:75]
	global_load_dwordx4 v[84:87], v236, s[2:3] offset:512
	s_waitcnt vmcnt(8)
	ds_write_b128 v3, v[76:79] offset:53248
	v_mfma_f32_16x16x32_bf16 v[32:35], v[160:163], v[64:67], v[32:35]
	v_mfma_f32_16x16x32_bf16 v[44:47], v[164:167], v[64:67], v[44:47]
	v_mfma_f32_16x16x32_bf16 v[16:19], v[172:175], v[64:67], v[16:19]
	v_mfma_f32_16x16x32_bf16 v[76:79], v[168:171], v[64:67], v[88:91]
	global_load_dwordx4 v[64:67], v239, s[2:3] offset:512
	v_mfma_f32_16x16x32_bf16 v[36:39], v[160:163], v[68:71], v[36:39]
	s_waitcnt vmcnt(8)
	ds_write_b128 v3, v[92:95] offset:57344
	v_mfma_f32_16x16x32_bf16 v[48:51], v[164:167], v[68:71], v[48:51]
	v_mfma_f32_16x16x32_bf16 v[88:91], v[168:171], v[68:71], v[100:103]
	v_mfma_f32_16x16x32_bf16 v[20:23], v[172:175], v[68:71], v[20:23]
	global_load_dwordx4 v[68:71], v240, s[2:3] offset:512
	v_mfma_f32_16x16x32_bf16 v[40:43], v[160:163], v[124:127], v[40:43]
	s_waitcnt vmcnt(8)
	ds_write_b128 v3, v[104:107] offset:61440
	v_mfma_f32_16x16x32_bf16 v[52:55], v[164:167], v[124:127], v[52:55]
	v_mfma_f32_16x16x32_bf16 v[56:59], v[168:171], v[124:127], v[56:59]
	v_mfma_f32_16x16x32_bf16 v[24:27], v[172:175], v[124:127], v[24:27]
	s_setprio 0
	s_waitcnt lgkmcnt(0)
	s_barrier
	ds_read_b128 v[92:95], v7 offset:32768
	ds_read_b128 v[100:103], v7 offset:34816
	ds_read_b128 v[104:107], v8 offset:49152
	ds_read_b128 v[116:119], v8 offset:51200
	ds_read_b128 v[124:127], v7 offset:36864
	ds_read_b128 v[132:135], v7 offset:38912
	ds_read_b128 v[136:139], v8 offset:53248
	ds_read_b128 v[148:151], v8 offset:55296
	s_setprio 2
	global_load_dwordx4 v[156:159], v234, s[0:1] offset:640
	s_waitcnt vmcnt(8)
	ds_write_b128 v3, v[152:155]
	ds_read_b128 v[152:155], v5 offset:32768
	ds_read_b128 v[160:163], v6 offset:49152
	s_waitcnt lgkmcnt(8)
	v_mfma_f32_16x16x32_bf16 v[28:31], v[104:107], v[92:95], v[28:31]
	s_waitcnt lgkmcnt(4)
	v_mfma_f32_16x16x32_bf16 v[80:83], v[136:139], v[92:95], v[80:83]
	s_waitcnt lgkmcnt(3)
	v_mfma_f32_16x16x32_bf16 v[12:15], v[148:151], v[92:95], v[12:15]
	v_mfma_f32_16x16x32_bf16 v[72:75], v[116:119], v[92:95], v[72:75]
	global_load_dwordx4 v[92:95], v237, s[0:1] offset:640
	v_mfma_f32_16x16x32_bf16 v[32:35], v[104:107], v[100:103], v[32:35]
	s_waitcnt vmcnt(8)
	ds_write_b128 v3, v[60:63] offset:4096
	v_mfma_f32_16x16x32_bf16 v[44:47], v[116:119], v[100:103], v[44:47]
	ds_read_b128 v[60:63], v5 offset:34816
	v_mfma_f32_16x16x32_bf16 v[16:19], v[148:151], v[100:103], v[16:19]
	ds_read_b128 v[164:167], v6 offset:51200
	v_mfma_f32_16x16x32_bf16 v[76:79], v[136:139], v[100:103], v[76:79]
	global_load_dwordx4 v[100:103], v238, s[0:1] offset:640
	v_mfma_f32_16x16x32_bf16 v[36:39], v[104:107], v[124:127], v[36:39]
	s_waitcnt vmcnt(8)
	ds_write_b128 v3, v[108:111] offset:8192
	v_mfma_f32_16x16x32_bf16 v[48:51], v[116:119], v[124:127], v[48:51]
	ds_read_b128 v[108:111], v5 offset:36864
	v_mfma_f32_16x16x32_bf16 v[88:91], v[136:139], v[124:127], v[88:91]
	ds_read_b128 v[168:171], v6 offset:53248
	v_mfma_f32_16x16x32_bf16 v[20:23], v[148:151], v[124:127], v[20:23]
	global_load_dwordx4 v[124:127], v235, s[0:1] offset:640
	v_mfma_f32_16x16x32_bf16 v[40:43], v[104:107], v[132:135], v[40:43]
	s_waitcnt vmcnt(8)
	ds_write_b128 v3, v[120:123] offset:12288
	v_mfma_f32_16x16x32_bf16 v[52:55], v[116:119], v[132:135], v[52:55]
	ds_read_b128 v[120:123], v5 offset:38912
	v_mfma_f32_16x16x32_bf16 v[56:59], v[136:139], v[132:135], v[56:59]
	ds_read_b128 v[172:175], v6 offset:55296
	v_mfma_f32_16x16x32_bf16 v[24:27], v[148:151], v[132:135], v[24:27]
	global_load_dwordx4 v[104:107], v4, s[2:3] offset:640
	s_waitcnt vmcnt(8)
	ds_write_b128 v3, v[112:115] offset:16384
	s_waitcnt lgkmcnt(10)
	v_mfma_f32_16x16x32_bf16 v[28:31], v[160:163], v[152:155], v[28:31]
	s_waitcnt lgkmcnt(4)
	v_mfma_f32_16x16x32_bf16 v[80:83], v[168:171], v[152:155], v[80:83]
	s_waitcnt lgkmcnt(1)
	v_mfma_f32_16x16x32_bf16 v[12:15], v[172:175], v[152:155], v[12:15]
	v_mfma_f32_16x16x32_bf16 v[72:75], v[164:167], v[152:155], v[72:75]
	global_load_dwordx4 v[112:115], v236, s[2:3] offset:640
	v_mfma_f32_16x16x32_bf16 v[32:35], v[160:163], v[60:63], v[32:35]
	s_waitcnt vmcnt(8)
	ds_write_b128 v3, v[84:87] offset:20480
	v_mfma_f32_16x16x32_bf16 v[44:47], v[164:167], v[60:63], v[44:47]
	v_mfma_f32_16x16x32_bf16 v[16:19], v[172:175], v[60:63], v[16:19]
	v_mfma_f32_16x16x32_bf16 v[76:79], v[168:171], v[60:63], v[76:79]
	global_load_dwordx4 v[60:63], v239, s[2:3] offset:640
	s_waitcnt vmcnt(8)
	ds_write_b128 v3, v[64:67] offset:24576
	v_mfma_f32_16x16x32_bf16 v[36:39], v[160:163], v[108:111], v[36:39]
	v_mfma_f32_16x16x32_bf16 v[48:51], v[164:167], v[108:111], v[48:51]
	v_mfma_f32_16x16x32_bf16 v[64:67], v[168:171], v[108:111], v[88:91]
	v_mfma_f32_16x16x32_bf16 v[20:23], v[172:175], v[108:111], v[20:23]
	global_load_dwordx4 v[84:87], v240, s[2:3] offset:640
	v_mfma_f32_16x16x32_bf16 v[40:43], v[160:163], v[120:123], v[40:43]
	s_waitcnt vmcnt(8)
	ds_write_b128 v3, v[68:71] offset:28672
	v_mfma_f32_16x16x32_bf16 v[52:55], v[164:167], v[120:123], v[52:55]
	v_mfma_f32_16x16x32_bf16 v[56:59], v[168:171], v[120:123], v[56:59]
	v_mfma_f32_16x16x32_bf16 v[24:27], v[172:175], v[120:123], v[24:27]
	s_setprio 0
	s_waitcnt lgkmcnt(0)
	s_barrier
; template <int MODE>
; __device__ __forceinline__ void gemm_tile(const Params& P, int tm, int tn, unsigned char* smem) {
;     ...
; #pragma unroll
;         for (int i = 0; i < 4; ++i) { fa[i] = *(const bf16x8*)(sA + arow_off + i * 2048 + ch0); fb[i] = *(const bf16x8*)(sB + brow_off + i * 2048 + ch0); }
;         __builtin_amdgcn_sched_barrier(0);
;         __builtin_amdgcn_s_setprio(2);
;         if (wr_ok) *(uint4*)(nA + soff0) = ra0;
;         if (ld_ok) ra0 = *(const uint4*)(Ab + (aoff + 0u * LDA + koa));
;         ga[0] = *(const bf16x8*)(sA + arow_off + 0 * 2048 + ch1); gb[0] = *(const bf16x8*)(sB + brow_off + 0 * 2048 + ch1);
;         __builtin_amdgcn_sched_barrier(0);
; #pragma unroll
;         for (int j = 0; j < 4; ++j) acc[0][j] = __builtin_amdgcn_mfma_f32_16x16x32_bf16(fb[j], fa[0], acc[0][j], 0, 0, 0);
;         __builtin_amdgcn_sched_barrier(0);
;         if (wr_ok) *(uint4*)(nA + soff0 + 4096) = ra1;
;         if (ld_ok) ra1 = *(const uint4*)(Ab + (aoff + 32u * LDA + koa));
;         ga[1] = *(const bf16x8*)(sA + arow_off + 1 * 2048 + ch1); gb[1] = *(const bf16x8*)(sB + brow_off + 1 * 2048 + ch1);
;         __builtin_amdgcn_sched_barrier(0);
; #pragma unroll
;         for (int j = 0; j < 4; ++j) acc[1][j] = __builtin_amdgcn_mfma_f32_16x16x32_bf16(fb[j], fa[1], acc[1][j], 0, 0, 0);
;         __builtin_amdgcn_sched_barrier(0);
;         if (wr_ok) *(uint4*)(nA + soff0 + 8192) = ra2;
;         if (ld_ok) ra2 = *(const uint4*)(Ab + (aoff + 64u * LDA + koa));
;         ga[2] = *(const bf16x8*)(sA + arow_off + 2 * 2048 + ch1); gb[2] = *(const bf16x8*)(sB + brow_off + 2 * 2048 + ch1);
;         __builtin_amdgcn_sched_barrier(0);
; #pragma unroll
;         for (int j = 0; j < 4; ++j) acc[2][j] = __builtin_amdgcn_mfma_f32_16x16x32_bf16(fb[j], fa[2], acc[2][j], 0, 0, 0);
;         __builtin_amdgcn_sched_barrier(0);
;         if (wr_ok) *(uint4*)(nA + soff0 + 12288) = ra3;
;         if (ld_ok) ra3 = *(const uint4*)(Ab + (aoff + 96u * LDA + koa));
;         ga[3] = *(const bf16x8*)(sA + arow_off + 3 * 2048 + ch1); gb[3] = *(const bf16x8*)(sB + brow_off + 3 * 2048 + ch1);
;         __builtin_amdgcn_sched_barrier(0);
; #pragma unroll
;         for (int j = 0; j < 4; ++j) acc[3][j] = __builtin_amdgcn_mfma_f32_16x16x32_bf16(fb[j], fa[3], acc[3][j], 0, 0, 0);
;         __builtin_amdgcn_sched_barrier(0);
;         if (wr_ok) *(uint4*)(nB + soff0) = rb0;
	ds_read_b128 v[68:71], v7
	ds_read_b128 v[88:91], v7 offset:2048
	ds_read_b128 v[108:111], v8 offset:16384
	ds_read_b128 v[116:119], v8 offset:18432
	ds_read_b128 v[120:123], v7 offset:4096
	ds_read_b128 v[132:135], v7 offset:6144
	ds_read_b128 v[136:139], v8 offset:20480
	ds_read_b128 v[148:151], v8 offset:22528
	s_setprio 2
	global_load_dwordx4 v[152:155], v234, s[0:1] offset:768
	s_waitcnt vmcnt(8)
	ds_write_b128 v3, v[156:159] offset:32768
	ds_read_b128 v[156:159], v5
	ds_read_b128 v[160:163], v6 offset:16384
	s_waitcnt lgkmcnt(8)
	v_mfma_f32_16x16x32_bf16 v[28:31], v[108:111], v[68:71], v[28:31]
	s_waitcnt lgkmcnt(4)
	v_mfma_f32_16x16x32_bf16 v[80:83], v[136:139], v[68:71], v[80:83]
	s_waitcnt lgkmcnt(3)
	v_mfma_f32_16x16x32_bf16 v[12:15], v[148:151], v[68:71], v[12:15]
	v_mfma_f32_16x16x32_bf16 v[72:75], v[116:119], v[68:71], v[72:75]
	global_load_dwordx4 v[68:71], v237, s[0:1] offset:768
	v_mfma_f32_16x16x32_bf16 v[32:35], v[108:111], v[88:91], v[32:35]
	s_waitcnt vmcnt(8)
	ds_write_b128 v3, v[92:95] offset:36864
	v_mfma_f32_16x16x32_bf16 v[44:47], v[116:119], v[88:91], v[44:47]
	ds_read_b128 v[92:95], v5 offset:2048
	v_mfma_f32_16x16x32_bf16 v[16:19], v[148:151], v[88:91], v[16:19]
	ds_read_b128 v[164:167], v6 offset:18432
	v_mfma_f32_16x16x32_bf16 v[76:79], v[136:139], v[88:91], v[76:79]
	global_load_dwordx4 v[88:91], v238, s[0:1] offset:768
	v_mfma_f32_16x16x32_bf16 v[36:39], v[108:111], v[120:123], v[36:39]
	s_waitcnt vmcnt(8)
	ds_write_b128 v3, v[100:103] offset:40960
	v_mfma_f32_16x16x32_bf16 v[48:51], v[116:119], v[120:123], v[48:51]
	ds_read_b128 v[100:103], v5 offset:4096
	v_mfma_f32_16x16x32_bf16 v[64:67], v[136:139], v[120:123], v[64:67]
	ds_read_b128 v[168:171], v6 offset:20480
	v_mfma_f32_16x16x32_bf16 v[20:23], v[148:151], v[120:123], v[20:23]
	global_load_dwordx4 v[120:123], v235, s[0:1] offset:768
	v_mfma_f32_16x16x32_bf16 v[40:43], v[108:111], v[132:135], v[40:43]
	s_waitcnt vmcnt(8)
	ds_write_b128 v3, v[124:127] offset:45056
	v_mfma_f32_16x16x32_bf16 v[52:55], v[116:119], v[132:135], v[52:55]
	ds_read_b128 v[124:127], v5 offset:6144
	v_mfma_f32_16x16x32_bf16 v[56:59], v[136:139], v[132:135], v[56:59]
	ds_read_b128 v[172:175], v6 offset:22528
	v_mfma_f32_16x16x32_bf16 v[24:27], v[148:151], v[132:135], v[24:27]
	global_load_dwordx4 v[108:111], v4, s[2:3] offset:768
	s_waitcnt vmcnt(8)
	ds_write_b128 v3, v[104:107] offset:49152
	s_waitcnt lgkmcnt(10)
	v_mfma_f32_16x16x32_bf16 v[28:31], v[160:163], v[156:159], v[28:31]
	s_waitcnt lgkmcnt(4)
	v_mfma_f32_16x16x32_bf16 v[80:83], v[168:171], v[156:159], v[80:83]
	s_waitcnt lgkmcnt(1)
	v_mfma_f32_16x16x32_bf16 v[12:15], v[172:175], v[156:159], v[12:15]
	v_mfma_f32_16x16x32_bf16 v[72:75], v[164:167], v[156:159], v[72:75]
	global_load_dwordx4 v[104:107], v236, s[2:3] offset:768
	v_mfma_f32_16x16x32_bf16 v[32:35], v[160:163], v[92:95], v[32:35]
	s_waitcnt vmcnt(8)
	ds_write_b128 v3, v[112:115] offset:53248
	v_mfma_f32_16x16x32_bf16 v[44:47], v[164:167], v[92:95], v[44:47]
	v_mfma_f32_16x16x32_bf16 v[16:19], v[172:175], v[92:95], v[16:19]
	v_mfma_f32_16x16x32_bf16 v[76:79], v[168:171], v[92:95], v[76:79]
	global_load_dwordx4 v[92:95], v239, s[2:3] offset:768
	s_waitcnt vmcnt(8)
	ds_write_b128 v3, v[60:63] offset:57344
	v_mfma_f32_16x16x32_bf16 v[36:39], v[160:163], v[100:103], v[36:39]
	v_mfma_f32_16x16x32_bf16 v[48:51], v[164:167], v[100:103], v[48:51]
	v_mfma_f32_16x16x32_bf16 v[60:63], v[168:171], v[100:103], v[64:67]
	v_mfma_f32_16x16x32_bf16 v[20:23], v[172:175], v[100:103], v[20:23]
	global_load_dwordx4 v[64:67], v240, s[2:3] offset:768
	v_mfma_f32_16x16x32_bf16 v[40:43], v[160:163], v[124:127], v[40:43]
	s_waitcnt vmcnt(8)
	ds_write_b128 v3, v[84:87] offset:61440
	v_mfma_f32_16x16x32_bf16 v[52:55], v[164:167], v[124:127], v[52:55]
	v_mfma_f32_16x16x32_bf16 v[56:59], v[168:171], v[124:127], v[56:59]
	v_mfma_f32_16x16x32_bf16 v[24:27], v[172:175], v[124:127], v[24:27]
	s_setprio 0
	s_waitcnt lgkmcnt(0)
	s_barrier
	ds_read_b128 v[84:87], v7 offset:32768
	ds_read_b128 v[100:103], v7 offset:34816
	ds_read_b128 v[112:115], v8 offset:49152
	ds_read_b128 v[116:119], v8 offset:51200
	ds_read_b128 v[124:127], v7 offset:36864
	ds_read_b128 v[132:135], v7 offset:38912
	ds_read_b128 v[136:139], v8 offset:53248
	ds_read_b128 v[148:151], v8 offset:55296
	s_setprio 2
	global_load_dwordx4 v[156:159], v234, s[0:1] offset:896
	s_waitcnt vmcnt(8)
	ds_write_b128 v3, v[152:155]
	ds_read_b128 v[152:155], v5 offset:32768
	ds_read_b128 v[160:163], v6 offset:49152
	s_waitcnt lgkmcnt(8)
	v_mfma_f32_16x16x32_bf16 v[28:31], v[112:115], v[84:87], v[28:31]
	s_waitcnt lgkmcnt(4)
	v_mfma_f32_16x16x32_bf16 v[80:83], v[136:139], v[84:87], v[80:83]
	s_waitcnt lgkmcnt(3)
	v_mfma_f32_16x16x32_bf16 v[12:15], v[148:151], v[84:87], v[12:15]
	v_mfma_f32_16x16x32_bf16 v[72:75], v[116:119], v[84:87], v[72:75]
	global_load_dwordx4 v[84:87], v237, s[0:1] offset:896
	v_mfma_f32_16x16x32_bf16 v[32:35], v[112:115], v[100:103], v[32:35]
	s_waitcnt vmcnt(8)
	ds_write_b128 v3, v[68:71] offset:4096
	v_mfma_f32_16x16x32_bf16 v[44:47], v[116:119], v[100:103], v[44:47]
	ds_read_b128 v[68:71], v5 offset:34816
	v_mfma_f32_16x16x32_bf16 v[16:19], v[148:151], v[100:103], v[16:19]
	ds_read_b128 v[164:167], v6 offset:51200
	v_mfma_f32_16x16x32_bf16 v[76:79], v[136:139], v[100:103], v[76:79]
	global_load_dwordx4 v[100:103], v238, s[0:1] offset:896
	v_mfma_f32_16x16x32_bf16 v[36:39], v[112:115], v[124:127], v[36:39]
	s_waitcnt vmcnt(8)
; template <int MODE>
; __device__ __forceinline__ void gemm_tile(const Params& P, int tm, int tn, unsigned char* smem) {
;     ...
;         const unsigned ko = (unsigned)(kt + 2) * 128u;
;         const unsigned koa = ko + ((MODE == 2 && kt + 2 >= 8) ? (unsigned)(ZC_FQ - 512) * 2u : 0u);
;         const bool wr_ok = kt < 15, ld_ok = kt < 14;
; #pragma unroll
;         for (int i = 0; i < 4; ++i) { fa[i] = *(const bf16x8*)(sA + arow_off + i * 2048 + ch0); fb[i] = *(const bf16x8*)(sB + brow_off + i * 2048 + ch0); }
;         __builtin_amdgcn_sched_barrier(0);
;         __builtin_amdgcn_s_setprio(2);
;         if (wr_ok) *(uint4*)(nA + soff0) = ra0;
;         if (ld_ok) ra0 = *(const uint4*)(Ab + (aoff + 0u * LDA + koa));
;         ga[0] = *(const bf16x8*)(sA + arow_off + 0 * 2048 + ch1); gb[0] = *(const bf16x8*)(sB + brow_off + 0 * 2048 + ch1);
;         __builtin_amdgcn_sched_barrier(0);
; #pragma unroll
;         for (int j = 0; j < 4; ++j) acc[0][j] = __builtin_amdgcn_mfma_f32_16x16x32_bf16(fb[j], fa[0], acc[0][j], 0, 0, 0);
;         __builtin_amdgcn_sched_barrier(0);
;         if (wr_ok) *(uint4*)(nA + soff0 + 4096) = ra1;
;         if (ld_ok) ra1 = *(const uint4*)(Ab + (aoff + 32u * LDA + koa));
;         ga[1] = *(const bf16x8*)(sA + arow_off + 1 * 2048 + ch1); gb[1] = *(const bf16x8*)(sB + brow_off + 1 * 2048 + ch1);
;         __builtin_amdgcn_sched_barrier(0);
; #pragma unroll
;         for (int j = 0; j < 4; ++j) acc[1][j] = __builtin_amdgcn_mfma_f32_16x16x32_bf16(fb[j], fa[1], acc[1][j], 0, 0, 0);
;         __builtin_amdgcn_sched_barrier(0);
;         if (wr_ok) *(uint4*)(nA + soff0 + 8192) = ra2;
;         if (ld_ok) ra2 = *(const uint4*)(Ab + (aoff + 64u * LDA + koa));
;         ga[2] = *(const bf16x8*)(sA + arow_off + 2 * 2048 + ch1); gb[2] = *(const bf16x8*)(sB + brow_off + 2 * 2048 + ch1);
;         __builtin_amdgcn_sched_barrier(0);
; #pragma unroll
;         for (int j = 0; j < 4; ++j) acc[2][j] = __builtin_amdgcn_mfma_f32_16x16x32_bf16(fb[j], fa[2], acc[2][j], 0, 0, 0);
;         __builtin_amdgcn_sched_barrier(0);
;         if (wr_ok) *(uint4*)(nA + soff0 + 12288) = ra3;
;         if (ld_ok) ra3 = *(const uint4*)(Ab + (aoff + 96u * LDA + koa));
;         ga[3] = *(const bf16x8*)(sA + arow_off + 3 * 2048 + ch1); gb[3] = *(const bf16x8*)(sB + brow_off + 3 * 2048 + ch1);
;         __builtin_amdgcn_sched_barrier(0);
; #pragma unroll
	ds_write_b128 v3, v[88:91] offset:8192
	v_mfma_f32_16x16x32_bf16 v[48:51], v[116:119], v[124:127], v[48:51]
	ds_read_b128 v[88:91], v5 offset:36864
	v_mfma_f32_16x16x32_bf16 v[60:63], v[136:139], v[124:127], v[60:63]
	ds_read_b128 v[168:171], v6 offset:53248
	v_mfma_f32_16x16x32_bf16 v[20:23], v[148:151], v[124:127], v[20:23]
	global_load_dwordx4 v[124:127], v235, s[0:1] offset:896
	v_mfma_f32_16x16x32_bf16 v[40:43], v[112:115], v[132:135], v[40:43]
	s_waitcnt vmcnt(8)
	ds_write_b128 v3, v[120:123] offset:12288
	v_mfma_f32_16x16x32_bf16 v[52:55], v[116:119], v[132:135], v[52:55]
	ds_read_b128 v[120:123], v5 offset:38912
	v_mfma_f32_16x16x32_bf16 v[56:59], v[136:139], v[132:135], v[56:59]
	ds_read_b128 v[172:175], v6 offset:55296
	v_mfma_f32_16x16x32_bf16 v[24:27], v[148:151], v[132:135], v[24:27]
	global_load_dwordx4 v[112:115], v4, s[2:3] offset:896
	s_waitcnt vmcnt(8)
	ds_write_b128 v3, v[108:111] offset:16384
	s_waitcnt lgkmcnt(10)
	v_mfma_f32_16x16x32_bf16 v[28:31], v[160:163], v[152:155], v[28:31]
	s_waitcnt lgkmcnt(4)
	v_mfma_f32_16x16x32_bf16 v[80:83], v[168:171], v[152:155], v[80:83]
	s_waitcnt lgkmcnt(1)
	v_mfma_f32_16x16x32_bf16 v[12:15], v[172:175], v[152:155], v[12:15]
	v_mfma_f32_16x16x32_bf16 v[72:75], v[164:167], v[152:155], v[72:75]
	global_load_dwordx4 v[108:111], v236, s[2:3] offset:896
	v_mfma_f32_16x16x32_bf16 v[32:35], v[160:163], v[68:71], v[32:35]
	s_waitcnt vmcnt(8)
	ds_write_b128 v3, v[104:107] offset:20480
	v_mfma_f32_16x16x32_bf16 v[44:47], v[164:167], v[68:71], v[44:47]
	v_mfma_f32_16x16x32_bf16 v[16:19], v[172:175], v[68:71], v[16:19]
	v_mfma_f32_16x16x32_bf16 v[76:79], v[168:171], v[68:71], v[76:79]
	global_load_dwordx4 v[68:71], v239, s[2:3] offset:896
	v_mfma_f32_16x16x32_bf16 v[36:39], v[160:163], v[88:91], v[36:39]
	s_waitcnt vmcnt(8)
	ds_write_b128 v3, v[92:95] offset:24576
	v_mfma_f32_16x16x32_bf16 v[48:51], v[164:167], v[88:91], v[48:51]
	v_mfma_f32_16x16x32_bf16 v[60:63], v[168:171], v[88:91], v[60:63]
	v_mfma_f32_16x16x32_bf16 v[20:23], v[172:175], v[88:91], v[20:23]
	global_load_dwordx4 v[88:91], v240, s[2:3] offset:896
	v_mfma_f32_16x16x32_bf16 v[40:43], v[160:163], v[120:123], v[40:43]
	s_waitcnt vmcnt(8)
	ds_write_b128 v3, v[64:67] offset:28672
	v_mfma_f32_16x16x32_bf16 v[52:55], v[164:167], v[120:123], v[52:55]
	v_mfma_f32_16x16x32_bf16 v[56:59], v[168:171], v[120:123], v[56:59]
	v_mfma_f32_16x16x32_bf16 v[24:27], v[172:175], v[120:123], v[24:27]
	s_setprio 0
	s_waitcnt lgkmcnt(0)
	s_barrier
	ds_read_b128 v[64:67], v7
	ds_read_b128 v[92:95], v7 offset:2048
	ds_read_b128 v[104:107], v8 offset:16384
	ds_read_b128 v[116:119], v8 offset:18432
	ds_read_b128 v[120:123], v7 offset:4096
	ds_read_b128 v[132:135], v7 offset:6144
	ds_read_b128 v[136:139], v8 offset:20480
	ds_read_b128 v[148:151], v8 offset:22528
	s_setprio 2
	v_add_u32_e32 v241, 0x1d000, v9
	global_load_dwordx4 v[152:155], v241, s[0:1]
	s_waitcnt vmcnt(8)
	ds_write_b128 v3, v[156:159] offset:32768
	ds_read_b128 v[156:159], v5
	ds_read_b128 v[160:163], v6 offset:16384
	s_waitcnt lgkmcnt(8)
	v_mfma_f32_16x16x32_bf16 v[28:31], v[104:107], v[64:67], v[28:31]
	s_waitcnt lgkmcnt(4)
	v_mfma_f32_16x16x32_bf16 v[80:83], v[136:139], v[64:67], v[80:83]
	s_waitcnt lgkmcnt(3)
	v_mfma_f32_16x16x32_bf16 v[12:15], v[148:151], v[64:67], v[12:15]
	v_mfma_f32_16x16x32_bf16 v[72:75], v[116:119], v[64:67], v[72:75]
	v_add_u32_e32 v242, 0x55000, v9
	global_load_dwordx4 v[64:67], v242, s[0:1]
	s_waitcnt vmcnt(8)
	ds_write_b128 v3, v[84:87] offset:36864
	ds_read_b128 v[84:87], v5 offset:2048
	ds_read_b128 v[164:167], v6 offset:18432
	v_mfma_f32_16x16x32_bf16 v[32:35], v[104:107], v[92:95], v[32:35]
	v_mfma_f32_16x16x32_bf16 v[44:47], v[116:119], v[92:95], v[44:47]
	v_mfma_f32_16x16x32_bf16 v[16:19], v[148:151], v[92:95], v[16:19]
	v_mfma_f32_16x16x32_bf16 v[76:79], v[136:139], v[92:95], v[76:79]
	v_add_u32_e32 v243, 0x8d000, v9
	global_load_dwordx4 v[92:95], v243, s[0:1]
	s_waitcnt vmcnt(8)
	ds_write_b128 v3, v[100:103] offset:40960
	ds_read_b128 v[100:103], v5 offset:4096
	ds_read_b128 v[168:171], v6 offset:20480
	v_mfma_f32_16x16x32_bf16 v[36:39], v[104:107], v[120:123], v[36:39]
	v_mfma_f32_16x16x32_bf16 v[48:51], v[116:119], v[120:123], v[48:51]
	v_mfma_f32_16x16x32_bf16 v[60:63], v[136:139], v[120:123], v[60:63]
	v_mfma_f32_16x16x32_bf16 v[20:23], v[148:151], v[120:123], v[20:23]
	v_add_u32_e32 v244, 0xc5000, v9
	global_load_dwordx4 v[120:123], v244, s[0:1]
	s_waitcnt vmcnt(8)
	ds_write_b128 v3, v[124:127] offset:45056
	ds_read_b128 v[124:127], v5 offset:6144
	ds_read_b128 v[172:175], v6 offset:22528
	v_mfma_f32_16x16x32_bf16 v[40:43], v[104:107], v[132:135], v[40:43]
	v_mfma_f32_16x16x32_bf16 v[52:55], v[116:119], v[132:135], v[52:55]
	v_mfma_f32_16x16x32_bf16 v[56:59], v[136:139], v[132:135], v[56:59]
	v_mfma_f32_16x16x32_bf16 v[24:27], v[148:151], v[132:135], v[24:27]
	global_load_dwordx4 v[104:107], v4, s[2:3] offset:1024
	s_waitcnt vmcnt(8)
	ds_write_b128 v3, v[112:115] offset:49152
	s_waitcnt lgkmcnt(10)
	v_mfma_f32_16x16x32_bf16 v[28:31], v[160:163], v[156:159], v[28:31]
	s_waitcnt lgkmcnt(4)
	v_mfma_f32_16x16x32_bf16 v[80:83], v[168:171], v[156:159], v[80:83]
	s_waitcnt lgkmcnt(1)
	v_mfma_f32_16x16x32_bf16 v[12:15], v[172:175], v[156:159], v[12:15]
	v_mfma_f32_16x16x32_bf16 v[72:75], v[164:167], v[156:159], v[72:75]
	global_load_dwordx4 v[112:115], v236, s[2:3] offset:1024
	v_mfma_f32_16x16x32_bf16 v[32:35], v[160:163], v[84:87], v[32:35]
	s_waitcnt vmcnt(8)
	ds_write_b128 v3, v[108:111] offset:53248
	v_mfma_f32_16x16x32_bf16 v[44:47], v[164:167], v[84:87], v[44:47]
	v_mfma_f32_16x16x32_bf16 v[16:19], v[172:175], v[84:87], v[16:19]
	v_mfma_f32_16x16x32_bf16 v[76:79], v[168:171], v[84:87], v[76:79]
	global_load_dwordx4 v[84:87], v239, s[2:3] offset:1024
	v_mfma_f32_16x16x32_bf16 v[36:39], v[160:163], v[100:103], v[36:39]
	s_waitcnt vmcnt(8)
	ds_write_b128 v3, v[68:71] offset:57344
	v_mfma_f32_16x16x32_bf16 v[48:51], v[164:167], v[100:103], v[48:51]
	v_mfma_f32_16x16x32_bf16 v[60:63], v[168:171], v[100:103], v[60:63]
	v_mfma_f32_16x16x32_bf16 v[20:23], v[172:175], v[100:103], v[20:23]
	global_load_dwordx4 v[68:71], v240, s[2:3] offset:1024
	v_mfma_f32_16x16x32_bf16 v[40:43], v[160:163], v[124:127], v[40:43]
	s_waitcnt vmcnt(8)
	ds_write_b128 v3, v[88:91] offset:61440
	v_mfma_f32_16x16x32_bf16 v[52:55], v[164:167], v[124:127], v[52:55]
	v_mfma_f32_16x16x32_bf16 v[56:59], v[168:171], v[124:127], v[56:59]
	v_mfma_f32_16x16x32_bf16 v[24:27], v[172:175], v[124:127], v[24:27]
	s_setprio 0
	s_waitcnt lgkmcnt(0)
	s_barrier
; template <int MODE>
; __device__ __forceinline__ void gemm_tile(const Params& P, int tm, int tn, unsigned char* smem) {
;     ...
; #pragma unroll
;         for (int i = 0; i < 4; ++i) { fa[i] = *(const bf16x8*)(sA + arow_off + i * 2048 + ch0); fb[i] = *(const bf16x8*)(sB + brow_off + i * 2048 + ch0); }
;         __builtin_amdgcn_sched_barrier(0);
;         __builtin_amdgcn_s_setprio(2);
;         if (wr_ok) *(uint4*)(nA + soff0) = ra0;
;         if (ld_ok) ra0 = *(const uint4*)(Ab + (aoff + 0u * LDA + koa));
;         ga[0] = *(const bf16x8*)(sA + arow_off + 0 * 2048 + ch1); gb[0] = *(const bf16x8*)(sB + brow_off + 0 * 2048 + ch1);
;         __builtin_amdgcn_sched_barrier(0);
; #pragma unroll
;         for (int j = 0; j < 4; ++j) acc[0][j] = __builtin_amdgcn_mfma_f32_16x16x32_bf16(fb[j], fa[0], acc[0][j], 0, 0, 0);
;         __builtin_amdgcn_sched_barrier(0);
;         if (wr_ok) *(uint4*)(nA + soff0 + 4096) = ra1;
;         if (ld_ok) ra1 = *(const uint4*)(Ab + (aoff + 32u * LDA + koa));
;         ga[1] = *(const bf16x8*)(sA + arow_off + 1 * 2048 + ch1); gb[1] = *(const bf16x8*)(sB + brow_off + 1 * 2048 + ch1);
;         __builtin_amdgcn_sched_barrier(0);
; #pragma unroll
;         for (int j = 0; j < 4; ++j) acc[1][j] = __builtin_amdgcn_mfma_f32_16x16x32_bf16(fb[j], fa[1], acc[1][j], 0, 0, 0);
;         __builtin_amdgcn_sched_barrier(0);
;         if (wr_ok) *(uint4*)(nA + soff0 + 8192) = ra2;
;         if (ld_ok) ra2 = *(const uint4*)(Ab + (aoff + 64u * LDA + koa));
;         ga[2] = *(const bf16x8*)(sA + arow_off + 2 * 2048 + ch1); gb[2] = *(const bf16x8*)(sB + brow_off + 2 * 2048 + ch1);
;         __builtin_amdgcn_sched_barrier(0);
; #pragma unroll
;         for (int j = 0; j < 4; ++j) acc[2][j] = __builtin_amdgcn_mfma_f32_16x16x32_bf16(fb[j], fa[2], acc[2][j], 0, 0, 0);
;         __builtin_amdgcn_sched_barrier(0);
;         if (wr_ok) *(uint4*)(nA + soff0 + 12288) = ra3;
;         if (ld_ok) ra3 = *(const uint4*)(Ab + (aoff + 96u * LDA + koa));
;         ga[3] = *(const bf16x8*)(sA + arow_off + 3 * 2048 + ch1); gb[3] = *(const bf16x8*)(sB + brow_off + 3 * 2048 + ch1);
;         __builtin_amdgcn_sched_barrier(0);
; #pragma unroll
;         for (int j = 0; j < 4; ++j) acc[3][j] = __builtin_amdgcn_mfma_f32_16x16x32_bf16(fb[j], fa[3], acc[3][j], 0, 0, 0);
;         __builtin_amdgcn_sched_barrier(0);
;         if (wr_ok) *(uint4*)(nB + soff0) = rb0;
	ds_read_b128 v[88:91], v7 offset:32768
	ds_read_b128 v[100:103], v7 offset:34816
	ds_read_b128 v[108:111], v8 offset:49152
	ds_read_b128 v[116:119], v8 offset:51200
	ds_read_b128 v[124:127], v7 offset:36864
	ds_read_b128 v[132:135], v7 offset:38912
	ds_read_b128 v[136:139], v8 offset:53248
	ds_read_b128 v[148:151], v8 offset:55296
	s_setprio 2
	global_load_dwordx4 v[156:159], v241, s[0:1] offset:128
	s_waitcnt vmcnt(8)
	ds_write_b128 v3, v[152:155]
	ds_read_b128 v[152:155], v5 offset:32768
	ds_read_b128 v[160:163], v6 offset:49152
	s_waitcnt lgkmcnt(8)
	v_mfma_f32_16x16x32_bf16 v[28:31], v[108:111], v[88:91], v[28:31]
	s_waitcnt lgkmcnt(4)
	v_mfma_f32_16x16x32_bf16 v[80:83], v[136:139], v[88:91], v[80:83]
	s_waitcnt lgkmcnt(3)
	v_mfma_f32_16x16x32_bf16 v[12:15], v[148:151], v[88:91], v[12:15]
	v_mfma_f32_16x16x32_bf16 v[72:75], v[116:119], v[88:91], v[72:75]
	global_load_dwordx4 v[88:91], v242, s[0:1] offset:128
	v_mfma_f32_16x16x32_bf16 v[32:35], v[108:111], v[100:103], v[32:35]
	s_waitcnt vmcnt(8)
	ds_write_b128 v3, v[64:67] offset:4096
	v_mfma_f32_16x16x32_bf16 v[44:47], v[116:119], v[100:103], v[44:47]
	ds_read_b128 v[64:67], v5 offset:34816
	v_mfma_f32_16x16x32_bf16 v[16:19], v[148:151], v[100:103], v[16:19]
	ds_read_b128 v[164:167], v6 offset:51200
	v_mfma_f32_16x16x32_bf16 v[76:79], v[136:139], v[100:103], v[76:79]
	global_load_dwordx4 v[100:103], v243, s[0:1] offset:128
	v_mfma_f32_16x16x32_bf16 v[36:39], v[108:111], v[124:127], v[36:39]
	s_waitcnt vmcnt(8)
	ds_write_b128 v3, v[92:95] offset:8192
	v_mfma_f32_16x16x32_bf16 v[48:51], v[116:119], v[124:127], v[48:51]
	ds_read_b128 v[92:95], v5 offset:36864
	v_mfma_f32_16x16x32_bf16 v[60:63], v[136:139], v[124:127], v[60:63]
	ds_read_b128 v[168:171], v6 offset:53248
	v_mfma_f32_16x16x32_bf16 v[20:23], v[148:151], v[124:127], v[20:23]
	global_load_dwordx4 v[124:127], v244, s[0:1] offset:128
	v_mfma_f32_16x16x32_bf16 v[40:43], v[108:111], v[132:135], v[40:43]
	s_waitcnt vmcnt(8)
	ds_write_b128 v3, v[120:123] offset:12288
	v_mfma_f32_16x16x32_bf16 v[52:55], v[116:119], v[132:135], v[52:55]
	ds_read_b128 v[120:123], v5 offset:38912
	v_mfma_f32_16x16x32_bf16 v[56:59], v[136:139], v[132:135], v[56:59]
	ds_read_b128 v[172:175], v6 offset:55296
	v_mfma_f32_16x16x32_bf16 v[24:27], v[148:151], v[132:135], v[24:27]
	global_load_dwordx4 v[108:111], v4, s[2:3] offset:1152
	s_waitcnt vmcnt(8)
	ds_write_b128 v3, v[104:107] offset:16384
	s_waitcnt lgkmcnt(10)
	v_mfma_f32_16x16x32_bf16 v[28:31], v[160:163], v[152:155], v[28:31]
	s_waitcnt lgkmcnt(4)
	v_mfma_f32_16x16x32_bf16 v[80:83], v[168:171], v[152:155], v[80:83]
	s_waitcnt lgkmcnt(1)
	v_mfma_f32_16x16x32_bf16 v[12:15], v[172:175], v[152:155], v[12:15]
	v_mfma_f32_16x16x32_bf16 v[72:75], v[164:167], v[152:155], v[72:75]
	global_load_dwordx4 v[104:107], v236, s[2:3] offset:1152
	v_mfma_f32_16x16x32_bf16 v[32:35], v[160:163], v[64:67], v[32:35]
	s_waitcnt vmcnt(8)
	ds_write_b128 v3, v[112:115] offset:20480
	v_mfma_f32_16x16x32_bf16 v[44:47], v[164:167], v[64:67], v[44:47]
	v_mfma_f32_16x16x32_bf16 v[16:19], v[172:175], v[64:67], v[16:19]
	v_mfma_f32_16x16x32_bf16 v[76:79], v[168:171], v[64:67], v[76:79]
	global_load_dwordx4 v[64:67], v239, s[2:3] offset:1152
	v_mfma_f32_16x16x32_bf16 v[36:39], v[160:163], v[92:95], v[36:39]
	s_waitcnt vmcnt(8)
	ds_write_b128 v3, v[84:87] offset:24576
	v_mfma_f32_16x16x32_bf16 v[48:51], v[164:167], v[92:95], v[48:51]
	v_mfma_f32_16x16x32_bf16 v[60:63], v[168:171], v[92:95], v[60:63]
	v_mfma_f32_16x16x32_bf16 v[20:23], v[172:175], v[92:95], v[20:23]
	global_load_dwordx4 v[84:87], v240, s[2:3] offset:1152
	v_mfma_f32_16x16x32_bf16 v[40:43], v[160:163], v[120:123], v[40:43]
	s_waitcnt vmcnt(8)
	ds_write_b128 v3, v[68:71] offset:28672
	v_mfma_f32_16x16x32_bf16 v[52:55], v[164:167], v[120:123], v[52:55]
	v_mfma_f32_16x16x32_bf16 v[56:59], v[168:171], v[120:123], v[56:59]
	v_mfma_f32_16x16x32_bf16 v[24:27], v[172:175], v[120:123], v[24:27]
	s_setprio 0
	s_waitcnt lgkmcnt(0)
	s_barrier
	ds_read_b128 v[68:71], v7
	ds_read_b128 v[92:95], v7 offset:2048
	ds_read_b128 v[112:115], v8 offset:16384
	ds_read_b128 v[116:119], v8 offset:18432
	ds_read_b128 v[120:123], v7 offset:4096
	ds_read_b128 v[132:135], v7 offset:6144
	ds_read_b128 v[136:139], v8 offset:20480
	ds_read_b128 v[148:151], v8 offset:22528
	s_setprio 2
	global_load_dwordx4 v[152:155], v241, s[0:1] offset:256
	s_waitcnt vmcnt(8)
	ds_write_b128 v3, v[156:159] offset:32768
	ds_read_b128 v[156:159], v5
	ds_read_b128 v[160:163], v6 offset:16384
	s_waitcnt lgkmcnt(8)
	v_mfma_f32_16x16x32_bf16 v[28:31], v[112:115], v[68:71], v[28:31]
	s_waitcnt lgkmcnt(4)
	v_mfma_f32_16x16x32_bf16 v[80:83], v[136:139], v[68:71], v[80:83]
	s_waitcnt lgkmcnt(3)
	v_mfma_f32_16x16x32_bf16 v[12:15], v[148:151], v[68:71], v[12:15]
	v_mfma_f32_16x16x32_bf16 v[72:75], v[116:119], v[68:71], v[72:75]
	global_load_dwordx4 v[68:71], v242, s[0:1] offset:256
	v_mfma_f32_16x16x32_bf16 v[32:35], v[112:115], v[92:95], v[32:35]
	s_waitcnt vmcnt(8)
	ds_write_b128 v3, v[88:91] offset:36864
	v_mfma_f32_16x16x32_bf16 v[44:47], v[116:119], v[92:95], v[44:47]
	ds_read_b128 v[88:91], v5 offset:2048
	v_mfma_f32_16x16x32_bf16 v[16:19], v[148:151], v[92:95], v[16:19]
	ds_read_b128 v[164:167], v6 offset:18432
	v_mfma_f32_16x16x32_bf16 v[76:79], v[136:139], v[92:95], v[76:79]
	global_load_dwordx4 v[92:95], v243, s[0:1] offset:256
	v_mfma_f32_16x16x32_bf16 v[36:39], v[112:115], v[120:123], v[36:39]
	s_waitcnt vmcnt(8)
; template <int MODE>
; __device__ __forceinline__ void gemm_tile(const Params& P, int tm, int tn, unsigned char* smem) {
;     ...
; #pragma unroll
;         for (int i = 0; i < 4; ++i) { fa[i] = *(const bf16x8*)(sA + arow_off + i * 2048 + ch0); fb[i] = *(const bf16x8*)(sB + brow_off + i * 2048 + ch0); }
;         __builtin_amdgcn_sched_barrier(0);
;         __builtin_amdgcn_s_setprio(2);
;         if (wr_ok) *(uint4*)(nA + soff0) = ra0;
;         if (ld_ok) ra0 = *(const uint4*)(Ab + (aoff + 0u * LDA + koa));
;         ga[0] = *(const bf16x8*)(sA + arow_off + 0 * 2048 + ch1); gb[0] = *(const bf16x8*)(sB + brow_off + 0 * 2048 + ch1);
;         __builtin_amdgcn_sched_barrier(0);
; #pragma unroll
;         for (int j = 0; j < 4; ++j) acc[0][j] = __builtin_amdgcn_mfma_f32_16x16x32_bf16(fb[j], fa[0], acc[0][j], 0, 0, 0);
;         __builtin_amdgcn_sched_barrier(0);
;         if (wr_ok) *(uint4*)(nA + soff0 + 4096) = ra1;
;         if (ld_ok) ra1 = *(const uint4*)(Ab + (aoff + 32u * LDA + koa));
;         ga[1] = *(const bf16x8*)(sA + arow_off + 1 * 2048 + ch1); gb[1] = *(const bf16x8*)(sB + brow_off + 1 * 2048 + ch1);
;         __builtin_amdgcn_sched_barrier(0);
; #pragma unroll
;         for (int j = 0; j < 4; ++j) acc[1][j] = __builtin_amdgcn_mfma_f32_16x16x32_bf16(fb[j], fa[1], acc[1][j], 0, 0, 0);
;         __builtin_amdgcn_sched_barrier(0);
;         if (wr_ok) *(uint4*)(nA + soff0 + 8192) = ra2;
;         if (ld_ok) ra2 = *(const uint4*)(Ab + (aoff + 64u * LDA + koa));
;         ga[2] = *(const bf16x8*)(sA + arow_off + 2 * 2048 + ch1); gb[2] = *(const bf16x8*)(sB + brow_off + 2 * 2048 + ch1);
;         __builtin_amdgcn_sched_barrier(0);
; #pragma unroll
;         for (int j = 0; j < 4; ++j) acc[2][j] = __builtin_amdgcn_mfma_f32_16x16x32_bf16(fb[j], fa[2], acc[2][j], 0, 0, 0);
;         __builtin_amdgcn_sched_barrier(0);
;         if (wr_ok) *(uint4*)(nA + soff0 + 12288) = ra3;
;         if (ld_ok) ra3 = *(const uint4*)(Ab + (aoff + 96u * LDA + koa));
;         ga[3] = *(const bf16x8*)(sA + arow_off + 3 * 2048 + ch1); gb[3] = *(const bf16x8*)(sB + brow_off + 3 * 2048 + ch1);
;         __builtin_amdgcn_sched_barrier(0);
; #pragma unroll
;         for (int j = 0; j < 4; ++j) acc[3][j] = __builtin_amdgcn_mfma_f32_16x16x32_bf16(fb[j], fa[3], acc[3][j], 0, 0, 0);
;         __builtin_amdgcn_sched_barrier(0);
;         if (wr_ok) *(uint4*)(nB + soff0) = rb0;
	ds_write_b128 v3, v[100:103] offset:40960
	v_mfma_f32_16x16x32_bf16 v[48:51], v[116:119], v[120:123], v[48:51]
	ds_read_b128 v[100:103], v5 offset:4096
	v_mfma_f32_16x16x32_bf16 v[60:63], v[136:139], v[120:123], v[60:63]
	ds_read_b128 v[168:171], v6 offset:20480
	v_mfma_f32_16x16x32_bf16 v[20:23], v[148:151], v[120:123], v[20:23]
	global_load_dwordx4 v[120:123], v244, s[0:1] offset:256
	v_mfma_f32_16x16x32_bf16 v[40:43], v[112:115], v[132:135], v[40:43]
	s_waitcnt vmcnt(8)
	ds_write_b128 v3, v[124:127] offset:45056
	v_mfma_f32_16x16x32_bf16 v[52:55], v[116:119], v[132:135], v[52:55]
	ds_read_b128 v[124:127], v5 offset:6144
	v_mfma_f32_16x16x32_bf16 v[56:59], v[136:139], v[132:135], v[56:59]
	ds_read_b128 v[172:175], v6 offset:22528
	v_mfma_f32_16x16x32_bf16 v[24:27], v[148:151], v[132:135], v[24:27]
	global_load_dwordx4 v[112:115], v4, s[2:3] offset:1280
	s_waitcnt vmcnt(8)
	ds_write_b128 v3, v[108:111] offset:49152
	s_waitcnt lgkmcnt(10)
	v_mfma_f32_16x16x32_bf16 v[28:31], v[160:163], v[156:159], v[28:31]
	s_waitcnt lgkmcnt(4)
	v_mfma_f32_16x16x32_bf16 v[80:83], v[168:171], v[156:159], v[80:83]
	s_waitcnt lgkmcnt(1)
	v_mfma_f32_16x16x32_bf16 v[12:15], v[172:175], v[156:159], v[12:15]
	v_mfma_f32_16x16x32_bf16 v[72:75], v[164:167], v[156:159], v[72:75]
	global_load_dwordx4 v[108:111], v236, s[2:3] offset:1280
	v_mfma_f32_16x16x32_bf16 v[32:35], v[160:163], v[88:91], v[32:35]
	s_waitcnt vmcnt(8)
	ds_write_b128 v3, v[104:107] offset:53248
	v_mfma_f32_16x16x32_bf16 v[44:47], v[164:167], v[88:91], v[44:47]
	v_mfma_f32_16x16x32_bf16 v[16:19], v[172:175], v[88:91], v[16:19]
	v_mfma_f32_16x16x32_bf16 v[76:79], v[168:171], v[88:91], v[76:79]
	global_load_dwordx4 v[88:91], v239, s[2:3] offset:1280
	v_mfma_f32_16x16x32_bf16 v[36:39], v[160:163], v[100:103], v[36:39]
	s_waitcnt vmcnt(8)
	ds_write_b128 v3, v[64:67] offset:57344
	v_mfma_f32_16x16x32_bf16 v[48:51], v[164:167], v[100:103], v[48:51]
	v_mfma_f32_16x16x32_bf16 v[60:63], v[168:171], v[100:103], v[60:63]
	v_mfma_f32_16x16x32_bf16 v[20:23], v[172:175], v[100:103], v[20:23]
	global_load_dwordx4 v[64:67], v240, s[2:3] offset:1280
	v_mfma_f32_16x16x32_bf16 v[40:43], v[160:163], v[124:127], v[40:43]
	s_waitcnt vmcnt(8)
	ds_write_b128 v3, v[84:87] offset:61440
	v_mfma_f32_16x16x32_bf16 v[52:55], v[164:167], v[124:127], v[52:55]
	v_mfma_f32_16x16x32_bf16 v[56:59], v[168:171], v[124:127], v[56:59]
	v_mfma_f32_16x16x32_bf16 v[24:27], v[172:175], v[124:127], v[24:27]
	s_setprio 0
	s_waitcnt lgkmcnt(0)
	s_barrier
	ds_read_b128 v[84:87], v7 offset:32768
	ds_read_b128 v[100:103], v7 offset:34816
	ds_read_b128 v[104:107], v8 offset:49152
	ds_read_b128 v[116:119], v8 offset:51200
	ds_read_b128 v[124:127], v7 offset:36864
	ds_read_b128 v[132:135], v7 offset:38912
	ds_read_b128 v[136:139], v8 offset:53248
	ds_read_b128 v[148:151], v8 offset:55296
	s_setprio 2
	global_load_dwordx4 v[156:159], v241, s[0:1] offset:384
	s_waitcnt vmcnt(8)
	ds_write_b128 v3, v[152:155]
	ds_read_b128 v[152:155], v5 offset:32768
	ds_read_b128 v[160:163], v6 offset:49152
	s_waitcnt lgkmcnt(8)
	v_mfma_f32_16x16x32_bf16 v[28:31], v[104:107], v[84:87], v[28:31]
	s_waitcnt lgkmcnt(4)
	v_mfma_f32_16x16x32_bf16 v[80:83], v[136:139], v[84:87], v[80:83]
	s_waitcnt lgkmcnt(3)
	v_mfma_f32_16x16x32_bf16 v[12:15], v[148:151], v[84:87], v[12:15]
	v_mfma_f32_16x16x32_bf16 v[72:75], v[116:119], v[84:87], v[72:75]
	global_load_dwordx4 v[84:87], v242, s[0:1] offset:384
	v_mfma_f32_16x16x32_bf16 v[32:35], v[104:107], v[100:103], v[32:35]
	s_waitcnt vmcnt(8)
	ds_write_b128 v3, v[68:71] offset:4096
	v_mfma_f32_16x16x32_bf16 v[44:47], v[116:119], v[100:103], v[44:47]
	ds_read_b128 v[68:71], v5 offset:34816
	v_mfma_f32_16x16x32_bf16 v[16:19], v[148:151], v[100:103], v[16:19]
	ds_read_b128 v[164:167], v6 offset:51200
	v_mfma_f32_16x16x32_bf16 v[76:79], v[136:139], v[100:103], v[76:79]
	global_load_dwordx4 v[100:103], v243, s[0:1] offset:384
	v_mfma_f32_16x16x32_bf16 v[36:39], v[104:107], v[124:127], v[36:39]
	s_waitcnt vmcnt(8)
	ds_write_b128 v3, v[92:95] offset:8192
	v_mfma_f32_16x16x32_bf16 v[48:51], v[116:119], v[124:127], v[48:51]
	ds_read_b128 v[92:95], v5 offset:36864
	v_mfma_f32_16x16x32_bf16 v[60:63], v[136:139], v[124:127], v[60:63]
	ds_read_b128 v[168:171], v6 offset:53248
	v_mfma_f32_16x16x32_bf16 v[20:23], v[148:151], v[124:127], v[20:23]
	global_load_dwordx4 v[124:127], v244, s[0:1] offset:384
	v_mfma_f32_16x16x32_bf16 v[40:43], v[104:107], v[132:135], v[40:43]
	s_waitcnt vmcnt(8)
	ds_write_b128 v3, v[120:123] offset:12288
	v_mfma_f32_16x16x32_bf16 v[52:55], v[116:119], v[132:135], v[52:55]
	ds_read_b128 v[120:123], v5 offset:38912
	v_mfma_f32_16x16x32_bf16 v[56:59], v[136:139], v[132:135], v[56:59]
	ds_read_b128 v[172:175], v6 offset:55296
	v_mfma_f32_16x16x32_bf16 v[24:27], v[148:151], v[132:135], v[24:27]
	global_load_dwordx4 v[104:107], v4, s[2:3] offset:1408
	s_waitcnt vmcnt(8)
	ds_write_b128 v3, v[112:115] offset:16384
	s_waitcnt lgkmcnt(10)
	v_mfma_f32_16x16x32_bf16 v[28:31], v[160:163], v[152:155], v[28:31]
	s_waitcnt lgkmcnt(4)
	v_mfma_f32_16x16x32_bf16 v[80:83], v[168:171], v[152:155], v[80:83]
	s_waitcnt lgkmcnt(1)
	v_mfma_f32_16x16x32_bf16 v[12:15], v[172:175], v[152:155], v[12:15]
	v_mfma_f32_16x16x32_bf16 v[72:75], v[164:167], v[152:155], v[72:75]
	global_load_dwordx4 v[112:115], v236, s[2:3] offset:1408
	v_mfma_f32_16x16x32_bf16 v[32:35], v[160:163], v[68:71], v[32:35]
	s_waitcnt vmcnt(8)
	ds_write_b128 v3, v[108:111] offset:20480
	v_mfma_f32_16x16x32_bf16 v[44:47], v[164:167], v[68:71], v[44:47]
	v_mfma_f32_16x16x32_bf16 v[16:19], v[172:175], v[68:71], v[16:19]
	v_mfma_f32_16x16x32_bf16 v[76:79], v[168:171], v[68:71], v[76:79]
	global_load_dwordx4 v[68:71], v239, s[2:3] offset:1408
	v_mfma_f32_16x16x32_bf16 v[36:39], v[160:163], v[92:95], v[36:39]
	s_waitcnt vmcnt(8)
	ds_write_b128 v3, v[88:91] offset:24576
	v_mfma_f32_16x16x32_bf16 v[48:51], v[164:167], v[92:95], v[48:51]
	v_mfma_f32_16x16x32_bf16 v[60:63], v[168:171], v[92:95], v[60:63]
	v_mfma_f32_16x16x32_bf16 v[20:23], v[172:175], v[92:95], v[20:23]
	global_load_dwordx4 v[88:91], v240, s[2:3] offset:1408
	v_mfma_f32_16x16x32_bf16 v[40:43], v[160:163], v[120:123], v[40:43]
	s_waitcnt vmcnt(8)
	ds_write_b128 v3, v[64:67] offset:28672
	v_mfma_f32_16x16x32_bf16 v[52:55], v[164:167], v[120:123], v[52:55]
	v_mfma_f32_16x16x32_bf16 v[56:59], v[168:171], v[120:123], v[56:59]
	v_mfma_f32_16x16x32_bf16 v[24:27], v[172:175], v[120:123], v[24:27]
	s_setprio 0
	s_waitcnt lgkmcnt(0)
	s_barrier
; template <int MODE>
; __device__ __forceinline__ void gemm_tile(const Params& P, int tm, int tn, unsigned char* smem) {
;     ...
; #pragma unroll
;         for (int i = 0; i < 4; ++i) { fa[i] = *(const bf16x8*)(sA + arow_off + i * 2048 + ch0); fb[i] = *(const bf16x8*)(sB + brow_off + i * 2048 + ch0); }
;         __builtin_amdgcn_sched_barrier(0);
;         __builtin_amdgcn_s_setprio(2);
;         if (wr_ok) *(uint4*)(nA + soff0) = ra0;
;         if (ld_ok) ra0 = *(const uint4*)(Ab + (aoff + 0u * LDA + koa));
;         ga[0] = *(const bf16x8*)(sA + arow_off + 0 * 2048 + ch1); gb[0] = *(const bf16x8*)(sB + brow_off + 0 * 2048 + ch1);
;         __builtin_amdgcn_sched_barrier(0);
; #pragma unroll
;         for (int j = 0; j < 4; ++j) acc[0][j] = __builtin_amdgcn_mfma_f32_16x16x32_bf16(fb[j], fa[0], acc[0][j], 0, 0, 0);
;         __builtin_amdgcn_sched_barrier(0);
;         if (wr_ok) *(uint4*)(nA + soff0 + 4096) = ra1;
;         if (ld_ok) ra1 = *(const uint4*)(Ab + (aoff + 32u * LDA + koa));
;         ga[1] = *(const bf16x8*)(sA + arow_off + 1 * 2048 + ch1); gb[1] = *(const bf16x8*)(sB + brow_off + 1 * 2048 + ch1);
;         __builtin_amdgcn_sched_barrier(0);
; #pragma unroll
;         for (int j = 0; j < 4; ++j) acc[1][j] = __builtin_amdgcn_mfma_f32_16x16x32_bf16(fb[j], fa[1], acc[1][j], 0, 0, 0);
;         __builtin_amdgcn_sched_barrier(0);
;         if (wr_ok) *(uint4*)(nA + soff0 + 8192) = ra2;
;         if (ld_ok) ra2 = *(const uint4*)(Ab + (aoff + 64u * LDA + koa));
;         ga[2] = *(const bf16x8*)(sA + arow_off + 2 * 2048 + ch1); gb[2] = *(const bf16x8*)(sB + brow_off + 2 * 2048 + ch1);
;         __builtin_amdgcn_sched_barrier(0);
; #pragma unroll
;         for (int j = 0; j < 4; ++j) acc[2][j] = __builtin_amdgcn_mfma_f32_16x16x32_bf16(fb[j], fa[2], acc[2][j], 0, 0, 0);
;         __builtin_amdgcn_sched_barrier(0);
;         if (wr_ok) *(uint4*)(nA + soff0 + 12288) = ra3;
;         if (ld_ok) ra3 = *(const uint4*)(Ab + (aoff + 96u * LDA + koa));
;         ga[3] = *(const bf16x8*)(sA + arow_off + 3 * 2048 + ch1); gb[3] = *(const bf16x8*)(sB + brow_off + 3 * 2048 + ch1);
;         __builtin_amdgcn_sched_barrier(0);
; #pragma unroll
;         for (int j = 0; j < 4; ++j) acc[3][j] = __builtin_amdgcn_mfma_f32_16x16x32_bf16(fb[j], fa[3], acc[3][j], 0, 0, 0);
;         __builtin_amdgcn_sched_barrier(0);
;         if (wr_ok) *(uint4*)(nB + soff0) = rb0;
	ds_read_b128 v[64:67], v7
	ds_read_b128 v[92:95], v7 offset:2048
	ds_read_b128 v[108:111], v8 offset:16384
	ds_read_b128 v[116:119], v8 offset:18432
	ds_read_b128 v[120:123], v7 offset:4096
	ds_read_b128 v[132:135], v7 offset:6144
	ds_read_b128 v[136:139], v8 offset:20480
	ds_read_b128 v[148:151], v8 offset:22528
	s_setprio 2
	global_load_dwordx4 v[152:155], v241, s[0:1] offset:512
	s_waitcnt vmcnt(8)
	ds_write_b128 v3, v[156:159] offset:32768
	ds_read_b128 v[156:159], v5
	ds_read_b128 v[160:163], v6 offset:16384
	s_waitcnt lgkmcnt(8)
	v_mfma_f32_16x16x32_bf16 v[28:31], v[108:111], v[64:67], v[28:31]
	s_waitcnt lgkmcnt(4)
	v_mfma_f32_16x16x32_bf16 v[80:83], v[136:139], v[64:67], v[80:83]
	s_waitcnt lgkmcnt(3)
	v_mfma_f32_16x16x32_bf16 v[12:15], v[148:151], v[64:67], v[12:15]
	v_mfma_f32_16x16x32_bf16 v[72:75], v[116:119], v[64:67], v[72:75]
	global_load_dwordx4 v[64:67], v242, s[0:1] offset:512
	v_mfma_f32_16x16x32_bf16 v[32:35], v[108:111], v[92:95], v[32:35]
	s_waitcnt vmcnt(8)
	ds_write_b128 v3, v[84:87] offset:36864
	v_mfma_f32_16x16x32_bf16 v[44:47], v[116:119], v[92:95], v[44:47]
	ds_read_b128 v[84:87], v5 offset:2048
	v_mfma_f32_16x16x32_bf16 v[16:19], v[148:151], v[92:95], v[16:19]
	ds_read_b128 v[164:167], v6 offset:18432
	v_mfma_f32_16x16x32_bf16 v[76:79], v[136:139], v[92:95], v[76:79]
	global_load_dwordx4 v[92:95], v243, s[0:1] offset:512
	v_mfma_f32_16x16x32_bf16 v[36:39], v[108:111], v[120:123], v[36:39]
	s_waitcnt vmcnt(8)
	ds_write_b128 v3, v[100:103] offset:40960
	v_mfma_f32_16x16x32_bf16 v[48:51], v[116:119], v[120:123], v[48:51]
	ds_read_b128 v[100:103], v5 offset:4096
	v_mfma_f32_16x16x32_bf16 v[60:63], v[136:139], v[120:123], v[60:63]
	ds_read_b128 v[168:171], v6 offset:20480
	v_mfma_f32_16x16x32_bf16 v[20:23], v[148:151], v[120:123], v[20:23]
	global_load_dwordx4 v[120:123], v244, s[0:1] offset:512
	v_mfma_f32_16x16x32_bf16 v[40:43], v[108:111], v[132:135], v[40:43]
	s_waitcnt vmcnt(8)
	ds_write_b128 v3, v[124:127] offset:45056
	v_mfma_f32_16x16x32_bf16 v[52:55], v[116:119], v[132:135], v[52:55]
	ds_read_b128 v[124:127], v5 offset:6144
	v_mfma_f32_16x16x32_bf16 v[56:59], v[136:139], v[132:135], v[56:59]
	ds_read_b128 v[172:175], v6 offset:22528
	v_mfma_f32_16x16x32_bf16 v[24:27], v[148:151], v[132:135], v[24:27]
	global_load_dwordx4 v[108:111], v4, s[2:3] offset:1536
	s_waitcnt vmcnt(8)
	ds_write_b128 v3, v[104:107] offset:49152
	s_waitcnt lgkmcnt(10)
	v_mfma_f32_16x16x32_bf16 v[28:31], v[160:163], v[156:159], v[28:31]
	s_waitcnt lgkmcnt(4)
	v_mfma_f32_16x16x32_bf16 v[80:83], v[168:171], v[156:159], v[80:83]
	s_waitcnt lgkmcnt(1)
	v_mfma_f32_16x16x32_bf16 v[12:15], v[172:175], v[156:159], v[12:15]
	v_mfma_f32_16x16x32_bf16 v[72:75], v[164:167], v[156:159], v[72:75]
	global_load_dwordx4 v[104:107], v236, s[2:3] offset:1536
	v_mfma_f32_16x16x32_bf16 v[32:35], v[160:163], v[84:87], v[32:35]
	s_waitcnt vmcnt(8)
	ds_write_b128 v3, v[112:115] offset:53248
	v_mfma_f32_16x16x32_bf16 v[44:47], v[164:167], v[84:87], v[44:47]
	v_mfma_f32_16x16x32_bf16 v[16:19], v[172:175], v[84:87], v[16:19]
	v_mfma_f32_16x16x32_bf16 v[76:79], v[168:171], v[84:87], v[76:79]
	global_load_dwordx4 v[84:87], v239, s[2:3] offset:1536
	v_mfma_f32_16x16x32_bf16 v[36:39], v[160:163], v[100:103], v[36:39]
	s_waitcnt vmcnt(8)
	ds_write_b128 v3, v[68:71] offset:57344
	v_mfma_f32_16x16x32_bf16 v[48:51], v[164:167], v[100:103], v[48:51]
	v_mfma_f32_16x16x32_bf16 v[60:63], v[168:171], v[100:103], v[60:63]
	v_mfma_f32_16x16x32_bf16 v[20:23], v[172:175], v[100:103], v[20:23]
	global_load_dwordx4 v[68:71], v240, s[2:3] offset:1536
	v_mfma_f32_16x16x32_bf16 v[40:43], v[160:163], v[124:127], v[40:43]
	s_waitcnt vmcnt(8)
	ds_write_b128 v3, v[88:91] offset:61440
	v_mfma_f32_16x16x32_bf16 v[52:55], v[164:167], v[124:127], v[52:55]
	v_mfma_f32_16x16x32_bf16 v[56:59], v[168:171], v[124:127], v[56:59]
	v_mfma_f32_16x16x32_bf16 v[24:27], v[172:175], v[124:127], v[24:27]
	s_setprio 0
	s_waitcnt lgkmcnt(0)
	s_barrier
	ds_read_b128 v[88:91], v7 offset:32768
	ds_read_b128 v[100:103], v7 offset:34816
	ds_read_b128 v[112:115], v8 offset:49152
	ds_read_b128 v[116:119], v8 offset:51200
	ds_read_b128 v[124:127], v7 offset:36864
	ds_read_b128 v[132:135], v7 offset:38912
	ds_read_b128 v[136:139], v8 offset:53248
	ds_read_b128 v[148:151], v8 offset:55296
	s_setprio 2
	global_load_dwordx4 v[156:159], v241, s[0:1] offset:640
	s_waitcnt vmcnt(8)
	ds_write_b128 v3, v[152:155]
	ds_read_b128 v[152:155], v5 offset:32768
	ds_read_b128 v[160:163], v6 offset:49152
	s_waitcnt lgkmcnt(8)
	v_mfma_f32_16x16x32_bf16 v[28:31], v[112:115], v[88:91], v[28:31]
	s_waitcnt lgkmcnt(4)
	v_mfma_f32_16x16x32_bf16 v[80:83], v[136:139], v[88:91], v[80:83]
	s_waitcnt lgkmcnt(3)
	v_mfma_f32_16x16x32_bf16 v[12:15], v[148:151], v[88:91], v[12:15]
	v_mfma_f32_16x16x32_bf16 v[72:75], v[116:119], v[88:91], v[72:75]
	global_load_dwordx4 v[88:91], v242, s[0:1] offset:640
	v_mfma_f32_16x16x32_bf16 v[32:35], v[112:115], v[100:103], v[32:35]
	s_waitcnt vmcnt(8)
	ds_write_b128 v3, v[64:67] offset:4096
	v_mfma_f32_16x16x32_bf16 v[44:47], v[116:119], v[100:103], v[44:47]
	ds_read_b128 v[64:67], v5 offset:34816
	v_mfma_f32_16x16x32_bf16 v[16:19], v[148:151], v[100:103], v[16:19]
	ds_read_b128 v[164:167], v6 offset:51200
	v_mfma_f32_16x16x32_bf16 v[76:79], v[136:139], v[100:103], v[76:79]
	global_load_dwordx4 v[100:103], v243, s[0:1] offset:640
	v_mfma_f32_16x16x32_bf16 v[36:39], v[112:115], v[124:127], v[36:39]
	s_waitcnt vmcnt(8)
; template <int MODE>
; __device__ __forceinline__ void gemm_tile(const Params& P, int tm, int tn, unsigned char* smem) {
;     ...
; #pragma unroll
;         for (int i = 0; i < 4; ++i) { fa[i] = *(const bf16x8*)(sA + arow_off + i * 2048 + ch0); fb[i] = *(const bf16x8*)(sB + brow_off + i * 2048 + ch0); }
;         __builtin_amdgcn_sched_barrier(0);
;         __builtin_amdgcn_s_setprio(2);
;         if (wr_ok) *(uint4*)(nA + soff0) = ra0;
;         if (ld_ok) ra0 = *(const uint4*)(Ab + (aoff + 0u * LDA + koa));
;         ga[0] = *(const bf16x8*)(sA + arow_off + 0 * 2048 + ch1); gb[0] = *(const bf16x8*)(sB + brow_off + 0 * 2048 + ch1);
;         __builtin_amdgcn_sched_barrier(0);
; #pragma unroll
;         for (int j = 0; j < 4; ++j) acc[0][j] = __builtin_amdgcn_mfma_f32_16x16x32_bf16(fb[j], fa[0], acc[0][j], 0, 0, 0);
;         __builtin_amdgcn_sched_barrier(0);
;         if (wr_ok) *(uint4*)(nA + soff0 + 4096) = ra1;
;         if (ld_ok) ra1 = *(const uint4*)(Ab + (aoff + 32u * LDA + koa));
;         ga[1] = *(const bf16x8*)(sA + arow_off + 1 * 2048 + ch1); gb[1] = *(const bf16x8*)(sB + brow_off + 1 * 2048 + ch1);
;         __builtin_amdgcn_sched_barrier(0);
; #pragma unroll
;         for (int j = 0; j < 4; ++j) acc[1][j] = __builtin_amdgcn_mfma_f32_16x16x32_bf16(fb[j], fa[1], acc[1][j], 0, 0, 0);
;         __builtin_amdgcn_sched_barrier(0);
;         if (wr_ok) *(uint4*)(nA + soff0 + 8192) = ra2;
;         if (ld_ok) ra2 = *(const uint4*)(Ab + (aoff + 64u * LDA + koa));
;         ga[2] = *(const bf16x8*)(sA + arow_off + 2 * 2048 + ch1); gb[2] = *(const bf16x8*)(sB + brow_off + 2 * 2048 + ch1);
;         __builtin_amdgcn_sched_barrier(0);
; #pragma unroll
;         for (int j = 0; j < 4; ++j) acc[2][j] = __builtin_amdgcn_mfma_f32_16x16x32_bf16(fb[j], fa[2], acc[2][j], 0, 0, 0);
;         __builtin_amdgcn_sched_barrier(0);
;         if (wr_ok) *(uint4*)(nA + soff0 + 12288) = ra3;
;         if (ld_ok) ra3 = *(const uint4*)(Ab + (aoff + 96u * LDA + koa));
;         ga[3] = *(const bf16x8*)(sA + arow_off + 3 * 2048 + ch1); gb[3] = *(const bf16x8*)(sB + brow_off + 3 * 2048 + ch1);
;         __builtin_amdgcn_sched_barrier(0);
; #pragma unroll
;         for (int j = 0; j < 4; ++j) acc[3][j] = __builtin_amdgcn_mfma_f32_16x16x32_bf16(fb[j], fa[3], acc[3][j], 0, 0, 0);
;         __builtin_amdgcn_sched_barrier(0);
;         if (wr_ok) *(uint4*)(nB + soff0) = rb0;
	ds_write_b128 v3, v[92:95] offset:8192
	v_mfma_f32_16x16x32_bf16 v[48:51], v[116:119], v[124:127], v[48:51]
	ds_read_b128 v[92:95], v5 offset:36864
	v_mfma_f32_16x16x32_bf16 v[60:63], v[136:139], v[124:127], v[60:63]
	ds_read_b128 v[168:171], v6 offset:53248
	v_mfma_f32_16x16x32_bf16 v[20:23], v[148:151], v[124:127], v[20:23]
	global_load_dwordx4 v[124:127], v244, s[0:1] offset:640
	v_mfma_f32_16x16x32_bf16 v[40:43], v[112:115], v[132:135], v[40:43]
	s_waitcnt vmcnt(8)
	ds_write_b128 v3, v[120:123] offset:12288
	v_mfma_f32_16x16x32_bf16 v[52:55], v[116:119], v[132:135], v[52:55]
	ds_read_b128 v[120:123], v5 offset:38912
	v_mfma_f32_16x16x32_bf16 v[56:59], v[136:139], v[132:135], v[56:59]
	ds_read_b128 v[172:175], v6 offset:55296
	v_mfma_f32_16x16x32_bf16 v[24:27], v[148:151], v[132:135], v[24:27]
	global_load_dwordx4 v[112:115], v4, s[2:3] offset:1664
	s_waitcnt vmcnt(8)
	ds_write_b128 v3, v[108:111] offset:16384
	s_waitcnt lgkmcnt(10)
	v_mfma_f32_16x16x32_bf16 v[28:31], v[160:163], v[152:155], v[28:31]
	s_waitcnt lgkmcnt(4)
	v_mfma_f32_16x16x32_bf16 v[80:83], v[168:171], v[152:155], v[80:83]
	s_waitcnt lgkmcnt(1)
	v_mfma_f32_16x16x32_bf16 v[12:15], v[172:175], v[152:155], v[12:15]
	v_mfma_f32_16x16x32_bf16 v[72:75], v[164:167], v[152:155], v[72:75]
	global_load_dwordx4 v[108:111], v236, s[2:3] offset:1664
	v_mfma_f32_16x16x32_bf16 v[32:35], v[160:163], v[64:67], v[32:35]
	s_waitcnt vmcnt(8)
	ds_write_b128 v3, v[104:107] offset:20480
	v_mfma_f32_16x16x32_bf16 v[44:47], v[164:167], v[64:67], v[44:47]
	v_mfma_f32_16x16x32_bf16 v[16:19], v[172:175], v[64:67], v[16:19]
	v_mfma_f32_16x16x32_bf16 v[76:79], v[168:171], v[64:67], v[76:79]
	global_load_dwordx4 v[64:67], v239, s[2:3] offset:1664
	v_mfma_f32_16x16x32_bf16 v[36:39], v[160:163], v[92:95], v[36:39]
	s_waitcnt vmcnt(8)
	ds_write_b128 v3, v[84:87] offset:24576
	v_mfma_f32_16x16x32_bf16 v[48:51], v[164:167], v[92:95], v[48:51]
	v_mfma_f32_16x16x32_bf16 v[60:63], v[168:171], v[92:95], v[60:63]
	v_mfma_f32_16x16x32_bf16 v[20:23], v[172:175], v[92:95], v[20:23]
	global_load_dwordx4 v[84:87], v240, s[2:3] offset:1664
	v_mfma_f32_16x16x32_bf16 v[40:43], v[160:163], v[120:123], v[40:43]
	s_waitcnt vmcnt(8)
	ds_write_b128 v3, v[68:71] offset:28672
	v_mfma_f32_16x16x32_bf16 v[52:55], v[164:167], v[120:123], v[52:55]
	v_mfma_f32_16x16x32_bf16 v[56:59], v[168:171], v[120:123], v[56:59]
	v_mfma_f32_16x16x32_bf16 v[24:27], v[172:175], v[120:123], v[24:27]
	s_setprio 0
	s_waitcnt lgkmcnt(0)
	s_barrier
	ds_read_b128 v[68:71], v7
	ds_read_b128 v[92:95], v7 offset:2048
	ds_read_b128 v[104:107], v8 offset:16384
	ds_read_b128 v[116:119], v8 offset:18432
	ds_read_b128 v[120:123], v7 offset:4096
	ds_read_b128 v[132:135], v7 offset:6144
	ds_read_b128 v[136:139], v8 offset:20480
	ds_read_b128 v[148:151], v8 offset:22528
	s_setprio 2
	global_load_dwordx4 v[152:155], v241, s[0:1] offset:768
	s_waitcnt vmcnt(8)
	ds_write_b128 v3, v[156:159] offset:32768
	ds_read_b128 v[156:159], v5
	ds_read_b128 v[160:163], v6 offset:16384
	s_waitcnt lgkmcnt(8)
	v_mfma_f32_16x16x32_bf16 v[28:31], v[104:107], v[68:71], v[28:31]
	s_waitcnt lgkmcnt(4)
	v_mfma_f32_16x16x32_bf16 v[80:83], v[136:139], v[68:71], v[80:83]
	s_waitcnt lgkmcnt(3)
	v_mfma_f32_16x16x32_bf16 v[12:15], v[148:151], v[68:71], v[12:15]
	v_mfma_f32_16x16x32_bf16 v[72:75], v[116:119], v[68:71], v[72:75]
	global_load_dwordx4 v[68:71], v242, s[0:1] offset:768
	v_mfma_f32_16x16x32_bf16 v[32:35], v[104:107], v[92:95], v[32:35]
	s_waitcnt vmcnt(8)
	ds_write_b128 v3, v[88:91] offset:36864
	v_mfma_f32_16x16x32_bf16 v[44:47], v[116:119], v[92:95], v[44:47]
	ds_read_b128 v[88:91], v5 offset:2048
	v_mfma_f32_16x16x32_bf16 v[16:19], v[148:151], v[92:95], v[16:19]
	ds_read_b128 v[164:167], v6 offset:18432
	v_mfma_f32_16x16x32_bf16 v[76:79], v[136:139], v[92:95], v[76:79]
	global_load_dwordx4 v[92:95], v243, s[0:1] offset:768
	v_mfma_f32_16x16x32_bf16 v[36:39], v[104:107], v[120:123], v[36:39]
	s_waitcnt vmcnt(8)
	ds_write_b128 v3, v[100:103] offset:40960
	v_mfma_f32_16x16x32_bf16 v[48:51], v[116:119], v[120:123], v[48:51]
	ds_read_b128 v[100:103], v5 offset:4096
	v_mfma_f32_16x16x32_bf16 v[60:63], v[136:139], v[120:123], v[60:63]
	ds_read_b128 v[168:171], v6 offset:20480
	v_mfma_f32_16x16x32_bf16 v[20:23], v[148:151], v[120:123], v[20:23]
	global_load_dwordx4 v[120:123], v244, s[0:1] offset:768
	v_mfma_f32_16x16x32_bf16 v[40:43], v[104:107], v[132:135], v[40:43]
	s_waitcnt vmcnt(8)
	ds_write_b128 v3, v[124:127] offset:45056
	v_mfma_f32_16x16x32_bf16 v[52:55], v[116:119], v[132:135], v[52:55]
	ds_read_b128 v[124:127], v5 offset:6144
	v_mfma_f32_16x16x32_bf16 v[56:59], v[136:139], v[132:135], v[56:59]
	ds_read_b128 v[172:175], v6 offset:22528
	v_mfma_f32_16x16x32_bf16 v[24:27], v[148:151], v[132:135], v[24:27]
	global_load_dwordx4 v[104:107], v4, s[2:3] offset:1792
	s_waitcnt vmcnt(8)
	ds_write_b128 v3, v[112:115] offset:49152
	s_waitcnt lgkmcnt(10)
	v_mfma_f32_16x16x32_bf16 v[28:31], v[160:163], v[156:159], v[28:31]
	s_waitcnt lgkmcnt(4)
	v_mfma_f32_16x16x32_bf16 v[80:83], v[168:171], v[156:159], v[80:83]
	s_waitcnt lgkmcnt(1)
	v_mfma_f32_16x16x32_bf16 v[12:15], v[172:175], v[156:159], v[12:15]
	v_mfma_f32_16x16x32_bf16 v[72:75], v[164:167], v[156:159], v[72:75]
	global_load_dwordx4 v[112:115], v236, s[2:3] offset:1792
	v_mfma_f32_16x16x32_bf16 v[32:35], v[160:163], v[88:91], v[32:35]
	s_waitcnt vmcnt(8)
	ds_write_b128 v3, v[108:111] offset:53248
	v_mfma_f32_16x16x32_bf16 v[44:47], v[164:167], v[88:91], v[44:47]
	v_mfma_f32_16x16x32_bf16 v[16:19], v[172:175], v[88:91], v[16:19]
	v_mfma_f32_16x16x32_bf16 v[76:79], v[168:171], v[88:91], v[76:79]
	global_load_dwordx4 v[88:91], v239, s[2:3] offset:1792
	v_mfma_f32_16x16x32_bf16 v[36:39], v[160:163], v[100:103], v[36:39]
	s_waitcnt vmcnt(8)
	ds_write_b128 v3, v[64:67] offset:57344
	v_mfma_f32_16x16x32_bf16 v[48:51], v[164:167], v[100:103], v[48:51]
	v_mfma_f32_16x16x32_bf16 v[60:63], v[168:171], v[100:103], v[60:63]
	v_mfma_f32_16x16x32_bf16 v[20:23], v[172:175], v[100:103], v[20:23]
	global_load_dwordx4 v[64:67], v240, s[2:3] offset:1792
	v_mfma_f32_16x16x32_bf16 v[40:43], v[160:163], v[124:127], v[40:43]
	s_waitcnt vmcnt(8)
	ds_write_b128 v3, v[84:87] offset:61440
	v_mfma_f32_16x16x32_bf16 v[52:55], v[164:167], v[124:127], v[52:55]
	v_mfma_f32_16x16x32_bf16 v[56:59], v[168:171], v[124:127], v[56:59]
	v_mfma_f32_16x16x32_bf16 v[24:27], v[172:175], v[124:127], v[24:27]
	s_setprio 0
	s_waitcnt lgkmcnt(0)
	s_barrier
; template <int MODE>
; __device__ __forceinline__ void gemm_tile(const Params& P, int tm, int tn, unsigned char* smem) {
;     ...
;         const unsigned ko = (unsigned)(kt + 2) * 128u;
;         const unsigned koa = ko + ((MODE == 2 && kt + 2 >= 8) ? (unsigned)(ZC_FQ - 512) * 2u : 0u);
;         const bool wr_ok = kt < 15, ld_ok = kt < 14;
; #pragma unroll
;         for (int i = 0; i < 4; ++i) { fa[i] = *(const bf16x8*)(sA + arow_off + i * 2048 + ch0); fb[i] = *(const bf16x8*)(sB + brow_off + i * 2048 + ch0); }
;         __builtin_amdgcn_sched_barrier(0);
;         __builtin_amdgcn_s_setprio(2);
;         if (wr_ok) *(uint4*)(nA + soff0) = ra0;
;         if (ld_ok) ra0 = *(const uint4*)(Ab + (aoff + 0u * LDA + koa));
;         ga[0] = *(const bf16x8*)(sA + arow_off + 0 * 2048 + ch1); gb[0] = *(const bf16x8*)(sB + brow_off + 0 * 2048 + ch1);
;         __builtin_amdgcn_sched_barrier(0);
; #pragma unroll
;         for (int j = 0; j < 4; ++j) acc[0][j] = __builtin_amdgcn_mfma_f32_16x16x32_bf16(fb[j], fa[0], acc[0][j], 0, 0, 0);
;         __builtin_amdgcn_sched_barrier(0);
;         if (wr_ok) *(uint4*)(nA + soff0 + 4096) = ra1;
;         if (ld_ok) ra1 = *(const uint4*)(Ab + (aoff + 32u * LDA + koa));
;         ga[1] = *(const bf16x8*)(sA + arow_off + 1 * 2048 + ch1); gb[1] = *(const bf16x8*)(sB + brow_off + 1 * 2048 + ch1);
;         __builtin_amdgcn_sched_barrier(0);
; #pragma unroll
;         for (int j = 0; j < 4; ++j) acc[1][j] = __builtin_amdgcn_mfma_f32_16x16x32_bf16(fb[j], fa[1], acc[1][j], 0, 0, 0);
;         __builtin_amdgcn_sched_barrier(0);
;         if (wr_ok) *(uint4*)(nA + soff0 + 8192) = ra2;
;         if (ld_ok) ra2 = *(const uint4*)(Ab + (aoff + 64u * LDA + koa));
;         ga[2] = *(const bf16x8*)(sA + arow_off + 2 * 2048 + ch1); gb[2] = *(const bf16x8*)(sB + brow_off + 2 * 2048 + ch1);
;         __builtin_amdgcn_sched_barrier(0);
; #pragma unroll
;         for (int j = 0; j < 4; ++j) acc[2][j] = __builtin_amdgcn_mfma_f32_16x16x32_bf16(fb[j], fa[2], acc[2][j], 0, 0, 0);
;         __builtin_amdgcn_sched_barrier(0);
;         if (wr_ok) *(uint4*)(nA + soff0 + 12288) = ra3;
;         if (ld_ok) ra3 = *(const uint4*)(Ab + (aoff + 96u * LDA + koa));
;         ga[3] = *(const bf16x8*)(sA + arow_off + 3 * 2048 + ch1); gb[3] = *(const bf16x8*)(sB + brow_off + 3 * 2048 + ch1);
;         __builtin_amdgcn_sched_barrier(0);
; #pragma unroll
	ds_read_b128 v[84:87], v7 offset:32768
	ds_read_b128 v[100:103], v7 offset:34816
	ds_read_b128 v[108:111], v8 offset:49152
	ds_read_b128 v[116:119], v8 offset:51200
	ds_read_b128 v[124:127], v7 offset:36864
	ds_read_b128 v[132:135], v7 offset:38912
	ds_read_b128 v[136:139], v8 offset:53248
	ds_read_b128 v[148:151], v8 offset:55296
	s_setprio 2
	global_load_dwordx4 v[156:159], v241, s[0:1] offset:896
	s_waitcnt vmcnt(8)
	ds_write_b128 v3, v[152:155]
	ds_read_b128 v[152:155], v5 offset:32768
	ds_read_b128 v[160:163], v6 offset:49152
	s_waitcnt lgkmcnt(8)
	v_mfma_f32_16x16x32_bf16 v[28:31], v[108:111], v[84:87], v[28:31]
	s_waitcnt lgkmcnt(4)
	v_mfma_f32_16x16x32_bf16 v[80:83], v[136:139], v[84:87], v[80:83]
	s_waitcnt lgkmcnt(3)
	v_mfma_f32_16x16x32_bf16 v[12:15], v[148:151], v[84:87], v[12:15]
	v_mfma_f32_16x16x32_bf16 v[72:75], v[116:119], v[84:87], v[72:75]
	global_load_dwordx4 v[84:87], v242, s[0:1] offset:896
	v_mfma_f32_16x16x32_bf16 v[32:35], v[108:111], v[100:103], v[32:35]
	s_waitcnt vmcnt(8)
	ds_write_b128 v3, v[68:71] offset:4096
	v_mfma_f32_16x16x32_bf16 v[44:47], v[116:119], v[100:103], v[44:47]
	ds_read_b128 v[68:71], v5 offset:34816
	v_mfma_f32_16x16x32_bf16 v[16:19], v[148:151], v[100:103], v[16:19]
	ds_read_b128 v[164:167], v6 offset:51200
	v_mfma_f32_16x16x32_bf16 v[76:79], v[136:139], v[100:103], v[76:79]
	global_load_dwordx4 v[100:103], v243, s[0:1] offset:896
	v_mfma_f32_16x16x32_bf16 v[36:39], v[108:111], v[124:127], v[36:39]
	s_waitcnt vmcnt(8)
	ds_write_b128 v3, v[92:95] offset:8192
	v_mfma_f32_16x16x32_bf16 v[48:51], v[116:119], v[124:127], v[48:51]
	ds_read_b128 v[92:95], v5 offset:36864
	v_mfma_f32_16x16x32_bf16 v[60:63], v[136:139], v[124:127], v[60:63]
	ds_read_b128 v[168:171], v6 offset:53248
	v_mfma_f32_16x16x32_bf16 v[20:23], v[148:151], v[124:127], v[20:23]
	v_add_u32_e32 v9, 0xc5380, v9
	global_load_dwordx4 v[124:127], v9, s[0:1]
	s_waitcnt vmcnt(8)
	ds_write_b128 v3, v[120:123] offset:12288
	ds_read_b128 v[120:123], v5 offset:38912
	ds_read_b128 v[172:175], v6 offset:55296
	v_mfma_f32_16x16x32_bf16 v[40:43], v[108:111], v[132:135], v[40:43]
	v_mfma_f32_16x16x32_bf16 v[52:55], v[116:119], v[132:135], v[52:55]
	v_mfma_f32_16x16x32_bf16 v[56:59], v[136:139], v[132:135], v[56:59]
	v_mfma_f32_16x16x32_bf16 v[24:27], v[148:151], v[132:135], v[24:27]
	global_load_dwordx4 v[108:111], v4, s[2:3] offset:1920
	s_waitcnt vmcnt(8)
	ds_write_b128 v3, v[104:107] offset:16384
	s_waitcnt lgkmcnt(10)
	v_mfma_f32_16x16x32_bf16 v[28:31], v[160:163], v[152:155], v[28:31]
	s_waitcnt lgkmcnt(4)
	v_mfma_f32_16x16x32_bf16 v[80:83], v[168:171], v[152:155], v[80:83]
	s_waitcnt lgkmcnt(1)
	v_mfma_f32_16x16x32_bf16 v[12:15], v[172:175], v[152:155], v[12:15]
	v_mfma_f32_16x16x32_bf16 v[72:75], v[164:167], v[152:155], v[72:75]
	global_load_dwordx4 v[104:107], v236, s[2:3] offset:1920
	v_mfma_f32_16x16x32_bf16 v[32:35], v[160:163], v[68:71], v[32:35]
	s_waitcnt vmcnt(8)
	ds_write_b128 v3, v[112:115] offset:20480
	v_mfma_f32_16x16x32_bf16 v[44:47], v[164:167], v[68:71], v[44:47]
	v_mfma_f32_16x16x32_bf16 v[16:19], v[172:175], v[68:71], v[16:19]
	v_mfma_f32_16x16x32_bf16 v[76:79], v[168:171], v[68:71], v[76:79]
	global_load_dwordx4 v[68:71], v239, s[2:3] offset:1920
	v_mfma_f32_16x16x32_bf16 v[36:39], v[160:163], v[92:95], v[36:39]
	s_waitcnt vmcnt(8)
	ds_write_b128 v3, v[88:91] offset:24576
	v_mfma_f32_16x16x32_bf16 v[48:51], v[164:167], v[92:95], v[48:51]
	v_mfma_f32_16x16x32_bf16 v[60:63], v[168:171], v[92:95], v[60:63]
	v_mfma_f32_16x16x32_bf16 v[20:23], v[172:175], v[92:95], v[20:23]
	v_add_u32_e32 v4, 0x30780, v4
	global_load_dwordx4 v[88:91], v4, s[2:3]
	s_waitcnt vmcnt(8)
	ds_write_b128 v3, v[64:67] offset:28672
	v_mfma_f32_16x16x32_bf16 v[40:43], v[160:163], v[120:123], v[40:43]
	v_mfma_f32_16x16x32_bf16 v[52:55], v[164:167], v[120:123], v[52:55]
	v_mfma_f32_16x16x32_bf16 v[56:59], v[168:171], v[120:123], v[56:59]
	v_mfma_f32_16x16x32_bf16 v[24:27], v[172:175], v[120:123], v[24:27]
	s_setprio 0
	s_waitcnt lgkmcnt(0)
	s_barrier
	ds_read_b128 v[64:67], v7
	ds_read_b128 v[92:95], v7 offset:2048
	ds_read_b128 v[112:115], v8 offset:16384
	ds_read_b128 v[116:119], v8 offset:18432
	ds_read_b128 v[120:123], v7 offset:4096
	ds_read_b128 v[132:135], v7 offset:6144
	ds_read_b128 v[136:139], v8 offset:20480
	ds_read_b128 v[148:151], v8 offset:22528
	s_setprio 2
	s_waitcnt vmcnt(7)
	ds_write_b128 v3, v[156:159] offset:32768
	ds_read_b128 v[152:155], v5
	ds_read_b128 v[156:159], v6 offset:16384
	s_waitcnt lgkmcnt(8)
	v_mfma_f32_16x16x32_bf16 v[28:31], v[112:115], v[64:67], v[28:31]
	s_waitcnt lgkmcnt(4)
	v_mfma_f32_16x16x32_bf16 v[80:83], v[136:139], v[64:67], v[80:83]
	s_waitcnt lgkmcnt(3)
	v_mfma_f32_16x16x32_bf16 v[12:15], v[148:151], v[64:67], v[12:15]
	v_mfma_f32_16x16x32_bf16 v[72:75], v[116:119], v[64:67], v[72:75]
	v_mfma_f32_16x16x32_bf16 v[32:35], v[112:115], v[92:95], v[32:35]
	s_waitcnt vmcnt(6)
	ds_write_b128 v3, v[84:87] offset:36864
	v_mfma_f32_16x16x32_bf16 v[44:47], v[116:119], v[92:95], v[44:47]
	ds_read_b128 v[64:67], v5 offset:2048
	v_mfma_f32_16x16x32_bf16 v[16:19], v[148:151], v[92:95], v[16:19]
	ds_read_b128 v[84:87], v6 offset:18432
	v_mfma_f32_16x16x32_bf16 v[76:79], v[136:139], v[92:95], v[76:79]
	v_mfma_f32_16x16x32_bf16 v[36:39], v[112:115], v[120:123], v[36:39]
	s_waitcnt vmcnt(5)
	ds_write_b128 v3, v[100:103] offset:40960
	v_mfma_f32_16x16x32_bf16 v[48:51], v[116:119], v[120:123], v[48:51]
	ds_read_b128 v[92:95], v5 offset:4096
	v_mfma_f32_16x16x32_bf16 v[60:63], v[136:139], v[120:123], v[60:63]
	ds_read_b128 v[100:103], v6 offset:20480
	v_mfma_f32_16x16x32_bf16 v[20:23], v[148:151], v[120:123], v[20:23]
	v_mfma_f32_16x16x32_bf16 v[40:43], v[112:115], v[132:135], v[40:43]
	s_waitcnt vmcnt(4)
; template <int MODE>
; __device__ __forceinline__ void gemm_tile(const Params& P, int tm, int tn, unsigned char* smem) {
;     ...
; #pragma unroll
;         for (int j = 0; j < 4; ++j) acc[2][j] = __builtin_amdgcn_mfma_f32_16x16x32_bf16(fb[j], fa[2], acc[2][j], 0, 0, 0);
;         __builtin_amdgcn_sched_barrier(0);
;         if (wr_ok) *(uint4*)(nA + soff0 + 12288) = ra3;
;         if (ld_ok) ra3 = *(const uint4*)(Ab + (aoff + 96u * LDA + koa));
;         ga[3] = *(const bf16x8*)(sA + arow_off + 3 * 2048 + ch1); gb[3] = *(const bf16x8*)(sB + brow_off + 3 * 2048 + ch1);
;         __builtin_amdgcn_sched_barrier(0);
; #pragma unroll
;         for (int j = 0; j < 4; ++j) acc[3][j] = __builtin_amdgcn_mfma_f32_16x16x32_bf16(fb[j], fa[3], acc[3][j], 0, 0, 0);
;         __builtin_amdgcn_sched_barrier(0);
;         if (wr_ok) *(uint4*)(nB + soff0) = rb0;
;         if (ld_ok) rb0 = *(const uint4*)(Bb + (boff + 0u * 2048u + ko));
;         __builtin_amdgcn_sched_barrier(0);
; #pragma unroll
;         for (int j = 0; j < 4; ++j) acc[0][j] = __builtin_amdgcn_mfma_f32_16x16x32_bf16(gb[j], ga[0], acc[0][j], 0, 0, 0);
;         __builtin_amdgcn_sched_barrier(0);
;         if (wr_ok) *(uint4*)(nB + soff0 + 4096) = rb1;
;         if (ld_ok) rb1 = *(const uint4*)(Bb + (boff + 32u * 2048u + ko));
;         __builtin_amdgcn_sched_barrier(0);
; #pragma unroll
;         for (int j = 0; j < 4; ++j) acc[1][j] = __builtin_amdgcn_mfma_f32_16x16x32_bf16(gb[j], ga[1], acc[1][j], 0, 0, 0);
;         __builtin_amdgcn_sched_barrier(0);
;         if (wr_ok) *(uint4*)(nB + soff0 + 8192) = rb2;
;         if (ld_ok) rb2 = *(const uint4*)(Bb + (boff + 64u * 2048u + ko));
;         __builtin_amdgcn_sched_barrier(0);
; #pragma unroll
;         for (int j = 0; j < 4; ++j) acc[2][j] = __builtin_amdgcn_mfma_f32_16x16x32_bf16(gb[j], ga[2], acc[2][j], 0, 0, 0);
;         __builtin_amdgcn_sched_barrier(0);
;         if (wr_ok) *(uint4*)(nB + soff0 + 12288) = rb3;
;         if (ld_ok) rb3 = *(const uint4*)(Bb + (boff + 96u * 2048u + ko));
;         __builtin_amdgcn_sched_barrier(0);
; #pragma unroll
;         for (int j = 0; j < 4; ++j) acc[3][j] = __builtin_amdgcn_mfma_f32_16x16x32_bf16(gb[j], ga[3], acc[3][j], 0, 0, 0);
;         __builtin_amdgcn_s_setprio(0);
;         __syncthreads();
;     }
;     ...
;     } else if (MODE == 2) {
;         float* ssq = (float*)(P.ws + WS_SSQ);
; #pragma unroll
	ds_write_b128 v3, v[124:127] offset:45056
	v_mfma_f32_16x16x32_bf16 v[52:55], v[116:119], v[132:135], v[52:55]
	ds_read_b128 v[120:123], v5 offset:6144
	v_mfma_f32_16x16x32_bf16 v[56:59], v[136:139], v[132:135], v[56:59]
	ds_read_b128 v[124:127], v6 offset:22528
	v_mfma_f32_16x16x32_bf16 v[24:27], v[148:151], v[132:135], v[24:27]
	s_waitcnt vmcnt(3)
	ds_write_b128 v3, v[108:111] offset:49152
	s_waitcnt lgkmcnt(10)
	v_mfma_f32_16x16x32_bf16 v[28:31], v[156:159], v[152:155], v[28:31]
	s_waitcnt lgkmcnt(4)
	v_mfma_f32_16x16x32_bf16 v[80:83], v[100:103], v[152:155], v[80:83]
	s_waitcnt lgkmcnt(1)
	v_mfma_f32_16x16x32_bf16 v[12:15], v[124:127], v[152:155], v[12:15]
	v_mfma_f32_16x16x32_bf16 v[72:75], v[84:87], v[152:155], v[72:75]
	v_mfma_f32_16x16x32_bf16 v[32:35], v[156:159], v[64:67], v[32:35]
	s_waitcnt vmcnt(2)
	ds_write_b128 v3, v[104:107] offset:53248
	v_mfma_f32_16x16x32_bf16 v[44:47], v[84:87], v[64:67], v[44:47]
	v_mfma_f32_16x16x32_bf16 v[16:19], v[124:127], v[64:67], v[16:19]
	v_mfma_f32_16x16x32_bf16 v[76:79], v[100:103], v[64:67], v[76:79]
	v_mfma_f32_16x16x32_bf16 v[36:39], v[156:159], v[92:95], v[36:39]
	s_waitcnt vmcnt(1)
	ds_write_b128 v3, v[68:71] offset:57344
	v_mfma_f32_16x16x32_bf16 v[48:51], v[84:87], v[92:95], v[48:51]
	v_mfma_f32_16x16x32_bf16 v[60:63], v[100:103], v[92:95], v[60:63]
	v_mfma_f32_16x16x32_bf16 v[20:23], v[124:127], v[92:95], v[20:23]
	v_mfma_f32_16x16x32_bf16 v[40:43], v[156:159], v[120:123], v[40:43]
	s_waitcnt vmcnt(0)
	ds_write_b128 v3, v[88:91] offset:61440
	v_mfma_f32_16x16x32_bf16 v[52:55], v[84:87], v[120:123], v[52:55]
	v_mfma_f32_16x16x32_bf16 v[56:59], v[100:103], v[120:123], v[56:59]
	v_mfma_f32_16x16x32_bf16 v[24:27], v[124:127], v[120:123], v[24:27]
	s_setprio 0
	s_waitcnt lgkmcnt(0)
	s_barrier
	ds_read_b128 v[64:67], v7 offset:32768
	ds_read_b128 v[68:71], v7 offset:34816
	ds_read_b128 v[84:87], v8 offset:49152
	ds_read_b128 v[88:91], v8 offset:51200
	ds_read_b128 v[92:95], v7 offset:36864
	ds_read_b128 v[100:103], v7 offset:38912
	ds_read_b128 v[104:107], v8 offset:53248
	ds_read_b128 v[108:111], v8 offset:55296
	s_setprio 2
	ds_read_b128 v[112:115], v5 offset:32768
	ds_read_b128 v[116:119], v6 offset:49152
	s_waitcnt lgkmcnt(7)
	v_mfma_f32_16x16x32_bf16 v[28:31], v[84:87], v[64:67], v[28:31]
	s_waitcnt lgkmcnt(3)
	v_mfma_f32_16x16x32_bf16 v[80:83], v[104:107], v[64:67], v[80:83]
	s_waitcnt lgkmcnt(2)
	v_mfma_f32_16x16x32_bf16 v[12:15], v[108:111], v[64:67], v[12:15]
	v_mfma_f32_16x16x32_bf16 v[72:75], v[88:91], v[64:67], v[72:75]
	v_mfma_f32_16x16x32_bf16 v[32:35], v[84:87], v[68:71], v[32:35]
	ds_read_b128 v[64:67], v5 offset:34816
	v_mfma_f32_16x16x32_bf16 v[44:47], v[88:91], v[68:71], v[44:47]
	ds_read_b128 v[120:123], v6 offset:51200
	v_mfma_f32_16x16x32_bf16 v[16:19], v[108:111], v[68:71], v[16:19]
	v_mfma_f32_16x16x32_bf16 v[76:79], v[104:107], v[68:71], v[76:79]
	v_mfma_f32_16x16x32_bf16 v[36:39], v[84:87], v[92:95], v[36:39]
	ds_read_b128 v[124:127], v5 offset:36864
	v_mfma_f32_16x16x32_bf16 v[48:51], v[88:91], v[92:95], v[48:51]
	ds_read_b128 v[132:135], v6 offset:53248
	v_mfma_f32_16x16x32_bf16 v[20:23], v[108:111], v[92:95], v[20:23]
	v_mfma_f32_16x16x32_bf16 v[136:139], v[104:107], v[92:95], v[60:63]
	v_mfma_f32_16x16x32_bf16 v[40:43], v[84:87], v[100:103], v[40:43]
	ds_read_b128 v[148:151], v5 offset:38912
	v_mfma_f32_16x16x32_bf16 v[152:155], v[88:91], v[100:103], v[52:55]
	ds_read_b128 v[4:7], v6 offset:55296
	v_mfma_f32_16x16x32_bf16 v[104:107], v[104:107], v[100:103], v[56:59]
	v_mfma_f32_16x16x32_bf16 v[100:103], v[108:111], v[100:103], v[24:27]
	s_waitcnt lgkmcnt(6)
	v_mfma_f32_16x16x32_bf16 v[108:111], v[116:119], v[112:115], v[28:31]
	s_waitcnt lgkmcnt(4)
	v_mfma_f32_16x16x32_bf16 v[70:73], v[120:123], v[112:115], v[72:75]
	s_waitcnt lgkmcnt(2)
	v_mfma_f32_16x16x32_bf16 v[156:159], v[132:135], v[112:115], v[80:83]
	s_waitcnt lgkmcnt(0)
	v_mfma_f32_16x16x32_bf16 v[160:163], v[4:7], v[112:115], v[12:15]
	v_mfma_f32_16x16x32_bf16 v[94:97], v[116:119], v[64:67], v[32:35]
	v_mfma_f32_16x16x32_bf16 v[90:93], v[120:123], v[64:67], v[44:47]
	v_mfma_f32_16x16x32_bf16 v[86:89], v[132:135], v[64:67], v[76:79]
	v_mfma_f32_16x16x32_bf16 v[82:85], v[4:7], v[64:67], v[16:19]
	v_mfma_f32_16x16x32_bf16 v[66:69], v[116:119], v[124:127], v[36:39]
	v_mfma_f32_16x16x32_bf16 v[62:65], v[120:123], v[124:127], v[48:51]
	v_mfma_f32_16x16x32_bf16 v[58:61], v[132:135], v[124:127], v[136:139]
	v_mfma_f32_16x16x32_bf16 v[54:57], v[4:7], v[124:127], v[20:23]
	v_mfma_f32_16x16x32_bf16 v[26:29], v[116:119], v[148:151], v[40:43]
	v_mfma_f32_16x16x32_bf16 v[22:25], v[120:123], v[148:151], v[152:155]
	v_mfma_f32_16x16x32_bf16 v[18:21], v[132:135], v[148:151], v[104:107]
	v_mfma_f32_16x16x32_bf16 v[14:17], v[4:7], v[148:151], v[100:103]
	s_setprio 0
	v_add_u32_e32 v10, s15, v10
	s_lshl_b32 s4, s4, 3
	v_or_b32_e32 v120, v10, v143
	v_lshlrev_b32_e32 v3, 2, v146
	s_add_u32 s4, s7, s4
	v_ashrrev_i32_e32 v121, 31, v120
	v_or3_b32 v2, v3, v2, s18
	s_addc_u32 s5, s8, 0
	v_lshlrev_b32_e32 v98, 2, v144
	v_lshlrev_b64 v[10:11], 12, v[120:121]
	v_lshl_add_u64 v[100:101], s[4:5], 0, v[98:99]
	v_lshlrev_b32_e32 v98, 2, v2
	v_lshl_add_u64 v[30:31], s[52:53], 0, v[10:11]
	s_barrier
; template <int MODE>
; __device__ __forceinline__ void gemm_tile(const Params& P, int tm, int tn, unsigned char* smem) {
;     ...
;     } else if (MODE == 2) {
;         float* ssq = (float*)(P.ws + WS_SSQ);
; #pragma unroll
;         for (int i = 0; i < 4; ++i) {
;             const int row = m0 + wr * 64 + 16 * i + lr;
;             float ss = 0.f;
; #pragma unroll
;             for (int j = 0; j < 4; ++j) {
;                 const int col = n0 + wc * 64 + 16 * j + 4 * g;
;                 const float4 xv = *(const float4*)(P.x + (size_t)row * DM + col);
;                 const float4 gv = *(const float4*)(P.norm_ffn + col);
;                 float4 hv; hv.x = acc[i][j][0] + xv.x; hv.y = acc[i][j][1] + xv.y; hv.z = acc[i][j][2] + xv.z; hv.w = acc[i][j][3] + xv.w;
;                 ss += hv.x * hv.x + hv.y * hv.y + hv.z * hv.z + hv.w * hv.w;
;                 acc[i][j][0] = hv.x * gv.x; acc[i][j][1] = hv.y * gv.y; acc[i][j][2] = hv.z * gv.z; acc[i][j][3] = hv.w * gv.w;
;             }
;             ss = x4_sum(ss);
;             if (g == 0) ssq[(size_t)row * 16 + tn * 2 + wc] = ss;
;         }
	global_load_dwordx4 v[6:9], v98, s[44:45] offset:64
	global_load_dwordx4 v[2:5], v98, s[44:45]
	global_load_dwordx4 v[10:13], v98, s[44:45] offset:128
	v_lshl_add_u64 v[34:35], v[30:31], 0, v[98:99]
	global_load_dwordx4 v[30:33], v98, s[44:45] offset:192
	global_load_dwordx4 v[74:77], v[34:35], off
	global_load_dwordx4 v[78:81], v[34:35], off offset:64
	global_load_dwordx4 v[112:115], v[34:35], off offset:128
	global_load_dwordx4 v[124:127], v[34:35], off offset:192
	v_cmp_eq_u32_e32 vcc, 0, v146
	v_lshl_add_u64 v[122:123], s[44:45], 0, v[98:99]
	s_waitcnt vmcnt(4)
	v_mov_b64_e32 v[48:49], v[32:33]
	s_waitcnt vmcnt(3)
	v_pk_add_f32 v[102:103], v[108:109], v[74:75]
	s_waitcnt vmcnt(2)
	v_pk_add_f32 v[106:107], v[70:71], v[78:79]
	v_pk_add_f32 v[104:105], v[110:111], v[76:77]
	s_waitcnt vmcnt(1)
	v_pk_add_f32 v[110:111], v[156:157], v[112:113]
	v_mul_f32_e32 v46, v103, v103
	v_mul_f32_e32 v52, v107, v107
	v_pk_add_f32 v[108:109], v[72:73], v[80:81]
	v_pk_add_f32 v[112:113], v[158:159], v[114:115]
	s_waitcnt vmcnt(0)
	v_pk_add_f32 v[114:115], v[160:161], v[124:125]
	v_mul_f32_e32 v72, v111, v111
	v_pk_fma_f32 v[46:47], v[102:103], v[102:103], v[46:47] op_sel_hi:[1,1,0]
	v_pk_fma_f32 v[52:53], v[106:107], v[106:107], v[52:53] op_sel_hi:[1,1,0]
	v_mov_b32_e32 v51, v7
	v_mul_f32_e32 v50, v105, v105
	v_mul_f32_e32 v70, v109, v109
	v_mul_f32_e32 v76, v115, v115
	v_pk_fma_f32 v[72:73], v[110:111], v[110:111], v[72:73] op_sel_hi:[1,1,0]
	v_pk_fma_f32 v[46:47], v[104:105], v[104:105], v[46:47]
	v_pk_fma_f32 v[52:53], v[108:109], v[108:109], v[52:53]
	v_pk_add_f32 v[116:117], v[162:163], v[126:127]
	v_mul_f32_e32 v74, v113, v113
	v_pk_fma_f32 v[76:77], v[114:115], v[114:115], v[76:77] op_sel_hi:[1,1,0]
	v_pk_fma_f32 v[72:73], v[112:113], v[112:113], v[72:73]
	v_pk_add_f32 v[46:47], v[50:51], v[46:47] op_sel_hi:[0,1]
	v_pk_add_f32 v[52:53], v[70:71], v[52:53] op_sel_hi:[0,1]
	v_mul_f32_e32 v78, v117, v117
	v_pk_fma_f32 v[76:77], v[116:117], v[116:117], v[76:77]
	v_pk_add_f32 v[70:71], v[74:75], v[72:73] op_sel_hi:[0,1]
	v_pk_add_f32 v[46:47], v[46:47], v[52:53]
	v_pk_add_f32 v[72:73], v[78:79], v[76:77] op_sel_hi:[0,1]
	v_pk_add_f32 v[46:47], v[46:47], v[70:71]
	v_mov_b32_e32 v34, v6
	v_pk_add_f32 v[46:47], v[46:47], v[72:73]
	v_mov_b32_e32 v40, v4
	v_mov_b32_e32 v41, v46
	s_nop 1
	v_permlane32_swap_b32_e32 v46, v41
	v_add_f32_e32 v41, v46, v41
	v_mov_b32_e32 v50, v41
	v_mov_b64_e32 v[118:119], v[4:5]
	v_mov_b64_e32 v[38:39], v[2:3]
	v_mov_b32_e32 v35, v7
	v_mov_b64_e32 v[36:37], v[8:9]
	v_mov_b64_e32 v[44:45], v[12:13]
	v_mov_b64_e32 v[42:43], v[10:11]
	v_permlane16_swap_b32_e32 v41, v50
	v_mov_b64_e32 v[46:47], v[30:31]
	s_and_saveexec_b64 s[4:5], vcc
	s_cbranch_execz .LBB0_1156
	v_lshlrev_b64 v[34:35], 6, v[120:121]
	v_lshl_add_u64 v[34:35], v[100:101], 0, v[34:35]
	v_add_f32_e32 v36, v41, v50
	global_store_dword v[34:35], v36, off
	global_load_dwordx4 v[34:37], v[122:123], off offset:64
	s_nop 0
	global_load_dwordx4 v[38:41], v[122:123], off
	global_load_dwordx4 v[42:45], v[122:123], off offset:128
	global_load_dwordx4 v[46:49], v[122:123], off offset:192
	s_waitcnt vmcnt(3)
	v_mov_b32_e32 v51, v35
	s_waitcnt vmcnt(2)
	v_mov_b64_e32 v[118:119], v[40:41]

; template <int MODE>
; __device__ __forceinline__ void gemm_tile(const Params& P, int tm, int tn, unsigned char* smem) {
;     ...
;     const int tid = opaque_tid(), lane = tid & 63, wave = tid >> 6, wr = wave >> 1, wc = wave & 1, g = lane >> 4, lr = lane & 15;
;     const int m0 = tm * 128, n0 = tn * 128;
;     const int srow = tid >> 3, sc = tid & 7;
;     constexpr unsigned LDA = (MODE == 2 ? NZ : 1024) * 2u;
;     unsigned aoff, boff; int soff0;
;     {
;         int ar = m0 + srow;
;         if (MODE == 2) { const int b = ar >> 11, t = ar & 2047; ar = b * L + NMETA + t; }
;         aoff = (unsigned)ar * LDA + (unsigned)sc * 16u;
;         boff = (unsigned)(n0 + srow) * 2048u + (unsigned)sc * 16u;
;         soff0 = srow * 128 + ((sc ^ (srow & 7)) << 4);
;     }
;     const unsigned char* Ab = (const unsigned char*)A; const unsigned char* Bb = (const unsigned char*)Bt;
;     float4 ssp0, ssp1, ssp2, ssp3;
;     if (MODE == 3) {
;         const float* ssq = (const float*)(P.ws + WS_SSQ) + (size_t)(m0 + wr * 64 + lr) * 16 + 4 * g;
;         ssp0 = *(const float4*)(ssq); ssp1 = *(const float4*)(ssq + 16 * 16); ssp2 = *(const float4*)(ssq + 32 * 16); ssp3 = *(const float4*)(ssq + 48 * 16);
;     }
;     f32x4 acc[4][4];
; #pragma unroll
;     for (int i = 0; i < 4; ++i)
; #pragma unroll
;         for (int j = 0; j < 4; ++j) acc[i][j] = (f32x4){0.f, 0.f, 0.f, 0.f};
;     uint4 ra0, ra1, ra2, ra3, rb0, rb1, rb2, rb3;
;     ...
;     unsigned char* sA0 = smem; unsigned char* sB0 = smem + 16384; unsigned char* sA1 = smem + 32768; unsigned char* sB1 = smem + 49152;
;     G_LOAD(0)
;     G_WRITE(sA0, sB0)
;     __syncthreads();
;     const int arow_off = (wr * 64 + lr) * 128, brow_off = (wc * 64 + lr) * 128, sw = lr & 7;
;     G_LOAD(1)
;     for (int kt = 0; kt < 16; ++kt) {
;         unsigned char* sA = (kt & 1) ? sA1 : sA0; unsigned char* sB = (kt & 1) ? sB1 : sB0;
;         unsigned char* nA = (kt & 1) ? sA0 : sA1; unsigned char* nB = (kt & 1) ? sB0 : sB1;
;         bf16x8 fa[4], fb[4], ga[4], gb[4];
;         const int ch0 = ((g ^ sw) << 4), ch1 = (((4 + g) ^ sw) << 4);
;         const unsigned ko = (unsigned)(kt + 2) * 128u;
;         const unsigned koa = ko + ((MODE == 2 && kt + 2 >= 8) ? (unsigned)(ZC_FQ - 512) * 2u : 0u);
;         const bool wr_ok = kt < 15, ld_ok = kt < 14;
; #pragma unroll
.LBB0_1263:
	s_lshr_b32 s0, s14, 4
	s_and_b32 s0, s0, 0x1fffff8
	s_and_b32 s1, s14, 7
	s_or_b32 s0, s0, s1
	v_mov_b32_e32 v88, v0
	s_bfe_u32 s2, s14, 0x40003
	s_lshl_b32 s23, s0, 7
	v_ashrrev_i32_e32 v6, 3, v88
	v_lshlrev_b32_e32 v3, 4, v88
	v_add_u32_e32 v2, s23, v6
	v_and_b32_e32 v3, 0x70, v3
	s_lshl_b32 s0, s2, 18
	v_lshl_add_u32 v4, v6, 11, s0
	v_lshl_or_b32 v24, v2, 11, v3
	v_or_b32_e32 v18, v4, v3
	v_add_u32_e32 v2, 0x10000, v24
	v_add_u32_e32 v3, 0x20000, v24
	global_load_dwordx4 v[20:23], v2, s[36:37]
	global_load_dwordx4 v[26:29], v3, s[36:37]
	v_add_u32_e32 v2, 0x20000, v18
	v_add_u32_e32 v3, 0x30000, v18
	global_load_dwordx4 v[30:33], v2, s[6:7]
	global_load_dwordx4 v[34:37], v3, s[6:7]
	v_add_u32_e32 v2, 0x30000, v24
	v_add_u32_e32 v3, 0x10000, v18
	global_load_dwordx4 v[38:41], v2, s[36:37]
	global_load_dwordx4 v[42:45], v3, s[6:7]
	global_load_dwordx4 v[46:49], v24, s[36:37]
	global_load_dwordx4 v[50:53], v18, s[6:7]
	v_ashrrev_i32_e32 v2, 1, v88
	v_and_b32_e32 v25, 0xffffffc0, v2
	v_and_b32_e32 v90, 15, v88
	v_add_u32_e32 v2, s23, v25
	v_or_b32_e32 v84, v2, v90
	v_ashrrev_i32_e32 v85, 31, v84
	v_xor_b32_e32 v7, v6, v88
	v_bfe_u32 v89, v88, 4, 2
	v_lshlrev_b64 v[2:3], 6, v[84:85]
	v_lshlrev_b32_e32 v6, 7, v6
	v_lshlrev_b32_e32 v7, 4, v7
	v_lshlrev_b32_e32 v82, 4, v89
	v_lshl_add_u64 v[2:3], s[4:5], 0, v[2:3]
	v_and_or_b32 v6, v7, s15, v6
	v_lshl_add_u64 v[54:55], v[2:3], 0, v[82:83]
	v_add_u32_e32 v19, 0, v6
	v_or_b32_e32 v62, 0x80, v24
	global_load_dwordx4 v[10:13], v[54:55], off
	global_load_dwordx4 v[2:5], v[54:55], off offset:3072
	v_or_b32_e32 v58, 0x80, v18
	v_add_u32_e32 v59, 0x10080, v18
	v_add_u32_e32 v60, 0x20080, v18
	v_add_u32_e32 v61, 0x30080, v18
	v_add_u32_e32 v63, 0x10080, v24
	v_add_u32_e32 v64, 0x20080, v24
	v_add_u32_e32 v65, 0x30080, v24
	global_load_dwordx4 v[14:17], v[54:55], off offset:1024
	global_load_dwordx4 v[6:9], v[54:55], off offset:2048
	v_or_b32_e32 v82, v25, v90
	v_and_b32_e32 v25, 7, v88
	v_bfe_u32 v91, v88, 6, 1
	v_lshl_add_u32 v104, v82, 7, 0
	s_waitcnt vmcnt(9)
	ds_write_b128 v19, v[30:33] offset:24576
	s_waitcnt vmcnt(8)
	ds_write_b128 v19, v[34:37] offset:28672
	ds_write_b128 v19, v[20:23] offset:4096
	ds_write_b128 v19, v[26:29] offset:8192
	s_waitcnt vmcnt(7)
	ds_write_b128 v19, v[38:41] offset:12288
	s_waitcnt vmcnt(6)
	ds_write_b128 v19, v[42:45] offset:20480
	s_waitcnt vmcnt(5)
	ds_write_b128 v19, v[46:49]
	s_waitcnt vmcnt(4)
	ds_write_b128 v19, v[50:53] offset:16384
	s_waitcnt lgkmcnt(0)
	s_barrier
	global_load_dwordx4 v[26:29], v62, s[36:37]
	global_load_dwordx4 v[30:33], v63, s[36:37]
	global_load_dwordx4 v[34:37], v64, s[36:37]
	global_load_dwordx4 v[38:41], v65, s[36:37]
	global_load_dwordx4 v[42:45], v58, s[6:7]
	global_load_dwordx4 v[46:49], v59, s[6:7]
	global_load_dwordx4 v[50:53], v60, s[6:7]
	global_load_dwordx4 v[54:57], v61, s[6:7]
	v_lshrrev_b32_e32 v20, 4, v88
	v_lshlrev_b32_e32 v21, 7, v90
	v_bitop3_b32 v20, v20, v25, 3 bitop3:0x6c
	v_lshl_or_b32 v21, v91, 13, v21
	v_lshlrev_b32_e32 v20, 4, v20
	v_add_u32_e32 v22, v104, v20
	v_add_u32_e32 v21, 0, v21
	v_add_u32_e32 v23, v21, v20
	ds_read_b128 v[58:61], v22
	ds_read_b128 v[62:65], v22 offset:2048
	ds_read_b128 v[66:69], v23 offset:16384
	ds_read_b128 v[70:73], v23 offset:18432
	ds_read_b128 v[74:77], v22 offset:4096
	ds_read_b128 v[78:81], v22 offset:6144
	ds_read_b128 v[92:95], v23 offset:20480
	ds_read_b128 v[96:99], v23 offset:22528
	v_bitop3_b32 v20, v89, v25, 4 bitop3:0x36
	v_lshlrev_b32_e32 v25, 4, v20
	s_setprio 2
	global_load_dwordx4 v[100:103], v24, s[36:37] offset:256
	s_waitcnt vmcnt(8)
	ds_write_b128 v19, v[26:29] offset:32768
	v_add_u32_e32 v20, v104, v25
	v_add_u32_e32 v21, v21, v25
	ds_read_b128 v[26:29], v20
	ds_read_b128 v[104:107], v21 offset:16384
	s_waitcnt lgkmcnt(8)
	v_mfma_f32_16x16x32_bf16 v[108:111], v[66:69], v[58:61], 0
	s_waitcnt lgkmcnt(7)
	v_mfma_f32_16x16x32_bf16 v[112:115], v[70:73], v[58:61], 0
	s_waitcnt lgkmcnt(4)
	v_mfma_f32_16x16x32_bf16 v[116:119], v[92:95], v[58:61], 0
	s_waitcnt lgkmcnt(3)
	v_mfma_f32_16x16x32_bf16 v[58:61], v[96:99], v[58:61], 0
	v_add_u32_e32 v245, 0x10000, v24
	global_load_dwordx4 v[120:123], v245, s[36:37] offset:256
	s_waitcnt vmcnt(8)
	ds_write_b128 v19, v[30:33] offset:36864
	ds_read_b128 v[30:33], v20 offset:2048
	ds_read_b128 v[124:127], v21 offset:18432
	v_mfma_f32_16x16x32_bf16 v[132:135], v[66:69], v[62:65], 0
	v_mfma_f32_16x16x32_bf16 v[136:139], v[70:73], v[62:65], 0
	v_mfma_f32_16x16x32_bf16 v[140:143], v[92:95], v[62:65], 0
	v_mfma_f32_16x16x32_bf16 v[62:65], v[96:99], v[62:65], 0
	v_add_u32_e32 v246, 0x20000, v24
	global_load_dwordx4 v[144:147], v246, s[36:37] offset:256
	s_waitcnt vmcnt(8)
	ds_write_b128 v19, v[34:37] offset:40960
	ds_read_b128 v[34:37], v20 offset:4096
	ds_read_b128 v[148:151], v21 offset:20480
	v_mfma_f32_16x16x32_bf16 v[152:155], v[66:69], v[74:77], 0
	v_mfma_f32_16x16x32_bf16 v[156:159], v[70:73], v[74:77], 0
	v_mfma_f32_16x16x32_bf16 v[160:163], v[92:95], v[74:77], 0
	v_mfma_f32_16x16x32_bf16 v[74:77], v[96:99], v[74:77], 0
	v_add_u32_e32 v247, 0x30000, v24
	global_load_dwordx4 v[164:167], v247, s[36:37] offset:256
	s_waitcnt vmcnt(8)
	ds_write_b128 v19, v[38:41] offset:45056
	ds_read_b128 v[38:41], v20 offset:6144
	ds_read_b128 v[168:171], v21 offset:22528
	v_mfma_f32_16x16x32_bf16 v[66:69], v[66:69], v[78:81], 0
	v_mfma_f32_16x16x32_bf16 v[70:73], v[70:73], v[78:81], 0
	v_mfma_f32_16x16x32_bf16 v[92:95], v[92:95], v[78:81], 0
	v_mfma_f32_16x16x32_bf16 v[78:81], v[96:99], v[78:81], 0
	global_load_dwordx4 v[96:99], v18, s[6:7] offset:256
	s_waitcnt vmcnt(8)
	ds_write_b128 v19, v[42:45] offset:49152
	s_waitcnt lgkmcnt(10)
; template <int MODE>
; __device__ __forceinline__ void gemm_tile(const Params& P, int tm, int tn, unsigned char* smem) {
;     ...
; #pragma unroll
;         for (int i = 0; i < 4; ++i) { fa[i] = *(const bf16x8*)(sA + arow_off + i * 2048 + ch0); fb[i] = *(const bf16x8*)(sB + brow_off + i * 2048 + ch0); }
;         __builtin_amdgcn_sched_barrier(0);
;         __builtin_amdgcn_s_setprio(2);
;         if (wr_ok) *(uint4*)(nA + soff0) = ra0;
;         if (ld_ok) ra0 = *(const uint4*)(Ab + (aoff + 0u * LDA + koa));
;         ga[0] = *(const bf16x8*)(sA + arow_off + 0 * 2048 + ch1); gb[0] = *(const bf16x8*)(sB + brow_off + 0 * 2048 + ch1);
;         __builtin_amdgcn_sched_barrier(0);
; #pragma unroll
;         for (int j = 0; j < 4; ++j) acc[0][j] = __builtin_amdgcn_mfma_f32_16x16x32_bf16(fb[j], fa[0], acc[0][j], 0, 0, 0);
;         __builtin_amdgcn_sched_barrier(0);
;         if (wr_ok) *(uint4*)(nA + soff0 + 4096) = ra1;
;         if (ld_ok) ra1 = *(const uint4*)(Ab + (aoff + 32u * LDA + koa));
;         ga[1] = *(const bf16x8*)(sA + arow_off + 1 * 2048 + ch1); gb[1] = *(const bf16x8*)(sB + brow_off + 1 * 2048 + ch1);
;         __builtin_amdgcn_sched_barrier(0);
; #pragma unroll
;         for (int j = 0; j < 4; ++j) acc[1][j] = __builtin_amdgcn_mfma_f32_16x16x32_bf16(fb[j], fa[1], acc[1][j], 0, 0, 0);
;         __builtin_amdgcn_sched_barrier(0);
;         if (wr_ok) *(uint4*)(nA + soff0 + 8192) = ra2;
;         if (ld_ok) ra2 = *(const uint4*)(Ab + (aoff + 64u * LDA + koa));
;         ga[2] = *(const bf16x8*)(sA + arow_off + 2 * 2048 + ch1); gb[2] = *(const bf16x8*)(sB + brow_off + 2 * 2048 + ch1);
;         __builtin_amdgcn_sched_barrier(0);
; #pragma unroll
;         for (int j = 0; j < 4; ++j) acc[2][j] = __builtin_amdgcn_mfma_f32_16x16x32_bf16(fb[j], fa[2], acc[2][j], 0, 0, 0);
;         __builtin_amdgcn_sched_barrier(0);
;         if (wr_ok) *(uint4*)(nA + soff0 + 12288) = ra3;
;         if (ld_ok) ra3 = *(const uint4*)(Ab + (aoff + 96u * LDA + koa));
;         ga[3] = *(const bf16x8*)(sA + arow_off + 3 * 2048 + ch1); gb[3] = *(const bf16x8*)(sB + brow_off + 3 * 2048 + ch1);
;         __builtin_amdgcn_sched_barrier(0);
; #pragma unroll
;         for (int j = 0; j < 4; ++j) acc[3][j] = __builtin_amdgcn_mfma_f32_16x16x32_bf16(fb[j], fa[3], acc[3][j], 0, 0, 0);
;         __builtin_amdgcn_sched_barrier(0);
;         if (wr_ok) *(uint4*)(nB + soff0) = rb0;
	v_mfma_f32_16x16x32_bf16 v[42:45], v[104:107], v[26:29], v[108:111]
	s_waitcnt lgkmcnt(7)
	v_mfma_f32_16x16x32_bf16 v[108:111], v[124:127], v[26:29], v[112:115]
	s_waitcnt lgkmcnt(4)
	v_mfma_f32_16x16x32_bf16 v[112:115], v[148:151], v[26:29], v[116:119]
	s_waitcnt lgkmcnt(1)
	v_mfma_f32_16x16x32_bf16 v[26:29], v[168:171], v[26:29], v[58:61]
	v_add_u32_e32 v248, 0x10000, v18
	global_load_dwordx4 v[58:61], v248, s[6:7] offset:256
	s_waitcnt vmcnt(8)
	ds_write_b128 v19, v[46:49] offset:53248
	v_mfma_f32_16x16x32_bf16 v[46:49], v[104:107], v[30:33], v[132:135]
	v_mfma_f32_16x16x32_bf16 v[116:119], v[124:127], v[30:33], v[136:139]
	v_mfma_f32_16x16x32_bf16 v[132:135], v[148:151], v[30:33], v[140:143]
	v_mfma_f32_16x16x32_bf16 v[30:33], v[168:171], v[30:33], v[62:65]
	v_add_u32_e32 v249, 0x20000, v18
	global_load_dwordx4 v[62:65], v249, s[6:7] offset:256
	s_waitcnt vmcnt(8)
	ds_write_b128 v19, v[50:53] offset:57344
	v_mfma_f32_16x16x32_bf16 v[50:53], v[104:107], v[34:37], v[152:155]
	v_mfma_f32_16x16x32_bf16 v[136:139], v[124:127], v[34:37], v[156:159]
	v_mfma_f32_16x16x32_bf16 v[140:143], v[148:151], v[34:37], v[160:163]
	v_mfma_f32_16x16x32_bf16 v[34:37], v[168:171], v[34:37], v[74:77]
	v_add_u32_e32 v250, 0x30000, v18
	global_load_dwordx4 v[74:77], v250, s[6:7] offset:256
	s_waitcnt vmcnt(8)
	ds_write_b128 v19, v[54:57] offset:61440
	v_mfma_f32_16x16x32_bf16 v[54:57], v[104:107], v[38:41], v[66:69]
	v_mfma_f32_16x16x32_bf16 v[66:69], v[124:127], v[38:41], v[70:73]
	v_mfma_f32_16x16x32_bf16 v[70:73], v[148:151], v[38:41], v[92:95]
	v_mfma_f32_16x16x32_bf16 v[38:41], v[168:171], v[38:41], v[78:81]
	s_setprio 0
	s_waitcnt lgkmcnt(0)
	s_barrier
	ds_read_b128 v[78:81], v22 offset:32768
	ds_read_b128 v[92:95], v22 offset:34816
	ds_read_b128 v[104:107], v23 offset:49152
	ds_read_b128 v[124:127], v23 offset:51200
	ds_read_b128 v[148:151], v22 offset:36864
	ds_read_b128 v[152:155], v22 offset:38912
	ds_read_b128 v[156:159], v23 offset:53248
	ds_read_b128 v[160:163], v23 offset:55296
	s_setprio 2
	global_load_dwordx4 v[168:171], v24, s[36:37] offset:384
	s_waitcnt vmcnt(8)
	ds_write_b128 v19, v[100:103]
	ds_read_b128 v[100:103], v20 offset:32768
	ds_read_b128 v[172:175], v21 offset:49152
	s_waitcnt lgkmcnt(8)
	v_mfma_f32_16x16x32_bf16 v[42:45], v[104:107], v[78:81], v[42:45]
	s_waitcnt lgkmcnt(3)
	v_mfma_f32_16x16x32_bf16 v[26:29], v[160:163], v[78:81], v[26:29]
	v_mfma_f32_16x16x32_bf16 v[108:111], v[124:127], v[78:81], v[108:111]
	v_mfma_f32_16x16x32_bf16 v[112:115], v[156:159], v[78:81], v[112:115]
	global_load_dwordx4 v[78:81], v245, s[36:37] offset:384
	v_mfma_f32_16x16x32_bf16 v[46:49], v[104:107], v[92:95], v[46:49]
	s_waitcnt vmcnt(8)
	ds_write_b128 v19, v[120:123] offset:4096
	v_mfma_f32_16x16x32_bf16 v[30:33], v[160:163], v[92:95], v[30:33]
	ds_read_b128 v[120:123], v20 offset:34816
	v_mfma_f32_16x16x32_bf16 v[116:119], v[124:127], v[92:95], v[116:119]
	ds_read_b128 v[176:179], v21 offset:51200
	v_mfma_f32_16x16x32_bf16 v[132:135], v[156:159], v[92:95], v[132:135]
	global_load_dwordx4 v[92:95], v246, s[36:37] offset:384
	v_mfma_f32_16x16x32_bf16 v[50:53], v[104:107], v[148:151], v[50:53]
	s_waitcnt vmcnt(8)
	ds_write_b128 v19, v[144:147] offset:8192
	v_mfma_f32_16x16x32_bf16 v[34:37], v[160:163], v[148:151], v[34:37]
	ds_read_b128 v[144:147], v20 offset:36864
	v_mfma_f32_16x16x32_bf16 v[136:139], v[124:127], v[148:151], v[136:139]
	ds_read_b128 v[180:183], v21 offset:53248
	v_mfma_f32_16x16x32_bf16 v[140:143], v[156:159], v[148:151], v[140:143]
	global_load_dwordx4 v[148:151], v247, s[36:37] offset:384
	v_mfma_f32_16x16x32_bf16 v[54:57], v[104:107], v[152:155], v[54:57]
	s_waitcnt vmcnt(8)
	ds_write_b128 v19, v[164:167] offset:12288
	v_mfma_f32_16x16x32_bf16 v[66:69], v[124:127], v[152:155], v[66:69]
	ds_read_b128 v[164:167], v20 offset:38912
	v_mfma_f32_16x16x32_bf16 v[70:73], v[156:159], v[152:155], v[70:73]
	ds_read_b128 v[184:187], v21 offset:55296
	v_mfma_f32_16x16x32_bf16 v[38:41], v[160:163], v[152:155], v[38:41]
	global_load_dwordx4 v[104:107], v18, s[6:7] offset:384
	s_waitcnt vmcnt(8)
	ds_write_b128 v19, v[96:99] offset:16384
	s_waitcnt lgkmcnt(10)
	v_mfma_f32_16x16x32_bf16 v[42:45], v[172:175], v[100:103], v[42:45]
	s_waitcnt lgkmcnt(1)
	v_mfma_f32_16x16x32_bf16 v[26:29], v[184:187], v[100:103], v[26:29]
	v_mfma_f32_16x16x32_bf16 v[96:99], v[176:179], v[100:103], v[108:111]
	v_mfma_f32_16x16x32_bf16 v[108:111], v[180:183], v[100:103], v[112:115]
	global_load_dwordx4 v[100:103], v248, s[6:7] offset:384
	s_waitcnt vmcnt(8)
	ds_write_b128 v19, v[58:61] offset:20480
	v_mfma_f32_16x16x32_bf16 v[46:49], v[172:175], v[120:123], v[46:49]
	v_mfma_f32_16x16x32_bf16 v[58:61], v[176:179], v[120:123], v[116:119]
	v_mfma_f32_16x16x32_bf16 v[30:33], v[184:187], v[120:123], v[30:33]
	v_mfma_f32_16x16x32_bf16 v[112:115], v[180:183], v[120:123], v[132:135]
	global_load_dwordx4 v[116:119], v249, s[6:7] offset:384
	s_waitcnt vmcnt(8)
	ds_write_b128 v19, v[62:65] offset:24576
	v_mfma_f32_16x16x32_bf16 v[50:53], v[172:175], v[144:147], v[50:53]
	v_mfma_f32_16x16x32_bf16 v[62:65], v[176:179], v[144:147], v[136:139]
	v_mfma_f32_16x16x32_bf16 v[34:37], v[184:187], v[144:147], v[34:37]
	v_mfma_f32_16x16x32_bf16 v[120:123], v[180:183], v[144:147], v[140:143]
	global_load_dwordx4 v[124:127], v250, s[6:7] offset:384
	v_mfma_f32_16x16x32_bf16 v[54:57], v[172:175], v[164:167], v[54:57]
	s_waitcnt vmcnt(8)
	ds_write_b128 v19, v[74:77] offset:28672
	v_mfma_f32_16x16x32_bf16 v[66:69], v[176:179], v[164:167], v[66:69]
	v_mfma_f32_16x16x32_bf16 v[70:73], v[180:183], v[164:167], v[70:73]
	v_mfma_f32_16x16x32_bf16 v[38:41], v[184:187], v[164:167], v[38:41]
	s_setprio 0
	s_waitcnt lgkmcnt(0)
	s_barrier
; template <int MODE>
; __device__ __forceinline__ void gemm_tile(const Params& P, int tm, int tn, unsigned char* smem) {
;     ...
; #pragma unroll
;         for (int i = 0; i < 4; ++i) { fa[i] = *(const bf16x8*)(sA + arow_off + i * 2048 + ch0); fb[i] = *(const bf16x8*)(sB + brow_off + i * 2048 + ch0); }
;         __builtin_amdgcn_sched_barrier(0);
;         __builtin_amdgcn_s_setprio(2);
;         if (wr_ok) *(uint4*)(nA + soff0) = ra0;
;         if (ld_ok) ra0 = *(const uint4*)(Ab + (aoff + 0u * LDA + koa));
;         ga[0] = *(const bf16x8*)(sA + arow_off + 0 * 2048 + ch1); gb[0] = *(const bf16x8*)(sB + brow_off + 0 * 2048 + ch1);
;         __builtin_amdgcn_sched_barrier(0);
; #pragma unroll
;         for (int j = 0; j < 4; ++j) acc[0][j] = __builtin_amdgcn_mfma_f32_16x16x32_bf16(fb[j], fa[0], acc[0][j], 0, 0, 0);
;         __builtin_amdgcn_sched_barrier(0);
;         if (wr_ok) *(uint4*)(nA + soff0 + 4096) = ra1;
;         if (ld_ok) ra1 = *(const uint4*)(Ab + (aoff + 32u * LDA + koa));
;         ga[1] = *(const bf16x8*)(sA + arow_off + 1 * 2048 + ch1); gb[1] = *(const bf16x8*)(sB + brow_off + 1 * 2048 + ch1);
;         __builtin_amdgcn_sched_barrier(0);
; #pragma unroll
;         for (int j = 0; j < 4; ++j) acc[1][j] = __builtin_amdgcn_mfma_f32_16x16x32_bf16(fb[j], fa[1], acc[1][j], 0, 0, 0);
;         __builtin_amdgcn_sched_barrier(0);
;         if (wr_ok) *(uint4*)(nA + soff0 + 8192) = ra2;
;         if (ld_ok) ra2 = *(const uint4*)(Ab + (aoff + 64u * LDA + koa));
;         ga[2] = *(const bf16x8*)(sA + arow_off + 2 * 2048 + ch1); gb[2] = *(const bf16x8*)(sB + brow_off + 2 * 2048 + ch1);
;         __builtin_amdgcn_sched_barrier(0);
; #pragma unroll
;         for (int j = 0; j < 4; ++j) acc[2][j] = __builtin_amdgcn_mfma_f32_16x16x32_bf16(fb[j], fa[2], acc[2][j], 0, 0, 0);
;         __builtin_amdgcn_sched_barrier(0);
;         if (wr_ok) *(uint4*)(nA + soff0 + 12288) = ra3;
;         if (ld_ok) ra3 = *(const uint4*)(Ab + (aoff + 96u * LDA + koa));
;         ga[3] = *(const bf16x8*)(sA + arow_off + 3 * 2048 + ch1); gb[3] = *(const bf16x8*)(sB + brow_off + 3 * 2048 + ch1);
;         __builtin_amdgcn_sched_barrier(0);
; #pragma unroll
;         for (int j = 0; j < 4; ++j) acc[3][j] = __builtin_amdgcn_mfma_f32_16x16x32_bf16(fb[j], fa[3], acc[3][j], 0, 0, 0);
;         __builtin_amdgcn_sched_barrier(0);
;         if (wr_ok) *(uint4*)(nB + soff0) = rb0;
	ds_read_b128 v[74:77], v22
	ds_read_b128 v[132:135], v22 offset:2048
	ds_read_b128 v[136:139], v23 offset:16384
	ds_read_b128 v[140:143], v23 offset:18432
	ds_read_b128 v[144:147], v22 offset:4096
	ds_read_b128 v[152:155], v22 offset:6144
	ds_read_b128 v[156:159], v23 offset:20480
	ds_read_b128 v[160:163], v23 offset:22528
	s_setprio 2
	global_load_dwordx4 v[164:167], v24, s[36:37] offset:512
	s_waitcnt vmcnt(8)
	ds_write_b128 v19, v[168:171] offset:32768
	ds_read_b128 v[168:171], v20
	ds_read_b128 v[172:175], v21 offset:16384
	s_waitcnt lgkmcnt(8)
	v_mfma_f32_16x16x32_bf16 v[42:45], v[136:139], v[74:77], v[42:45]
	s_waitcnt lgkmcnt(3)
	v_mfma_f32_16x16x32_bf16 v[26:29], v[160:163], v[74:77], v[26:29]
	v_mfma_f32_16x16x32_bf16 v[96:99], v[140:143], v[74:77], v[96:99]
	v_mfma_f32_16x16x32_bf16 v[108:111], v[156:159], v[74:77], v[108:111]
	global_load_dwordx4 v[74:77], v245, s[36:37] offset:512
	v_mfma_f32_16x16x32_bf16 v[46:49], v[136:139], v[132:135], v[46:49]
	s_waitcnt vmcnt(8)
	ds_write_b128 v19, v[78:81] offset:36864
	v_mfma_f32_16x16x32_bf16 v[58:61], v[140:143], v[132:135], v[58:61]
	ds_read_b128 v[78:81], v20 offset:2048
	v_mfma_f32_16x16x32_bf16 v[30:33], v[160:163], v[132:135], v[30:33]
	ds_read_b128 v[176:179], v21 offset:18432
	v_mfma_f32_16x16x32_bf16 v[112:115], v[156:159], v[132:135], v[112:115]
	global_load_dwordx4 v[132:135], v246, s[36:37] offset:512
	v_mfma_f32_16x16x32_bf16 v[50:53], v[136:139], v[144:147], v[50:53]
	s_waitcnt vmcnt(8)
	ds_write_b128 v19, v[92:95] offset:40960
	v_mfma_f32_16x16x32_bf16 v[62:65], v[140:143], v[144:147], v[62:65]
	ds_read_b128 v[92:95], v20 offset:4096
	v_mfma_f32_16x16x32_bf16 v[34:37], v[160:163], v[144:147], v[34:37]
	ds_read_b128 v[180:183], v21 offset:20480
	v_mfma_f32_16x16x32_bf16 v[120:123], v[156:159], v[144:147], v[120:123]
	global_load_dwordx4 v[144:147], v247, s[36:37] offset:512
	v_mfma_f32_16x16x32_bf16 v[54:57], v[136:139], v[152:155], v[54:57]
	s_waitcnt vmcnt(8)
	ds_write_b128 v19, v[148:151] offset:45056
	v_mfma_f32_16x16x32_bf16 v[66:69], v[140:143], v[152:155], v[66:69]
	ds_read_b128 v[148:151], v20 offset:6144
	v_mfma_f32_16x16x32_bf16 v[70:73], v[156:159], v[152:155], v[70:73]
	ds_read_b128 v[184:187], v21 offset:22528
	v_mfma_f32_16x16x32_bf16 v[38:41], v[160:163], v[152:155], v[38:41]
	global_load_dwordx4 v[136:139], v18, s[6:7] offset:512
	s_waitcnt vmcnt(8)
	ds_write_b128 v19, v[104:107] offset:49152
	s_waitcnt lgkmcnt(10)
	v_mfma_f32_16x16x32_bf16 v[42:45], v[172:175], v[168:171], v[42:45]
	s_waitcnt lgkmcnt(1)
	v_mfma_f32_16x16x32_bf16 v[26:29], v[184:187], v[168:171], v[26:29]
	v_mfma_f32_16x16x32_bf16 v[96:99], v[176:179], v[168:171], v[96:99]
	v_mfma_f32_16x16x32_bf16 v[104:107], v[180:183], v[168:171], v[108:111]
	global_load_dwordx4 v[108:111], v248, s[6:7] offset:512
	s_waitcnt vmcnt(8)
	ds_write_b128 v19, v[100:103] offset:53248
	v_mfma_f32_16x16x32_bf16 v[46:49], v[172:175], v[78:81], v[46:49]
	v_mfma_f32_16x16x32_bf16 v[58:61], v[176:179], v[78:81], v[58:61]
	v_mfma_f32_16x16x32_bf16 v[30:33], v[184:187], v[78:81], v[30:33]
	v_mfma_f32_16x16x32_bf16 v[100:103], v[180:183], v[78:81], v[112:115]
	global_load_dwordx4 v[78:81], v249, s[6:7] offset:512
	v_mfma_f32_16x16x32_bf16 v[50:53], v[172:175], v[92:95], v[50:53]
	s_waitcnt vmcnt(8)
	ds_write_b128 v19, v[116:119] offset:57344
	v_mfma_f32_16x16x32_bf16 v[62:65], v[176:179], v[92:95], v[62:65]
	v_mfma_f32_16x16x32_bf16 v[34:37], v[184:187], v[92:95], v[34:37]
	v_mfma_f32_16x16x32_bf16 v[112:115], v[180:183], v[92:95], v[120:123]
	global_load_dwordx4 v[92:95], v250, s[6:7] offset:512
	v_mfma_f32_16x16x32_bf16 v[54:57], v[172:175], v[148:151], v[54:57]
	s_waitcnt vmcnt(8)
	ds_write_b128 v19, v[124:127] offset:61440
	v_mfma_f32_16x16x32_bf16 v[66:69], v[176:179], v[148:151], v[66:69]
	v_mfma_f32_16x16x32_bf16 v[70:73], v[180:183], v[148:151], v[70:73]
	v_mfma_f32_16x16x32_bf16 v[38:41], v[184:187], v[148:151], v[38:41]
	s_setprio 0
	s_waitcnt lgkmcnt(0)
	s_barrier
	ds_read_b128 v[116:119], v22 offset:32768
	ds_read_b128 v[120:123], v22 offset:34816
	ds_read_b128 v[124:127], v23 offset:49152
	ds_read_b128 v[140:143], v23 offset:51200
	ds_read_b128 v[148:151], v22 offset:36864
	ds_read_b128 v[152:155], v22 offset:38912
	ds_read_b128 v[156:159], v23 offset:53248
	ds_read_b128 v[160:163], v23 offset:55296
	s_setprio 2
	global_load_dwordx4 v[168:171], v24, s[36:37] offset:640
	s_waitcnt vmcnt(8)
	ds_write_b128 v19, v[164:167]
	ds_read_b128 v[164:167], v20 offset:32768
	ds_read_b128 v[172:175], v21 offset:49152
	s_waitcnt lgkmcnt(8)
	v_mfma_f32_16x16x32_bf16 v[42:45], v[124:127], v[116:119], v[42:45]
	s_waitcnt lgkmcnt(3)
	v_mfma_f32_16x16x32_bf16 v[26:29], v[160:163], v[116:119], v[26:29]
	v_mfma_f32_16x16x32_bf16 v[96:99], v[140:143], v[116:119], v[96:99]
	v_mfma_f32_16x16x32_bf16 v[104:107], v[156:159], v[116:119], v[104:107]
	global_load_dwordx4 v[116:119], v245, s[36:37] offset:640
	v_mfma_f32_16x16x32_bf16 v[46:49], v[124:127], v[120:123], v[46:49]
	s_waitcnt vmcnt(8)
	ds_write_b128 v19, v[74:77] offset:4096
	v_mfma_f32_16x16x32_bf16 v[58:61], v[140:143], v[120:123], v[58:61]
	ds_read_b128 v[74:77], v20 offset:34816
	v_mfma_f32_16x16x32_bf16 v[30:33], v[160:163], v[120:123], v[30:33]
	ds_read_b128 v[176:179], v21 offset:51200
	v_mfma_f32_16x16x32_bf16 v[100:103], v[156:159], v[120:123], v[100:103]
	global_load_dwordx4 v[120:123], v246, s[36:37] offset:640
	v_mfma_f32_16x16x32_bf16 v[50:53], v[124:127], v[148:151], v[50:53]
	s_waitcnt vmcnt(8)
; template <int MODE>
; __device__ __forceinline__ void gemm_tile(const Params& P, int tm, int tn, unsigned char* smem) {
;     ...
; #pragma unroll
;         for (int i = 0; i < 4; ++i) { fa[i] = *(const bf16x8*)(sA + arow_off + i * 2048 + ch0); fb[i] = *(const bf16x8*)(sB + brow_off + i * 2048 + ch0); }
;         __builtin_amdgcn_sched_barrier(0);
;         __builtin_amdgcn_s_setprio(2);
;         if (wr_ok) *(uint4*)(nA + soff0) = ra0;
;         if (ld_ok) ra0 = *(const uint4*)(Ab + (aoff + 0u * LDA + koa));
;         ga[0] = *(const bf16x8*)(sA + arow_off + 0 * 2048 + ch1); gb[0] = *(const bf16x8*)(sB + brow_off + 0 * 2048 + ch1);
;         __builtin_amdgcn_sched_barrier(0);
; #pragma unroll
;         for (int j = 0; j < 4; ++j) acc[0][j] = __builtin_amdgcn_mfma_f32_16x16x32_bf16(fb[j], fa[0], acc[0][j], 0, 0, 0);
;         __builtin_amdgcn_sched_barrier(0);
;         if (wr_ok) *(uint4*)(nA + soff0 + 4096) = ra1;
;         if (ld_ok) ra1 = *(const uint4*)(Ab + (aoff + 32u * LDA + koa));
;         ga[1] = *(const bf16x8*)(sA + arow_off + 1 * 2048 + ch1); gb[1] = *(const bf16x8*)(sB + brow_off + 1 * 2048 + ch1);
;         __builtin_amdgcn_sched_barrier(0);
; #pragma unroll
;         for (int j = 0; j < 4; ++j) acc[1][j] = __builtin_amdgcn_mfma_f32_16x16x32_bf16(fb[j], fa[1], acc[1][j], 0, 0, 0);
;         __builtin_amdgcn_sched_barrier(0);
;         if (wr_ok) *(uint4*)(nA + soff0 + 8192) = ra2;
;         if (ld_ok) ra2 = *(const uint4*)(Ab + (aoff + 64u * LDA + koa));
;         ga[2] = *(const bf16x8*)(sA + arow_off + 2 * 2048 + ch1); gb[2] = *(const bf16x8*)(sB + brow_off + 2 * 2048 + ch1);
;         __builtin_amdgcn_sched_barrier(0);
; #pragma unroll
;         for (int j = 0; j < 4; ++j) acc[2][j] = __builtin_amdgcn_mfma_f32_16x16x32_bf16(fb[j], fa[2], acc[2][j], 0, 0, 0);
;         __builtin_amdgcn_sched_barrier(0);
;         if (wr_ok) *(uint4*)(nA + soff0 + 12288) = ra3;
;         if (ld_ok) ra3 = *(const uint4*)(Ab + (aoff + 96u * LDA + koa));
;         ga[3] = *(const bf16x8*)(sA + arow_off + 3 * 2048 + ch1); gb[3] = *(const bf16x8*)(sB + brow_off + 3 * 2048 + ch1);
;         __builtin_amdgcn_sched_barrier(0);
; #pragma unroll
;         for (int j = 0; j < 4; ++j) acc[3][j] = __builtin_amdgcn_mfma_f32_16x16x32_bf16(fb[j], fa[3], acc[3][j], 0, 0, 0);
;         __builtin_amdgcn_sched_barrier(0);
;         if (wr_ok) *(uint4*)(nB + soff0) = rb0;
	ds_write_b128 v19, v[132:135] offset:8192
	v_mfma_f32_16x16x32_bf16 v[62:65], v[140:143], v[148:151], v[62:65]
	ds_read_b128 v[132:135], v20 offset:36864
	v_mfma_f32_16x16x32_bf16 v[34:37], v[160:163], v[148:151], v[34:37]
	ds_read_b128 v[180:183], v21 offset:53248
	v_mfma_f32_16x16x32_bf16 v[112:115], v[156:159], v[148:151], v[112:115]
	global_load_dwordx4 v[148:151], v247, s[36:37] offset:640
	v_mfma_f32_16x16x32_bf16 v[54:57], v[124:127], v[152:155], v[54:57]
	s_waitcnt vmcnt(8)
	ds_write_b128 v19, v[144:147] offset:12288
	v_mfma_f32_16x16x32_bf16 v[66:69], v[140:143], v[152:155], v[66:69]
	ds_read_b128 v[144:147], v20 offset:38912
	v_mfma_f32_16x16x32_bf16 v[70:73], v[156:159], v[152:155], v[70:73]
	ds_read_b128 v[184:187], v21 offset:55296
	v_mfma_f32_16x16x32_bf16 v[38:41], v[160:163], v[152:155], v[38:41]
	global_load_dwordx4 v[124:127], v18, s[6:7] offset:640
	s_waitcnt vmcnt(8)
	ds_write_b128 v19, v[136:139] offset:16384
	s_waitcnt lgkmcnt(10)
	v_mfma_f32_16x16x32_bf16 v[42:45], v[172:175], v[164:167], v[42:45]
	s_waitcnt lgkmcnt(1)
	v_mfma_f32_16x16x32_bf16 v[26:29], v[184:187], v[164:167], v[26:29]
	v_mfma_f32_16x16x32_bf16 v[96:99], v[176:179], v[164:167], v[96:99]
	v_mfma_f32_16x16x32_bf16 v[104:107], v[180:183], v[164:167], v[104:107]
	global_load_dwordx4 v[136:139], v248, s[6:7] offset:640
	v_mfma_f32_16x16x32_bf16 v[46:49], v[172:175], v[74:77], v[46:49]
	s_waitcnt vmcnt(8)
	ds_write_b128 v19, v[108:111] offset:20480
	v_mfma_f32_16x16x32_bf16 v[58:61], v[176:179], v[74:77], v[58:61]
	v_mfma_f32_16x16x32_bf16 v[30:33], v[184:187], v[74:77], v[30:33]
	v_mfma_f32_16x16x32_bf16 v[100:103], v[180:183], v[74:77], v[100:103]
	global_load_dwordx4 v[74:77], v249, s[6:7] offset:640
	s_waitcnt vmcnt(8)
	ds_write_b128 v19, v[78:81] offset:24576
	v_mfma_f32_16x16x32_bf16 v[50:53], v[172:175], v[132:135], v[50:53]
	v_mfma_f32_16x16x32_bf16 v[62:65], v[176:179], v[132:135], v[62:65]
	v_mfma_f32_16x16x32_bf16 v[78:81], v[180:183], v[132:135], v[112:115]
	v_mfma_f32_16x16x32_bf16 v[34:37], v[184:187], v[132:135], v[34:37]
	global_load_dwordx4 v[108:111], v250, s[6:7] offset:640
	v_mfma_f32_16x16x32_bf16 v[54:57], v[172:175], v[144:147], v[54:57]
	s_waitcnt vmcnt(8)
	ds_write_b128 v19, v[92:95] offset:28672
	v_mfma_f32_16x16x32_bf16 v[66:69], v[176:179], v[144:147], v[66:69]
	v_mfma_f32_16x16x32_bf16 v[70:73], v[180:183], v[144:147], v[70:73]
	v_mfma_f32_16x16x32_bf16 v[38:41], v[184:187], v[144:147], v[38:41]
	s_setprio 0
	s_waitcnt lgkmcnt(0)
	s_barrier
	ds_read_b128 v[92:95], v22
	ds_read_b128 v[112:115], v22 offset:2048
	ds_read_b128 v[132:135], v23 offset:16384
	ds_read_b128 v[140:143], v23 offset:18432
	ds_read_b128 v[144:147], v22 offset:4096
	ds_read_b128 v[152:155], v22 offset:6144
	ds_read_b128 v[156:159], v23 offset:20480
	ds_read_b128 v[160:163], v23 offset:22528
	s_setprio 2
	global_load_dwordx4 v[164:167], v24, s[36:37] offset:768
	s_waitcnt vmcnt(8)
	ds_write_b128 v19, v[168:171] offset:32768
	ds_read_b128 v[168:171], v20
	ds_read_b128 v[172:175], v21 offset:16384
	s_waitcnt lgkmcnt(8)
	v_mfma_f32_16x16x32_bf16 v[42:45], v[132:135], v[92:95], v[42:45]
	s_waitcnt lgkmcnt(3)
	v_mfma_f32_16x16x32_bf16 v[26:29], v[160:163], v[92:95], v[26:29]
	v_mfma_f32_16x16x32_bf16 v[96:99], v[140:143], v[92:95], v[96:99]
	v_mfma_f32_16x16x32_bf16 v[104:107], v[156:159], v[92:95], v[104:107]
	global_load_dwordx4 v[92:95], v245, s[36:37] offset:768
	v_mfma_f32_16x16x32_bf16 v[46:49], v[132:135], v[112:115], v[46:49]
	s_waitcnt vmcnt(8)
	ds_write_b128 v19, v[116:119] offset:36864
	v_mfma_f32_16x16x32_bf16 v[58:61], v[140:143], v[112:115], v[58:61]
	ds_read_b128 v[116:119], v20 offset:2048
	v_mfma_f32_16x16x32_bf16 v[30:33], v[160:163], v[112:115], v[30:33]
	ds_read_b128 v[176:179], v21 offset:18432
	v_mfma_f32_16x16x32_bf16 v[100:103], v[156:159], v[112:115], v[100:103]
	global_load_dwordx4 v[112:115], v246, s[36:37] offset:768
	v_mfma_f32_16x16x32_bf16 v[50:53], v[132:135], v[144:147], v[50:53]
	s_waitcnt vmcnt(8)
	ds_write_b128 v19, v[120:123] offset:40960
	v_mfma_f32_16x16x32_bf16 v[62:65], v[140:143], v[144:147], v[62:65]
	ds_read_b128 v[120:123], v20 offset:4096
	v_mfma_f32_16x16x32_bf16 v[78:81], v[156:159], v[144:147], v[78:81]
	ds_read_b128 v[180:183], v21 offset:20480
	v_mfma_f32_16x16x32_bf16 v[34:37], v[160:163], v[144:147], v[34:37]
	global_load_dwordx4 v[144:147], v247, s[36:37] offset:768
	v_mfma_f32_16x16x32_bf16 v[54:57], v[132:135], v[152:155], v[54:57]
	s_waitcnt vmcnt(8)
	ds_write_b128 v19, v[148:151] offset:45056
	v_mfma_f32_16x16x32_bf16 v[66:69], v[140:143], v[152:155], v[66:69]
	ds_read_b128 v[148:151], v20 offset:6144
	v_mfma_f32_16x16x32_bf16 v[70:73], v[156:159], v[152:155], v[70:73]
	ds_read_b128 v[184:187], v21 offset:22528
	v_mfma_f32_16x16x32_bf16 v[38:41], v[160:163], v[152:155], v[38:41]
	global_load_dwordx4 v[132:135], v18, s[6:7] offset:768
	s_waitcnt vmcnt(8)
	ds_write_b128 v19, v[124:127] offset:49152
	s_waitcnt lgkmcnt(10)
	v_mfma_f32_16x16x32_bf16 v[42:45], v[172:175], v[168:171], v[42:45]
	s_waitcnt lgkmcnt(1)
	v_mfma_f32_16x16x32_bf16 v[26:29], v[184:187], v[168:171], v[26:29]
	v_mfma_f32_16x16x32_bf16 v[96:99], v[176:179], v[168:171], v[96:99]
	v_mfma_f32_16x16x32_bf16 v[104:107], v[180:183], v[168:171], v[104:107]
	global_load_dwordx4 v[124:127], v248, s[6:7] offset:768
	v_mfma_f32_16x16x32_bf16 v[46:49], v[172:175], v[116:119], v[46:49]
	s_waitcnt vmcnt(8)
	ds_write_b128 v19, v[136:139] offset:53248
	v_mfma_f32_16x16x32_bf16 v[58:61], v[176:179], v[116:119], v[58:61]
	v_mfma_f32_16x16x32_bf16 v[30:33], v[184:187], v[116:119], v[30:33]
	v_mfma_f32_16x16x32_bf16 v[100:103], v[180:183], v[116:119], v[100:103]
	global_load_dwordx4 v[116:119], v249, s[6:7] offset:768
	s_waitcnt vmcnt(8)
	ds_write_b128 v19, v[74:77] offset:57344
	v_mfma_f32_16x16x32_bf16 v[50:53], v[172:175], v[120:123], v[50:53]
	v_mfma_f32_16x16x32_bf16 v[62:65], v[176:179], v[120:123], v[62:65]
	v_mfma_f32_16x16x32_bf16 v[74:77], v[180:183], v[120:123], v[78:81]
	v_mfma_f32_16x16x32_bf16 v[34:37], v[184:187], v[120:123], v[34:37]
	global_load_dwordx4 v[78:81], v250, s[6:7] offset:768
	v_mfma_f32_16x16x32_bf16 v[54:57], v[172:175], v[148:151], v[54:57]
	s_waitcnt vmcnt(8)
	ds_write_b128 v19, v[108:111] offset:61440
	v_mfma_f32_16x16x32_bf16 v[66:69], v[176:179], v[148:151], v[66:69]
	v_mfma_f32_16x16x32_bf16 v[70:73], v[180:183], v[148:151], v[70:73]
	v_mfma_f32_16x16x32_bf16 v[38:41], v[184:187], v[148:151], v[38:41]
	s_setprio 0
	s_waitcnt lgkmcnt(0)
	s_barrier
; template <int MODE>
; __device__ __forceinline__ void gemm_tile(const Params& P, int tm, int tn, unsigned char* smem) {
;     ...
; #pragma unroll
;         for (int i = 0; i < 4; ++i) { fa[i] = *(const bf16x8*)(sA + arow_off + i * 2048 + ch0); fb[i] = *(const bf16x8*)(sB + brow_off + i * 2048 + ch0); }
;         __builtin_amdgcn_sched_barrier(0);
;         __builtin_amdgcn_s_setprio(2);
;         if (wr_ok) *(uint4*)(nA + soff0) = ra0;
;         if (ld_ok) ra0 = *(const uint4*)(Ab + (aoff + 0u * LDA + koa));
;         ga[0] = *(const bf16x8*)(sA + arow_off + 0 * 2048 + ch1); gb[0] = *(const bf16x8*)(sB + brow_off + 0 * 2048 + ch1);
;         __builtin_amdgcn_sched_barrier(0);
; #pragma unroll
;         for (int j = 0; j < 4; ++j) acc[0][j] = __builtin_amdgcn_mfma_f32_16x16x32_bf16(fb[j], fa[0], acc[0][j], 0, 0, 0);
;         __builtin_amdgcn_sched_barrier(0);
;         if (wr_ok) *(uint4*)(nA + soff0 + 4096) = ra1;
;         if (ld_ok) ra1 = *(const uint4*)(Ab + (aoff + 32u * LDA + koa));
;         ga[1] = *(const bf16x8*)(sA + arow_off + 1 * 2048 + ch1); gb[1] = *(const bf16x8*)(sB + brow_off + 1 * 2048 + ch1);
;         __builtin_amdgcn_sched_barrier(0);
; #pragma unroll
;         for (int j = 0; j < 4; ++j) acc[1][j] = __builtin_amdgcn_mfma_f32_16x16x32_bf16(fb[j], fa[1], acc[1][j], 0, 0, 0);
;         __builtin_amdgcn_sched_barrier(0);
;         if (wr_ok) *(uint4*)(nA + soff0 + 8192) = ra2;
;         if (ld_ok) ra2 = *(const uint4*)(Ab + (aoff + 64u * LDA + koa));
;         ga[2] = *(const bf16x8*)(sA + arow_off + 2 * 2048 + ch1); gb[2] = *(const bf16x8*)(sB + brow_off + 2 * 2048 + ch1);
;         __builtin_amdgcn_sched_barrier(0);
; #pragma unroll
;         for (int j = 0; j < 4; ++j) acc[2][j] = __builtin_amdgcn_mfma_f32_16x16x32_bf16(fb[j], fa[2], acc[2][j], 0, 0, 0);
;         __builtin_amdgcn_sched_barrier(0);
;         if (wr_ok) *(uint4*)(nA + soff0 + 12288) = ra3;
;         if (ld_ok) ra3 = *(const uint4*)(Ab + (aoff + 96u * LDA + koa));
;         ga[3] = *(const bf16x8*)(sA + arow_off + 3 * 2048 + ch1); gb[3] = *(const bf16x8*)(sB + brow_off + 3 * 2048 + ch1);
;         __builtin_amdgcn_sched_barrier(0);
; #pragma unroll
;         for (int j = 0; j < 4; ++j) acc[3][j] = __builtin_amdgcn_mfma_f32_16x16x32_bf16(fb[j], fa[3], acc[3][j], 0, 0, 0);
;         __builtin_amdgcn_sched_barrier(0);
;         if (wr_ok) *(uint4*)(nB + soff0) = rb0;
	ds_read_b128 v[108:111], v22 offset:32768
	ds_read_b128 v[120:123], v22 offset:34816
	ds_read_b128 v[136:139], v23 offset:49152
	ds_read_b128 v[140:143], v23 offset:51200
	ds_read_b128 v[148:151], v22 offset:36864
	ds_read_b128 v[152:155], v22 offset:38912
	ds_read_b128 v[156:159], v23 offset:53248
	ds_read_b128 v[160:163], v23 offset:55296
	s_setprio 2
	global_load_dwordx4 v[168:171], v24, s[36:37] offset:896
	s_waitcnt vmcnt(8)
	ds_write_b128 v19, v[164:167]
	ds_read_b128 v[164:167], v20 offset:32768
	ds_read_b128 v[172:175], v21 offset:49152
	s_waitcnt lgkmcnt(8)
	v_mfma_f32_16x16x32_bf16 v[42:45], v[136:139], v[108:111], v[42:45]
	s_waitcnt lgkmcnt(3)
	v_mfma_f32_16x16x32_bf16 v[26:29], v[160:163], v[108:111], v[26:29]
	v_mfma_f32_16x16x32_bf16 v[96:99], v[140:143], v[108:111], v[96:99]
	v_mfma_f32_16x16x32_bf16 v[104:107], v[156:159], v[108:111], v[104:107]
	global_load_dwordx4 v[108:111], v245, s[36:37] offset:896
	v_mfma_f32_16x16x32_bf16 v[46:49], v[136:139], v[120:123], v[46:49]
	s_waitcnt vmcnt(8)
	ds_write_b128 v19, v[92:95] offset:4096
	v_mfma_f32_16x16x32_bf16 v[58:61], v[140:143], v[120:123], v[58:61]
	ds_read_b128 v[92:95], v20 offset:34816
	v_mfma_f32_16x16x32_bf16 v[30:33], v[160:163], v[120:123], v[30:33]
	ds_read_b128 v[176:179], v21 offset:51200
	v_mfma_f32_16x16x32_bf16 v[100:103], v[156:159], v[120:123], v[100:103]
	global_load_dwordx4 v[120:123], v246, s[36:37] offset:896
	v_mfma_f32_16x16x32_bf16 v[50:53], v[136:139], v[148:151], v[50:53]
	s_waitcnt vmcnt(8)
	ds_write_b128 v19, v[112:115] offset:8192
	v_mfma_f32_16x16x32_bf16 v[62:65], v[140:143], v[148:151], v[62:65]
	ds_read_b128 v[112:115], v20 offset:36864
	v_mfma_f32_16x16x32_bf16 v[74:77], v[156:159], v[148:151], v[74:77]
	ds_read_b128 v[180:183], v21 offset:53248
	v_mfma_f32_16x16x32_bf16 v[34:37], v[160:163], v[148:151], v[34:37]
	global_load_dwordx4 v[148:151], v247, s[36:37] offset:896
	v_mfma_f32_16x16x32_bf16 v[54:57], v[136:139], v[152:155], v[54:57]
	s_waitcnt vmcnt(8)
	ds_write_b128 v19, v[144:147] offset:12288
	v_mfma_f32_16x16x32_bf16 v[66:69], v[140:143], v[152:155], v[66:69]
	ds_read_b128 v[144:147], v20 offset:38912
	v_mfma_f32_16x16x32_bf16 v[70:73], v[156:159], v[152:155], v[70:73]
	ds_read_b128 v[184:187], v21 offset:55296
	v_mfma_f32_16x16x32_bf16 v[38:41], v[160:163], v[152:155], v[38:41]
	global_load_dwordx4 v[136:139], v18, s[6:7] offset:896
	s_waitcnt vmcnt(8)
	ds_write_b128 v19, v[132:135] offset:16384
	s_waitcnt lgkmcnt(10)
	v_mfma_f32_16x16x32_bf16 v[42:45], v[172:175], v[164:167], v[42:45]
	s_waitcnt lgkmcnt(1)
	v_mfma_f32_16x16x32_bf16 v[26:29], v[184:187], v[164:167], v[26:29]
	v_mfma_f32_16x16x32_bf16 v[96:99], v[176:179], v[164:167], v[96:99]
	v_mfma_f32_16x16x32_bf16 v[104:107], v[180:183], v[164:167], v[104:107]
	global_load_dwordx4 v[132:135], v248, s[6:7] offset:896
	v_mfma_f32_16x16x32_bf16 v[46:49], v[172:175], v[92:95], v[46:49]
	s_waitcnt vmcnt(8)
	ds_write_b128 v19, v[124:127] offset:20480
	v_mfma_f32_16x16x32_bf16 v[58:61], v[176:179], v[92:95], v[58:61]
	v_mfma_f32_16x16x32_bf16 v[30:33], v[184:187], v[92:95], v[30:33]
	v_mfma_f32_16x16x32_bf16 v[100:103], v[180:183], v[92:95], v[100:103]
	global_load_dwordx4 v[92:95], v249, s[6:7] offset:896
	v_mfma_f32_16x16x32_bf16 v[50:53], v[172:175], v[112:115], v[50:53]
	s_waitcnt vmcnt(8)
	ds_write_b128 v19, v[116:119] offset:24576
	v_mfma_f32_16x16x32_bf16 v[62:65], v[176:179], v[112:115], v[62:65]
	v_mfma_f32_16x16x32_bf16 v[74:77], v[180:183], v[112:115], v[74:77]
	v_mfma_f32_16x16x32_bf16 v[34:37], v[184:187], v[112:115], v[34:37]
	global_load_dwordx4 v[112:115], v250, s[6:7] offset:896
	v_mfma_f32_16x16x32_bf16 v[54:57], v[172:175], v[144:147], v[54:57]
	s_waitcnt vmcnt(8)
	ds_write_b128 v19, v[78:81] offset:28672
	v_mfma_f32_16x16x32_bf16 v[66:69], v[176:179], v[144:147], v[66:69]
	v_mfma_f32_16x16x32_bf16 v[70:73], v[180:183], v[144:147], v[70:73]
	v_mfma_f32_16x16x32_bf16 v[38:41], v[184:187], v[144:147], v[38:41]
	s_setprio 0
	s_waitcnt lgkmcnt(0)
	s_barrier
	ds_read_b128 v[78:81], v22
	ds_read_b128 v[116:119], v22 offset:2048
	ds_read_b128 v[124:127], v23 offset:16384
	ds_read_b128 v[140:143], v23 offset:18432
	ds_read_b128 v[144:147], v22 offset:4096
	ds_read_b128 v[152:155], v22 offset:6144
	ds_read_b128 v[156:159], v23 offset:20480
	ds_read_b128 v[160:163], v23 offset:22528
	s_setprio 2
	global_load_dwordx4 v[164:167], v24, s[36:37] offset:1024
	s_waitcnt vmcnt(8)
	ds_write_b128 v19, v[168:171] offset:32768
	ds_read_b128 v[168:171], v20
	ds_read_b128 v[172:175], v21 offset:16384
	s_waitcnt lgkmcnt(8)
	v_mfma_f32_16x16x32_bf16 v[42:45], v[124:127], v[78:81], v[42:45]
	s_waitcnt lgkmcnt(3)
	v_mfma_f32_16x16x32_bf16 v[26:29], v[160:163], v[78:81], v[26:29]
	v_mfma_f32_16x16x32_bf16 v[96:99], v[140:143], v[78:81], v[96:99]
	v_mfma_f32_16x16x32_bf16 v[104:107], v[156:159], v[78:81], v[104:107]
	global_load_dwordx4 v[78:81], v245, s[36:37] offset:1024
	v_mfma_f32_16x16x32_bf16 v[46:49], v[124:127], v[116:119], v[46:49]
	s_waitcnt vmcnt(8)
	ds_write_b128 v19, v[108:111] offset:36864
	v_mfma_f32_16x16x32_bf16 v[58:61], v[140:143], v[116:119], v[58:61]
	ds_read_b128 v[108:111], v20 offset:2048
	v_mfma_f32_16x16x32_bf16 v[30:33], v[160:163], v[116:119], v[30:33]
	ds_read_b128 v[176:179], v21 offset:18432
	v_mfma_f32_16x16x32_bf16 v[100:103], v[156:159], v[116:119], v[100:103]
	global_load_dwordx4 v[116:119], v246, s[36:37] offset:1024
	v_mfma_f32_16x16x32_bf16 v[50:53], v[124:127], v[144:147], v[50:53]
	s_waitcnt vmcnt(8)
; template <int MODE>
; __device__ __forceinline__ void gemm_tile(const Params& P, int tm, int tn, unsigned char* smem) {
;     ...
; #pragma unroll
;         for (int i = 0; i < 4; ++i) { fa[i] = *(const bf16x8*)(sA + arow_off + i * 2048 + ch0); fb[i] = *(const bf16x8*)(sB + brow_off + i * 2048 + ch0); }
;         __builtin_amdgcn_sched_barrier(0);
;         __builtin_amdgcn_s_setprio(2);
;         if (wr_ok) *(uint4*)(nA + soff0) = ra0;
;         if (ld_ok) ra0 = *(const uint4*)(Ab + (aoff + 0u * LDA + koa));
;         ga[0] = *(const bf16x8*)(sA + arow_off + 0 * 2048 + ch1); gb[0] = *(const bf16x8*)(sB + brow_off + 0 * 2048 + ch1);
;         __builtin_amdgcn_sched_barrier(0);
; #pragma unroll
;         for (int j = 0; j < 4; ++j) acc[0][j] = __builtin_amdgcn_mfma_f32_16x16x32_bf16(fb[j], fa[0], acc[0][j], 0, 0, 0);
;         __builtin_amdgcn_sched_barrier(0);
;         if (wr_ok) *(uint4*)(nA + soff0 + 4096) = ra1;
;         if (ld_ok) ra1 = *(const uint4*)(Ab + (aoff + 32u * LDA + koa));
;         ga[1] = *(const bf16x8*)(sA + arow_off + 1 * 2048 + ch1); gb[1] = *(const bf16x8*)(sB + brow_off + 1 * 2048 + ch1);
;         __builtin_amdgcn_sched_barrier(0);
; #pragma unroll
;         for (int j = 0; j < 4; ++j) acc[1][j] = __builtin_amdgcn_mfma_f32_16x16x32_bf16(fb[j], fa[1], acc[1][j], 0, 0, 0);
;         __builtin_amdgcn_sched_barrier(0);
;         if (wr_ok) *(uint4*)(nA + soff0 + 8192) = ra2;
;         if (ld_ok) ra2 = *(const uint4*)(Ab + (aoff + 64u * LDA + koa));
;         ga[2] = *(const bf16x8*)(sA + arow_off + 2 * 2048 + ch1); gb[2] = *(const bf16x8*)(sB + brow_off + 2 * 2048 + ch1);
;         __builtin_amdgcn_sched_barrier(0);
; #pragma unroll
;         for (int j = 0; j < 4; ++j) acc[2][j] = __builtin_amdgcn_mfma_f32_16x16x32_bf16(fb[j], fa[2], acc[2][j], 0, 0, 0);
;         __builtin_amdgcn_sched_barrier(0);
;         if (wr_ok) *(uint4*)(nA + soff0 + 12288) = ra3;
;         if (ld_ok) ra3 = *(const uint4*)(Ab + (aoff + 96u * LDA + koa));
;         ga[3] = *(const bf16x8*)(sA + arow_off + 3 * 2048 + ch1); gb[3] = *(const bf16x8*)(sB + brow_off + 3 * 2048 + ch1);
;         __builtin_amdgcn_sched_barrier(0);
; #pragma unroll
;         for (int j = 0; j < 4; ++j) acc[3][j] = __builtin_amdgcn_mfma_f32_16x16x32_bf16(fb[j], fa[3], acc[3][j], 0, 0, 0);
;         __builtin_amdgcn_sched_barrier(0);
;         if (wr_ok) *(uint4*)(nB + soff0) = rb0;
	ds_write_b128 v19, v[120:123] offset:40960
	v_mfma_f32_16x16x32_bf16 v[62:65], v[140:143], v[144:147], v[62:65]
	ds_read_b128 v[120:123], v20 offset:4096
	v_mfma_f32_16x16x32_bf16 v[74:77], v[156:159], v[144:147], v[74:77]
	ds_read_b128 v[180:183], v21 offset:20480
	v_mfma_f32_16x16x32_bf16 v[34:37], v[160:163], v[144:147], v[34:37]
	global_load_dwordx4 v[144:147], v247, s[36:37] offset:1024
	v_mfma_f32_16x16x32_bf16 v[54:57], v[124:127], v[152:155], v[54:57]
	s_waitcnt vmcnt(8)
	ds_write_b128 v19, v[148:151] offset:45056
	v_mfma_f32_16x16x32_bf16 v[66:69], v[140:143], v[152:155], v[66:69]
	ds_read_b128 v[148:151], v20 offset:6144
	v_mfma_f32_16x16x32_bf16 v[70:73], v[156:159], v[152:155], v[70:73]
	ds_read_b128 v[184:187], v21 offset:22528
	v_mfma_f32_16x16x32_bf16 v[38:41], v[160:163], v[152:155], v[38:41]
	global_load_dwordx4 v[124:127], v18, s[6:7] offset:1024
	s_waitcnt vmcnt(8)
	ds_write_b128 v19, v[136:139] offset:49152
	s_waitcnt lgkmcnt(10)
	v_mfma_f32_16x16x32_bf16 v[42:45], v[172:175], v[168:171], v[42:45]
	s_waitcnt lgkmcnt(1)
	v_mfma_f32_16x16x32_bf16 v[26:29], v[184:187], v[168:171], v[26:29]
	v_mfma_f32_16x16x32_bf16 v[96:99], v[176:179], v[168:171], v[96:99]
	v_mfma_f32_16x16x32_bf16 v[104:107], v[180:183], v[168:171], v[104:107]
	global_load_dwordx4 v[136:139], v248, s[6:7] offset:1024
	v_mfma_f32_16x16x32_bf16 v[46:49], v[172:175], v[108:111], v[46:49]
	s_waitcnt vmcnt(8)
	ds_write_b128 v19, v[132:135] offset:53248
	v_mfma_f32_16x16x32_bf16 v[58:61], v[176:179], v[108:111], v[58:61]
	v_mfma_f32_16x16x32_bf16 v[30:33], v[184:187], v[108:111], v[30:33]
	v_mfma_f32_16x16x32_bf16 v[100:103], v[180:183], v[108:111], v[100:103]
	global_load_dwordx4 v[108:111], v249, s[6:7] offset:1024
	v_mfma_f32_16x16x32_bf16 v[50:53], v[172:175], v[120:123], v[50:53]
	s_waitcnt vmcnt(8)
	ds_write_b128 v19, v[92:95] offset:57344
	v_mfma_f32_16x16x32_bf16 v[62:65], v[176:179], v[120:123], v[62:65]
	v_mfma_f32_16x16x32_bf16 v[74:77], v[180:183], v[120:123], v[74:77]
	v_mfma_f32_16x16x32_bf16 v[34:37], v[184:187], v[120:123], v[34:37]
	global_load_dwordx4 v[92:95], v250, s[6:7] offset:1024
	v_mfma_f32_16x16x32_bf16 v[54:57], v[172:175], v[148:151], v[54:57]
	s_waitcnt vmcnt(8)
	ds_write_b128 v19, v[112:115] offset:61440
	v_mfma_f32_16x16x32_bf16 v[66:69], v[176:179], v[148:151], v[66:69]
	v_mfma_f32_16x16x32_bf16 v[70:73], v[180:183], v[148:151], v[70:73]
	v_mfma_f32_16x16x32_bf16 v[38:41], v[184:187], v[148:151], v[38:41]
	s_setprio 0
	s_waitcnt lgkmcnt(0)
	s_barrier
	ds_read_b128 v[112:115], v22 offset:32768
	ds_read_b128 v[120:123], v22 offset:34816
	ds_read_b128 v[132:135], v23 offset:49152
	ds_read_b128 v[140:143], v23 offset:51200
	ds_read_b128 v[148:151], v22 offset:36864
	ds_read_b128 v[152:155], v22 offset:38912
	ds_read_b128 v[156:159], v23 offset:53248
	ds_read_b128 v[160:163], v23 offset:55296
	s_setprio 2
	global_load_dwordx4 v[168:171], v24, s[36:37] offset:1152
	s_waitcnt vmcnt(8)
	ds_write_b128 v19, v[164:167]
	ds_read_b128 v[164:167], v20 offset:32768
	ds_read_b128 v[172:175], v21 offset:49152
	s_waitcnt lgkmcnt(8)
	v_mfma_f32_16x16x32_bf16 v[42:45], v[132:135], v[112:115], v[42:45]
	s_waitcnt lgkmcnt(3)
	v_mfma_f32_16x16x32_bf16 v[26:29], v[160:163], v[112:115], v[26:29]
	v_mfma_f32_16x16x32_bf16 v[96:99], v[140:143], v[112:115], v[96:99]
	v_mfma_f32_16x16x32_bf16 v[104:107], v[156:159], v[112:115], v[104:107]
	global_load_dwordx4 v[112:115], v245, s[36:37] offset:1152
	v_mfma_f32_16x16x32_bf16 v[46:49], v[132:135], v[120:123], v[46:49]
	s_waitcnt vmcnt(8)
	ds_write_b128 v19, v[78:81] offset:4096
	v_mfma_f32_16x16x32_bf16 v[58:61], v[140:143], v[120:123], v[58:61]
	ds_read_b128 v[78:81], v20 offset:34816
	v_mfma_f32_16x16x32_bf16 v[30:33], v[160:163], v[120:123], v[30:33]
	ds_read_b128 v[176:179], v21 offset:51200
	v_mfma_f32_16x16x32_bf16 v[100:103], v[156:159], v[120:123], v[100:103]
	global_load_dwordx4 v[120:123], v246, s[36:37] offset:1152
	v_mfma_f32_16x16x32_bf16 v[50:53], v[132:135], v[148:151], v[50:53]
	s_waitcnt vmcnt(8)
	ds_write_b128 v19, v[116:119] offset:8192
	v_mfma_f32_16x16x32_bf16 v[62:65], v[140:143], v[148:151], v[62:65]
	ds_read_b128 v[116:119], v20 offset:36864
	v_mfma_f32_16x16x32_bf16 v[74:77], v[156:159], v[148:151], v[74:77]
	ds_read_b128 v[180:183], v21 offset:53248
	v_mfma_f32_16x16x32_bf16 v[34:37], v[160:163], v[148:151], v[34:37]
	global_load_dwordx4 v[148:151], v247, s[36:37] offset:1152
	v_mfma_f32_16x16x32_bf16 v[54:57], v[132:135], v[152:155], v[54:57]
	s_waitcnt vmcnt(8)
	ds_write_b128 v19, v[144:147] offset:12288
	v_mfma_f32_16x16x32_bf16 v[66:69], v[140:143], v[152:155], v[66:69]
	ds_read_b128 v[144:147], v20 offset:38912
	v_mfma_f32_16x16x32_bf16 v[70:73], v[156:159], v[152:155], v[70:73]
	ds_read_b128 v[184:187], v21 offset:55296
	v_mfma_f32_16x16x32_bf16 v[38:41], v[160:163], v[152:155], v[38:41]
	global_load_dwordx4 v[132:135], v18, s[6:7] offset:1152
	s_waitcnt vmcnt(8)
	ds_write_b128 v19, v[124:127] offset:16384
	s_waitcnt lgkmcnt(10)
	v_mfma_f32_16x16x32_bf16 v[42:45], v[172:175], v[164:167], v[42:45]
	s_waitcnt lgkmcnt(1)
	v_mfma_f32_16x16x32_bf16 v[26:29], v[184:187], v[164:167], v[26:29]
	v_mfma_f32_16x16x32_bf16 v[96:99], v[176:179], v[164:167], v[96:99]
	v_mfma_f32_16x16x32_bf16 v[104:107], v[180:183], v[164:167], v[104:107]
	global_load_dwordx4 v[124:127], v248, s[6:7] offset:1152
	v_mfma_f32_16x16x32_bf16 v[46:49], v[172:175], v[78:81], v[46:49]
	s_waitcnt vmcnt(8)
	ds_write_b128 v19, v[136:139] offset:20480
	v_mfma_f32_16x16x32_bf16 v[58:61], v[176:179], v[78:81], v[58:61]
	v_mfma_f32_16x16x32_bf16 v[30:33], v[184:187], v[78:81], v[30:33]
	v_mfma_f32_16x16x32_bf16 v[100:103], v[180:183], v[78:81], v[100:103]
	global_load_dwordx4 v[78:81], v249, s[6:7] offset:1152
	v_mfma_f32_16x16x32_bf16 v[50:53], v[172:175], v[116:119], v[50:53]
	s_waitcnt vmcnt(8)
	ds_write_b128 v19, v[108:111] offset:24576
	v_mfma_f32_16x16x32_bf16 v[62:65], v[176:179], v[116:119], v[62:65]
	v_mfma_f32_16x16x32_bf16 v[74:77], v[180:183], v[116:119], v[74:77]
	v_mfma_f32_16x16x32_bf16 v[34:37], v[184:187], v[116:119], v[34:37]
	global_load_dwordx4 v[108:111], v250, s[6:7] offset:1152
	v_mfma_f32_16x16x32_bf16 v[54:57], v[172:175], v[144:147], v[54:57]
	s_waitcnt vmcnt(8)
	ds_write_b128 v19, v[92:95] offset:28672
	v_mfma_f32_16x16x32_bf16 v[66:69], v[176:179], v[144:147], v[66:69]
	v_mfma_f32_16x16x32_bf16 v[70:73], v[180:183], v[144:147], v[70:73]
	v_mfma_f32_16x16x32_bf16 v[38:41], v[184:187], v[144:147], v[38:41]
	s_setprio 0
	s_waitcnt lgkmcnt(0)
	s_barrier
; template <int MODE>
; __device__ __forceinline__ void gemm_tile(const Params& P, int tm, int tn, unsigned char* smem) {
;     ...
; #pragma unroll
;         for (int i = 0; i < 4; ++i) { fa[i] = *(const bf16x8*)(sA + arow_off + i * 2048 + ch0); fb[i] = *(const bf16x8*)(sB + brow_off + i * 2048 + ch0); }
;         __builtin_amdgcn_sched_barrier(0);
;         __builtin_amdgcn_s_setprio(2);
;         if (wr_ok) *(uint4*)(nA + soff0) = ra0;
;         if (ld_ok) ra0 = *(const uint4*)(Ab + (aoff + 0u * LDA + koa));
;         ga[0] = *(const bf16x8*)(sA + arow_off + 0 * 2048 + ch1); gb[0] = *(const bf16x8*)(sB + brow_off + 0 * 2048 + ch1);
;         __builtin_amdgcn_sched_barrier(0);
; #pragma unroll
;         for (int j = 0; j < 4; ++j) acc[0][j] = __builtin_amdgcn_mfma_f32_16x16x32_bf16(fb[j], fa[0], acc[0][j], 0, 0, 0);
;         __builtin_amdgcn_sched_barrier(0);
;         if (wr_ok) *(uint4*)(nA + soff0 + 4096) = ra1;
;         if (ld_ok) ra1 = *(const uint4*)(Ab + (aoff + 32u * LDA + koa));
;         ga[1] = *(const bf16x8*)(sA + arow_off + 1 * 2048 + ch1); gb[1] = *(const bf16x8*)(sB + brow_off + 1 * 2048 + ch1);
;         __builtin_amdgcn_sched_barrier(0);
; #pragma unroll
;         for (int j = 0; j < 4; ++j) acc[1][j] = __builtin_amdgcn_mfma_f32_16x16x32_bf16(fb[j], fa[1], acc[1][j], 0, 0, 0);
;         __builtin_amdgcn_sched_barrier(0);
;         if (wr_ok) *(uint4*)(nA + soff0 + 8192) = ra2;
;         if (ld_ok) ra2 = *(const uint4*)(Ab + (aoff + 64u * LDA + koa));
;         ga[2] = *(const bf16x8*)(sA + arow_off + 2 * 2048 + ch1); gb[2] = *(const bf16x8*)(sB + brow_off + 2 * 2048 + ch1);
;         __builtin_amdgcn_sched_barrier(0);
; #pragma unroll
;         for (int j = 0; j < 4; ++j) acc[2][j] = __builtin_amdgcn_mfma_f32_16x16x32_bf16(fb[j], fa[2], acc[2][j], 0, 0, 0);
;         __builtin_amdgcn_sched_barrier(0);
;         if (wr_ok) *(uint4*)(nA + soff0 + 12288) = ra3;
;         if (ld_ok) ra3 = *(const uint4*)(Ab + (aoff + 96u * LDA + koa));
;         ga[3] = *(const bf16x8*)(sA + arow_off + 3 * 2048 + ch1); gb[3] = *(const bf16x8*)(sB + brow_off + 3 * 2048 + ch1);
;         __builtin_amdgcn_sched_barrier(0);
; #pragma unroll
;         for (int j = 0; j < 4; ++j) acc[3][j] = __builtin_amdgcn_mfma_f32_16x16x32_bf16(fb[j], fa[3], acc[3][j], 0, 0, 0);
;         __builtin_amdgcn_sched_barrier(0);
;         if (wr_ok) *(uint4*)(nB + soff0) = rb0;
	ds_read_b128 v[92:95], v22
	ds_read_b128 v[116:119], v22 offset:2048
	ds_read_b128 v[136:139], v23 offset:16384
	ds_read_b128 v[140:143], v23 offset:18432
	ds_read_b128 v[144:147], v22 offset:4096
	ds_read_b128 v[152:155], v22 offset:6144
	ds_read_b128 v[156:159], v23 offset:20480
	ds_read_b128 v[160:163], v23 offset:22528
	s_setprio 2
	global_load_dwordx4 v[164:167], v24, s[36:37] offset:1280
	s_waitcnt vmcnt(8)
	ds_write_b128 v19, v[168:171] offset:32768
	ds_read_b128 v[168:171], v20
	ds_read_b128 v[172:175], v21 offset:16384
	s_waitcnt lgkmcnt(8)
	v_mfma_f32_16x16x32_bf16 v[42:45], v[136:139], v[92:95], v[42:45]
	s_waitcnt lgkmcnt(3)
	v_mfma_f32_16x16x32_bf16 v[26:29], v[160:163], v[92:95], v[26:29]
	v_mfma_f32_16x16x32_bf16 v[96:99], v[140:143], v[92:95], v[96:99]
	v_mfma_f32_16x16x32_bf16 v[104:107], v[156:159], v[92:95], v[104:107]
	global_load_dwordx4 v[92:95], v245, s[36:37] offset:1280
	v_mfma_f32_16x16x32_bf16 v[46:49], v[136:139], v[116:119], v[46:49]
	s_waitcnt vmcnt(8)
	ds_write_b128 v19, v[112:115] offset:36864
	v_mfma_f32_16x16x32_bf16 v[58:61], v[140:143], v[116:119], v[58:61]
	ds_read_b128 v[112:115], v20 offset:2048
	v_mfma_f32_16x16x32_bf16 v[30:33], v[160:163], v[116:119], v[30:33]
	ds_read_b128 v[176:179], v21 offset:18432
	v_mfma_f32_16x16x32_bf16 v[100:103], v[156:159], v[116:119], v[100:103]
	global_load_dwordx4 v[116:119], v246, s[36:37] offset:1280
	v_mfma_f32_16x16x32_bf16 v[50:53], v[136:139], v[144:147], v[50:53]
	s_waitcnt vmcnt(8)
	ds_write_b128 v19, v[120:123] offset:40960
	v_mfma_f32_16x16x32_bf16 v[62:65], v[140:143], v[144:147], v[62:65]
	ds_read_b128 v[120:123], v20 offset:4096
	v_mfma_f32_16x16x32_bf16 v[74:77], v[156:159], v[144:147], v[74:77]
	ds_read_b128 v[180:183], v21 offset:20480
	v_mfma_f32_16x16x32_bf16 v[34:37], v[160:163], v[144:147], v[34:37]
	global_load_dwordx4 v[144:147], v247, s[36:37] offset:1280
	v_mfma_f32_16x16x32_bf16 v[54:57], v[136:139], v[152:155], v[54:57]
	s_waitcnt vmcnt(8)
	ds_write_b128 v19, v[148:151] offset:45056
	v_mfma_f32_16x16x32_bf16 v[66:69], v[140:143], v[152:155], v[66:69]
	ds_read_b128 v[148:151], v20 offset:6144
	v_mfma_f32_16x16x32_bf16 v[70:73], v[156:159], v[152:155], v[70:73]
	ds_read_b128 v[184:187], v21 offset:22528
	v_mfma_f32_16x16x32_bf16 v[38:41], v[160:163], v[152:155], v[38:41]
	global_load_dwordx4 v[136:139], v18, s[6:7] offset:1280
	s_waitcnt vmcnt(8)
	ds_write_b128 v19, v[132:135] offset:49152
	s_waitcnt lgkmcnt(10)
	v_mfma_f32_16x16x32_bf16 v[42:45], v[172:175], v[168:171], v[42:45]
	s_waitcnt lgkmcnt(1)
	v_mfma_f32_16x16x32_bf16 v[26:29], v[184:187], v[168:171], v[26:29]
	v_mfma_f32_16x16x32_bf16 v[96:99], v[176:179], v[168:171], v[96:99]
	v_mfma_f32_16x16x32_bf16 v[104:107], v[180:183], v[168:171], v[104:107]
	global_load_dwordx4 v[132:135], v248, s[6:7] offset:1280
	v_mfma_f32_16x16x32_bf16 v[46:49], v[172:175], v[112:115], v[46:49]
	s_waitcnt vmcnt(8)
	ds_write_b128 v19, v[124:127] offset:53248
	v_mfma_f32_16x16x32_bf16 v[58:61], v[176:179], v[112:115], v[58:61]
	v_mfma_f32_16x16x32_bf16 v[30:33], v[184:187], v[112:115], v[30:33]
	v_mfma_f32_16x16x32_bf16 v[100:103], v[180:183], v[112:115], v[100:103]
	global_load_dwordx4 v[112:115], v249, s[6:7] offset:1280
	v_mfma_f32_16x16x32_bf16 v[50:53], v[172:175], v[120:123], v[50:53]
	s_waitcnt vmcnt(8)
	ds_write_b128 v19, v[78:81] offset:57344
	v_mfma_f32_16x16x32_bf16 v[62:65], v[176:179], v[120:123], v[62:65]
	v_mfma_f32_16x16x32_bf16 v[74:77], v[180:183], v[120:123], v[74:77]
	v_mfma_f32_16x16x32_bf16 v[34:37], v[184:187], v[120:123], v[34:37]
	global_load_dwordx4 v[78:81], v250, s[6:7] offset:1280
	v_mfma_f32_16x16x32_bf16 v[54:57], v[172:175], v[148:151], v[54:57]
	s_waitcnt vmcnt(8)
	ds_write_b128 v19, v[108:111] offset:61440
	v_mfma_f32_16x16x32_bf16 v[66:69], v[176:179], v[148:151], v[66:69]
	v_mfma_f32_16x16x32_bf16 v[70:73], v[180:183], v[148:151], v[70:73]
	v_mfma_f32_16x16x32_bf16 v[38:41], v[184:187], v[148:151], v[38:41]
	s_setprio 0
	s_waitcnt lgkmcnt(0)
	s_barrier
	ds_read_b128 v[108:111], v22 offset:32768
	ds_read_b128 v[120:123], v22 offset:34816
	ds_read_b128 v[124:127], v23 offset:49152
	ds_read_b128 v[140:143], v23 offset:51200
	ds_read_b128 v[148:151], v22 offset:36864
	ds_read_b128 v[152:155], v22 offset:38912
	ds_read_b128 v[156:159], v23 offset:53248
	ds_read_b128 v[160:163], v23 offset:55296
	s_setprio 2
	global_load_dwordx4 v[168:171], v24, s[36:37] offset:1408
	s_waitcnt vmcnt(8)
	ds_write_b128 v19, v[164:167]
	ds_read_b128 v[164:167], v20 offset:32768
	ds_read_b128 v[172:175], v21 offset:49152
	s_waitcnt lgkmcnt(8)
	v_mfma_f32_16x16x32_bf16 v[42:45], v[124:127], v[108:111], v[42:45]
	s_waitcnt lgkmcnt(3)
	v_mfma_f32_16x16x32_bf16 v[26:29], v[160:163], v[108:111], v[26:29]
	v_mfma_f32_16x16x32_bf16 v[96:99], v[140:143], v[108:111], v[96:99]
	v_mfma_f32_16x16x32_bf16 v[104:107], v[156:159], v[108:111], v[104:107]
	global_load_dwordx4 v[108:111], v245, s[36:37] offset:1408
	v_mfma_f32_16x16x32_bf16 v[46:49], v[124:127], v[120:123], v[46:49]
	s_waitcnt vmcnt(8)
	ds_write_b128 v19, v[92:95] offset:4096
	v_mfma_f32_16x16x32_bf16 v[58:61], v[140:143], v[120:123], v[58:61]
	ds_read_b128 v[92:95], v20 offset:34816
	v_mfma_f32_16x16x32_bf16 v[30:33], v[160:163], v[120:123], v[30:33]
	ds_read_b128 v[176:179], v21 offset:51200
	v_mfma_f32_16x16x32_bf16 v[100:103], v[156:159], v[120:123], v[100:103]
	global_load_dwordx4 v[120:123], v246, s[36:37] offset:1408
	v_mfma_f32_16x16x32_bf16 v[50:53], v[124:127], v[148:151], v[50:53]
	s_waitcnt vmcnt(8)
; template <int MODE>
; __device__ __forceinline__ void gemm_tile(const Params& P, int tm, int tn, unsigned char* smem) {
;     ...
; #pragma unroll
;         for (int i = 0; i < 4; ++i) { fa[i] = *(const bf16x8*)(sA + arow_off + i * 2048 + ch0); fb[i] = *(const bf16x8*)(sB + brow_off + i * 2048 + ch0); }
;         __builtin_amdgcn_sched_barrier(0);
;         __builtin_amdgcn_s_setprio(2);
;         if (wr_ok) *(uint4*)(nA + soff0) = ra0;
;         if (ld_ok) ra0 = *(const uint4*)(Ab + (aoff + 0u * LDA + koa));
;         ga[0] = *(const bf16x8*)(sA + arow_off + 0 * 2048 + ch1); gb[0] = *(const bf16x8*)(sB + brow_off + 0 * 2048 + ch1);
;         __builtin_amdgcn_sched_barrier(0);
; #pragma unroll
;         for (int j = 0; j < 4; ++j) acc[0][j] = __builtin_amdgcn_mfma_f32_16x16x32_bf16(fb[j], fa[0], acc[0][j], 0, 0, 0);
;         __builtin_amdgcn_sched_barrier(0);
;         if (wr_ok) *(uint4*)(nA + soff0 + 4096) = ra1;
;         if (ld_ok) ra1 = *(const uint4*)(Ab + (aoff + 32u * LDA + koa));
;         ga[1] = *(const bf16x8*)(sA + arow_off + 1 * 2048 + ch1); gb[1] = *(const bf16x8*)(sB + brow_off + 1 * 2048 + ch1);
;         __builtin_amdgcn_sched_barrier(0);
; #pragma unroll
;         for (int j = 0; j < 4; ++j) acc[1][j] = __builtin_amdgcn_mfma_f32_16x16x32_bf16(fb[j], fa[1], acc[1][j], 0, 0, 0);
;         __builtin_amdgcn_sched_barrier(0);
;         if (wr_ok) *(uint4*)(nA + soff0 + 8192) = ra2;
;         if (ld_ok) ra2 = *(const uint4*)(Ab + (aoff + 64u * LDA + koa));
;         ga[2] = *(const bf16x8*)(sA + arow_off + 2 * 2048 + ch1); gb[2] = *(const bf16x8*)(sB + brow_off + 2 * 2048 + ch1);
;         __builtin_amdgcn_sched_barrier(0);
; #pragma unroll
;         for (int j = 0; j < 4; ++j) acc[2][j] = __builtin_amdgcn_mfma_f32_16x16x32_bf16(fb[j], fa[2], acc[2][j], 0, 0, 0);
;         __builtin_amdgcn_sched_barrier(0);
;         if (wr_ok) *(uint4*)(nA + soff0 + 12288) = ra3;
;         if (ld_ok) ra3 = *(const uint4*)(Ab + (aoff + 96u * LDA + koa));
;         ga[3] = *(const bf16x8*)(sA + arow_off + 3 * 2048 + ch1); gb[3] = *(const bf16x8*)(sB + brow_off + 3 * 2048 + ch1);
;         __builtin_amdgcn_sched_barrier(0);
; #pragma unroll
;         for (int j = 0; j < 4; ++j) acc[3][j] = __builtin_amdgcn_mfma_f32_16x16x32_bf16(fb[j], fa[3], acc[3][j], 0, 0, 0);
;         __builtin_amdgcn_sched_barrier(0);
;         if (wr_ok) *(uint4*)(nB + soff0) = rb0;
	ds_write_b128 v19, v[116:119] offset:8192
	v_mfma_f32_16x16x32_bf16 v[62:65], v[140:143], v[148:151], v[62:65]
	ds_read_b128 v[116:119], v20 offset:36864
	v_mfma_f32_16x16x32_bf16 v[74:77], v[156:159], v[148:151], v[74:77]
	ds_read_b128 v[180:183], v21 offset:53248
	v_mfma_f32_16x16x32_bf16 v[34:37], v[160:163], v[148:151], v[34:37]
	global_load_dwordx4 v[148:151], v247, s[36:37] offset:1408
	v_mfma_f32_16x16x32_bf16 v[54:57], v[124:127], v[152:155], v[54:57]
	s_waitcnt vmcnt(8)
	ds_write_b128 v19, v[144:147] offset:12288
	v_mfma_f32_16x16x32_bf16 v[66:69], v[140:143], v[152:155], v[66:69]
	ds_read_b128 v[144:147], v20 offset:38912
	v_mfma_f32_16x16x32_bf16 v[70:73], v[156:159], v[152:155], v[70:73]
	ds_read_b128 v[184:187], v21 offset:55296
	v_mfma_f32_16x16x32_bf16 v[38:41], v[160:163], v[152:155], v[38:41]
	global_load_dwordx4 v[124:127], v18, s[6:7] offset:1408
	s_waitcnt vmcnt(8)
	ds_write_b128 v19, v[136:139] offset:16384
	s_waitcnt lgkmcnt(10)
	v_mfma_f32_16x16x32_bf16 v[42:45], v[172:175], v[164:167], v[42:45]
	s_waitcnt lgkmcnt(1)
	v_mfma_f32_16x16x32_bf16 v[26:29], v[184:187], v[164:167], v[26:29]
	v_mfma_f32_16x16x32_bf16 v[96:99], v[176:179], v[164:167], v[96:99]
	v_mfma_f32_16x16x32_bf16 v[104:107], v[180:183], v[164:167], v[104:107]
	global_load_dwordx4 v[136:139], v248, s[6:7] offset:1408
	v_mfma_f32_16x16x32_bf16 v[46:49], v[172:175], v[92:95], v[46:49]
	s_waitcnt vmcnt(8)
	ds_write_b128 v19, v[132:135] offset:20480
	v_mfma_f32_16x16x32_bf16 v[58:61], v[176:179], v[92:95], v[58:61]
	v_mfma_f32_16x16x32_bf16 v[30:33], v[184:187], v[92:95], v[30:33]
	v_mfma_f32_16x16x32_bf16 v[100:103], v[180:183], v[92:95], v[100:103]
	global_load_dwordx4 v[92:95], v249, s[6:7] offset:1408
	v_mfma_f32_16x16x32_bf16 v[50:53], v[172:175], v[116:119], v[50:53]
	s_waitcnt vmcnt(8)
	ds_write_b128 v19, v[112:115] offset:24576
	v_mfma_f32_16x16x32_bf16 v[62:65], v[176:179], v[116:119], v[62:65]
	v_mfma_f32_16x16x32_bf16 v[74:77], v[180:183], v[116:119], v[74:77]
	v_mfma_f32_16x16x32_bf16 v[34:37], v[184:187], v[116:119], v[34:37]
	global_load_dwordx4 v[112:115], v250, s[6:7] offset:1408
	v_mfma_f32_16x16x32_bf16 v[54:57], v[172:175], v[144:147], v[54:57]
	s_waitcnt vmcnt(8)
	ds_write_b128 v19, v[78:81] offset:28672
	v_mfma_f32_16x16x32_bf16 v[66:69], v[176:179], v[144:147], v[66:69]
	v_mfma_f32_16x16x32_bf16 v[70:73], v[180:183], v[144:147], v[70:73]
	v_mfma_f32_16x16x32_bf16 v[38:41], v[184:187], v[144:147], v[38:41]
	s_setprio 0
	s_waitcnt lgkmcnt(0)
	s_barrier
	ds_read_b128 v[78:81], v22
	ds_read_b128 v[116:119], v22 offset:2048
	ds_read_b128 v[132:135], v23 offset:16384
	ds_read_b128 v[140:143], v23 offset:18432
	ds_read_b128 v[144:147], v22 offset:4096
	ds_read_b128 v[152:155], v22 offset:6144
	ds_read_b128 v[156:159], v23 offset:20480
	ds_read_b128 v[160:163], v23 offset:22528
	s_setprio 2
	global_load_dwordx4 v[164:167], v24, s[36:37] offset:1536
	s_waitcnt vmcnt(8)
	ds_write_b128 v19, v[168:171] offset:32768
	ds_read_b128 v[168:171], v20
	ds_read_b128 v[172:175], v21 offset:16384
	s_waitcnt lgkmcnt(8)
	v_mfma_f32_16x16x32_bf16 v[42:45], v[132:135], v[78:81], v[42:45]
	s_waitcnt lgkmcnt(3)
	v_mfma_f32_16x16x32_bf16 v[26:29], v[160:163], v[78:81], v[26:29]
	v_mfma_f32_16x16x32_bf16 v[96:99], v[140:143], v[78:81], v[96:99]
	v_mfma_f32_16x16x32_bf16 v[104:107], v[156:159], v[78:81], v[104:107]
	global_load_dwordx4 v[78:81], v245, s[36:37] offset:1536
	v_mfma_f32_16x16x32_bf16 v[46:49], v[132:135], v[116:119], v[46:49]
	s_waitcnt vmcnt(8)
	ds_write_b128 v19, v[108:111] offset:36864
	v_mfma_f32_16x16x32_bf16 v[58:61], v[140:143], v[116:119], v[58:61]
	ds_read_b128 v[108:111], v20 offset:2048
	v_mfma_f32_16x16x32_bf16 v[30:33], v[160:163], v[116:119], v[30:33]
	ds_read_b128 v[176:179], v21 offset:18432
	v_mfma_f32_16x16x32_bf16 v[100:103], v[156:159], v[116:119], v[100:103]
	global_load_dwordx4 v[116:119], v246, s[36:37] offset:1536
	v_mfma_f32_16x16x32_bf16 v[50:53], v[132:135], v[144:147], v[50:53]
	s_waitcnt vmcnt(8)
	ds_write_b128 v19, v[120:123] offset:40960
	v_mfma_f32_16x16x32_bf16 v[62:65], v[140:143], v[144:147], v[62:65]
	ds_read_b128 v[120:123], v20 offset:4096
	v_mfma_f32_16x16x32_bf16 v[74:77], v[156:159], v[144:147], v[74:77]
	ds_read_b128 v[180:183], v21 offset:20480
	v_mfma_f32_16x16x32_bf16 v[34:37], v[160:163], v[144:147], v[34:37]
	global_load_dwordx4 v[144:147], v247, s[36:37] offset:1536
	v_mfma_f32_16x16x32_bf16 v[54:57], v[132:135], v[152:155], v[54:57]
	s_waitcnt vmcnt(8)
	ds_write_b128 v19, v[148:151] offset:45056
	v_mfma_f32_16x16x32_bf16 v[66:69], v[140:143], v[152:155], v[66:69]
	ds_read_b128 v[148:151], v20 offset:6144
	v_mfma_f32_16x16x32_bf16 v[70:73], v[156:159], v[152:155], v[70:73]
	ds_read_b128 v[184:187], v21 offset:22528
	v_mfma_f32_16x16x32_bf16 v[38:41], v[160:163], v[152:155], v[38:41]
	global_load_dwordx4 v[132:135], v18, s[6:7] offset:1536
	s_waitcnt vmcnt(8)
	ds_write_b128 v19, v[124:127] offset:49152
	s_waitcnt lgkmcnt(10)
	v_mfma_f32_16x16x32_bf16 v[42:45], v[172:175], v[168:171], v[42:45]
	s_waitcnt lgkmcnt(1)
	v_mfma_f32_16x16x32_bf16 v[26:29], v[184:187], v[168:171], v[26:29]
	v_mfma_f32_16x16x32_bf16 v[96:99], v[176:179], v[168:171], v[96:99]
	v_mfma_f32_16x16x32_bf16 v[104:107], v[180:183], v[168:171], v[104:107]
	global_load_dwordx4 v[124:127], v248, s[6:7] offset:1536
	v_mfma_f32_16x16x32_bf16 v[46:49], v[172:175], v[108:111], v[46:49]
	s_waitcnt vmcnt(8)
	ds_write_b128 v19, v[136:139] offset:53248
	v_mfma_f32_16x16x32_bf16 v[58:61], v[176:179], v[108:111], v[58:61]
	v_mfma_f32_16x16x32_bf16 v[30:33], v[184:187], v[108:111], v[30:33]
	v_mfma_f32_16x16x32_bf16 v[100:103], v[180:183], v[108:111], v[100:103]
	global_load_dwordx4 v[108:111], v249, s[6:7] offset:1536
	v_mfma_f32_16x16x32_bf16 v[50:53], v[172:175], v[120:123], v[50:53]
	s_waitcnt vmcnt(8)
	ds_write_b128 v19, v[92:95] offset:57344
	v_mfma_f32_16x16x32_bf16 v[62:65], v[176:179], v[120:123], v[62:65]
	v_mfma_f32_16x16x32_bf16 v[74:77], v[180:183], v[120:123], v[74:77]
	v_mfma_f32_16x16x32_bf16 v[34:37], v[184:187], v[120:123], v[34:37]
	global_load_dwordx4 v[92:95], v250, s[6:7] offset:1536
	v_mfma_f32_16x16x32_bf16 v[54:57], v[172:175], v[148:151], v[54:57]
	s_waitcnt vmcnt(8)
	ds_write_b128 v19, v[112:115] offset:61440
	v_mfma_f32_16x16x32_bf16 v[66:69], v[176:179], v[148:151], v[66:69]
	v_mfma_f32_16x16x32_bf16 v[70:73], v[180:183], v[148:151], v[70:73]
	v_mfma_f32_16x16x32_bf16 v[38:41], v[184:187], v[148:151], v[38:41]
	s_setprio 0
	s_waitcnt lgkmcnt(0)
	s_barrier
; template <int MODE>
; __device__ __forceinline__ void gemm_tile(const Params& P, int tm, int tn, unsigned char* smem) {
;     ...
; #pragma unroll
;         for (int i = 0; i < 4; ++i) { fa[i] = *(const bf16x8*)(sA + arow_off + i * 2048 + ch0); fb[i] = *(const bf16x8*)(sB + brow_off + i * 2048 + ch0); }
;         __builtin_amdgcn_sched_barrier(0);
;         __builtin_amdgcn_s_setprio(2);
;         if (wr_ok) *(uint4*)(nA + soff0) = ra0;
;         if (ld_ok) ra0 = *(const uint4*)(Ab + (aoff + 0u * LDA + koa));
;         ga[0] = *(const bf16x8*)(sA + arow_off + 0 * 2048 + ch1); gb[0] = *(const bf16x8*)(sB + brow_off + 0 * 2048 + ch1);
;         __builtin_amdgcn_sched_barrier(0);
; #pragma unroll
;         for (int j = 0; j < 4; ++j) acc[0][j] = __builtin_amdgcn_mfma_f32_16x16x32_bf16(fb[j], fa[0], acc[0][j], 0, 0, 0);
;         __builtin_amdgcn_sched_barrier(0);
;         if (wr_ok) *(uint4*)(nA + soff0 + 4096) = ra1;
;         if (ld_ok) ra1 = *(const uint4*)(Ab + (aoff + 32u * LDA + koa));
;         ga[1] = *(const bf16x8*)(sA + arow_off + 1 * 2048 + ch1); gb[1] = *(const bf16x8*)(sB + brow_off + 1 * 2048 + ch1);
;         __builtin_amdgcn_sched_barrier(0);
; #pragma unroll
;         for (int j = 0; j < 4; ++j) acc[1][j] = __builtin_amdgcn_mfma_f32_16x16x32_bf16(fb[j], fa[1], acc[1][j], 0, 0, 0);
;         __builtin_amdgcn_sched_barrier(0);
;         if (wr_ok) *(uint4*)(nA + soff0 + 8192) = ra2;
;         if (ld_ok) ra2 = *(const uint4*)(Ab + (aoff + 64u * LDA + koa));
;         ga[2] = *(const bf16x8*)(sA + arow_off + 2 * 2048 + ch1); gb[2] = *(const bf16x8*)(sB + brow_off + 2 * 2048 + ch1);
;         __builtin_amdgcn_sched_barrier(0);
; #pragma unroll
;         for (int j = 0; j < 4; ++j) acc[2][j] = __builtin_amdgcn_mfma_f32_16x16x32_bf16(fb[j], fa[2], acc[2][j], 0, 0, 0);
;         __builtin_amdgcn_sched_barrier(0);
;         if (wr_ok) *(uint4*)(nA + soff0 + 12288) = ra3;
;         if (ld_ok) ra3 = *(const uint4*)(Ab + (aoff + 96u * LDA + koa));
;         ga[3] = *(const bf16x8*)(sA + arow_off + 3 * 2048 + ch1); gb[3] = *(const bf16x8*)(sB + brow_off + 3 * 2048 + ch1);
;         __builtin_amdgcn_sched_barrier(0);
; #pragma unroll
;         for (int j = 0; j < 4; ++j) acc[3][j] = __builtin_amdgcn_mfma_f32_16x16x32_bf16(fb[j], fa[3], acc[3][j], 0, 0, 0);
;         __builtin_amdgcn_sched_barrier(0);
;         if (wr_ok) *(uint4*)(nB + soff0) = rb0;
	ds_read_b128 v[112:115], v22 offset:32768
	ds_read_b128 v[120:123], v22 offset:34816
	ds_read_b128 v[136:139], v23 offset:49152
	ds_read_b128 v[140:143], v23 offset:51200
	ds_read_b128 v[148:151], v22 offset:36864
	ds_read_b128 v[152:155], v22 offset:38912
	ds_read_b128 v[156:159], v23 offset:53248
	ds_read_b128 v[160:163], v23 offset:55296
	s_setprio 2
	global_load_dwordx4 v[168:171], v24, s[36:37] offset:1664
	s_waitcnt vmcnt(8)
	ds_write_b128 v19, v[164:167]
	ds_read_b128 v[164:167], v20 offset:32768
	ds_read_b128 v[172:175], v21 offset:49152
	s_waitcnt lgkmcnt(8)
	v_mfma_f32_16x16x32_bf16 v[42:45], v[136:139], v[112:115], v[42:45]
	s_waitcnt lgkmcnt(3)
	v_mfma_f32_16x16x32_bf16 v[26:29], v[160:163], v[112:115], v[26:29]
	v_mfma_f32_16x16x32_bf16 v[96:99], v[140:143], v[112:115], v[96:99]
	v_mfma_f32_16x16x32_bf16 v[104:107], v[156:159], v[112:115], v[104:107]
	global_load_dwordx4 v[112:115], v245, s[36:37] offset:1664
	v_mfma_f32_16x16x32_bf16 v[46:49], v[136:139], v[120:123], v[46:49]
	s_waitcnt vmcnt(8)
	ds_write_b128 v19, v[78:81] offset:4096
	v_mfma_f32_16x16x32_bf16 v[58:61], v[140:143], v[120:123], v[58:61]
	ds_read_b128 v[78:81], v20 offset:34816
	v_mfma_f32_16x16x32_bf16 v[30:33], v[160:163], v[120:123], v[30:33]
	ds_read_b128 v[176:179], v21 offset:51200
	v_mfma_f32_16x16x32_bf16 v[100:103], v[156:159], v[120:123], v[100:103]
	global_load_dwordx4 v[120:123], v246, s[36:37] offset:1664
	v_mfma_f32_16x16x32_bf16 v[50:53], v[136:139], v[148:151], v[50:53]
	s_waitcnt vmcnt(8)
	ds_write_b128 v19, v[116:119] offset:8192
	v_mfma_f32_16x16x32_bf16 v[62:65], v[140:143], v[148:151], v[62:65]
	ds_read_b128 v[116:119], v20 offset:36864
	v_mfma_f32_16x16x32_bf16 v[74:77], v[156:159], v[148:151], v[74:77]
	ds_read_b128 v[180:183], v21 offset:53248
	v_mfma_f32_16x16x32_bf16 v[34:37], v[160:163], v[148:151], v[34:37]
	global_load_dwordx4 v[148:151], v247, s[36:37] offset:1664
	v_mfma_f32_16x16x32_bf16 v[54:57], v[136:139], v[152:155], v[54:57]
	s_waitcnt vmcnt(8)
	ds_write_b128 v19, v[144:147] offset:12288
	v_mfma_f32_16x16x32_bf16 v[66:69], v[140:143], v[152:155], v[66:69]
	ds_read_b128 v[144:147], v20 offset:38912
	v_mfma_f32_16x16x32_bf16 v[70:73], v[156:159], v[152:155], v[70:73]
	ds_read_b128 v[184:187], v21 offset:55296
	v_mfma_f32_16x16x32_bf16 v[38:41], v[160:163], v[152:155], v[38:41]
	global_load_dwordx4 v[136:139], v18, s[6:7] offset:1664
	s_waitcnt vmcnt(8)
	ds_write_b128 v19, v[132:135] offset:16384
	s_waitcnt lgkmcnt(10)
	v_mfma_f32_16x16x32_bf16 v[42:45], v[172:175], v[164:167], v[42:45]
	s_waitcnt lgkmcnt(1)
	v_mfma_f32_16x16x32_bf16 v[26:29], v[184:187], v[164:167], v[26:29]
	v_mfma_f32_16x16x32_bf16 v[96:99], v[176:179], v[164:167], v[96:99]
	v_mfma_f32_16x16x32_bf16 v[104:107], v[180:183], v[164:167], v[104:107]
	global_load_dwordx4 v[132:135], v248, s[6:7] offset:1664
	v_mfma_f32_16x16x32_bf16 v[46:49], v[172:175], v[78:81], v[46:49]
	s_waitcnt vmcnt(8)
	ds_write_b128 v19, v[124:127] offset:20480
	v_mfma_f32_16x16x32_bf16 v[58:61], v[176:179], v[78:81], v[58:61]
	v_mfma_f32_16x16x32_bf16 v[30:33], v[184:187], v[78:81], v[30:33]
	v_mfma_f32_16x16x32_bf16 v[100:103], v[180:183], v[78:81], v[100:103]
	global_load_dwordx4 v[78:81], v249, s[6:7] offset:1664
	v_mfma_f32_16x16x32_bf16 v[50:53], v[172:175], v[116:119], v[50:53]
	s_waitcnt vmcnt(8)
	ds_write_b128 v19, v[108:111] offset:24576
	v_mfma_f32_16x16x32_bf16 v[62:65], v[176:179], v[116:119], v[62:65]
	v_mfma_f32_16x16x32_bf16 v[74:77], v[180:183], v[116:119], v[74:77]
	v_mfma_f32_16x16x32_bf16 v[34:37], v[184:187], v[116:119], v[34:37]
	global_load_dwordx4 v[108:111], v250, s[6:7] offset:1664
	v_mfma_f32_16x16x32_bf16 v[54:57], v[172:175], v[144:147], v[54:57]
	s_waitcnt vmcnt(8)
	ds_write_b128 v19, v[92:95] offset:28672
	v_mfma_f32_16x16x32_bf16 v[66:69], v[176:179], v[144:147], v[66:69]
	v_mfma_f32_16x16x32_bf16 v[70:73], v[180:183], v[144:147], v[70:73]
	v_mfma_f32_16x16x32_bf16 v[38:41], v[184:187], v[144:147], v[38:41]
	s_setprio 0
	s_waitcnt lgkmcnt(0)
	s_barrier
	ds_read_b128 v[92:95], v22
	ds_read_b128 v[116:119], v22 offset:2048
	ds_read_b128 v[124:127], v23 offset:16384
	ds_read_b128 v[140:143], v23 offset:18432
	ds_read_b128 v[144:147], v22 offset:4096
	ds_read_b128 v[152:155], v22 offset:6144
	ds_read_b128 v[156:159], v23 offset:20480
	ds_read_b128 v[160:163], v23 offset:22528
	s_setprio 2
	global_load_dwordx4 v[164:167], v24, s[36:37] offset:1792
	s_waitcnt vmcnt(8)
	ds_write_b128 v19, v[168:171] offset:32768
	ds_read_b128 v[168:171], v20
	ds_read_b128 v[172:175], v21 offset:16384
	s_waitcnt lgkmcnt(8)
	v_mfma_f32_16x16x32_bf16 v[42:45], v[124:127], v[92:95], v[42:45]
	s_waitcnt lgkmcnt(3)
	v_mfma_f32_16x16x32_bf16 v[26:29], v[160:163], v[92:95], v[26:29]
	v_mfma_f32_16x16x32_bf16 v[96:99], v[140:143], v[92:95], v[96:99]
	v_mfma_f32_16x16x32_bf16 v[104:107], v[156:159], v[92:95], v[104:107]
	global_load_dwordx4 v[92:95], v245, s[36:37] offset:1792
	v_mfma_f32_16x16x32_bf16 v[46:49], v[124:127], v[116:119], v[46:49]
	s_waitcnt vmcnt(8)
	ds_write_b128 v19, v[112:115] offset:36864
	v_mfma_f32_16x16x32_bf16 v[58:61], v[140:143], v[116:119], v[58:61]
	ds_read_b128 v[112:115], v20 offset:2048
	v_mfma_f32_16x16x32_bf16 v[30:33], v[160:163], v[116:119], v[30:33]
	ds_read_b128 v[176:179], v21 offset:18432
	v_mfma_f32_16x16x32_bf16 v[100:103], v[156:159], v[116:119], v[100:103]
	global_load_dwordx4 v[116:119], v246, s[36:37] offset:1792
	v_mfma_f32_16x16x32_bf16 v[50:53], v[124:127], v[144:147], v[50:53]
	s_waitcnt vmcnt(8)
; template <int MODE>
; __device__ __forceinline__ void gemm_tile(const Params& P, int tm, int tn, unsigned char* smem) {
;     ...
;     for (int kt = 0; kt < 16; ++kt) {
;         unsigned char* sA = (kt & 1) ? sA1 : sA0; unsigned char* sB = (kt & 1) ? sB1 : sB0;
;         unsigned char* nA = (kt & 1) ? sA0 : sA1; unsigned char* nB = (kt & 1) ? sB0 : sB1;
;         bf16x8 fa[4], fb[4], ga[4], gb[4];
;         const int ch0 = ((g ^ sw) << 4), ch1 = (((4 + g) ^ sw) << 4);
;         const unsigned ko = (unsigned)(kt + 2) * 128u;
;         const unsigned koa = ko + ((MODE == 2 && kt + 2 >= 8) ? (unsigned)(ZC_FQ - 512) * 2u : 0u);
;         const bool wr_ok = kt < 15, ld_ok = kt < 14;
; #pragma unroll
;         for (int i = 0; i < 4; ++i) { fa[i] = *(const bf16x8*)(sA + arow_off + i * 2048 + ch0); fb[i] = *(const bf16x8*)(sB + brow_off + i * 2048 + ch0); }
;         __builtin_amdgcn_sched_barrier(0);
;         __builtin_amdgcn_s_setprio(2);
;         if (wr_ok) *(uint4*)(nA + soff0) = ra0;
;         if (ld_ok) ra0 = *(const uint4*)(Ab + (aoff + 0u * LDA + koa));
;         ga[0] = *(const bf16x8*)(sA + arow_off + 0 * 2048 + ch1); gb[0] = *(const bf16x8*)(sB + brow_off + 0 * 2048 + ch1);
;         __builtin_amdgcn_sched_barrier(0);
; #pragma unroll
;         for (int j = 0; j < 4; ++j) acc[0][j] = __builtin_amdgcn_mfma_f32_16x16x32_bf16(fb[j], fa[0], acc[0][j], 0, 0, 0);
;         __builtin_amdgcn_sched_barrier(0);
;         if (wr_ok) *(uint4*)(nA + soff0 + 4096) = ra1;
;         if (ld_ok) ra1 = *(const uint4*)(Ab + (aoff + 32u * LDA + koa));
;         ga[1] = *(const bf16x8*)(sA + arow_off + 1 * 2048 + ch1); gb[1] = *(const bf16x8*)(sB + brow_off + 1 * 2048 + ch1);
;         __builtin_amdgcn_sched_barrier(0);
; #pragma unroll
;         for (int j = 0; j < 4; ++j) acc[1][j] = __builtin_amdgcn_mfma_f32_16x16x32_bf16(fb[j], fa[1], acc[1][j], 0, 0, 0);
;         __builtin_amdgcn_sched_barrier(0);
;         if (wr_ok) *(uint4*)(nA + soff0 + 8192) = ra2;
;         if (ld_ok) ra2 = *(const uint4*)(Ab + (aoff + 64u * LDA + koa));
;         ga[2] = *(const bf16x8*)(sA + arow_off + 2 * 2048 + ch1); gb[2] = *(const bf16x8*)(sB + brow_off + 2 * 2048 + ch1);
;         __builtin_amdgcn_sched_barrier(0);
; #pragma unroll
;         for (int j = 0; j < 4; ++j) acc[2][j] = __builtin_amdgcn_mfma_f32_16x16x32_bf16(fb[j], fa[2], acc[2][j], 0, 0, 0);
	ds_write_b128 v19, v[120:123] offset:40960
	v_mfma_f32_16x16x32_bf16 v[62:65], v[140:143], v[144:147], v[62:65]
	ds_read_b128 v[120:123], v20 offset:4096
	v_mfma_f32_16x16x32_bf16 v[74:77], v[156:159], v[144:147], v[74:77]
	ds_read_b128 v[180:183], v21 offset:20480
	v_mfma_f32_16x16x32_bf16 v[34:37], v[160:163], v[144:147], v[34:37]
	global_load_dwordx4 v[144:147], v247, s[36:37] offset:1792
	v_mfma_f32_16x16x32_bf16 v[54:57], v[124:127], v[152:155], v[54:57]
	s_waitcnt vmcnt(8)
	ds_write_b128 v19, v[148:151] offset:45056
	v_mfma_f32_16x16x32_bf16 v[66:69], v[140:143], v[152:155], v[66:69]
	ds_read_b128 v[148:151], v20 offset:6144
	v_mfma_f32_16x16x32_bf16 v[70:73], v[156:159], v[152:155], v[70:73]
	ds_read_b128 v[184:187], v21 offset:22528
	v_mfma_f32_16x16x32_bf16 v[38:41], v[160:163], v[152:155], v[38:41]
	global_load_dwordx4 v[124:127], v18, s[6:7] offset:1792
	s_waitcnt vmcnt(8)
	ds_write_b128 v19, v[136:139] offset:49152
	s_waitcnt lgkmcnt(10)
	v_mfma_f32_16x16x32_bf16 v[42:45], v[172:175], v[168:171], v[42:45]
	s_waitcnt lgkmcnt(1)
	v_mfma_f32_16x16x32_bf16 v[26:29], v[184:187], v[168:171], v[26:29]
	v_mfma_f32_16x16x32_bf16 v[96:99], v[176:179], v[168:171], v[96:99]
	v_mfma_f32_16x16x32_bf16 v[104:107], v[180:183], v[168:171], v[104:107]
	global_load_dwordx4 v[136:139], v248, s[6:7] offset:1792
	v_mfma_f32_16x16x32_bf16 v[46:49], v[172:175], v[112:115], v[46:49]
	s_waitcnt vmcnt(8)
	ds_write_b128 v19, v[132:135] offset:53248
	v_mfma_f32_16x16x32_bf16 v[58:61], v[176:179], v[112:115], v[58:61]
	v_mfma_f32_16x16x32_bf16 v[30:33], v[184:187], v[112:115], v[30:33]
	v_mfma_f32_16x16x32_bf16 v[100:103], v[180:183], v[112:115], v[100:103]
	global_load_dwordx4 v[112:115], v249, s[6:7] offset:1792
	v_mfma_f32_16x16x32_bf16 v[50:53], v[172:175], v[120:123], v[50:53]
	s_waitcnt vmcnt(8)
	ds_write_b128 v19, v[78:81] offset:57344
	v_mfma_f32_16x16x32_bf16 v[62:65], v[176:179], v[120:123], v[62:65]
	v_mfma_f32_16x16x32_bf16 v[74:77], v[180:183], v[120:123], v[74:77]
	v_mfma_f32_16x16x32_bf16 v[34:37], v[184:187], v[120:123], v[34:37]
	global_load_dwordx4 v[78:81], v250, s[6:7] offset:1792
	v_mfma_f32_16x16x32_bf16 v[54:57], v[172:175], v[148:151], v[54:57]
	s_waitcnt vmcnt(8)
	ds_write_b128 v19, v[108:111] offset:61440
	v_mfma_f32_16x16x32_bf16 v[66:69], v[176:179], v[148:151], v[66:69]
	v_mfma_f32_16x16x32_bf16 v[70:73], v[180:183], v[148:151], v[70:73]
	v_mfma_f32_16x16x32_bf16 v[38:41], v[184:187], v[148:151], v[38:41]
	s_setprio 0
	s_waitcnt lgkmcnt(0)
	s_barrier
	ds_read_b128 v[108:111], v22 offset:32768
	ds_read_b128 v[120:123], v22 offset:34816
	ds_read_b128 v[132:135], v23 offset:49152
	ds_read_b128 v[140:143], v23 offset:51200
	ds_read_b128 v[148:151], v22 offset:36864
	ds_read_b128 v[152:155], v22 offset:38912
	ds_read_b128 v[156:159], v23 offset:53248
	ds_read_b128 v[160:163], v23 offset:55296
	s_setprio 2
	global_load_dwordx4 v[168:171], v24, s[36:37] offset:1920
	s_waitcnt vmcnt(8)
	ds_write_b128 v19, v[164:167]
	ds_read_b128 v[164:167], v20 offset:32768
	ds_read_b128 v[172:175], v21 offset:49152
	s_waitcnt lgkmcnt(8)
	v_mfma_f32_16x16x32_bf16 v[42:45], v[132:135], v[108:111], v[42:45]
	s_waitcnt lgkmcnt(3)
	v_mfma_f32_16x16x32_bf16 v[26:29], v[160:163], v[108:111], v[26:29]
	v_mfma_f32_16x16x32_bf16 v[96:99], v[140:143], v[108:111], v[96:99]
	v_mfma_f32_16x16x32_bf16 v[104:107], v[156:159], v[108:111], v[104:107]
	global_load_dwordx4 v[108:111], v245, s[36:37] offset:1920
	v_mfma_f32_16x16x32_bf16 v[46:49], v[132:135], v[120:123], v[46:49]
	s_waitcnt vmcnt(8)
	ds_write_b128 v19, v[92:95] offset:4096
	v_mfma_f32_16x16x32_bf16 v[58:61], v[140:143], v[120:123], v[58:61]
	ds_read_b128 v[92:95], v20 offset:34816
	v_mfma_f32_16x16x32_bf16 v[30:33], v[160:163], v[120:123], v[30:33]
	ds_read_b128 v[176:179], v21 offset:51200
	v_mfma_f32_16x16x32_bf16 v[100:103], v[156:159], v[120:123], v[100:103]
	global_load_dwordx4 v[120:123], v246, s[36:37] offset:1920
	v_mfma_f32_16x16x32_bf16 v[50:53], v[132:135], v[148:151], v[50:53]
	s_waitcnt vmcnt(8)
	ds_write_b128 v19, v[116:119] offset:8192
	v_mfma_f32_16x16x32_bf16 v[62:65], v[140:143], v[148:151], v[62:65]
	ds_read_b128 v[116:119], v20 offset:36864
	v_mfma_f32_16x16x32_bf16 v[74:77], v[156:159], v[148:151], v[74:77]
	ds_read_b128 v[180:183], v21 offset:53248
	v_mfma_f32_16x16x32_bf16 v[34:37], v[160:163], v[148:151], v[34:37]
	v_add_u32_e32 v24, 0x30780, v24
	global_load_dwordx4 v[148:151], v24, s[36:37]
	s_waitcnt vmcnt(8)
	ds_write_b128 v19, v[144:147] offset:12288
	ds_read_b128 v[144:147], v20 offset:38912
	ds_read_b128 v[184:187], v21 offset:55296
	v_mfma_f32_16x16x32_bf16 v[54:57], v[132:135], v[152:155], v[54:57]
	v_mfma_f32_16x16x32_bf16 v[66:69], v[140:143], v[152:155], v[66:69]
	v_mfma_f32_16x16x32_bf16 v[70:73], v[156:159], v[152:155], v[70:73]
	v_mfma_f32_16x16x32_bf16 v[38:41], v[160:163], v[152:155], v[38:41]
	global_load_dwordx4 v[132:135], v18, s[6:7] offset:1920
	s_waitcnt vmcnt(8)
	ds_write_b128 v19, v[124:127] offset:16384
	s_waitcnt lgkmcnt(10)
	v_mfma_f32_16x16x32_bf16 v[42:45], v[172:175], v[164:167], v[42:45]
	s_waitcnt lgkmcnt(1)
	v_mfma_f32_16x16x32_bf16 v[24:27], v[184:187], v[164:167], v[26:29]
	v_mfma_f32_16x16x32_bf16 v[96:99], v[176:179], v[164:167], v[96:99]
	v_mfma_f32_16x16x32_bf16 v[104:107], v[180:183], v[164:167], v[104:107]
	s_nop 0
	global_load_dwordx4 v[124:127], v248, s[6:7] offset:1920
	s_waitcnt vmcnt(8)
	ds_write_b128 v19, v[136:139] offset:20480
	v_mfma_f32_16x16x32_bf16 v[46:49], v[172:175], v[92:95], v[46:49]
	v_mfma_f32_16x16x32_bf16 v[58:61], v[176:179], v[92:95], v[58:61]
	v_mfma_f32_16x16x32_bf16 v[28:31], v[184:187], v[92:95], v[30:33]
	v_mfma_f32_16x16x32_bf16 v[100:103], v[180:183], v[92:95], v[100:103]
	s_nop 1
	global_load_dwordx4 v[92:95], v249, s[6:7] offset:1920
	s_waitcnt vmcnt(8)
	ds_write_b128 v19, v[112:115] offset:24576
	v_mfma_f32_16x16x32_bf16 v[50:53], v[172:175], v[116:119], v[50:53]
	v_mfma_f32_16x16x32_bf16 v[62:65], v[176:179], v[116:119], v[62:65]
	v_mfma_f32_16x16x32_bf16 v[74:77], v[180:183], v[116:119], v[74:77]
	v_mfma_f32_16x16x32_bf16 v[32:35], v[184:187], v[116:119], v[34:37]
	v_add_u32_e32 v18, 0x30780, v18
	global_load_dwordx4 v[112:115], v18, s[6:7]
	s_waitcnt vmcnt(8)
	ds_write_b128 v19, v[78:81] offset:28672
	v_mfma_f32_16x16x32_bf16 v[54:57], v[172:175], v[144:147], v[54:57]
	v_mfma_f32_16x16x32_bf16 v[66:69], v[176:179], v[144:147], v[66:69]
	v_mfma_f32_16x16x32_bf16 v[70:73], v[180:183], v[144:147], v[70:73]
	v_mfma_f32_16x16x32_bf16 v[36:39], v[184:187], v[144:147], v[38:41]
	s_setprio 0
	s_waitcnt lgkmcnt(0)
	s_barrier
; template <int MODE>
; __device__ __forceinline__ void gemm_tile(const Params& P, int tm, int tn, unsigned char* smem) {
;     ...
;     for (int kt = 0; kt < 16; ++kt) {
;         unsigned char* sA = (kt & 1) ? sA1 : sA0; unsigned char* sB = (kt & 1) ? sB1 : sB0;
;         unsigned char* nA = (kt & 1) ? sA0 : sA1; unsigned char* nB = (kt & 1) ? sB0 : sB1;
;         bf16x8 fa[4], fb[4], ga[4], gb[4];
;         const int ch0 = ((g ^ sw) << 4), ch1 = (((4 + g) ^ sw) << 4);
;         const unsigned ko = (unsigned)(kt + 2) * 128u;
;         const unsigned koa = ko + ((MODE == 2 && kt + 2 >= 8) ? (unsigned)(ZC_FQ - 512) * 2u : 0u);
;         const bool wr_ok = kt < 15, ld_ok = kt < 14;
; #pragma unroll
;         for (int i = 0; i < 4; ++i) { fa[i] = *(const bf16x8*)(sA + arow_off + i * 2048 + ch0); fb[i] = *(const bf16x8*)(sB + brow_off + i * 2048 + ch0); }
;         __builtin_amdgcn_sched_barrier(0);
;         __builtin_amdgcn_s_setprio(2);
;         if (wr_ok) *(uint4*)(nA + soff0) = ra0;
;         if (ld_ok) ra0 = *(const uint4*)(Ab + (aoff + 0u * LDA + koa));
;         ga[0] = *(const bf16x8*)(sA + arow_off + 0 * 2048 + ch1); gb[0] = *(const bf16x8*)(sB + brow_off + 0 * 2048 + ch1);
;         __builtin_amdgcn_sched_barrier(0);
; #pragma unroll
;         for (int j = 0; j < 4; ++j) acc[0][j] = __builtin_amdgcn_mfma_f32_16x16x32_bf16(fb[j], fa[0], acc[0][j], 0, 0, 0);
;         __builtin_amdgcn_sched_barrier(0);
;         if (wr_ok) *(uint4*)(nA + soff0 + 4096) = ra1;
;         if (ld_ok) ra1 = *(const uint4*)(Ab + (aoff + 32u * LDA + koa));
;         ga[1] = *(const bf16x8*)(sA + arow_off + 1 * 2048 + ch1); gb[1] = *(const bf16x8*)(sB + brow_off + 1 * 2048 + ch1);
;         __builtin_amdgcn_sched_barrier(0);
; #pragma unroll
;         for (int j = 0; j < 4; ++j) acc[1][j] = __builtin_amdgcn_mfma_f32_16x16x32_bf16(fb[j], fa[1], acc[1][j], 0, 0, 0);
;         __builtin_amdgcn_sched_barrier(0);
;         if (wr_ok) *(uint4*)(nA + soff0 + 8192) = ra2;
;         if (ld_ok) ra2 = *(const uint4*)(Ab + (aoff + 64u * LDA + koa));
;         ga[2] = *(const bf16x8*)(sA + arow_off + 2 * 2048 + ch1); gb[2] = *(const bf16x8*)(sB + brow_off + 2 * 2048 + ch1);
;         __builtin_amdgcn_sched_barrier(0);
; #pragma unroll
;         for (int j = 0; j < 4; ++j) acc[2][j] = __builtin_amdgcn_mfma_f32_16x16x32_bf16(fb[j], fa[2], acc[2][j], 0, 0, 0);
	ds_read_b128 v[78:81], v22
	ds_read_b128 v[116:119], v22 offset:2048
	ds_read_b128 v[136:139], v23 offset:16384
	ds_read_b128 v[140:143], v23 offset:18432
	ds_read_b128 v[144:147], v22 offset:4096
	ds_read_b128 v[152:155], v22 offset:6144
	ds_read_b128 v[156:159], v23 offset:20480
	ds_read_b128 v[160:163], v23 offset:22528
	s_setprio 2
	s_waitcnt vmcnt(7)
	ds_write_b128 v19, v[168:171] offset:32768
	ds_read_b128 v[164:167], v20
	ds_read_b128 v[168:171], v21 offset:16384
	s_waitcnt lgkmcnt(8)
	v_mfma_f32_16x16x32_bf16 v[40:43], v[136:139], v[78:81], v[42:45]
	s_waitcnt lgkmcnt(3)
	v_mfma_f32_16x16x32_bf16 v[24:27], v[160:163], v[78:81], v[24:27]
	v_mfma_f32_16x16x32_bf16 v[96:99], v[140:143], v[78:81], v[96:99]
	v_mfma_f32_16x16x32_bf16 v[104:107], v[156:159], v[78:81], v[104:107]
	v_mfma_f32_16x16x32_bf16 v[44:47], v[136:139], v[116:119], v[46:49]
	s_waitcnt vmcnt(6)
	ds_write_b128 v19, v[108:111] offset:36864
	v_mfma_f32_16x16x32_bf16 v[58:61], v[140:143], v[116:119], v[58:61]
	ds_read_b128 v[78:81], v20 offset:2048
	v_mfma_f32_16x16x32_bf16 v[28:31], v[160:163], v[116:119], v[28:31]
	ds_read_b128 v[108:111], v21 offset:18432
	v_mfma_f32_16x16x32_bf16 v[100:103], v[156:159], v[116:119], v[100:103]
	v_mfma_f32_16x16x32_bf16 v[48:51], v[136:139], v[144:147], v[50:53]
	s_waitcnt vmcnt(5)
	ds_write_b128 v19, v[120:123] offset:40960
	v_mfma_f32_16x16x32_bf16 v[62:65], v[140:143], v[144:147], v[62:65]
	ds_read_b128 v[116:119], v20 offset:4096
	v_mfma_f32_16x16x32_bf16 v[74:77], v[156:159], v[144:147], v[74:77]
	ds_read_b128 v[120:123], v21 offset:20480
	v_mfma_f32_16x16x32_bf16 v[32:35], v[160:163], v[144:147], v[32:35]
	v_mfma_f32_16x16x32_bf16 v[52:55], v[136:139], v[152:155], v[54:57]
	s_waitcnt vmcnt(4)
	ds_write_b128 v19, v[148:151] offset:45056
	v_mfma_f32_16x16x32_bf16 v[66:69], v[140:143], v[152:155], v[66:69]
	ds_read_b128 v[144:147], v20 offset:6144
	v_mfma_f32_16x16x32_bf16 v[70:73], v[156:159], v[152:155], v[70:73]
	ds_read_b128 v[148:151], v21 offset:22528
	v_mfma_f32_16x16x32_bf16 v[36:39], v[160:163], v[152:155], v[36:39]
	s_waitcnt vmcnt(3)
	ds_write_b128 v19, v[132:135] offset:49152
	s_waitcnt lgkmcnt(10)
	v_mfma_f32_16x16x32_bf16 v[40:43], v[168:171], v[164:167], v[40:43]
	s_waitcnt lgkmcnt(1)
	v_mfma_f32_16x16x32_bf16 v[24:27], v[148:151], v[164:167], v[24:27]
	v_mfma_f32_16x16x32_bf16 v[96:99], v[108:111], v[164:167], v[96:99]
	v_mfma_f32_16x16x32_bf16 v[104:107], v[120:123], v[164:167], v[104:107]
	v_mfma_f32_16x16x32_bf16 v[44:47], v[168:171], v[78:81], v[44:47]
	s_waitcnt vmcnt(2)
	ds_write_b128 v19, v[124:127] offset:53248
	v_mfma_f32_16x16x32_bf16 v[56:59], v[108:111], v[78:81], v[58:61]
	v_mfma_f32_16x16x32_bf16 v[28:31], v[148:151], v[78:81], v[28:31]
	v_mfma_f32_16x16x32_bf16 v[100:103], v[120:123], v[78:81], v[100:103]
	v_mfma_f32_16x16x32_bf16 v[48:51], v[168:171], v[116:119], v[48:51]
	s_waitcnt vmcnt(1)
	ds_write_b128 v19, v[92:95] offset:57344
	v_mfma_f32_16x16x32_bf16 v[60:63], v[108:111], v[116:119], v[62:65]
	v_mfma_f32_16x16x32_bf16 v[74:77], v[120:123], v[116:119], v[74:77]
	v_mfma_f32_16x16x32_bf16 v[32:35], v[148:151], v[116:119], v[32:35]
	v_mfma_f32_16x16x32_bf16 v[52:55], v[168:171], v[144:147], v[52:55]
	s_waitcnt vmcnt(0)
	ds_write_b128 v19, v[112:115] offset:61440
	v_mfma_f32_16x16x32_bf16 v[64:67], v[108:111], v[144:147], v[66:69]
	v_mfma_f32_16x16x32_bf16 v[68:71], v[120:123], v[144:147], v[70:73]
	v_mfma_f32_16x16x32_bf16 v[36:39], v[148:151], v[144:147], v[36:39]
	s_setprio 0
	s_waitcnt lgkmcnt(0)
	s_barrier
; template <int MODE>
; __device__ __forceinline__ void gemm_tile(const Params& P, int tm, int tn, unsigned char* smem) {
;     ...
;     for (int kt = 0; kt < 16; ++kt) {
;         unsigned char* sA = (kt & 1) ? sA1 : sA0; unsigned char* sB = (kt & 1) ? sB1 : sB0;
;         unsigned char* nA = (kt & 1) ? sA0 : sA1; unsigned char* nB = (kt & 1) ? sB0 : sB1;
;         bf16x8 fa[4], fb[4], ga[4], gb[4];
;         const int ch0 = ((g ^ sw) << 4), ch1 = (((4 + g) ^ sw) << 4);
;         const unsigned ko = (unsigned)(kt + 2) * 128u;
;         const unsigned koa = ko + ((MODE == 2 && kt + 2 >= 8) ? (unsigned)(ZC_FQ - 512) * 2u : 0u);
;         const bool wr_ok = kt < 15, ld_ok = kt < 14;
; #pragma unroll
;         for (int i = 0; i < 4; ++i) { fa[i] = *(const bf16x8*)(sA + arow_off + i * 2048 + ch0); fb[i] = *(const bf16x8*)(sB + brow_off + i * 2048 + ch0); }
;         __builtin_amdgcn_sched_barrier(0);
;         __builtin_amdgcn_s_setprio(2);
;         if (wr_ok) *(uint4*)(nA + soff0) = ra0;
;         if (ld_ok) ra0 = *(const uint4*)(Ab + (aoff + 0u * LDA + koa));
;         ga[0] = *(const bf16x8*)(sA + arow_off + 0 * 2048 + ch1); gb[0] = *(const bf16x8*)(sB + brow_off + 0 * 2048 + ch1);
;         __builtin_amdgcn_sched_barrier(0);
; #pragma unroll
;         for (int j = 0; j < 4; ++j) acc[0][j] = __builtin_amdgcn_mfma_f32_16x16x32_bf16(fb[j], fa[0], acc[0][j], 0, 0, 0);
;         __builtin_amdgcn_sched_barrier(0);
;         if (wr_ok) *(uint4*)(nA + soff0 + 4096) = ra1;
;         if (ld_ok) ra1 = *(const uint4*)(Ab + (aoff + 32u * LDA + koa));
;         ga[1] = *(const bf16x8*)(sA + arow_off + 1 * 2048 + ch1); gb[1] = *(const bf16x8*)(sB + brow_off + 1 * 2048 + ch1);
;         __builtin_amdgcn_sched_barrier(0);
; #pragma unroll
;         for (int j = 0; j < 4; ++j) acc[1][j] = __builtin_amdgcn_mfma_f32_16x16x32_bf16(fb[j], fa[1], acc[1][j], 0, 0, 0);
;         __builtin_amdgcn_sched_barrier(0);
;         if (wr_ok) *(uint4*)(nA + soff0 + 8192) = ra2;
;         if (ld_ok) ra2 = *(const uint4*)(Ab + (aoff + 64u * LDA + koa));
;         ga[2] = *(const bf16x8*)(sA + arow_off + 2 * 2048 + ch1); gb[2] = *(const bf16x8*)(sB + brow_off + 2 * 2048 + ch1);
;         __builtin_amdgcn_sched_barrier(0);
; #pragma unroll
;         for (int j = 0; j < 4; ++j) acc[2][j] = __builtin_amdgcn_mfma_f32_16x16x32_bf16(fb[j], fa[2], acc[2][j], 0, 0, 0);
	ds_read_b128 v[78:81], v22 offset:32768
	ds_read_b128 v[92:95], v22 offset:34816
	ds_read_b128 v[108:111], v23 offset:49152
	ds_read_b128 v[112:115], v23 offset:51200
	ds_read_b128 v[116:119], v22 offset:36864
	ds_read_b128 v[120:123], v22 offset:38912
	ds_read_b128 v[124:127], v23 offset:53248
	ds_read_b128 v[132:135], v23 offset:55296
	s_setprio 2
	ds_read_b128 v[136:139], v20 offset:32768
	ds_read_b128 v[140:143], v21 offset:49152
	s_waitcnt lgkmcnt(7)
	v_mfma_f32_16x16x32_bf16 v[40:43], v[108:111], v[78:81], v[40:43]
	s_waitcnt lgkmcnt(2)
	v_mfma_f32_16x16x32_bf16 v[22:25], v[132:135], v[78:81], v[24:27]
	v_mfma_f32_16x16x32_bf16 v[96:99], v[112:115], v[78:81], v[96:99]
	v_mfma_f32_16x16x32_bf16 v[104:107], v[124:127], v[78:81], v[104:107]
	v_mfma_f32_16x16x32_bf16 v[44:47], v[108:111], v[92:95], v[44:47]
	ds_read_b128 v[144:147], v20 offset:34816
	v_mfma_f32_16x16x32_bf16 v[56:59], v[112:115], v[92:95], v[56:59]
	ds_read_b128 v[148:151], v21 offset:51200
	v_mfma_f32_16x16x32_bf16 v[26:29], v[132:135], v[92:95], v[28:31]
	v_mfma_f32_16x16x32_bf16 v[100:103], v[124:127], v[92:95], v[100:103]
	v_mfma_f32_16x16x32_bf16 v[30:33], v[132:135], v[116:119], v[32:35]
	ds_read_b128 v[92:95], v20 offset:36864
	v_mfma_f32_16x16x32_bf16 v[156:159], v[108:111], v[116:119], v[48:51]
	ds_read_b128 v[152:155], v21 offset:53248
	v_mfma_f32_16x16x32_bf16 v[160:163], v[112:115], v[116:119], v[60:63]
	v_mfma_f32_16x16x32_bf16 v[164:167], v[124:127], v[116:119], v[74:77]
	v_mfma_f32_16x16x32_bf16 v[108:111], v[108:111], v[120:123], v[52:55]
	ds_read_b128 v[116:119], v20 offset:38912
	v_mfma_f32_16x16x32_bf16 v[112:115], v[112:115], v[120:123], v[64:67]
	ds_read_b128 v[18:21], v21 offset:55296
	v_mfma_f32_16x16x32_bf16 v[124:127], v[124:127], v[120:123], v[68:71]
	v_mfma_f32_16x16x32_bf16 v[120:123], v[132:135], v[120:123], v[36:39]
	s_waitcnt lgkmcnt(6)
	v_mfma_f32_16x16x32_bf16 v[78:81], v[140:143], v[136:139], v[40:43]
	s_waitcnt lgkmcnt(4)
	v_mfma_f32_16x16x32_bf16 v[74:77], v[148:151], v[136:139], v[96:99]
	s_waitcnt lgkmcnt(2)
	v_mfma_f32_16x16x32_bf16 v[70:73], v[152:155], v[136:139], v[104:107]
	s_waitcnt lgkmcnt(0)
	v_mfma_f32_16x16x32_bf16 v[66:69], v[18:21], v[136:139], v[22:25]
	v_mfma_f32_16x16x32_bf16 v[62:65], v[140:143], v[144:147], v[44:47]
	v_mfma_f32_16x16x32_bf16 v[58:61], v[148:151], v[144:147], v[56:59]
	v_mfma_f32_16x16x32_bf16 v[54:57], v[152:155], v[144:147], v[100:103]
	v_mfma_f32_16x16x32_bf16 v[50:53], v[18:21], v[144:147], v[26:29]
	v_mfma_f32_16x16x32_bf16 v[46:49], v[140:143], v[92:95], v[156:159]
	v_mfma_f32_16x16x32_bf16 v[42:45], v[148:151], v[92:95], v[160:163]
	v_mfma_f32_16x16x32_bf16 v[38:41], v[152:155], v[92:95], v[164:167]
	v_mfma_f32_16x16x32_bf16 v[34:37], v[18:21], v[92:95], v[30:33]
	v_mfma_f32_16x16x32_bf16 v[30:33], v[140:143], v[116:119], v[108:111]
	v_mfma_f32_16x16x32_bf16 v[26:29], v[148:151], v[116:119], v[112:115]
	v_mfma_f32_16x16x32_bf16 v[22:25], v[152:155], v[116:119], v[124:127]
	v_mfma_f32_16x16x32_bf16 v[18:21], v[18:21], v[116:119], v[120:123]
	s_setprio 0
	v_add_f32_e32 v10, v10, v11
	v_add_f32_e32 v11, v12, v13
	v_add_f32_e32 v10, v10, v11
	v_mov_b32_e32 v11, v10
	s_nop 1
	v_permlane32_swap_b32_e32 v10, v11
	v_add_f32_e32 v10, v10, v11
	v_mov_b32_e32 v11, v10
	s_nop 1
	v_permlane16_swap_b32_e32 v10, v11
	v_add_f32_e32 v10, v10, v11
	v_fmamk_f32 v10, v10, 0x3a800000, v86
	v_mul_f32_e32 v11, 0x4b800000, v10
	v_cmp_gt_f32_e64 s[0:1], s19, v10
	v_lshl_add_u64 v[84:85], v[84:85], 2, s[8:9]
	s_nop 0
	v_cndmask_b32_e64 v10, v10, v11, s[0:1]
	v_rsq_f32_e32 v10, v10
	v_or3_b32 v11, v91, s2, v89
	v_cmp_eq_u32_e32 vcc, 0, v11
	s_barrier
	v_mul_f32_e32 v11, 0x45800000, v10
	v_cndmask_b32_e64 v12, v10, v11, s[0:1]
	s_and_saveexec_b64 s[0:1], vcc
	s_cbranch_execz .LBB0_1265
	global_store_dword v[84:85], v12, off
